# hand-scheduled FoX 128-key step and DSA 64-key step; counted vmcnt(2) in 64-key attention loops; flat->global
# speedup vs baseline: 1.0432x; 1.0141x over previous
.LBB0_27:
	v_add_u32_e32 v15, 0x1450, v14
	ds_write2_b32 v15, v12, v13 offset1:1
	v_pk_mul_f32 v[12:13], v[72:73], v[6:7] op_sel_hi:[1,0]
	v_add_u32_e32 v6, 0x1658, v14
	ds_write2_b32 v6, v12, v13 offset1:1
	s_add_u32 s4, s50, s84
	s_waitcnt lgkmcnt(0)
	s_addc_u32 s5, s51, s83
	ds_read_b32 v12, v84
	ds_read_b32 v13, v84 offset:260
	ds_read_b32 v16, v84 offset:520
	ds_read_b32 v17, v84 offset:780
	ds_read_b32 v18, v84 offset:1040
	ds_read_b32 v19, v84 offset:1300
	ds_read_b32 v20, v84 offset:1560
	ds_read_b32 v21, v84 offset:1820
	v_lshl_add_u64 v[10:11], v[10:11], 1, s[4:5]
	v_lshlrev_b32_e32 v6, 1, v4
	v_lshl_add_u64 v[14:15], v[10:11], 0, v[6:7]
	s_waitcnt lgkmcnt(4)
	v_cvt_pk_bf16_f32 v11, v16, v17
	v_add3_u32 v16, v83, v129, v131
	v_ashrrev_i32_e32 v17, 31, v16
	v_cvt_pk_bf16_f32 v10, v12, v13
	s_waitcnt lgkmcnt(2)
	v_cvt_pk_bf16_f32 v12, v18, v19
	v_lshlrev_b64 v[18:19], 11, v[16:17]
	s_waitcnt lgkmcnt(0)
	v_cvt_pk_bf16_f32 v13, v20, v21
	v_lshl_add_u64 v[18:19], v[14:15], 0, v[18:19]
	global_store_dwordx4 v[18:19], v[10:13], off
	ds_read_b32 v6, v84 offset:32
	ds_read_b32 v10, v84 offset:292
	ds_read_b32 v11, v84 offset:552
	ds_read_b32 v12, v84 offset:812
	ds_read_b32 v13, v84 offset:1072
	ds_read_b32 v17, v84 offset:1332
	ds_read_b32 v18, v84 offset:1592
	ds_read_b32 v19, v84 offset:1852
	s_waitcnt lgkmcnt(0)
	v_cvt_pk_bf16_f32 v11, v11, v12
	v_cvt_pk_bf16_f32 v10, v6, v10
	v_cvt_pk_bf16_f32 v12, v13, v17
	v_cvt_pk_bf16_f32 v13, v18, v19
	v_add_u32_e32 v18, 8, v16
	v_ashrrev_i32_e32 v19, 31, v18
	v_lshlrev_b64 v[18:19], 11, v[18:19]
	v_lshl_add_u64 v[18:19], v[14:15], 0, v[18:19]
	global_store_dwordx4 v[18:19], v[10:13], off
	ds_read_b32 v6, v84 offset:64
	ds_read_b32 v10, v84 offset:324
	ds_read_b32 v11, v84 offset:584
	ds_read_b32 v12, v84 offset:844
	ds_read_b32 v13, v84 offset:1104
	ds_read_b32 v17, v84 offset:1364
	ds_read_b32 v18, v84 offset:1624
	ds_read_b32 v19, v84 offset:1884
	s_waitcnt lgkmcnt(0)
	v_cvt_pk_bf16_f32 v11, v11, v12
	v_cvt_pk_bf16_f32 v10, v6, v10
	v_cvt_pk_bf16_f32 v12, v13, v17
	v_cvt_pk_bf16_f32 v13, v18, v19
	v_add_u32_e32 v18, 16, v16
	v_ashrrev_i32_e32 v19, 31, v18
	v_lshlrev_b64 v[18:19], 11, v[18:19]
	v_lshl_add_u64 v[18:19], v[14:15], 0, v[18:19]
	global_store_dwordx4 v[18:19], v[10:13], off
	ds_read_b32 v6, v84 offset:96
	ds_read_b32 v10, v84 offset:356
	ds_read_b32 v11, v84 offset:616
	ds_read_b32 v12, v84 offset:876
	ds_read_b32 v13, v84 offset:1136
	ds_read_b32 v17, v84 offset:1396
	ds_read_b32 v18, v84 offset:1656
	ds_read_b32 v19, v84 offset:1916
	s_waitcnt lgkmcnt(0)
	v_cvt_pk_bf16_f32 v11, v11, v12
	v_cvt_pk_bf16_f32 v10, v6, v10
	v_cvt_pk_bf16_f32 v12, v13, v17
	v_cvt_pk_bf16_f32 v13, v18, v19
	v_add_u32_e32 v18, 24, v16
	v_ashrrev_i32_e32 v19, 31, v18
	v_lshlrev_b64 v[18:19], 11, v[18:19]
	v_lshl_add_u64 v[18:19], v[14:15], 0, v[18:19]
	global_store_dwordx4 v[18:19], v[10:13], off
	ds_read_b32 v6, v84 offset:128
	ds_read_b32 v10, v84 offset:388
	ds_read_b32 v11, v84 offset:648
	ds_read_b32 v12, v84 offset:908
	ds_read_b32 v13, v84 offset:1168
	ds_read_b32 v17, v84 offset:1428
	ds_read_b32 v18, v84 offset:1688
	ds_read_b32 v19, v84 offset:1948
	s_waitcnt lgkmcnt(0)
	v_cvt_pk_bf16_f32 v11, v11, v12
	v_cvt_pk_bf16_f32 v10, v6, v10
	v_cvt_pk_bf16_f32 v12, v13, v17
	v_cvt_pk_bf16_f32 v13, v18, v19
	v_add_u32_e32 v18, 32, v16
	v_ashrrev_i32_e32 v19, 31, v18
	v_lshlrev_b64 v[18:19], 11, v[18:19]
	v_lshl_add_u64 v[18:19], v[14:15], 0, v[18:19]
	global_store_dwordx4 v[18:19], v[10:13], off
	ds_read_b32 v6, v84 offset:160
	ds_read_b32 v10, v84 offset:420
	ds_read_b32 v11, v84 offset:680
	ds_read_b32 v12, v84 offset:940
	ds_read_b32 v13, v84 offset:1200
	ds_read_b32 v17, v84 offset:1460
	ds_read_b32 v18, v84 offset:1720
	ds_read_b32 v19, v84 offset:1980
	s_waitcnt lgkmcnt(0)
	v_cvt_pk_bf16_f32 v11, v11, v12
	v_cvt_pk_bf16_f32 v10, v6, v10
	v_cvt_pk_bf16_f32 v12, v13, v17
	v_cvt_pk_bf16_f32 v13, v18, v19
	v_add_u32_e32 v18, 40, v16
	v_ashrrev_i32_e32 v19, 31, v18
	v_lshlrev_b64 v[18:19], 11, v[18:19]
	v_lshl_add_u64 v[18:19], v[14:15], 0, v[18:19]
	global_store_dwordx4 v[18:19], v[10:13], off
	ds_read_b32 v6, v84 offset:192
	ds_read_b32 v10, v84 offset:452
	ds_read_b32 v11, v84 offset:712
	ds_read_b32 v12, v84 offset:972
	ds_read_b32 v13, v84 offset:1232
	ds_read_b32 v17, v84 offset:1492
	ds_read_b32 v18, v84 offset:1752
	ds_read_b32 v19, v84 offset:2012
	s_waitcnt lgkmcnt(0)
	v_cvt_pk_bf16_f32 v11, v11, v12
	v_cvt_pk_bf16_f32 v10, v6, v10
	v_cvt_pk_bf16_f32 v12, v13, v17
	v_cvt_pk_bf16_f32 v13, v18, v19
	v_add_u32_e32 v18, 48, v16
	v_ashrrev_i32_e32 v19, 31, v18
	v_lshlrev_b64 v[18:19], 11, v[18:19]
	v_lshl_add_u64 v[18:19], v[14:15], 0, v[18:19]
	global_store_dwordx4 v[18:19], v[10:13], off
	ds_read_b32 v6, v84 offset:224
	ds_read_b32 v10, v84 offset:484
	ds_read_b32 v11, v84 offset:744
	ds_read_b32 v12, v84 offset:1004
	ds_read_b32 v13, v84 offset:1264
	ds_read_b32 v17, v84 offset:1524
	ds_read_b32 v18, v84 offset:1784
	ds_read_b32 v19, v84 offset:2044
	v_add_u32_e32 v16, 56, v16
	s_waitcnt lgkmcnt(0)
	v_cvt_pk_bf16_f32 v11, v11, v12
	v_cvt_pk_bf16_f32 v12, v13, v17
	v_ashrrev_i32_e32 v17, 31, v16
	v_lshlrev_b64 v[16:17], 11, v[16:17]
	v_cvt_pk_bf16_f32 v10, v6, v10
	v_cvt_pk_bf16_f32 v13, v18, v19
	v_lshl_add_u64 v[14:15], v[14:15], 0, v[16:17]
	global_store_dwordx4 v[14:15], v[10:13], off
	s_waitcnt lgkmcnt(0)

.LBB0_29:
	v_add_u32_e32 v6, 0x3c0, v128
	v_cmp_lt_i32_e32 vcc, s25, v6
	s_and_saveexec_b64 s[4:5], vcc
	s_xor_b64 s[48:49], exec, s[4:5]
	s_cbranch_execz .LBB0_254
	v_cmp_lt_u32_e32 vcc, s65, v6
	s_and_saveexec_b64 s[4:5], vcc
	s_xor_b64 s[50:51], exec, s[4:5]
	s_cbranch_execz .LBB0_187
	v_cmp_lt_u32_e32 vcc, s66, v6
	s_and_saveexec_b64 s[4:5], vcc
	s_xor_b64 s[52:53], exec, s[4:5]
	s_cbranch_execz .LBB0_97
	v_lshlrev_b32_e32 v6, 6, v130
	v_and_b32_e32 v11, 0xfffffc00, v6
	v_lshl_add_u32 v6, v128, 2, v125
	v_and_b32_e32 v10, 0xffffffc0, v6
	v_add_u32_e32 v6, v113, v129
	s_mov_b64 s[4:5], s[14:15]
	v_sub_u32_e32 v6, v6, v11
	s_add_u32 s56, s4, s82
	v_cmp_gt_i32_e32 vcc, s67, v6
	s_addc_u32 s57, s5, s81
	v_or_b32_e32 v12, v10, v2
	v_cndmask_b32_e32 v6, -1, v6, vcc
	s_mov_b64 s[54:55], s[22:23]
	v_cmp_lt_i32_e64 s[4:5], -1, v6
	v_lshl_add_u64 v[16:17], v[6:7], 2, s[56:57]
	v_mov_b32_e32 v14, 0
	v_lshlrev_b32_e32 v6, 10, v12
	v_mov_b32_e32 v12, 0
	v_mov_b32_e32 v13, 0
	s_and_saveexec_b64 s[56:57], s[4:5]
	s_cbranch_execz .LBB0_34
	v_lshl_add_u64 v[12:13], v[6:7], 2, v[16:17]
	global_load_dwordx2 v[12:13], v[12:13], off
.LBB0_34:
	s_or_b64 exec, exec, s[56:57]
	v_mov_b32_e32 v15, 0
	s_and_saveexec_b64 s[56:57], s[4:5]
	s_cbranch_execz .LBB0_36
	v_lshl_add_u64 v[14:15], v[6:7], 2, v[16:17]
	v_add_co_u32_e32 v14, vcc, 0x2000, v14
	s_nop 1
	v_addc_co_u32_e32 v15, vcc, 0, v15, vcc
	global_load_dwordx2 v[14:15], v[14:15], off
.LBB0_36:
	s_or_b64 exec, exec, s[56:57]
	v_mov_b32_e32 v18, 0
	v_mov_b32_e32 v20, 0
	v_mov_b32_e32 v21, 0
	s_and_saveexec_b64 s[56:57], s[4:5]
	s_cbranch_execz .LBB0_38
	v_lshl_add_u64 v[20:21], v[6:7], 2, v[16:17]
	v_add_co_u32_e32 v20, vcc, 0x4000, v20
	s_nop 1
	v_addc_co_u32_e32 v21, vcc, 0, v21, vcc
	global_load_dwordx2 v[20:21], v[20:21], off
.LBB0_38:
	s_or_b64 exec, exec, s[56:57]
	v_mov_b32_e32 v19, 0
	s_and_saveexec_b64 s[56:57], s[4:5]
	s_cbranch_execz .LBB0_40
	v_lshl_add_u64 v[18:19], v[6:7], 2, v[16:17]
	v_add_co_u32_e32 v18, vcc, 0x6000, v18
	s_nop 1
	v_addc_co_u32_e32 v19, vcc, 0, v19, vcc
	global_load_dwordx2 v[18:19], v[18:19], off
.LBB0_40:
	s_or_b64 exec, exec, s[56:57]
	v_mov_b32_e32 v22, 0
	v_mov_b32_e32 v24, 0
	v_mov_b32_e32 v25, 0
	s_and_saveexec_b64 s[56:57], s[4:5]
	s_cbranch_execz .LBB0_42
	v_lshl_add_u64 v[24:25], v[6:7], 2, v[16:17]
	v_add_co_u32_e32 v24, vcc, 0x8000, v24
	s_nop 1
	v_addc_co_u32_e32 v25, vcc, 0, v25, vcc
	global_load_dwordx2 v[24:25], v[24:25], off
.LBB0_42:
	s_or_b64 exec, exec, s[56:57]
	v_mov_b32_e32 v23, 0
	s_and_saveexec_b64 s[56:57], s[4:5]
	s_cbranch_execz .LBB0_44
	v_lshl_add_u64 v[22:23], v[6:7], 2, v[16:17]
	v_add_co_u32_e32 v22, vcc, 0xa000, v22
	s_nop 1
	v_addc_co_u32_e32 v23, vcc, 0, v23, vcc
	global_load_dwordx2 v[22:23], v[22:23], off
.LBB0_44:
	s_or_b64 exec, exec, s[56:57]
	v_mov_b32_e32 v26, 0
	v_mov_b32_e32 v28, 0
	v_mov_b32_e32 v29, 0
	s_and_saveexec_b64 s[56:57], s[4:5]
	s_cbranch_execz .LBB0_46
	v_lshl_add_u64 v[28:29], v[6:7], 2, v[16:17]
	v_add_co_u32_e32 v28, vcc, 0xc000, v28
	s_nop 1
	v_addc_co_u32_e32 v29, vcc, 0, v29, vcc
	global_load_dwordx2 v[28:29], v[28:29], off
.LBB0_46:
	s_or_b64 exec, exec, s[56:57]
	v_mov_b32_e32 v27, 0
	s_and_saveexec_b64 s[56:57], s[4:5]
	s_cbranch_execz .LBB0_48
	v_lshl_add_u64 v[26:27], v[6:7], 2, v[16:17]
	v_add_co_u32_e32 v26, vcc, 0xe000, v26
	s_nop 1
	v_addc_co_u32_e32 v27, vcc, 0, v27, vcc
	global_load_dwordx2 v[26:27], v[26:27], off
.LBB0_48:
	s_or_b64 exec, exec, s[56:57]
	v_mov_b32_e32 v30, 0
	v_mov_b32_e32 v32, 0
	v_mov_b32_e32 v33, 0
	s_and_saveexec_b64 s[56:57], s[4:5]
	s_cbranch_execz .LBB0_50
	v_lshl_add_u64 v[32:33], v[6:7], 2, v[16:17]
	v_add_co_u32_e32 v32, vcc, 0x10000, v32
	s_nop 1
	v_addc_co_u32_e32 v33, vcc, 0, v33, vcc
	global_load_dwordx2 v[32:33], v[32:33], off
.LBB0_50:
	s_or_b64 exec, exec, s[56:57]
	v_mov_b32_e32 v31, 0
	s_and_saveexec_b64 s[56:57], s[4:5]
	s_cbranch_execz .LBB0_52
	v_lshl_add_u64 v[30:31], v[6:7], 2, v[16:17]
	v_add_co_u32_e32 v30, vcc, 0x12000, v30
	s_nop 1
	v_addc_co_u32_e32 v31, vcc, 0, v31, vcc
	global_load_dwordx2 v[30:31], v[30:31], off
.LBB0_52:
	s_or_b64 exec, exec, s[56:57]
	v_mov_b32_e32 v34, 0
	v_mov_b32_e32 v36, 0
	v_mov_b32_e32 v37, 0
	s_and_saveexec_b64 s[56:57], s[4:5]
	s_cbranch_execz .LBB0_54
	v_lshl_add_u64 v[36:37], v[6:7], 2, v[16:17]
	v_add_co_u32_e32 v36, vcc, 0x14000, v36
	s_nop 1
	v_addc_co_u32_e32 v37, vcc, 0, v37, vcc
	global_load_dwordx2 v[36:37], v[36:37], off
.LBB0_54:
	s_or_b64 exec, exec, s[56:57]
	v_mov_b32_e32 v35, 0
	s_and_saveexec_b64 s[56:57], s[4:5]
	s_cbranch_execz .LBB0_56
	v_lshl_add_u64 v[34:35], v[6:7], 2, v[16:17]
	v_add_co_u32_e32 v34, vcc, 0x16000, v34
	s_nop 1
	v_addc_co_u32_e32 v35, vcc, 0, v35, vcc
	global_load_dwordx2 v[34:35], v[34:35], off
.LBB0_56:
	s_or_b64 exec, exec, s[56:57]
	v_mov_b32_e32 v38, 0
	v_mov_b32_e32 v40, 0
	v_mov_b32_e32 v41, 0
	s_and_saveexec_b64 s[56:57], s[4:5]
	s_cbranch_execz .LBB0_58
	v_lshl_add_u64 v[40:41], v[6:7], 2, v[16:17]
	v_add_co_u32_e32 v40, vcc, 0x18000, v40
	s_nop 1
	v_addc_co_u32_e32 v41, vcc, 0, v41, vcc
	global_load_dwordx2 v[40:41], v[40:41], off
.LBB0_58:
	s_or_b64 exec, exec, s[56:57]
	v_mov_b32_e32 v39, 0
	s_and_saveexec_b64 s[56:57], s[4:5]
	s_cbranch_execz .LBB0_60
	v_lshl_add_u64 v[38:39], v[6:7], 2, v[16:17]
	v_add_co_u32_e32 v38, vcc, 0x1a000, v38
	s_nop 1
	v_addc_co_u32_e32 v39, vcc, 0, v39, vcc
	global_load_dwordx2 v[38:39], v[38:39], off
.LBB0_60:
	s_or_b64 exec, exec, s[56:57]
	v_mov_b32_e32 v42, 0
	v_mov_b32_e32 v44, 0
	v_mov_b32_e32 v45, 0
	s_and_saveexec_b64 s[56:57], s[4:5]
	s_cbranch_execz .LBB0_62
	v_lshl_add_u64 v[44:45], v[6:7], 2, v[16:17]
	v_add_co_u32_e32 v44, vcc, 0x1c000, v44
	s_nop 1
	v_addc_co_u32_e32 v45, vcc, 0, v45, vcc
	global_load_dwordx2 v[44:45], v[44:45], off
.LBB0_62:
	s_or_b64 exec, exec, s[56:57]
	v_mov_b32_e32 v43, 0
	s_and_saveexec_b64 s[56:57], s[4:5]
	s_cbranch_execz .LBB0_64
	v_lshl_add_u64 v[42:43], v[6:7], 2, v[16:17]
	v_add_co_u32_e32 v42, vcc, 0x1e000, v42
	s_nop 1
	v_addc_co_u32_e32 v43, vcc, 0, v43, vcc
	global_load_dwordx2 v[42:43], v[42:43], off
.LBB0_64:
	s_or_b64 exec, exec, s[56:57]
	v_mov_b32_e32 v46, 0
	v_mov_b32_e32 v48, 0
	v_mov_b32_e32 v49, 0
	s_and_saveexec_b64 s[56:57], s[4:5]
	s_cbranch_execz .LBB0_66
	v_lshl_add_u64 v[48:49], v[6:7], 2, v[16:17]
	v_add_co_u32_e32 v48, vcc, 0x20000, v48
	s_nop 1
	v_addc_co_u32_e32 v49, vcc, 0, v49, vcc
	global_load_dwordx2 v[48:49], v[48:49], off
.LBB0_66:
	s_or_b64 exec, exec, s[56:57]
	v_mov_b32_e32 v47, 0
	s_and_saveexec_b64 s[56:57], s[4:5]
	s_cbranch_execz .LBB0_68
	v_lshl_add_u64 v[46:47], v[6:7], 2, v[16:17]
	v_add_co_u32_e32 v46, vcc, 0x22000, v46
	s_nop 1
	v_addc_co_u32_e32 v47, vcc, 0, v47, vcc
	global_load_dwordx2 v[46:47], v[46:47], off
.LBB0_68:
	s_or_b64 exec, exec, s[56:57]
	v_mov_b32_e32 v50, 0
	v_mov_b32_e32 v52, 0
	v_mov_b32_e32 v53, 0
	s_and_saveexec_b64 s[56:57], s[4:5]
	s_cbranch_execz .LBB0_70
	v_lshl_add_u64 v[52:53], v[6:7], 2, v[16:17]
	v_add_co_u32_e32 v52, vcc, 0x24000, v52
	s_nop 1
	v_addc_co_u32_e32 v53, vcc, 0, v53, vcc
	global_load_dwordx2 v[52:53], v[52:53], off
.LBB0_70:
	s_or_b64 exec, exec, s[56:57]
	v_mov_b32_e32 v51, 0
	s_and_saveexec_b64 s[56:57], s[4:5]
	s_cbranch_execz .LBB0_72
	v_lshl_add_u64 v[50:51], v[6:7], 2, v[16:17]
	v_add_co_u32_e32 v50, vcc, 0x26000, v50
	s_nop 1
	v_addc_co_u32_e32 v51, vcc, 0, v51, vcc
	global_load_dwordx2 v[50:51], v[50:51], off
.LBB0_72:
	s_or_b64 exec, exec, s[56:57]
	v_mov_b32_e32 v54, 0
	v_mov_b32_e32 v56, 0
	v_mov_b32_e32 v57, 0
	s_and_saveexec_b64 s[56:57], s[4:5]
	s_cbranch_execz .LBB0_74
	v_lshl_add_u64 v[56:57], v[6:7], 2, v[16:17]
	v_add_co_u32_e32 v56, vcc, 0x28000, v56
	s_nop 1
	v_addc_co_u32_e32 v57, vcc, 0, v57, vcc
	global_load_dwordx2 v[56:57], v[56:57], off
.LBB0_74:
	s_or_b64 exec, exec, s[56:57]
	v_mov_b32_e32 v55, 0
	s_and_saveexec_b64 s[56:57], s[4:5]
	s_cbranch_execz .LBB0_76
	v_lshl_add_u64 v[54:55], v[6:7], 2, v[16:17]
	v_add_co_u32_e32 v54, vcc, 0x2a000, v54
	s_nop 1
	v_addc_co_u32_e32 v55, vcc, 0, v55, vcc
	global_load_dwordx2 v[54:55], v[54:55], off
.LBB0_76:
	s_or_b64 exec, exec, s[56:57]
	v_mov_b32_e32 v58, 0
	v_mov_b32_e32 v60, 0
	v_mov_b32_e32 v61, 0
	s_and_saveexec_b64 s[56:57], s[4:5]
	s_cbranch_execz .LBB0_78
	v_lshl_add_u64 v[60:61], v[6:7], 2, v[16:17]
	v_add_co_u32_e32 v60, vcc, 0x2c000, v60
	s_nop 1
	v_addc_co_u32_e32 v61, vcc, 0, v61, vcc
	global_load_dwordx2 v[60:61], v[60:61], off
.LBB0_78:
	s_or_b64 exec, exec, s[56:57]
	v_mov_b32_e32 v59, 0
	s_and_saveexec_b64 s[56:57], s[4:5]
	s_cbranch_execz .LBB0_80
	v_lshl_add_u64 v[58:59], v[6:7], 2, v[16:17]
	v_add_co_u32_e32 v58, vcc, 0x2e000, v58
	s_nop 1
	v_addc_co_u32_e32 v59, vcc, 0, v59, vcc
	global_load_dwordx2 v[58:59], v[58:59], off
.LBB0_80:
	s_or_b64 exec, exec, s[56:57]
	v_mov_b32_e32 v62, 0
	v_mov_b32_e32 v64, 0
	v_mov_b32_e32 v65, 0
	s_and_saveexec_b64 s[56:57], s[4:5]
	s_cbranch_execz .LBB0_82
	v_lshl_add_u64 v[64:65], v[6:7], 2, v[16:17]
	v_add_co_u32_e32 v64, vcc, 0x30000, v64
	s_nop 1
	v_addc_co_u32_e32 v65, vcc, 0, v65, vcc
	global_load_dwordx2 v[64:65], v[64:65], off
.LBB0_82:
	s_or_b64 exec, exec, s[56:57]
	v_mov_b32_e32 v63, 0
	s_and_saveexec_b64 s[56:57], s[4:5]
	s_cbranch_execz .LBB0_84
	v_lshl_add_u64 v[62:63], v[6:7], 2, v[16:17]
	v_add_co_u32_e32 v62, vcc, 0x32000, v62
	s_nop 1
	v_addc_co_u32_e32 v63, vcc, 0, v63, vcc
	global_load_dwordx2 v[62:63], v[62:63], off
.LBB0_84:
	s_or_b64 exec, exec, s[56:57]
	v_mov_b32_e32 v66, 0
	v_mov_b32_e32 v68, 0
	v_mov_b32_e32 v69, 0
	s_and_saveexec_b64 s[56:57], s[4:5]
	s_cbranch_execz .LBB0_86
	v_lshl_add_u64 v[68:69], v[6:7], 2, v[16:17]
	v_add_co_u32_e32 v68, vcc, 0x34000, v68
	s_nop 1
	v_addc_co_u32_e32 v69, vcc, 0, v69, vcc
	global_load_dwordx2 v[68:69], v[68:69], off
.LBB0_86:
	s_or_b64 exec, exec, s[56:57]
	v_mov_b32_e32 v67, 0
	s_and_saveexec_b64 s[56:57], s[4:5]
	s_cbranch_execz .LBB0_88
	v_lshl_add_u64 v[66:67], v[6:7], 2, v[16:17]
	v_add_co_u32_e32 v66, vcc, 0x36000, v66
	s_nop 1
	v_addc_co_u32_e32 v67, vcc, 0, v67, vcc
	global_load_dwordx2 v[66:67], v[66:67], off
.LBB0_88:
	s_or_b64 exec, exec, s[56:57]
	v_mov_b32_e32 v70, 0
	v_mov_b32_e32 v72, 0
	v_mov_b32_e32 v73, 0
	s_and_saveexec_b64 s[56:57], s[4:5]
	s_cbranch_execz .LBB0_90
	v_lshl_add_u64 v[72:73], v[6:7], 2, v[16:17]
	v_add_co_u32_e32 v72, vcc, 0x38000, v72
	s_nop 1
	v_addc_co_u32_e32 v73, vcc, 0, v73, vcc
	global_load_dwordx2 v[72:73], v[72:73], off
.LBB0_90:
	s_or_b64 exec, exec, s[56:57]
	v_mov_b32_e32 v71, 0
	s_and_saveexec_b64 s[56:57], s[4:5]
	s_cbranch_execz .LBB0_92
	v_lshl_add_u64 v[70:71], v[6:7], 2, v[16:17]
	v_add_co_u32_e32 v70, vcc, 0x3a000, v70
	s_nop 1
	v_addc_co_u32_e32 v71, vcc, 0, v71, vcc
	global_load_dwordx2 v[70:71], v[70:71], off
.LBB0_92:
	s_or_b64 exec, exec, s[56:57]
	v_mov_b32_e32 v74, 0
	v_mov_b32_e32 v76, 0
	v_mov_b32_e32 v77, 0
	s_and_saveexec_b64 s[56:57], s[4:5]
	s_cbranch_execz .LBB0_94
	v_lshl_add_u64 v[76:77], v[6:7], 2, v[16:17]
	v_add_co_u32_e32 v76, vcc, 0x3c000, v76
	s_nop 1
	v_addc_co_u32_e32 v77, vcc, 0, v77, vcc
	global_load_dwordx2 v[76:77], v[76:77], off
.LBB0_94:
	s_or_b64 exec, exec, s[56:57]
	v_mov_b32_e32 v75, 0
	s_and_saveexec_b64 s[56:57], s[4:5]
	s_cbranch_execz .LBB0_96
	v_lshl_add_u64 v[16:17], v[6:7], 2, v[16:17]
	v_add_co_u32_e32 v16, vcc, 0x3e000, v16
	s_nop 1
	v_addc_co_u32_e32 v17, vcc, 0, v17, vcc
	global_load_dwordx2 v[74:75], v[16:17], off
.LBB0_96:
	s_or_b64 exec, exec, s[56:57]
	v_add_u32_e32 v6, v5, v82
	v_sub_u32_e32 v78, 0, v11
	v_add_u32_e32 v11, 0x410, v6
	s_waitcnt vmcnt(0) lgkmcnt(0)
	ds_write2_b32 v6, v12, v13 offset1:1
	ds_write2_b32 v6, v14, v15 offset0:130 offset1:131
	ds_write2_b32 v11, v20, v21 offset1:1
	v_add_u32_e32 v11, 0x618, v6
	ds_write2_b32 v11, v18, v19 offset1:1
	v_add_u32_e32 v11, 0x820, v6
	ds_write2_b32 v11, v24, v25 offset1:1
	v_add_u32_e32 v11, 0xa28, v6
	ds_write2_b32 v11, v22, v23 offset1:1
	v_add_u32_e32 v11, 0xc30, v6
	ds_write2_b32 v11, v28, v29 offset1:1
	v_add_u32_e32 v11, 0xe38, v6
	ds_write2_b32 v11, v26, v27 offset1:1
	v_add_u32_e32 v11, 0x1040, v6
	ds_write2_b32 v11, v32, v33 offset1:1
	v_add_u32_e32 v11, 0x1248, v6
	ds_write2_b32 v11, v30, v31 offset1:1
	v_add_u32_e32 v11, 0x1450, v6
	ds_write2_b32 v11, v36, v37 offset1:1
	v_add_u32_e32 v11, 0x1658, v6
	ds_write2_b32 v11, v34, v35 offset1:1
	v_add_u32_e32 v11, 0x1860, v6
	ds_write2_b32 v11, v40, v41 offset1:1
	v_add_u32_e32 v11, 0x1a68, v6
	ds_write2_b32 v11, v38, v39 offset1:1
	v_add_u32_e32 v11, 0x1c70, v6
	ds_write2_b32 v11, v44, v45 offset1:1
	v_add_u32_e32 v11, 0x1e78, v6
	ds_write2_b32 v11, v42, v43 offset1:1
	v_add_u32_e32 v11, 0x2080, v6
	ds_write2_b32 v11, v48, v49 offset1:1
	v_add_u32_e32 v11, 0x2288, v6
	ds_write2_b32 v11, v46, v47 offset1:1
	v_add_u32_e32 v11, 0x2490, v6
	ds_write2_b32 v11, v52, v53 offset1:1
	v_add_u32_e32 v11, 0x2698, v6
	ds_write2_b32 v11, v50, v51 offset1:1
	v_add_u32_e32 v11, 0x28a0, v6
	ds_write2_b32 v11, v56, v57 offset1:1
	v_add_u32_e32 v11, 0x2aa8, v6
	ds_write2_b32 v11, v54, v55 offset1:1
	v_add_u32_e32 v11, 0x2cb0, v6
	ds_write2_b32 v11, v60, v61 offset1:1
	v_add_u32_e32 v11, 0x2eb8, v6
	ds_write2_b32 v11, v58, v59 offset1:1
	v_add_u32_e32 v11, 0x30c0, v6
	ds_write2_b32 v11, v64, v65 offset1:1
	v_add_u32_e32 v11, 0x32c8, v6
	ds_write2_b32 v11, v62, v63 offset1:1
	v_add_u32_e32 v11, 0x34d0, v6
	ds_write2_b32 v11, v68, v69 offset1:1
	v_add_u32_e32 v11, 0x36d8, v6
	ds_write2_b32 v11, v66, v67 offset1:1
	v_add_u32_e32 v11, 0x38e0, v6
	ds_write2_b32 v11, v72, v73 offset1:1
	v_add_u32_e32 v11, 0x3ae8, v6
	s_add_u32 s4, s54, s84
	ds_write2_b32 v11, v70, v71 offset1:1
	v_add_u32_e32 v11, 0x3cf0, v6
	v_add_u32_e32 v6, 0x3ef8, v6
	s_addc_u32 s5, s55, s83
	ds_write2_b32 v11, v76, v77 offset1:1
	ds_write2_b32 v6, v74, v75 offset1:1
	v_mov_b32_e32 v11, v7
	s_waitcnt lgkmcnt(0)
	v_lshl_add_u64 v[10:11], v[10:11], 1, s[4:5]
	v_lshlrev_b32_e32 v6, 1, v4
	v_lshl_add_u64 v[10:11], v[10:11], 0, v[6:7]
	ds_read_b32 v6, v84
	ds_read_b32 v12, v84 offset:260
	ds_read_b32 v13, v84 offset:520
	ds_read_b32 v16, v84 offset:780
	ds_read_b32 v17, v84 offset:1040
	ds_read_b32 v18, v84 offset:1300
	ds_read_b32 v19, v84 offset:1560
	ds_read_b32 v20, v84 offset:1820
	v_lshl_add_u64 v[14:15], v[10:11], 0, s[34:35]
	s_waitcnt lgkmcnt(6)
	v_cvt_pk_bf16_f32 v10, v6, v12
	v_add3_u32 v6, v112, v129, v78
	s_waitcnt lgkmcnt(4)
	v_cvt_pk_bf16_f32 v11, v13, v16
	s_waitcnt lgkmcnt(2)
	v_cvt_pk_bf16_f32 v12, v17, v18
	s_waitcnt lgkmcnt(0)
	v_cvt_pk_bf16_f32 v13, v19, v20
	v_mad_i64_i32 v[16:17], s[4:5], v6, s68, v[14:15]
	global_store_dwordx4 v[16:17], v[10:13], off
	ds_read_b32 v6, v84 offset:32
	ds_read_b32 v10, v84 offset:292
	ds_read_b32 v11, v84 offset:552
	ds_read_b32 v12, v84 offset:812
	ds_read_b32 v13, v84 offset:1072
	ds_read_b32 v16, v84 offset:1332
	ds_read_b32 v17, v84 offset:1592
	ds_read_b32 v18, v84 offset:1852
	s_waitcnt lgkmcnt(0)
	v_cvt_pk_bf16_f32 v10, v6, v10
	v_add3_u32 v6, v111, v129, v78
	v_cvt_pk_bf16_f32 v11, v11, v12
	v_cvt_pk_bf16_f32 v12, v13, v16
	v_cvt_pk_bf16_f32 v13, v17, v18
	v_mad_i64_i32 v[16:17], s[4:5], v6, s68, v[14:15]
	global_store_dwordx4 v[16:17], v[10:13], off
	ds_read_b32 v6, v84 offset:64
	ds_read_b32 v10, v84 offset:324
	ds_read_b32 v11, v84 offset:584
	ds_read_b32 v12, v84 offset:844
	ds_read_b32 v13, v84 offset:1104
	ds_read_b32 v16, v84 offset:1364
	ds_read_b32 v17, v84 offset:1624
	ds_read_b32 v18, v84 offset:1884
	s_waitcnt lgkmcnt(0)
	v_cvt_pk_bf16_f32 v10, v6, v10
	v_add3_u32 v6, v110, v129, v78
	v_cvt_pk_bf16_f32 v11, v11, v12
	v_cvt_pk_bf16_f32 v12, v13, v16
	v_cvt_pk_bf16_f32 v13, v17, v18
	v_mad_i64_i32 v[16:17], s[4:5], v6, s68, v[14:15]
	global_store_dwordx4 v[16:17], v[10:13], off
	ds_read_b32 v6, v84 offset:96
	ds_read_b32 v10, v84 offset:356
	ds_read_b32 v11, v84 offset:616
	ds_read_b32 v12, v84 offset:876
	ds_read_b32 v13, v84 offset:1136
	ds_read_b32 v16, v84 offset:1396
	ds_read_b32 v17, v84 offset:1656
	ds_read_b32 v18, v84 offset:1916
	s_waitcnt lgkmcnt(0)
	v_cvt_pk_bf16_f32 v10, v6, v10
	v_add3_u32 v6, v109, v129, v78
	v_cvt_pk_bf16_f32 v11, v11, v12
	v_cvt_pk_bf16_f32 v12, v13, v16
	v_cvt_pk_bf16_f32 v13, v17, v18
	v_mad_i64_i32 v[16:17], s[4:5], v6, s68, v[14:15]
	global_store_dwordx4 v[16:17], v[10:13], off
	ds_read_b32 v6, v84 offset:128
	ds_read_b32 v10, v84 offset:388
	ds_read_b32 v11, v84 offset:648
	ds_read_b32 v12, v84 offset:908
	ds_read_b32 v13, v84 offset:1168
	ds_read_b32 v16, v84 offset:1428
	ds_read_b32 v17, v84 offset:1688
	ds_read_b32 v18, v84 offset:1948
	s_waitcnt lgkmcnt(0)
	v_cvt_pk_bf16_f32 v10, v6, v10
	v_add3_u32 v6, v108, v129, v78
	v_cvt_pk_bf16_f32 v11, v11, v12
	v_cvt_pk_bf16_f32 v12, v13, v16
	v_cvt_pk_bf16_f32 v13, v17, v18
	v_mad_i64_i32 v[16:17], s[4:5], v6, s68, v[14:15]
	global_store_dwordx4 v[16:17], v[10:13], off
	ds_read_b32 v6, v84 offset:160
	ds_read_b32 v10, v84 offset:420
	ds_read_b32 v11, v84 offset:680
	ds_read_b32 v12, v84 offset:940
	ds_read_b32 v13, v84 offset:1200
	ds_read_b32 v16, v84 offset:1460
	ds_read_b32 v17, v84 offset:1720
	ds_read_b32 v18, v84 offset:1980
	s_waitcnt lgkmcnt(0)
	v_cvt_pk_bf16_f32 v10, v6, v10
	v_add3_u32 v6, v107, v129, v78
	v_cvt_pk_bf16_f32 v11, v11, v12
	v_cvt_pk_bf16_f32 v12, v13, v16
	v_cvt_pk_bf16_f32 v13, v17, v18
	v_mad_i64_i32 v[16:17], s[4:5], v6, s68, v[14:15]
	global_store_dwordx4 v[16:17], v[10:13], off
	ds_read_b32 v6, v84 offset:192
	ds_read_b32 v10, v84 offset:452
	ds_read_b32 v11, v84 offset:712
	ds_read_b32 v12, v84 offset:972
	ds_read_b32 v13, v84 offset:1232
	ds_read_b32 v16, v84 offset:1492
	ds_read_b32 v17, v84 offset:1752
	ds_read_b32 v18, v84 offset:2012
	s_waitcnt lgkmcnt(0)
	v_cvt_pk_bf16_f32 v10, v6, v10
	v_add3_u32 v6, v106, v129, v78
	v_cvt_pk_bf16_f32 v11, v11, v12
	v_cvt_pk_bf16_f32 v12, v13, v16
	v_cvt_pk_bf16_f32 v13, v17, v18
	v_mad_i64_i32 v[16:17], s[4:5], v6, s68, v[14:15]
	global_store_dwordx4 v[16:17], v[10:13], off
	ds_read_b32 v6, v84 offset:224
	ds_read_b32 v10, v84 offset:484
	ds_read_b32 v11, v84 offset:744
	ds_read_b32 v12, v84 offset:1004
	ds_read_b32 v13, v84 offset:1264
	ds_read_b32 v16, v84 offset:1524
	ds_read_b32 v17, v84 offset:1784
	ds_read_b32 v18, v84 offset:2044
	s_waitcnt lgkmcnt(0)
	v_cvt_pk_bf16_f32 v10, v6, v10
	v_add3_u32 v6, v103, v129, v78
	v_cvt_pk_bf16_f32 v11, v11, v12
	v_cvt_pk_bf16_f32 v12, v13, v16
	v_cvt_pk_bf16_f32 v13, v17, v18
	v_mad_i64_i32 v[14:15], s[4:5], v6, s68, v[14:15]
	global_store_dwordx4 v[14:15], v[10:13], off
	s_waitcnt lgkmcnt(0)
.LBB0_97:
	s_andn2_saveexec_b64 s[52:53], s[52:53]
	s_cbranch_execz .LBB0_360
	v_mul_u32_u24_e32 v6, 0xba2f, v128
	v_lshrrev_b32_e32 v6, 22, v6
	v_mad_i32_i24 v12, v6, s69, v128
	v_lshlrev_b32_e32 v11, 6, v12
	v_lshlrev_b32_e32 v10, 6, v6
	v_and_b32_e32 v6, 0xc0, v11
	v_lshlrev_b32_e32 v12, 5, v12
	s_mov_b64 s[4:5], s[12:13]
	v_or_b32_e32 v13, v6, v1
	v_and_b32_e32 v12, 0xffffff80, v12
	s_add_u32 s58, s4, s86
	v_or_b32_e32 v14, v13, v12
	v_add3_u32 v12, v12, v13, s71
	v_cmp_gt_u32_e32 vcc, s70, v6
	s_addc_u32 s59, s5, s85
	v_or_b32_e32 v131, v10, v2
	v_cndmask_b32_e32 v6, v12, v14, vcc
	v_cmp_lt_i32_e64 s[4:5], -1, v6
	v_lshl_add_u64 v[28:29], v[6:7], 2, s[58:59]
	v_mov_b32_e32 v14, 0
	v_mul_u32_u24_e32 v6, 0x1600, v131
	s_mov_b64 s[56:57], s[10:11]
	s_mov_b64 s[54:55], s[22:23]
	v_lshlrev_b32_e32 v30, 2, v6
	v_mov_b32_e32 v12, 0
	v_mov_b32_e32 v13, v14
	s_and_saveexec_b64 s[58:59], s[4:5]
	s_cbranch_execz .LBB0_100
	v_mov_b32_e32 v31, v7
	v_lshl_add_u64 v[12:13], v[28:29], 0, v[30:31]
	global_load_dwordx2 v[12:13], v[12:13], off
.LBB0_100:
	s_or_b64 exec, exec, s[58:59]
	v_mov_b32_e32 v15, 0
	s_and_saveexec_b64 s[58:59], s[4:5]
	s_cbranch_execz .LBB0_102
	v_mov_b32_e32 v31, v7
	v_lshl_add_u64 v[14:15], v[28:29], 0, v[30:31]
	v_add_co_u32_e32 v14, vcc, 0xb000, v14
	s_nop 1
	v_addc_co_u32_e32 v15, vcc, 0, v15, vcc
	global_load_dwordx2 v[14:15], v[14:15], off
.LBB0_102:
	s_or_b64 exec, exec, s[58:59]
	v_mov_b32_e32 v6, v7
	v_mov_b64_e32 v[20:21], v[6:7]
	s_and_saveexec_b64 s[58:59], s[4:5]
	s_cbranch_execz .LBB0_104
	v_mov_b32_e32 v31, v7
	v_lshl_add_u64 v[16:17], v[28:29], 0, v[30:31]
	v_add_co_u32_e32 v16, vcc, 0x16000, v16
	s_nop 1
	v_addc_co_u32_e32 v17, vcc, 0, v17, vcc
	global_load_dwordx2 v[20:21], v[16:17], off
.LBB0_104:
	s_or_b64 exec, exec, s[58:59]
	v_mov_b32_e32 v16, 0
	v_mov_b32_e32 v24, 0
	v_mov_b32_e32 v25, 0
	s_and_saveexec_b64 s[58:59], s[4:5]
	s_cbranch_execz .LBB0_106
	v_mov_b32_e32 v31, v7
	v_lshl_add_u64 v[18:19], v[28:29], 0, v[30:31]
	v_add_co_u32_e32 v18, vcc, 0x21000, v18
	s_nop 1
	v_addc_co_u32_e32 v19, vcc, 0, v19, vcc
	global_load_dwordx2 v[24:25], v[18:19], off
.LBB0_106:
	s_or_b64 exec, exec, s[58:59]
	v_mov_b32_e32 v17, 0
	s_and_saveexec_b64 s[58:59], s[4:5]
	s_cbranch_execz .LBB0_108
	v_mov_b32_e32 v31, v7
	v_lshl_add_u64 v[16:17], v[28:29], 0, v[30:31]
	v_add_co_u32_e32 v16, vcc, 0x2c000, v16
	s_nop 1
	v_addc_co_u32_e32 v17, vcc, 0, v17, vcc
	global_load_dwordx2 v[16:17], v[16:17], off
.LBB0_108:
	s_or_b64 exec, exec, s[58:59]
	v_mov_b32_e32 v22, 0
	v_mov_b32_e32 v23, v22
	s_and_saveexec_b64 s[58:59], s[4:5]
	s_cbranch_execz .LBB0_110
	v_mov_b32_e32 v31, v7
	v_lshl_add_u64 v[18:19], v[28:29], 0, v[30:31]
	v_add_co_u32_e32 v18, vcc, 0x37000, v18
	s_nop 1
	v_addc_co_u32_e32 v19, vcc, 0, v19, vcc
	global_load_dwordx2 v[22:23], v[18:19], off
.LBB0_110:
	s_or_b64 exec, exec, s[58:59]
	v_mov_b32_e32 v6, v7
	v_mov_b64_e32 v[32:33], v[6:7]
	s_and_saveexec_b64 s[58:59], s[4:5]
	s_cbranch_execz .LBB0_112
	v_mov_b32_e32 v31, v7
	v_lshl_add_u64 v[18:19], v[28:29], 0, v[30:31]
	v_add_co_u32_e32 v18, vcc, 0x42000, v18
	s_nop 1
	v_addc_co_u32_e32 v19, vcc, 0, v19, vcc
	global_load_dwordx2 v[32:33], v[18:19], off
.LBB0_112:
	s_or_b64 exec, exec, s[58:59]
	v_mov_b32_e32 v18, 0
	v_mov_b32_e32 v36, 0
	v_mov_b32_e32 v37, 0
	s_and_saveexec_b64 s[58:59], s[4:5]
	s_cbranch_execz .LBB0_114
	v_mov_b32_e32 v31, v7
	v_lshl_add_u64 v[26:27], v[28:29], 0, v[30:31]
	v_add_co_u32_e32 v26, vcc, 0x4d000, v26
	s_nop 1
	v_addc_co_u32_e32 v27, vcc, 0, v27, vcc
	global_load_dwordx2 v[36:37], v[26:27], off
.LBB0_114:
	s_or_b64 exec, exec, s[58:59]
	v_mov_b32_e32 v19, 0
	s_and_saveexec_b64 s[58:59], s[4:5]
	s_cbranch_execz .LBB0_116
	v_mov_b32_e32 v31, v7
	v_lshl_add_u64 v[18:19], v[28:29], 0, v[30:31]
	v_add_co_u32_e32 v18, vcc, 0x58000, v18
	s_nop 1
	v_addc_co_u32_e32 v19, vcc, 0, v19, vcc
	global_load_dwordx2 v[18:19], v[18:19], off
.LBB0_116:
	s_or_b64 exec, exec, s[58:59]
	v_mov_b32_e32 v34, 0
	v_mov_b32_e32 v35, v34
	s_and_saveexec_b64 s[58:59], s[4:5]
	s_cbranch_execz .LBB0_118
	v_mov_b32_e32 v31, v7
	v_lshl_add_u64 v[26:27], v[28:29], 0, v[30:31]
	v_add_co_u32_e32 v26, vcc, 0x63000, v26
	s_nop 1
	v_addc_co_u32_e32 v27, vcc, 0, v27, vcc
	global_load_dwordx2 v[34:35], v[26:27], off
.LBB0_118:
	s_or_b64 exec, exec, s[58:59]
	v_mov_b32_e32 v6, v7
	v_mov_b64_e32 v[40:41], v[6:7]
	s_and_saveexec_b64 s[58:59], s[4:5]
	s_cbranch_execz .LBB0_120
	v_mov_b32_e32 v31, v7
	v_lshl_add_u64 v[26:27], v[28:29], 0, v[30:31]
	v_add_co_u32_e32 v26, vcc, 0x6e000, v26
	s_nop 1
	v_addc_co_u32_e32 v27, vcc, 0, v27, vcc
	global_load_dwordx2 v[40:41], v[26:27], off
.LBB0_120:
	s_or_b64 exec, exec, s[58:59]
	v_mov_b32_e32 v26, 0
	v_mov_b32_e32 v44, 0
	v_mov_b32_e32 v45, 0
	s_and_saveexec_b64 s[58:59], s[4:5]
	s_cbranch_execz .LBB0_122
	v_mov_b32_e32 v31, v7
	v_lshl_add_u64 v[38:39], v[28:29], 0, v[30:31]
	v_add_co_u32_e32 v38, vcc, 0x79000, v38
	s_nop 1
	v_addc_co_u32_e32 v39, vcc, 0, v39, vcc
	global_load_dwordx2 v[44:45], v[38:39], off
.LBB0_122:
	s_or_b64 exec, exec, s[58:59]
	v_mov_b32_e32 v27, 0
	s_and_saveexec_b64 s[58:59], s[4:5]
	s_cbranch_execz .LBB0_124
	v_mov_b32_e32 v31, v7
	v_lshl_add_u64 v[26:27], v[28:29], 0, v[30:31]
	v_add_co_u32_e32 v26, vcc, 0x84000, v26
	s_nop 1
	v_addc_co_u32_e32 v27, vcc, 0, v27, vcc
	global_load_dwordx2 v[26:27], v[26:27], off
.LBB0_124:
	s_or_b64 exec, exec, s[58:59]
	v_mov_b32_e32 v42, 0
	v_mov_b32_e32 v43, v42
	s_and_saveexec_b64 s[58:59], s[4:5]
	s_cbranch_execz .LBB0_126
	v_mov_b32_e32 v31, v7
	v_lshl_add_u64 v[38:39], v[28:29], 0, v[30:31]
	v_add_co_u32_e32 v38, vcc, 0x8f000, v38
	s_nop 1
	v_addc_co_u32_e32 v39, vcc, 0, v39, vcc
	global_load_dwordx2 v[42:43], v[38:39], off
.LBB0_126:
	s_or_b64 exec, exec, s[58:59]
	v_mov_b32_e32 v6, v7
	v_mov_b64_e32 v[48:49], v[6:7]
	s_and_saveexec_b64 s[58:59], s[4:5]
	s_cbranch_execz .LBB0_128
	v_mov_b32_e32 v31, v7
	v_lshl_add_u64 v[38:39], v[28:29], 0, v[30:31]
	v_add_co_u32_e32 v38, vcc, 0x9a000, v38
	s_nop 1
	v_addc_co_u32_e32 v39, vcc, 0, v39, vcc
	global_load_dwordx2 v[48:49], v[38:39], off
.LBB0_128:
	s_or_b64 exec, exec, s[58:59]
	v_mov_b32_e32 v38, 0
	v_mov_b32_e32 v52, 0
	v_mov_b32_e32 v53, 0
	s_and_saveexec_b64 s[58:59], s[4:5]
	s_cbranch_execz .LBB0_130
	v_mov_b32_e32 v31, v7
	v_lshl_add_u64 v[46:47], v[28:29], 0, v[30:31]
	v_add_co_u32_e32 v46, vcc, 0xa5000, v46
	s_nop 1
	v_addc_co_u32_e32 v47, vcc, 0, v47, vcc
	global_load_dwordx2 v[52:53], v[46:47], off
.LBB0_130:
	s_or_b64 exec, exec, s[58:59]
	v_mov_b32_e32 v39, 0
	s_and_saveexec_b64 s[58:59], s[4:5]
	s_cbranch_execz .LBB0_132
	v_mov_b32_e32 v31, v7
	v_lshl_add_u64 v[38:39], v[28:29], 0, v[30:31]
	v_add_co_u32_e32 v38, vcc, 0xb0000, v38
	s_nop 1
	v_addc_co_u32_e32 v39, vcc, 0, v39, vcc
	global_load_dwordx2 v[38:39], v[38:39], off
.LBB0_132:
	s_or_b64 exec, exec, s[58:59]
	v_mov_b32_e32 v50, 0
	v_mov_b32_e32 v51, v50
	s_and_saveexec_b64 s[58:59], s[4:5]
	s_cbranch_execz .LBB0_134
	v_mov_b32_e32 v31, v7
	v_lshl_add_u64 v[46:47], v[28:29], 0, v[30:31]
	v_add_co_u32_e32 v46, vcc, 0xbb000, v46
	s_nop 1
	v_addc_co_u32_e32 v47, vcc, 0, v47, vcc
	global_load_dwordx2 v[50:51], v[46:47], off
.LBB0_134:
	s_or_b64 exec, exec, s[58:59]
	v_mov_b32_e32 v6, v7
	v_mov_b64_e32 v[56:57], v[6:7]
	s_and_saveexec_b64 s[58:59], s[4:5]
	s_cbranch_execz .LBB0_136
	v_mov_b32_e32 v31, v7
	v_lshl_add_u64 v[46:47], v[28:29], 0, v[30:31]
	v_add_co_u32_e32 v46, vcc, 0xc6000, v46
	s_nop 1
	v_addc_co_u32_e32 v47, vcc, 0, v47, vcc
	global_load_dwordx2 v[56:57], v[46:47], off
.LBB0_136:
	s_or_b64 exec, exec, s[58:59]
	v_mov_b32_e32 v46, 0
	v_mov_b32_e32 v60, 0
	v_mov_b32_e32 v61, 0
	s_and_saveexec_b64 s[58:59], s[4:5]
	s_cbranch_execz .LBB0_138
	v_mov_b32_e32 v31, v7
	v_lshl_add_u64 v[54:55], v[28:29], 0, v[30:31]
	v_add_co_u32_e32 v54, vcc, 0xd1000, v54
	s_nop 1
	v_addc_co_u32_e32 v55, vcc, 0, v55, vcc
	global_load_dwordx2 v[60:61], v[54:55], off
.LBB0_138:
	s_or_b64 exec, exec, s[58:59]
	v_mov_b32_e32 v47, 0
	s_and_saveexec_b64 s[58:59], s[4:5]
	s_cbranch_execz .LBB0_140
	v_mov_b32_e32 v31, v7
	v_lshl_add_u64 v[46:47], v[28:29], 0, v[30:31]
	v_add_co_u32_e32 v46, vcc, 0xdc000, v46
	s_nop 1
	v_addc_co_u32_e32 v47, vcc, 0, v47, vcc
	global_load_dwordx2 v[46:47], v[46:47], off
.LBB0_140:
	s_or_b64 exec, exec, s[58:59]
	v_mov_b32_e32 v58, 0
	v_mov_b32_e32 v59, v58
	s_and_saveexec_b64 s[58:59], s[4:5]
	s_cbranch_execz .LBB0_142
	v_mov_b32_e32 v31, v7
	v_lshl_add_u64 v[54:55], v[28:29], 0, v[30:31]
	v_add_co_u32_e32 v54, vcc, 0xe7000, v54
	s_nop 1
	v_addc_co_u32_e32 v55, vcc, 0, v55, vcc
	global_load_dwordx2 v[58:59], v[54:55], off
.LBB0_142:
	s_or_b64 exec, exec, s[58:59]
	v_mov_b32_e32 v6, v7
	v_mov_b64_e32 v[64:65], v[6:7]
	s_and_saveexec_b64 s[58:59], s[4:5]
	s_cbranch_execz .LBB0_144
	v_mov_b32_e32 v31, v7
	v_lshl_add_u64 v[54:55], v[28:29], 0, v[30:31]
	v_add_co_u32_e32 v54, vcc, 0xf2000, v54
	s_nop 1
	v_addc_co_u32_e32 v55, vcc, 0, v55, vcc
	global_load_dwordx2 v[64:65], v[54:55], off
.LBB0_144:
	s_or_b64 exec, exec, s[58:59]
	v_mov_b32_e32 v54, 0
	v_mov_b32_e32 v68, 0
	v_mov_b32_e32 v69, 0
	s_and_saveexec_b64 s[58:59], s[4:5]
	s_cbranch_execz .LBB0_146
	v_mov_b32_e32 v31, v7
	v_lshl_add_u64 v[62:63], v[28:29], 0, v[30:31]
	v_add_co_u32_e32 v62, vcc, 0xfd000, v62
	s_nop 1
	v_addc_co_u32_e32 v63, vcc, 0, v63, vcc
	global_load_dwordx2 v[68:69], v[62:63], off
.LBB0_146:
	s_or_b64 exec, exec, s[58:59]
	v_mov_b32_e32 v55, 0
	s_and_saveexec_b64 s[58:59], s[4:5]
	s_cbranch_execz .LBB0_148
	v_mov_b32_e32 v31, v7
	v_lshl_add_u64 v[54:55], v[28:29], 0, v[30:31]
	v_add_co_u32_e32 v54, vcc, 0x108000, v54
	s_nop 1
	v_addc_co_u32_e32 v55, vcc, 0, v55, vcc
	global_load_dwordx2 v[54:55], v[54:55], off
.LBB0_148:
	s_or_b64 exec, exec, s[58:59]
	v_mov_b32_e32 v66, 0
	v_mov_b32_e32 v67, v66
	s_and_saveexec_b64 s[58:59], s[4:5]
	s_cbranch_execz .LBB0_150
	v_mov_b32_e32 v31, v7
	v_lshl_add_u64 v[62:63], v[28:29], 0, v[30:31]
	v_add_co_u32_e32 v62, vcc, 0x113000, v62
	s_nop 1
	v_addc_co_u32_e32 v63, vcc, 0, v63, vcc
	global_load_dwordx2 v[66:67], v[62:63], off
.LBB0_150:
	s_or_b64 exec, exec, s[58:59]
	v_mov_b32_e32 v6, v7
	v_mov_b64_e32 v[70:71], v[6:7]
	s_and_saveexec_b64 s[58:59], s[4:5]
	s_cbranch_execz .LBB0_152
	v_mov_b32_e32 v31, v7
	v_lshl_add_u64 v[62:63], v[28:29], 0, v[30:31]
	v_add_co_u32_e32 v62, vcc, 0x11e000, v62
	s_nop 1
	v_addc_co_u32_e32 v63, vcc, 0, v63, vcc
	global_load_dwordx2 v[70:71], v[62:63], off
.LBB0_152:
	s_or_b64 exec, exec, s[58:59]
	v_mov_b32_e32 v62, 0
	v_mov_b32_e32 v74, 0
	v_mov_b32_e32 v75, 0
	s_and_saveexec_b64 s[58:59], s[4:5]
	s_cbranch_execz .LBB0_154
	v_mov_b32_e32 v31, v7
	v_lshl_add_u64 v[72:73], v[28:29], 0, v[30:31]
	v_add_co_u32_e32 v72, vcc, 0x129000, v72
	s_nop 1
	v_addc_co_u32_e32 v73, vcc, 0, v73, vcc
	global_load_dwordx2 v[74:75], v[72:73], off
.LBB0_154:
	s_or_b64 exec, exec, s[58:59]
	v_mov_b32_e32 v63, 0
	s_and_saveexec_b64 s[58:59], s[4:5]
	s_cbranch_execz .LBB0_156
	v_mov_b32_e32 v31, v7
	v_lshl_add_u64 v[62:63], v[28:29], 0, v[30:31]
	v_add_co_u32_e32 v62, vcc, 0x134000, v62
	s_nop 1
	v_addc_co_u32_e32 v63, vcc, 0, v63, vcc
	global_load_dwordx2 v[62:63], v[62:63], off
.LBB0_156:
	s_or_b64 exec, exec, s[58:59]
	v_mov_b32_e32 v72, 0
	v_mov_b32_e32 v73, v72
	s_and_saveexec_b64 s[58:59], s[4:5]
	s_cbranch_execz .LBB0_158
	v_mov_b32_e32 v31, v7
	v_lshl_add_u64 v[72:73], v[28:29], 0, v[30:31]
	v_add_co_u32_e32 v72, vcc, 0x13f000, v72
	s_nop 1
	v_addc_co_u32_e32 v73, vcc, 0, v73, vcc
	global_load_dwordx2 v[72:73], v[72:73], off
.LBB0_158:
	s_or_b64 exec, exec, s[58:59]
	v_mov_b32_e32 v6, v7
	v_mov_b64_e32 v[76:77], v[6:7]
	s_and_saveexec_b64 s[58:59], s[4:5]
	s_cbranch_execz .LBB0_160
	v_mov_b32_e32 v31, v7
	v_lshl_add_u64 v[76:77], v[28:29], 0, v[30:31]
	v_add_co_u32_e32 v76, vcc, 0x14a000, v76
	s_nop 1
	v_addc_co_u32_e32 v77, vcc, 0, v77, vcc
	global_load_dwordx2 v[76:77], v[76:77], off
.LBB0_160:
	s_or_b64 exec, exec, s[58:59]
	v_mov_b32_e32 v78, 0
	v_mov_b32_e32 v79, 0
	s_and_saveexec_b64 s[58:59], s[4:5]
	s_cbranch_execz .LBB0_162
	v_mov_b32_e32 v31, v7
	v_lshl_add_u64 v[28:29], v[28:29], 0, v[30:31]
	v_add_co_u32_e32 v28, vcc, 0x155000, v28
	s_nop 1
	v_addc_co_u32_e32 v29, vcc, 0, v29, vcc
	global_load_dwordx2 v[78:79], v[28:29], off
.LBB0_162:
	s_or_b64 exec, exec, s[58:59]
	s_lshl_b64 s[4:5], s[26:27], 2
	s_add_u32 s58, s56, s4
	s_addc_u32 s59, s57, s5
	s_cmp_lg_u64 s[56:57], 0
	s_cselect_b64 s[60:61], -1, 0
	s_cmp_eq_u64 s[56:57], 0
	v_add_lshl_u32 v28, v10, v2, 2
	s_cbranch_scc1 .LBB0_361
	v_lshlrev_b32_e32 v6, 2, v131
	v_lshl_add_u64 v[30:31], s[58:59], 0, v[6:7]
	v_mov_b32_e32 v29, v7
	v_lshl_add_u64 v[132:133], s[58:59], 0, v[28:29]
	global_load_dword v30, v[30:31], off
	s_nop 0
	global_load_dword v134, v[132:133], off offset:8
	global_load_dword v136, v[132:133], off offset:16
	global_load_dword v6, v[132:133], off offset:24
	v_add_u32_e32 v29, v5, v82
	v_add_u32_e32 v131, v5, v92
	s_waitcnt vmcnt(0) lgkmcnt(0)
	v_pk_mul_f32 v[132:133], v[12:13], v[30:31] op_sel_hi:[1,0]
	v_pk_mul_f32 v[134:135], v[14:15], v[134:135] op_sel_hi:[1,0]
	v_pk_mul_f32 v[30:31], v[20:21], v[136:137] op_sel_hi:[1,0]
	ds_write2_b32 v29, v132, v133 offset1:1
	ds_write2_b32 v131, v134, v135 offset1:1
	s_cbranch_execnz .LBB0_165

.LBB0_165:
	s_waitcnt vmcnt(0) lgkmcnt(0)
	v_pk_mul_f32 v[12:13], v[24:25], v[6:7] op_sel_hi:[1,0]
	v_cndmask_b32_e64 v6, 0, 1, s[60:61]
	v_add_u32_e32 v14, v5, v93
	v_cmp_ne_u32_e64 s[4:5], 1, v6
	s_andn2_b64 vcc, exec, s[60:61]
	ds_write2_b32 v14, v30, v31 offset1:1
	ds_write2_b32 v14, v12, v13 offset0:130 offset1:131
	s_cbranch_vccnz .LBB0_362
	v_mov_b32_e32 v29, v7
	v_lshl_add_u64 v[12:13], s[58:59], 0, v[28:29]
	global_load_dword v14, v[12:13], off offset:32
	global_load_dword v20, v[12:13], off offset:40
	global_load_dword v24, v[12:13], off offset:48
	global_load_dword v6, v[12:13], off offset:56
	v_add_u32_e32 v25, v5, v94
	s_waitcnt vmcnt(0) lgkmcnt(0)
	v_pk_mul_f32 v[14:15], v[16:17], v[14:15] op_sel_hi:[1,0]
	v_pk_mul_f32 v[20:21], v[22:23], v[20:21] op_sel_hi:[1,0]
	v_pk_mul_f32 v[12:13], v[32:33], v[24:25] op_sel_hi:[1,0]
	ds_write2_b32 v25, v14, v15 offset1:1
	ds_write2_b32 v25, v20, v21 offset0:130 offset1:131
	s_cbranch_execnz .LBB0_168

.LBB0_168:
	v_add_u32_e32 v14, v5, v95
	ds_write2_b32 v14, v12, v13 offset1:1
	v_pk_mul_f32 v[12:13], v[36:37], v[6:7] op_sel_hi:[1,0]
	s_and_b64 vcc, exec, s[4:5]
	ds_write2_b32 v14, v12, v13 offset0:130 offset1:131
	s_cbranch_vccnz .LBB0_363
	v_mov_b32_e32 v29, v7
	v_lshl_add_u64 v[12:13], s[58:59], 0, v[28:29]
	global_load_dword v14, v[12:13], off offset:64
	global_load_dword v16, v[12:13], off offset:72
	global_load_dword v20, v[12:13], off offset:80
	global_load_dword v6, v[12:13], off offset:88
	v_add_u32_e32 v21, v5, v96
	s_waitcnt vmcnt(0) lgkmcnt(0)
	v_pk_mul_f32 v[14:15], v[18:19], v[14:15] op_sel_hi:[1,0]
	v_pk_mul_f32 v[16:17], v[34:35], v[16:17] op_sel_hi:[1,0]
	v_pk_mul_f32 v[12:13], v[40:41], v[20:21] op_sel_hi:[1,0]
	ds_write2_b32 v21, v14, v15 offset1:1
	ds_write2_b32 v21, v16, v17 offset0:130 offset1:131
	s_cbranch_execnz .LBB0_171

.LBB0_171:
	v_add_u32_e32 v14, v5, v97
	ds_write2_b32 v14, v12, v13 offset1:1
	v_pk_mul_f32 v[12:13], v[44:45], v[6:7] op_sel_hi:[1,0]
	s_and_b64 vcc, exec, s[4:5]
	ds_write2_b32 v14, v12, v13 offset0:130 offset1:131
	s_cbranch_vccnz .LBB0_364
	v_mov_b32_e32 v29, v7
	v_lshl_add_u64 v[12:13], s[58:59], 0, v[28:29]
	global_load_dword v14, v[12:13], off offset:96
	global_load_dword v16, v[12:13], off offset:104
	global_load_dword v18, v[12:13], off offset:112
	global_load_dword v6, v[12:13], off offset:120
	v_add_u32_e32 v19, v5, v98
	s_waitcnt vmcnt(0) lgkmcnt(0)
	v_pk_mul_f32 v[14:15], v[26:27], v[14:15] op_sel_hi:[1,0]
	v_pk_mul_f32 v[16:17], v[42:43], v[16:17] op_sel_hi:[1,0]
	v_pk_mul_f32 v[12:13], v[48:49], v[18:19] op_sel_hi:[1,0]
	ds_write2_b32 v19, v14, v15 offset1:1
	ds_write2_b32 v19, v16, v17 offset0:130 offset1:131
	s_cbranch_execnz .LBB0_174

.LBB0_174:
	v_add_u32_e32 v14, v5, v99
	ds_write2_b32 v14, v12, v13 offset1:1
	v_pk_mul_f32 v[12:13], v[52:53], v[6:7] op_sel_hi:[1,0]
	s_and_b64 vcc, exec, s[4:5]
	ds_write2_b32 v14, v12, v13 offset0:130 offset1:131
	s_cbranch_vccnz .LBB0_365
	v_mov_b32_e32 v29, v7
	v_lshl_add_u64 v[12:13], s[58:59], 0, v[28:29]
	global_load_dword v14, v[12:13], off offset:128
	global_load_dword v16, v[12:13], off offset:136
	global_load_dword v18, v[12:13], off offset:144
	global_load_dword v6, v[12:13], off offset:152
	v_add_u32_e32 v19, v5, v100
	s_waitcnt vmcnt(0) lgkmcnt(0)
	v_pk_mul_f32 v[14:15], v[38:39], v[14:15] op_sel_hi:[1,0]
	v_pk_mul_f32 v[16:17], v[50:51], v[16:17] op_sel_hi:[1,0]
	v_pk_mul_f32 v[12:13], v[56:57], v[18:19] op_sel_hi:[1,0]
	ds_write2_b32 v19, v14, v15 offset1:1
	ds_write2_b32 v19, v16, v17 offset0:130 offset1:131
	s_cbranch_execnz .LBB0_177

.LBB0_177:
	v_add_u32_e32 v14, v5, v101
	ds_write2_b32 v14, v12, v13 offset1:1
	v_pk_mul_f32 v[12:13], v[60:61], v[6:7] op_sel_hi:[1,0]
	s_and_b64 vcc, exec, s[4:5]
	ds_write2_b32 v14, v12, v13 offset0:130 offset1:131
	s_cbranch_vccnz .LBB0_366
	v_mov_b32_e32 v29, v7
	v_lshl_add_u64 v[12:13], s[58:59], 0, v[28:29]
	global_load_dword v14, v[12:13], off offset:160
	global_load_dword v16, v[12:13], off offset:168
	global_load_dword v18, v[12:13], off offset:176
	global_load_dword v6, v[12:13], off offset:184
	v_add_u32_e32 v19, v5, v102
	s_waitcnt vmcnt(0) lgkmcnt(0)
	v_pk_mul_f32 v[14:15], v[46:47], v[14:15] op_sel_hi:[1,0]
	v_pk_mul_f32 v[16:17], v[58:59], v[16:17] op_sel_hi:[1,0]
	v_pk_mul_f32 v[12:13], v[64:65], v[18:19] op_sel_hi:[1,0]
	ds_write2_b32 v19, v14, v15 offset1:1
	ds_write2_b32 v19, v16, v17 offset0:130 offset1:131
	s_cbranch_execnz .LBB0_180

.LBB0_180:
	v_add_u32_e32 v14, v5, v102
	v_add_u32_e32 v15, 0x410, v14
	ds_write2_b32 v15, v12, v13 offset1:1
	v_pk_mul_f32 v[12:13], v[68:69], v[6:7] op_sel_hi:[1,0]
	v_add_u32_e32 v6, 0x618, v14
	s_and_b64 vcc, exec, s[4:5]
	v_add_u32_e32 v15, 0x820, v14
	v_add_u32_e32 v16, 0xa28, v14
	ds_write2_b32 v6, v12, v13 offset1:1
	s_cbranch_vccnz .LBB0_367
	v_mov_b32_e32 v29, v7
	v_lshl_add_u64 v[12:13], s[58:59], 0, v[28:29]
	global_load_dword v18, v[12:13], off offset:192
	global_load_dword v20, v[12:13], off offset:200
	global_load_dword v22, v[12:13], off offset:208
	global_load_dword v6, v[12:13], off offset:216
	s_waitcnt vmcnt(0) lgkmcnt(0)
	v_pk_mul_f32 v[18:19], v[54:55], v[18:19] op_sel_hi:[1,0]
	v_pk_mul_f32 v[20:21], v[66:67], v[20:21] op_sel_hi:[1,0]
	v_pk_mul_f32 v[12:13], v[70:71], v[22:23] op_sel_hi:[1,0]
	ds_write2_b32 v15, v18, v19 offset1:1
	ds_write2_b32 v16, v20, v21 offset1:1
	s_cbranch_execnz .LBB0_183

.LBB0_183:
	v_add_u32_e32 v15, 0xc30, v14
	ds_write2_b32 v15, v12, v13 offset1:1
	v_pk_mul_f32 v[12:13], v[74:75], v[6:7] op_sel_hi:[1,0]
	v_add_u32_e32 v6, 0xe38, v14
	s_and_b64 vcc, exec, s[4:5]
	v_add_u32_e32 v15, 0x1040, v14
	v_add_u32_e32 v16, 0x1248, v14
	ds_write2_b32 v6, v12, v13 offset1:1
	s_cbranch_vccnz .LBB0_368
	v_mov_b32_e32 v29, v7
	v_lshl_add_u64 v[12:13], s[58:59], 0, v[28:29]
	global_load_dword v18, v[12:13], off offset:224
	global_load_dword v20, v[12:13], off offset:232
	global_load_dword v22, v[12:13], off offset:240
	global_load_dword v6, v[12:13], off offset:248
	s_waitcnt vmcnt(0) lgkmcnt(0)
	v_pk_mul_f32 v[18:19], v[62:63], v[18:19] op_sel_hi:[1,0]
	v_pk_mul_f32 v[20:21], v[72:73], v[20:21] op_sel_hi:[1,0]
	v_pk_mul_f32 v[12:13], v[76:77], v[22:23] op_sel_hi:[1,0]
	ds_write2_b32 v15, v18, v19 offset1:1
	ds_write2_b32 v16, v20, v21 offset1:1
	s_cbranch_execnz .LBB0_186

.LBB0_186:
	v_add_u32_e32 v15, 0x1450, v14
	s_add_u32 s4, s54, s82
	ds_write2_b32 v15, v12, v13 offset1:1
	v_pk_mul_f32 v[12:13], v[78:79], v[6:7] op_sel_hi:[1,0]
	v_add_u32_e32 v6, 0x1658, v14
	s_addc_u32 s5, s55, s81
	ds_write2_b32 v6, v12, v13 offset1:1
	v_lshlrev_b32_e32 v6, 1, v10
	s_waitcnt lgkmcnt(0)
	v_lshl_add_u64 v[12:13], s[4:5], 0, v[6:7]
	v_lshlrev_b32_e32 v6, 1, v4
	v_lshl_add_u64 v[12:13], v[12:13], 0, v[6:7]
	ds_read_b32 v6, v84
	ds_read_b32 v10, v84 offset:260
	ds_read_b32 v14, v84 offset:520
	ds_read_b32 v15, v84 offset:780
	ds_read_b32 v18, v84 offset:1040
	ds_read_b32 v19, v84 offset:1300
	ds_read_b32 v20, v84 offset:1560
	ds_read_b32 v21, v84 offset:1820
	v_lshl_add_u64 v[16:17], v[12:13], 0, s[36:37]
	s_waitcnt lgkmcnt(4)
	v_cvt_pk_bf16_f32 v13, v14, v15
	s_waitcnt lgkmcnt(2)
	v_cvt_pk_bf16_f32 v14, v18, v19
	v_or_b32_e32 v18, v11, v83
	v_ashrrev_i32_e32 v19, 31, v18
	v_lshlrev_b64 v[18:19], 11, v[18:19]
	v_cvt_pk_bf16_f32 v12, v6, v10
	s_waitcnt lgkmcnt(0)
	v_cvt_pk_bf16_f32 v15, v20, v21
	v_lshl_add_u64 v[18:19], v[16:17], 0, v[18:19]
	global_store_dwordx4 v[18:19], v[12:15], off
	ds_read_b32 v6, v84 offset:32
	ds_read_b32 v10, v84 offset:292
	ds_read_b32 v13, v84 offset:552
	ds_read_b32 v14, v84 offset:812
	ds_read_b32 v15, v84 offset:1072
	ds_read_b32 v18, v84 offset:1332
	ds_read_b32 v19, v84 offset:1592
	ds_read_b32 v20, v84 offset:1852
	s_waitcnt lgkmcnt(0)
	v_cvt_pk_bf16_f32 v13, v13, v14
	v_cvt_pk_bf16_f32 v12, v6, v10
	v_cvt_pk_bf16_f32 v14, v15, v18
	v_or_b32_e32 v18, v11, v85
	v_cvt_pk_bf16_f32 v15, v19, v20
	v_ashrrev_i32_e32 v19, 31, v18
	v_lshlrev_b64 v[18:19], 11, v[18:19]
	v_lshl_add_u64 v[18:19], v[16:17], 0, v[18:19]
	global_store_dwordx4 v[18:19], v[12:15], off
	ds_read_b32 v6, v84 offset:64
	ds_read_b32 v10, v84 offset:324
	ds_read_b32 v13, v84 offset:584
	ds_read_b32 v14, v84 offset:844
	ds_read_b32 v15, v84 offset:1104
	ds_read_b32 v18, v84 offset:1364
	ds_read_b32 v19, v84 offset:1624
	ds_read_b32 v20, v84 offset:1884
	s_waitcnt lgkmcnt(0)
	v_cvt_pk_bf16_f32 v13, v13, v14
	v_cvt_pk_bf16_f32 v12, v6, v10
	v_cvt_pk_bf16_f32 v14, v15, v18
	v_or_b32_e32 v18, v11, v86
	v_cvt_pk_bf16_f32 v15, v19, v20
	v_ashrrev_i32_e32 v19, 31, v18
	v_lshlrev_b64 v[18:19], 11, v[18:19]
	v_lshl_add_u64 v[18:19], v[16:17], 0, v[18:19]
	global_store_dwordx4 v[18:19], v[12:15], off
	ds_read_b32 v6, v84 offset:96
	ds_read_b32 v10, v84 offset:356
	ds_read_b32 v13, v84 offset:616
	ds_read_b32 v14, v84 offset:876
	ds_read_b32 v15, v84 offset:1136
	ds_read_b32 v18, v84 offset:1396
	ds_read_b32 v19, v84 offset:1656
	ds_read_b32 v20, v84 offset:1916
	s_waitcnt lgkmcnt(0)
	v_cvt_pk_bf16_f32 v13, v13, v14
	v_cvt_pk_bf16_f32 v12, v6, v10
	v_cvt_pk_bf16_f32 v14, v15, v18
	v_or_b32_e32 v18, v11, v87
	v_cvt_pk_bf16_f32 v15, v19, v20
	v_ashrrev_i32_e32 v19, 31, v18
	v_lshlrev_b64 v[18:19], 11, v[18:19]
	v_lshl_add_u64 v[18:19], v[16:17], 0, v[18:19]
	global_store_dwordx4 v[18:19], v[12:15], off
	ds_read_b32 v6, v84 offset:128
	ds_read_b32 v10, v84 offset:388
	ds_read_b32 v13, v84 offset:648
	ds_read_b32 v14, v84 offset:908
	ds_read_b32 v15, v84 offset:1168
	ds_read_b32 v18, v84 offset:1428
	ds_read_b32 v19, v84 offset:1688
	ds_read_b32 v20, v84 offset:1948
	s_waitcnt lgkmcnt(0)
	v_cvt_pk_bf16_f32 v13, v13, v14
	v_cvt_pk_bf16_f32 v12, v6, v10
	v_cvt_pk_bf16_f32 v14, v15, v18
	v_or_b32_e32 v18, v11, v88
	v_cvt_pk_bf16_f32 v15, v19, v20
	v_ashrrev_i32_e32 v19, 31, v18
	v_lshlrev_b64 v[18:19], 11, v[18:19]
	v_lshl_add_u64 v[18:19], v[16:17], 0, v[18:19]
	global_store_dwordx4 v[18:19], v[12:15], off
	ds_read_b32 v6, v84 offset:160
	ds_read_b32 v10, v84 offset:420
	ds_read_b32 v13, v84 offset:680
	ds_read_b32 v14, v84 offset:940
	ds_read_b32 v15, v84 offset:1200
	ds_read_b32 v18, v84 offset:1460
	ds_read_b32 v19, v84 offset:1720
	ds_read_b32 v20, v84 offset:1980
	s_waitcnt lgkmcnt(0)
	v_cvt_pk_bf16_f32 v13, v13, v14
	v_cvt_pk_bf16_f32 v12, v6, v10
	v_cvt_pk_bf16_f32 v14, v15, v18
	v_or_b32_e32 v18, v11, v89
	v_cvt_pk_bf16_f32 v15, v19, v20
	v_ashrrev_i32_e32 v19, 31, v18
	v_lshlrev_b64 v[18:19], 11, v[18:19]
	v_lshl_add_u64 v[18:19], v[16:17], 0, v[18:19]
	global_store_dwordx4 v[18:19], v[12:15], off
	ds_read_b32 v6, v84 offset:192
	ds_read_b32 v10, v84 offset:452
	ds_read_b32 v13, v84 offset:712
	ds_read_b32 v14, v84 offset:972
	ds_read_b32 v15, v84 offset:1232
	ds_read_b32 v18, v84 offset:1492
	ds_read_b32 v19, v84 offset:1752
	ds_read_b32 v20, v84 offset:2012
	s_waitcnt lgkmcnt(0)
	v_cvt_pk_bf16_f32 v13, v13, v14
	v_cvt_pk_bf16_f32 v12, v6, v10
	v_cvt_pk_bf16_f32 v14, v15, v18
	v_or_b32_e32 v18, v11, v90
	v_cvt_pk_bf16_f32 v15, v19, v20
	v_ashrrev_i32_e32 v19, 31, v18
	v_lshlrev_b64 v[18:19], 11, v[18:19]
	v_lshl_add_u64 v[18:19], v[16:17], 0, v[18:19]
	global_store_dwordx4 v[18:19], v[12:15], off
	ds_read_b32 v6, v84 offset:224
	ds_read_b32 v10, v84 offset:484
	ds_read_b32 v13, v84 offset:744
	ds_read_b32 v14, v84 offset:1004
	ds_read_b32 v15, v84 offset:1264
	ds_read_b32 v18, v84 offset:1524
	ds_read_b32 v19, v84 offset:1784
	ds_read_b32 v20, v84 offset:2044
	s_waitcnt lgkmcnt(0)
	v_cvt_pk_bf16_f32 v12, v6, v10
	v_or_b32_e32 v10, v11, v91
	v_ashrrev_i32_e32 v11, 31, v10
	v_lshlrev_b64 v[10:11], 11, v[10:11]
	v_cvt_pk_bf16_f32 v13, v13, v14
	v_cvt_pk_bf16_f32 v14, v15, v18
	v_cvt_pk_bf16_f32 v15, v19, v20
	v_lshl_add_u64 v[10:11], v[16:17], 0, v[10:11]
	global_store_dwordx4 v[10:11], v[12:15], off
	s_waitcnt lgkmcnt(0)
	s_or_b64 exec, exec, s[52:53]

.LBB0_188:
	v_lshlrev_b32_e32 v6, 6, v127
	v_and_b32_e32 v11, 0xfffffc00, v6
	v_lshl_add_u32 v6, v128, 2, v126
	v_and_b32_e32 v10, 0xffffffc0, v6
	v_add_u32_e32 v6, v124, v129
	s_mov_b64 s[4:5], s[8:9]
	s_lshl_b64 s[52:53], s[44:45], 2
	v_sub_u32_e32 v6, v6, v11
	s_add_u32 s54, s4, s52
	v_cmp_gt_i32_e32 vcc, s67, v6
	s_addc_u32 s55, s5, s53
	v_or_b32_e32 v12, v10, v2
	v_cndmask_b32_e32 v6, -1, v6, vcc
	s_mov_b64 s[52:53], s[22:23]
	v_cmp_lt_i32_e64 s[4:5], -1, v6
	v_lshl_add_u64 v[16:17], v[6:7], 2, s[54:55]
	v_mov_b32_e32 v14, 0
	v_lshlrev_b32_e32 v6, 10, v12
	v_mov_b32_e32 v12, 0
	v_mov_b32_e32 v13, 0
	s_and_saveexec_b64 s[54:55], s[4:5]
	s_cbranch_execz .LBB0_190
	v_lshl_add_u64 v[12:13], v[6:7], 2, v[16:17]
	global_load_dwordx2 v[12:13], v[12:13], off
.LBB0_190:
	s_or_b64 exec, exec, s[54:55]
	v_mov_b32_e32 v15, 0
	s_and_saveexec_b64 s[54:55], s[4:5]
	s_cbranch_execz .LBB0_192
	v_lshl_add_u64 v[14:15], v[6:7], 2, v[16:17]
	v_add_co_u32_e32 v14, vcc, 0x2000, v14
	s_nop 1
	v_addc_co_u32_e32 v15, vcc, 0, v15, vcc
	global_load_dwordx2 v[14:15], v[14:15], off
.LBB0_192:
	s_or_b64 exec, exec, s[54:55]
	v_mov_b32_e32 v18, 0
	v_mov_b32_e32 v20, 0
	v_mov_b32_e32 v21, 0
	s_and_saveexec_b64 s[54:55], s[4:5]
	s_cbranch_execz .LBB0_194
	v_lshl_add_u64 v[20:21], v[6:7], 2, v[16:17]
	v_add_co_u32_e32 v20, vcc, 0x4000, v20
	s_nop 1
	v_addc_co_u32_e32 v21, vcc, 0, v21, vcc
	global_load_dwordx2 v[20:21], v[20:21], off
.LBB0_194:
	s_or_b64 exec, exec, s[54:55]
	v_mov_b32_e32 v19, 0
	s_and_saveexec_b64 s[54:55], s[4:5]
	s_cbranch_execz .LBB0_196
	v_lshl_add_u64 v[18:19], v[6:7], 2, v[16:17]
	v_add_co_u32_e32 v18, vcc, 0x6000, v18
	s_nop 1
	v_addc_co_u32_e32 v19, vcc, 0, v19, vcc
	global_load_dwordx2 v[18:19], v[18:19], off
.LBB0_196:
	s_or_b64 exec, exec, s[54:55]
	v_mov_b32_e32 v22, 0
	v_mov_b32_e32 v24, 0
	v_mov_b32_e32 v25, 0
	s_and_saveexec_b64 s[54:55], s[4:5]
	s_cbranch_execz .LBB0_198
	v_lshl_add_u64 v[24:25], v[6:7], 2, v[16:17]
	v_add_co_u32_e32 v24, vcc, 0x8000, v24
	s_nop 1
	v_addc_co_u32_e32 v25, vcc, 0, v25, vcc
	global_load_dwordx2 v[24:25], v[24:25], off
.LBB0_198:
	s_or_b64 exec, exec, s[54:55]
	v_mov_b32_e32 v23, 0
	s_and_saveexec_b64 s[54:55], s[4:5]
	s_cbranch_execz .LBB0_200
	v_lshl_add_u64 v[22:23], v[6:7], 2, v[16:17]
	v_add_co_u32_e32 v22, vcc, 0xa000, v22
	s_nop 1
	v_addc_co_u32_e32 v23, vcc, 0, v23, vcc
	global_load_dwordx2 v[22:23], v[22:23], off
.LBB0_200:
	s_or_b64 exec, exec, s[54:55]
	v_mov_b32_e32 v26, 0
	v_mov_b32_e32 v28, 0
	v_mov_b32_e32 v29, 0
	s_and_saveexec_b64 s[54:55], s[4:5]
	s_cbranch_execz .LBB0_202
	v_lshl_add_u64 v[28:29], v[6:7], 2, v[16:17]
	v_add_co_u32_e32 v28, vcc, 0xc000, v28
	s_nop 1
	v_addc_co_u32_e32 v29, vcc, 0, v29, vcc
	global_load_dwordx2 v[28:29], v[28:29], off
.LBB0_202:
	s_or_b64 exec, exec, s[54:55]
	v_mov_b32_e32 v27, 0
	s_and_saveexec_b64 s[54:55], s[4:5]
	s_cbranch_execz .LBB0_204
	v_lshl_add_u64 v[26:27], v[6:7], 2, v[16:17]
	v_add_co_u32_e32 v26, vcc, 0xe000, v26
	s_nop 1
	v_addc_co_u32_e32 v27, vcc, 0, v27, vcc
	global_load_dwordx2 v[26:27], v[26:27], off
.LBB0_204:
	s_or_b64 exec, exec, s[54:55]
	v_mov_b32_e32 v30, 0
	v_mov_b32_e32 v32, 0
	v_mov_b32_e32 v33, 0
	s_and_saveexec_b64 s[54:55], s[4:5]
	s_cbranch_execz .LBB0_206
	v_lshl_add_u64 v[32:33], v[6:7], 2, v[16:17]
	v_add_co_u32_e32 v32, vcc, 0x10000, v32
	s_nop 1
	v_addc_co_u32_e32 v33, vcc, 0, v33, vcc
	global_load_dwordx2 v[32:33], v[32:33], off
.LBB0_206:
	s_or_b64 exec, exec, s[54:55]
	v_mov_b32_e32 v31, 0
	s_and_saveexec_b64 s[54:55], s[4:5]
	s_cbranch_execz .LBB0_208
	v_lshl_add_u64 v[30:31], v[6:7], 2, v[16:17]
	v_add_co_u32_e32 v30, vcc, 0x12000, v30
	s_nop 1
	v_addc_co_u32_e32 v31, vcc, 0, v31, vcc
	global_load_dwordx2 v[30:31], v[30:31], off
.LBB0_208:
	s_or_b64 exec, exec, s[54:55]
	v_mov_b32_e32 v34, 0
	v_mov_b32_e32 v36, 0
	v_mov_b32_e32 v37, 0
	s_and_saveexec_b64 s[54:55], s[4:5]
	s_cbranch_execz .LBB0_210
	v_lshl_add_u64 v[36:37], v[6:7], 2, v[16:17]
	v_add_co_u32_e32 v36, vcc, 0x14000, v36
	s_nop 1
	v_addc_co_u32_e32 v37, vcc, 0, v37, vcc
	global_load_dwordx2 v[36:37], v[36:37], off
.LBB0_210:
	s_or_b64 exec, exec, s[54:55]
	v_mov_b32_e32 v35, 0
	s_and_saveexec_b64 s[54:55], s[4:5]
	s_cbranch_execz .LBB0_212
	v_lshl_add_u64 v[34:35], v[6:7], 2, v[16:17]
	v_add_co_u32_e32 v34, vcc, 0x16000, v34
	s_nop 1
	v_addc_co_u32_e32 v35, vcc, 0, v35, vcc
	global_load_dwordx2 v[34:35], v[34:35], off
.LBB0_212:
	s_or_b64 exec, exec, s[54:55]
	v_mov_b32_e32 v38, 0
	v_mov_b32_e32 v40, 0
	v_mov_b32_e32 v41, 0
	s_and_saveexec_b64 s[54:55], s[4:5]
	s_cbranch_execz .LBB0_214
	v_lshl_add_u64 v[40:41], v[6:7], 2, v[16:17]
	v_add_co_u32_e32 v40, vcc, 0x18000, v40
	s_nop 1
	v_addc_co_u32_e32 v41, vcc, 0, v41, vcc
	global_load_dwordx2 v[40:41], v[40:41], off
.LBB0_214:
	s_or_b64 exec, exec, s[54:55]
	v_mov_b32_e32 v39, 0
	s_and_saveexec_b64 s[54:55], s[4:5]
	s_cbranch_execz .LBB0_216
	v_lshl_add_u64 v[38:39], v[6:7], 2, v[16:17]
	v_add_co_u32_e32 v38, vcc, 0x1a000, v38
	s_nop 1
	v_addc_co_u32_e32 v39, vcc, 0, v39, vcc
	global_load_dwordx2 v[38:39], v[38:39], off
.LBB0_216:
	s_or_b64 exec, exec, s[54:55]
	v_mov_b32_e32 v42, 0
	v_mov_b32_e32 v44, 0
	v_mov_b32_e32 v45, 0
	s_and_saveexec_b64 s[54:55], s[4:5]
	s_cbranch_execz .LBB0_218
	v_lshl_add_u64 v[44:45], v[6:7], 2, v[16:17]
	v_add_co_u32_e32 v44, vcc, 0x1c000, v44
	s_nop 1
	v_addc_co_u32_e32 v45, vcc, 0, v45, vcc
	global_load_dwordx2 v[44:45], v[44:45], off
.LBB0_218:
	s_or_b64 exec, exec, s[54:55]
	v_mov_b32_e32 v43, 0
	s_and_saveexec_b64 s[54:55], s[4:5]
	s_cbranch_execz .LBB0_220
	v_lshl_add_u64 v[42:43], v[6:7], 2, v[16:17]
	v_add_co_u32_e32 v42, vcc, 0x1e000, v42
	s_nop 1
	v_addc_co_u32_e32 v43, vcc, 0, v43, vcc
	global_load_dwordx2 v[42:43], v[42:43], off
.LBB0_220:
	s_or_b64 exec, exec, s[54:55]
	v_mov_b32_e32 v46, 0
	v_mov_b32_e32 v48, 0
	v_mov_b32_e32 v49, 0
	s_and_saveexec_b64 s[54:55], s[4:5]
	s_cbranch_execz .LBB0_222
	v_lshl_add_u64 v[48:49], v[6:7], 2, v[16:17]
	v_add_co_u32_e32 v48, vcc, 0x20000, v48
	s_nop 1
	v_addc_co_u32_e32 v49, vcc, 0, v49, vcc
	global_load_dwordx2 v[48:49], v[48:49], off
.LBB0_222:
	s_or_b64 exec, exec, s[54:55]
	v_mov_b32_e32 v47, 0
	s_and_saveexec_b64 s[54:55], s[4:5]
	s_cbranch_execz .LBB0_224
	v_lshl_add_u64 v[46:47], v[6:7], 2, v[16:17]
	v_add_co_u32_e32 v46, vcc, 0x22000, v46
	s_nop 1
	v_addc_co_u32_e32 v47, vcc, 0, v47, vcc
	global_load_dwordx2 v[46:47], v[46:47], off
.LBB0_224:
	s_or_b64 exec, exec, s[54:55]
	v_mov_b32_e32 v50, 0
	v_mov_b32_e32 v52, 0
	v_mov_b32_e32 v53, 0
	s_and_saveexec_b64 s[54:55], s[4:5]
	s_cbranch_execz .LBB0_226
	v_lshl_add_u64 v[52:53], v[6:7], 2, v[16:17]
	v_add_co_u32_e32 v52, vcc, 0x24000, v52
	s_nop 1
	v_addc_co_u32_e32 v53, vcc, 0, v53, vcc
	global_load_dwordx2 v[52:53], v[52:53], off
.LBB0_226:
	s_or_b64 exec, exec, s[54:55]
	v_mov_b32_e32 v51, 0
	s_and_saveexec_b64 s[54:55], s[4:5]
	s_cbranch_execz .LBB0_228
	v_lshl_add_u64 v[50:51], v[6:7], 2, v[16:17]
	v_add_co_u32_e32 v50, vcc, 0x26000, v50
	s_nop 1
	v_addc_co_u32_e32 v51, vcc, 0, v51, vcc
	global_load_dwordx2 v[50:51], v[50:51], off
.LBB0_228:
	s_or_b64 exec, exec, s[54:55]
	v_mov_b32_e32 v54, 0
	v_mov_b32_e32 v56, 0
	v_mov_b32_e32 v57, 0
	s_and_saveexec_b64 s[54:55], s[4:5]
	s_cbranch_execz .LBB0_230
	v_lshl_add_u64 v[56:57], v[6:7], 2, v[16:17]
	v_add_co_u32_e32 v56, vcc, 0x28000, v56
	s_nop 1
	v_addc_co_u32_e32 v57, vcc, 0, v57, vcc
	global_load_dwordx2 v[56:57], v[56:57], off
.LBB0_230:
	s_or_b64 exec, exec, s[54:55]
	v_mov_b32_e32 v55, 0
	s_and_saveexec_b64 s[54:55], s[4:5]
	s_cbranch_execz .LBB0_232
	v_lshl_add_u64 v[54:55], v[6:7], 2, v[16:17]
	v_add_co_u32_e32 v54, vcc, 0x2a000, v54
	s_nop 1
	v_addc_co_u32_e32 v55, vcc, 0, v55, vcc
	global_load_dwordx2 v[54:55], v[54:55], off
.LBB0_232:
	s_or_b64 exec, exec, s[54:55]
	v_mov_b32_e32 v58, 0
	v_mov_b32_e32 v60, 0
	v_mov_b32_e32 v61, 0
	s_and_saveexec_b64 s[54:55], s[4:5]
	s_cbranch_execz .LBB0_234
	v_lshl_add_u64 v[60:61], v[6:7], 2, v[16:17]
	v_add_co_u32_e32 v60, vcc, 0x2c000, v60
	s_nop 1
	v_addc_co_u32_e32 v61, vcc, 0, v61, vcc
	global_load_dwordx2 v[60:61], v[60:61], off
.LBB0_234:
	s_or_b64 exec, exec, s[54:55]
	v_mov_b32_e32 v59, 0
	s_and_saveexec_b64 s[54:55], s[4:5]
	s_cbranch_execz .LBB0_236
	v_lshl_add_u64 v[58:59], v[6:7], 2, v[16:17]
	v_add_co_u32_e32 v58, vcc, 0x2e000, v58
	s_nop 1
	v_addc_co_u32_e32 v59, vcc, 0, v59, vcc
	global_load_dwordx2 v[58:59], v[58:59], off
.LBB0_236:
	s_or_b64 exec, exec, s[54:55]
	v_mov_b32_e32 v62, 0
	v_mov_b32_e32 v64, 0
	v_mov_b32_e32 v65, 0
	s_and_saveexec_b64 s[54:55], s[4:5]
	s_cbranch_execz .LBB0_238
	v_lshl_add_u64 v[64:65], v[6:7], 2, v[16:17]
	v_add_co_u32_e32 v64, vcc, 0x30000, v64
	s_nop 1
	v_addc_co_u32_e32 v65, vcc, 0, v65, vcc
	global_load_dwordx2 v[64:65], v[64:65], off
.LBB0_238:
	s_or_b64 exec, exec, s[54:55]
	v_mov_b32_e32 v63, 0
	s_and_saveexec_b64 s[54:55], s[4:5]
	s_cbranch_execz .LBB0_240
	v_lshl_add_u64 v[62:63], v[6:7], 2, v[16:17]
	v_add_co_u32_e32 v62, vcc, 0x32000, v62
	s_nop 1
	v_addc_co_u32_e32 v63, vcc, 0, v63, vcc
	global_load_dwordx2 v[62:63], v[62:63], off
.LBB0_240:
	s_or_b64 exec, exec, s[54:55]
	v_mov_b32_e32 v66, 0
	v_mov_b32_e32 v68, 0
	v_mov_b32_e32 v69, 0
	s_and_saveexec_b64 s[54:55], s[4:5]
	s_cbranch_execz .LBB0_242
	v_lshl_add_u64 v[68:69], v[6:7], 2, v[16:17]
	v_add_co_u32_e32 v68, vcc, 0x34000, v68
	s_nop 1
	v_addc_co_u32_e32 v69, vcc, 0, v69, vcc
	global_load_dwordx2 v[68:69], v[68:69], off
.LBB0_242:
	s_or_b64 exec, exec, s[54:55]
	v_mov_b32_e32 v67, 0
	s_and_saveexec_b64 s[54:55], s[4:5]
	s_cbranch_execz .LBB0_244
	v_lshl_add_u64 v[66:67], v[6:7], 2, v[16:17]
	v_add_co_u32_e32 v66, vcc, 0x36000, v66
	s_nop 1
	v_addc_co_u32_e32 v67, vcc, 0, v67, vcc
	global_load_dwordx2 v[66:67], v[66:67], off
.LBB0_244:
	s_or_b64 exec, exec, s[54:55]
	v_mov_b32_e32 v70, 0
	v_mov_b32_e32 v72, 0
	v_mov_b32_e32 v73, 0
	s_and_saveexec_b64 s[54:55], s[4:5]
	s_cbranch_execz .LBB0_246
	v_lshl_add_u64 v[72:73], v[6:7], 2, v[16:17]
	v_add_co_u32_e32 v72, vcc, 0x38000, v72
	s_nop 1
	v_addc_co_u32_e32 v73, vcc, 0, v73, vcc
	global_load_dwordx2 v[72:73], v[72:73], off
.LBB0_246:
	s_or_b64 exec, exec, s[54:55]
	v_mov_b32_e32 v71, 0
	s_and_saveexec_b64 s[54:55], s[4:5]
	s_cbranch_execz .LBB0_248
	v_lshl_add_u64 v[70:71], v[6:7], 2, v[16:17]
	v_add_co_u32_e32 v70, vcc, 0x3a000, v70
	s_nop 1
	v_addc_co_u32_e32 v71, vcc, 0, v71, vcc
	global_load_dwordx2 v[70:71], v[70:71], off
.LBB0_248:
	s_or_b64 exec, exec, s[54:55]
	v_mov_b32_e32 v74, 0
	v_mov_b32_e32 v76, 0
	v_mov_b32_e32 v77, 0
	s_and_saveexec_b64 s[54:55], s[4:5]
	s_cbranch_execz .LBB0_250
	v_lshl_add_u64 v[76:77], v[6:7], 2, v[16:17]
	v_add_co_u32_e32 v76, vcc, 0x3c000, v76
	s_nop 1
	v_addc_co_u32_e32 v77, vcc, 0, v77, vcc
	global_load_dwordx2 v[76:77], v[76:77], off
.LBB0_250:
	s_or_b64 exec, exec, s[54:55]
	v_mov_b32_e32 v75, 0
	s_and_saveexec_b64 s[54:55], s[4:5]
	s_cbranch_execz .LBB0_252
	v_lshl_add_u64 v[16:17], v[6:7], 2, v[16:17]
	v_add_co_u32_e32 v16, vcc, 0x3e000, v16
	s_nop 1
	v_addc_co_u32_e32 v17, vcc, 0, v17, vcc
	global_load_dwordx2 v[74:75], v[16:17], off
.LBB0_252:
	s_or_b64 exec, exec, s[54:55]
	v_add_u32_e32 v6, v5, v82
	v_sub_u32_e32 v78, 0, v11
	v_add_u32_e32 v11, 0x410, v6
	s_waitcnt vmcnt(0) lgkmcnt(0)
	ds_write2_b32 v6, v12, v13 offset1:1
	ds_write2_b32 v6, v14, v15 offset0:130 offset1:131
	ds_write2_b32 v11, v20, v21 offset1:1
	v_add_u32_e32 v11, 0x618, v6
	ds_write2_b32 v11, v18, v19 offset1:1
	v_add_u32_e32 v11, 0x820, v6
	ds_write2_b32 v11, v24, v25 offset1:1
	v_add_u32_e32 v11, 0xa28, v6
	ds_write2_b32 v11, v22, v23 offset1:1
	v_add_u32_e32 v11, 0xc30, v6
	ds_write2_b32 v11, v28, v29 offset1:1
	v_add_u32_e32 v11, 0xe38, v6
	ds_write2_b32 v11, v26, v27 offset1:1
	v_add_u32_e32 v11, 0x1040, v6
	ds_write2_b32 v11, v32, v33 offset1:1
	v_add_u32_e32 v11, 0x1248, v6
	ds_write2_b32 v11, v30, v31 offset1:1
	v_add_u32_e32 v11, 0x1450, v6
	ds_write2_b32 v11, v36, v37 offset1:1
	v_add_u32_e32 v11, 0x1658, v6
	ds_write2_b32 v11, v34, v35 offset1:1
	v_add_u32_e32 v11, 0x1860, v6
	ds_write2_b32 v11, v40, v41 offset1:1
	v_add_u32_e32 v11, 0x1a68, v6
	ds_write2_b32 v11, v38, v39 offset1:1
	v_add_u32_e32 v11, 0x1c70, v6
	ds_write2_b32 v11, v44, v45 offset1:1
	v_add_u32_e32 v11, 0x1e78, v6
	ds_write2_b32 v11, v42, v43 offset1:1
	v_add_u32_e32 v11, 0x2080, v6
	ds_write2_b32 v11, v48, v49 offset1:1
	v_add_u32_e32 v11, 0x2288, v6
	ds_write2_b32 v11, v46, v47 offset1:1
	v_add_u32_e32 v11, 0x2490, v6
	ds_write2_b32 v11, v52, v53 offset1:1
	v_add_u32_e32 v11, 0x2698, v6
	ds_write2_b32 v11, v50, v51 offset1:1
	v_add_u32_e32 v11, 0x28a0, v6
	ds_write2_b32 v11, v56, v57 offset1:1
	v_add_u32_e32 v11, 0x2aa8, v6
	ds_write2_b32 v11, v54, v55 offset1:1
	v_add_u32_e32 v11, 0x2cb0, v6
	ds_write2_b32 v11, v60, v61 offset1:1
	v_add_u32_e32 v11, 0x2eb8, v6
	ds_write2_b32 v11, v58, v59 offset1:1
	v_add_u32_e32 v11, 0x30c0, v6
	ds_write2_b32 v11, v64, v65 offset1:1
	v_add_u32_e32 v11, 0x32c8, v6
	ds_write2_b32 v11, v62, v63 offset1:1
	v_add_u32_e32 v11, 0x34d0, v6
	ds_write2_b32 v11, v68, v69 offset1:1
	v_add_u32_e32 v11, 0x36d8, v6
	ds_write2_b32 v11, v66, v67 offset1:1
	v_add_u32_e32 v11, 0x38e0, v6
	s_lshl_b64 s[4:5], s[44:45], 1
	ds_write2_b32 v11, v72, v73 offset1:1
	v_add_u32_e32 v11, 0x3ae8, v6
	s_add_u32 s4, s52, s4
	ds_write2_b32 v11, v70, v71 offset1:1
	v_add_u32_e32 v11, 0x3cf0, v6
	v_add_u32_e32 v6, 0x3ef8, v6
	s_addc_u32 s5, s53, s5
	ds_write2_b32 v11, v76, v77 offset1:1
	ds_write2_b32 v6, v74, v75 offset1:1
	v_mov_b32_e32 v11, v7
	s_waitcnt lgkmcnt(0)
	v_lshl_add_u64 v[10:11], v[10:11], 1, s[4:5]
	v_lshlrev_b32_e32 v6, 1, v4
	v_lshl_add_u64 v[10:11], v[10:11], 0, v[6:7]
	ds_read_b32 v6, v84
	ds_read_b32 v12, v84 offset:260
	ds_read_b32 v13, v84 offset:520
	ds_read_b32 v16, v84 offset:780
	ds_read_b32 v17, v84 offset:1040
	ds_read_b32 v18, v84 offset:1300
	ds_read_b32 v19, v84 offset:1560
	ds_read_b32 v20, v84 offset:1820
	v_lshl_add_u64 v[14:15], v[10:11], 0, s[38:39]
	s_waitcnt lgkmcnt(4)
	v_cvt_pk_bf16_f32 v11, v13, v16
	v_add3_u32 v16, v123, v129, v78
	v_cvt_pk_bf16_f32 v10, v6, v12
	s_waitcnt lgkmcnt(2)
	v_cvt_pk_bf16_f32 v12, v17, v18
	v_ashrrev_i32_e32 v17, 31, v16
	v_lshlrev_b64 v[16:17], 11, v[16:17]
	s_waitcnt lgkmcnt(0)
	v_cvt_pk_bf16_f32 v13, v19, v20
	v_lshl_add_u64 v[16:17], v[14:15], 0, v[16:17]
	global_store_dwordx4 v[16:17], v[10:13], off
	ds_read_b32 v6, v84 offset:32
	ds_read_b32 v10, v84 offset:292
	ds_read_b32 v11, v84 offset:552
	ds_read_b32 v12, v84 offset:812
	ds_read_b32 v13, v84 offset:1072
	ds_read_b32 v16, v84 offset:1332
	ds_read_b32 v17, v84 offset:1592
	ds_read_b32 v18, v84 offset:1852
	s_waitcnt lgkmcnt(0)
	v_cvt_pk_bf16_f32 v11, v11, v12
	v_cvt_pk_bf16_f32 v10, v6, v10
	v_cvt_pk_bf16_f32 v12, v13, v16
	v_add3_u32 v16, v122, v129, v78
	v_cvt_pk_bf16_f32 v13, v17, v18
	v_ashrrev_i32_e32 v17, 31, v16
	v_lshlrev_b64 v[16:17], 11, v[16:17]
	v_lshl_add_u64 v[16:17], v[14:15], 0, v[16:17]
	global_store_dwordx4 v[16:17], v[10:13], off
	ds_read_b32 v6, v84 offset:64
	ds_read_b32 v10, v84 offset:324
	ds_read_b32 v11, v84 offset:584
	ds_read_b32 v12, v84 offset:844
	ds_read_b32 v13, v84 offset:1104
	ds_read_b32 v16, v84 offset:1364
	ds_read_b32 v17, v84 offset:1624
	ds_read_b32 v18, v84 offset:1884
	s_waitcnt lgkmcnt(0)
	v_cvt_pk_bf16_f32 v11, v11, v12
	v_cvt_pk_bf16_f32 v10, v6, v10
	v_cvt_pk_bf16_f32 v12, v13, v16
	v_add3_u32 v16, v121, v129, v78
	v_cvt_pk_bf16_f32 v13, v17, v18
	v_ashrrev_i32_e32 v17, 31, v16
	v_lshlrev_b64 v[16:17], 11, v[16:17]
	v_lshl_add_u64 v[16:17], v[14:15], 0, v[16:17]
	global_store_dwordx4 v[16:17], v[10:13], off
	ds_read_b32 v6, v84 offset:96
	ds_read_b32 v10, v84 offset:356
	ds_read_b32 v11, v84 offset:616
	ds_read_b32 v12, v84 offset:876
	ds_read_b32 v13, v84 offset:1136
	ds_read_b32 v16, v84 offset:1396
	ds_read_b32 v17, v84 offset:1656
	ds_read_b32 v18, v84 offset:1916
	s_waitcnt lgkmcnt(0)
	v_cvt_pk_bf16_f32 v11, v11, v12
	v_cvt_pk_bf16_f32 v10, v6, v10
	v_cvt_pk_bf16_f32 v12, v13, v16
	v_add3_u32 v16, v120, v129, v78
	v_cvt_pk_bf16_f32 v13, v17, v18
	v_ashrrev_i32_e32 v17, 31, v16
	v_lshlrev_b64 v[16:17], 11, v[16:17]
	v_lshl_add_u64 v[16:17], v[14:15], 0, v[16:17]
	global_store_dwordx4 v[16:17], v[10:13], off
	ds_read_b32 v6, v84 offset:128
	ds_read_b32 v10, v84 offset:388
	ds_read_b32 v11, v84 offset:648
	ds_read_b32 v12, v84 offset:908
	ds_read_b32 v13, v84 offset:1168
	ds_read_b32 v16, v84 offset:1428
	ds_read_b32 v17, v84 offset:1688
	ds_read_b32 v18, v84 offset:1948
	s_waitcnt lgkmcnt(0)
	v_cvt_pk_bf16_f32 v11, v11, v12
	v_cvt_pk_bf16_f32 v10, v6, v10
	v_cvt_pk_bf16_f32 v12, v13, v16
	v_add3_u32 v16, v119, v129, v78
	v_cvt_pk_bf16_f32 v13, v17, v18
	v_ashrrev_i32_e32 v17, 31, v16
	v_lshlrev_b64 v[16:17], 11, v[16:17]
	v_lshl_add_u64 v[16:17], v[14:15], 0, v[16:17]
	global_store_dwordx4 v[16:17], v[10:13], off
	ds_read_b32 v6, v84 offset:160
	ds_read_b32 v10, v84 offset:420
	ds_read_b32 v11, v84 offset:680
	ds_read_b32 v12, v84 offset:940
	ds_read_b32 v13, v84 offset:1200
	ds_read_b32 v16, v84 offset:1460
	ds_read_b32 v17, v84 offset:1720
	ds_read_b32 v18, v84 offset:1980
	s_waitcnt lgkmcnt(0)
	v_cvt_pk_bf16_f32 v11, v11, v12
	v_cvt_pk_bf16_f32 v10, v6, v10
	v_cvt_pk_bf16_f32 v12, v13, v16
	v_add3_u32 v16, v118, v129, v78
	v_cvt_pk_bf16_f32 v13, v17, v18
	v_ashrrev_i32_e32 v17, 31, v16
	v_lshlrev_b64 v[16:17], 11, v[16:17]
	v_lshl_add_u64 v[16:17], v[14:15], 0, v[16:17]
	global_store_dwordx4 v[16:17], v[10:13], off
	ds_read_b32 v6, v84 offset:192
	ds_read_b32 v10, v84 offset:452
	ds_read_b32 v11, v84 offset:712
	ds_read_b32 v12, v84 offset:972
	ds_read_b32 v13, v84 offset:1232
	ds_read_b32 v16, v84 offset:1492
	ds_read_b32 v17, v84 offset:1752
	ds_read_b32 v18, v84 offset:2012
	s_waitcnt lgkmcnt(0)
	v_cvt_pk_bf16_f32 v11, v11, v12
	v_cvt_pk_bf16_f32 v10, v6, v10
	v_cvt_pk_bf16_f32 v12, v13, v16
	v_add3_u32 v16, v117, v129, v78
	v_cvt_pk_bf16_f32 v13, v17, v18
	v_ashrrev_i32_e32 v17, 31, v16
	v_lshlrev_b64 v[16:17], 11, v[16:17]
	v_lshl_add_u64 v[16:17], v[14:15], 0, v[16:17]
	global_store_dwordx4 v[16:17], v[10:13], off
	ds_read_b32 v6, v84 offset:224
	ds_read_b32 v10, v84 offset:484
	ds_read_b32 v11, v84 offset:744
	ds_read_b32 v12, v84 offset:1004
	ds_read_b32 v13, v84 offset:1264
	ds_read_b32 v16, v84 offset:1524
	ds_read_b32 v17, v84 offset:1784
	ds_read_b32 v18, v84 offset:2044
	s_waitcnt lgkmcnt(0)
	v_cvt_pk_bf16_f32 v11, v11, v12
	v_cvt_pk_bf16_f32 v10, v6, v10
	v_cvt_pk_bf16_f32 v12, v13, v16
	v_add3_u32 v16, v115, v129, v78
	v_cvt_pk_bf16_f32 v13, v17, v18
	v_ashrrev_i32_e32 v17, 31, v16
	v_lshlrev_b64 v[16:17], 11, v[16:17]
	v_lshl_add_u64 v[14:15], v[14:15], 0, v[16:17]
	global_store_dwordx4 v[14:15], v[10:13], off
	s_waitcnt lgkmcnt(0)

.LBB0_265:
	s_or_b64 exec, exec, s[54:55]
	s_add_u32 s52, s52, s87
	s_addc_u32 s53, s53, s41
	v_lshlrev_b32_e32 v10, 6, v10
	v_cmp_lt_i32_e32 vcc, -1, v6
	v_or_b32_e32 v36, v10, v2
	v_lshl_add_u64 v[64:65], v[6:7], 2, s[52:53]
	v_mov_b32_e32 v16, 0
	v_mov_b32_e32 v18, 0
	v_mov_b32_e32 v19, 0
	s_and_saveexec_b64 s[52:53], vcc
	s_cbranch_execz .LBB0_267
	v_mad_i64_i32 v[12:13], s[54:55], v36, s79, v[64:65]
	global_load_dwordx2 v[18:19], v[12:13], off
.LBB0_267:
	s_or_b64 exec, exec, s[52:53]
	v_mov_b32_e32 v17, 0
	s_and_saveexec_b64 s[52:53], vcc
	s_cbranch_execz .LBB0_269
	v_or_b32_e32 v6, 2, v36
	v_mad_i64_i32 v[12:13], s[54:55], v6, s79, v[64:65]
	global_load_dwordx2 v[16:17], v[12:13], off
.LBB0_269:
	s_or_b64 exec, exec, s[52:53]
	v_mov_b32_e32 v6, v7
	v_mov_b64_e32 v[34:35], v[6:7]
	s_and_saveexec_b64 s[52:53], vcc
	s_cbranch_execz .LBB0_271
	v_or_b32_e32 v6, 4, v36
	v_mad_i64_i32 v[12:13], s[54:55], v6, s79, v[64:65]
	global_load_dwordx2 v[34:35], v[12:13], off
.LBB0_271:
	s_or_b64 exec, exec, s[52:53]
	v_mov_b32_e32 v12, 0
	v_mov_b32_e32 v38, 0
	v_mov_b32_e32 v39, 0
	s_and_saveexec_b64 s[52:53], vcc
	s_cbranch_execz .LBB0_273
	v_or_b32_e32 v6, 6, v36
	v_mad_i64_i32 v[14:15], s[54:55], v6, s79, v[64:65]
	global_load_dwordx2 v[38:39], v[14:15], off
.LBB0_273:
	s_or_b64 exec, exec, s[52:53]
	v_mov_b32_e32 v13, 0
	s_and_saveexec_b64 s[52:53], vcc
	s_cbranch_execz .LBB0_275
	v_or_b32_e32 v6, 8, v36
	v_mad_i64_i32 v[12:13], s[54:55], v6, s79, v[64:65]
	global_load_dwordx2 v[12:13], v[12:13], off
.LBB0_275:
	s_or_b64 exec, exec, s[52:53]
	v_mov_b32_e32 v26, 0
	v_mov_b32_e32 v27, v26
	s_and_saveexec_b64 s[52:53], vcc
	s_cbranch_execz .LBB0_277
	v_or_b32_e32 v6, 10, v36
	v_mad_i64_i32 v[14:15], s[54:55], v6, s79, v[64:65]
	global_load_dwordx2 v[26:27], v[14:15], off
.LBB0_277:
	s_or_b64 exec, exec, s[52:53]
	v_mov_b32_e32 v6, v7
	v_mov_b64_e32 v[42:43], v[6:7]
	s_and_saveexec_b64 s[52:53], vcc
	s_cbranch_execz .LBB0_279
	v_or_b32_e32 v6, 12, v36
	v_mad_i64_i32 v[14:15], s[54:55], v6, s79, v[64:65]
	global_load_dwordx2 v[42:43], v[14:15], off
.LBB0_279:
	s_or_b64 exec, exec, s[52:53]
	v_mov_b32_e32 v14, 0
	v_mov_b32_e32 v44, 0
	v_mov_b32_e32 v45, 0
	s_and_saveexec_b64 s[52:53], vcc
	s_cbranch_execz .LBB0_281
	v_or_b32_e32 v6, 14, v36
	v_mad_i64_i32 v[20:21], s[54:55], v6, s79, v[64:65]
	global_load_dwordx2 v[44:45], v[20:21], off
.LBB0_281:
	s_or_b64 exec, exec, s[52:53]
	v_mov_b32_e32 v15, 0
	s_and_saveexec_b64 s[52:53], vcc
	s_cbranch_execz .LBB0_283
	v_or_b32_e32 v6, 16, v36
	v_mad_i64_i32 v[14:15], s[54:55], v6, s79, v[64:65]
	global_load_dwordx2 v[14:15], v[14:15], off
.LBB0_283:
	s_or_b64 exec, exec, s[52:53]
	v_mov_b32_e32 v32, 0
	v_mov_b32_e32 v33, v32
	s_and_saveexec_b64 s[52:53], vcc
	s_cbranch_execz .LBB0_285
	v_or_b32_e32 v6, 18, v36
	v_mad_i64_i32 v[20:21], s[54:55], v6, s79, v[64:65]
	global_load_dwordx2 v[32:33], v[20:21], off
.LBB0_285:
	s_or_b64 exec, exec, s[52:53]
	v_mov_b32_e32 v6, v7
	v_mov_b64_e32 v[48:49], v[6:7]
	s_and_saveexec_b64 s[52:53], vcc
	s_cbranch_execz .LBB0_287
	v_or_b32_e32 v6, 20, v36
	v_mad_i64_i32 v[20:21], s[54:55], v6, s79, v[64:65]
	global_load_dwordx2 v[48:49], v[20:21], off
.LBB0_287:
	s_or_b64 exec, exec, s[52:53]
	v_mov_b32_e32 v20, 0
	v_mov_b32_e32 v50, 0
	v_mov_b32_e32 v51, 0
	s_and_saveexec_b64 s[52:53], vcc
	s_cbranch_execz .LBB0_289
	v_or_b32_e32 v6, 22, v36
	v_mad_i64_i32 v[22:23], s[54:55], v6, s79, v[64:65]
	global_load_dwordx2 v[50:51], v[22:23], off
.LBB0_289:
	s_or_b64 exec, exec, s[52:53]
	v_mov_b32_e32 v21, 0
	s_and_saveexec_b64 s[52:53], vcc
	s_cbranch_execz .LBB0_291
	v_or_b32_e32 v6, 24, v36
	v_mad_i64_i32 v[20:21], s[54:55], v6, s79, v[64:65]
	global_load_dwordx2 v[20:21], v[20:21], off
.LBB0_291:
	s_or_b64 exec, exec, s[52:53]
	v_mov_b32_e32 v40, 0
	v_mov_b32_e32 v41, v40
	s_and_saveexec_b64 s[52:53], vcc
	s_cbranch_execz .LBB0_293
	v_or_b32_e32 v6, 26, v36
	v_mad_i64_i32 v[22:23], s[54:55], v6, s79, v[64:65]
	global_load_dwordx2 v[40:41], v[22:23], off
.LBB0_293:
	s_or_b64 exec, exec, s[52:53]
	v_mov_b32_e32 v6, v7
	v_mov_b64_e32 v[54:55], v[6:7]
	s_and_saveexec_b64 s[52:53], vcc
	s_cbranch_execz .LBB0_295
	v_or_b32_e32 v6, 28, v36
	v_mad_i64_i32 v[22:23], s[54:55], v6, s79, v[64:65]
	global_load_dwordx2 v[54:55], v[22:23], off
.LBB0_295:
	s_or_b64 exec, exec, s[52:53]
	v_mov_b32_e32 v22, 0
	v_mov_b32_e32 v56, 0
	v_mov_b32_e32 v57, 0
	s_and_saveexec_b64 s[52:53], vcc
	s_cbranch_execz .LBB0_297
	v_or_b32_e32 v6, 30, v36
	v_mad_i64_i32 v[24:25], s[54:55], v6, s79, v[64:65]
	global_load_dwordx2 v[56:57], v[24:25], off
.LBB0_297:
	s_or_b64 exec, exec, s[52:53]
	v_mov_b32_e32 v23, 0
	s_and_saveexec_b64 s[52:53], vcc
	s_cbranch_execz .LBB0_299
	v_or_b32_e32 v6, 32, v36
	v_mad_i64_i32 v[22:23], s[54:55], v6, s79, v[64:65]
	global_load_dwordx2 v[22:23], v[22:23], off
.LBB0_299:
	s_or_b64 exec, exec, s[52:53]
	v_mov_b32_e32 v46, 0
	v_mov_b32_e32 v47, v46
	s_and_saveexec_b64 s[52:53], vcc
	s_cbranch_execz .LBB0_301
	v_or_b32_e32 v6, 34, v36
	v_mad_i64_i32 v[24:25], s[54:55], v6, s79, v[64:65]
	global_load_dwordx2 v[46:47], v[24:25], off
.LBB0_301:
	s_or_b64 exec, exec, s[52:53]
	v_mov_b32_e32 v6, v7
	v_mov_b64_e32 v[62:63], v[6:7]
	s_and_saveexec_b64 s[52:53], vcc
	s_cbranch_execz .LBB0_303
	v_or_b32_e32 v6, 36, v36
	v_mad_i64_i32 v[24:25], s[54:55], v6, s79, v[64:65]
	global_load_dwordx2 v[62:63], v[24:25], off
.LBB0_303:
	s_or_b64 exec, exec, s[52:53]
	v_mov_b32_e32 v24, 0
	v_mov_b32_e32 v66, 0
	v_mov_b32_e32 v67, 0
	s_and_saveexec_b64 s[52:53], vcc
	s_cbranch_execz .LBB0_305
	v_or_b32_e32 v6, 38, v36
	v_mad_i64_i32 v[28:29], s[54:55], v6, s79, v[64:65]
	global_load_dwordx2 v[66:67], v[28:29], off
.LBB0_305:
	s_or_b64 exec, exec, s[52:53]
	v_mov_b32_e32 v25, 0
	s_and_saveexec_b64 s[52:53], vcc
	s_cbranch_execz .LBB0_307
	v_or_b32_e32 v6, 40, v36
	v_mad_i64_i32 v[24:25], s[54:55], v6, s79, v[64:65]
	global_load_dwordx2 v[24:25], v[24:25], off
.LBB0_307:
	s_or_b64 exec, exec, s[52:53]
	v_mov_b32_e32 v52, 0
	v_mov_b32_e32 v53, v52
	s_and_saveexec_b64 s[52:53], vcc
	s_cbranch_execz .LBB0_309
	v_or_b32_e32 v6, 42, v36
	v_mad_i64_i32 v[28:29], s[54:55], v6, s79, v[64:65]
	global_load_dwordx2 v[52:53], v[28:29], off
.LBB0_309:
	s_or_b64 exec, exec, s[52:53]
	v_mov_b32_e32 v6, v7
	v_mov_b64_e32 v[68:69], v[6:7]
	s_and_saveexec_b64 s[52:53], vcc
	s_cbranch_execz .LBB0_311
	v_or_b32_e32 v6, 44, v36
	v_mad_i64_i32 v[28:29], s[54:55], v6, s79, v[64:65]
	global_load_dwordx2 v[68:69], v[28:29], off
.LBB0_311:
	s_or_b64 exec, exec, s[52:53]
	v_mov_b32_e32 v28, 0
	v_mov_b32_e32 v70, 0
	v_mov_b32_e32 v71, 0
	s_and_saveexec_b64 s[52:53], vcc
	s_cbranch_execz .LBB0_313
	v_or_b32_e32 v6, 46, v36
	v_mad_i64_i32 v[30:31], s[54:55], v6, s79, v[64:65]
	global_load_dwordx2 v[70:71], v[30:31], off
.LBB0_313:
	s_or_b64 exec, exec, s[52:53]
	v_mov_b32_e32 v29, 0
	s_and_saveexec_b64 s[52:53], vcc
	s_cbranch_execz .LBB0_315
	v_or_b32_e32 v6, 48, v36
	v_mad_i64_i32 v[28:29], s[54:55], v6, s79, v[64:65]
	global_load_dwordx2 v[28:29], v[28:29], off
.LBB0_315:
	s_or_b64 exec, exec, s[52:53]
	v_mov_b32_e32 v58, 0
	v_mov_b32_e32 v59, v58
	s_and_saveexec_b64 s[52:53], vcc
	s_cbranch_execz .LBB0_317
	v_or_b32_e32 v6, 50, v36
	v_mad_i64_i32 v[30:31], s[54:55], v6, s79, v[64:65]
	global_load_dwordx2 v[58:59], v[30:31], off
.LBB0_317:
	s_or_b64 exec, exec, s[52:53]
	v_mov_b32_e32 v6, v7
	v_mov_b64_e32 v[76:77], v[6:7]
	s_and_saveexec_b64 s[52:53], vcc
	s_cbranch_execz .LBB0_319
	v_or_b32_e32 v6, 52, v36
	v_mad_i64_i32 v[30:31], s[54:55], v6, s79, v[64:65]
	global_load_dwordx2 v[76:77], v[30:31], off
.LBB0_319:
	s_or_b64 exec, exec, s[52:53]
	v_mov_b32_e32 v30, 0
	v_mov_b32_e32 v78, 0
	v_mov_b32_e32 v79, 0
	s_and_saveexec_b64 s[52:53], vcc
	s_cbranch_execz .LBB0_321
	v_or_b32_e32 v6, 54, v36
	v_mad_i64_i32 v[60:61], s[54:55], v6, s79, v[64:65]
	global_load_dwordx2 v[78:79], v[60:61], off
.LBB0_321:
	s_or_b64 exec, exec, s[52:53]
	v_mov_b32_e32 v31, 0
	s_and_saveexec_b64 s[52:53], vcc
	s_cbranch_execz .LBB0_323
	v_or_b32_e32 v6, 56, v36
	v_mad_i64_i32 v[30:31], s[54:55], v6, s79, v[64:65]
	global_load_dwordx2 v[30:31], v[30:31], off
.LBB0_323:
	s_or_b64 exec, exec, s[52:53]
	v_mov_b32_e32 v60, 0
	v_mov_b32_e32 v61, v60
	s_and_saveexec_b64 s[52:53], vcc
	s_cbranch_execz .LBB0_325
	v_or_b32_e32 v6, 58, v36
	v_mad_i64_i32 v[60:61], s[54:55], v6, s79, v[64:65]
	global_load_dwordx2 v[60:61], v[60:61], off
.LBB0_325:
	s_or_b64 exec, exec, s[52:53]
	v_mov_b32_e32 v6, v7
	v_mov_b64_e32 v[74:75], v[6:7]
	s_and_saveexec_b64 s[52:53], vcc
	s_cbranch_execz .LBB0_327
	v_or_b32_e32 v6, 60, v36
	v_mad_i64_i32 v[72:73], s[54:55], v6, s79, v[64:65]
	global_load_dwordx2 v[74:75], v[72:73], off
.LBB0_327:
	s_or_b64 exec, exec, s[52:53]
	v_mov_b32_e32 v72, 0
	v_mov_b32_e32 v73, 0
	s_and_saveexec_b64 s[52:53], vcc
	s_cbranch_execz .LBB0_329
	v_or_b32_e32 v6, 62, v36
	v_mad_i64_i32 v[64:65], s[54:55], v6, s79, v[64:65]
	global_load_dwordx2 v[72:73], v[64:65], off
.LBB0_329:
	s_or_b64 exec, exec, s[52:53]
	s_lshl_b64 s[52:53], s[26:27], 2
	s_add_u32 s52, s4, s52
	s_addc_u32 s53, s5, s53
	s_cmp_lg_u64 s[4:5], 0
	s_cselect_b64 s[54:55], -1, 0
	s_cmp_eq_u64 s[4:5], 0
	v_ashrrev_i32_e32 v11, 31, v10
	v_add_u32_e32 v64, v5, v82
	v_add_u32_e32 v65, v5, v92
	s_cbranch_scc1 .LBB0_352
	v_ashrrev_i32_e32 v37, 31, v36
	v_lshl_add_u64 v[36:37], v[36:37], 2, s[52:53]
	v_lshl_add_u64 v[132:133], v[10:11], 0, v[2:3]
	v_lshl_add_u64 v[132:133], v[132:133], 2, s[52:53]
	global_load_dword v36, v[36:37], off
	s_nop 0
	global_load_dword v134, v[132:133], off offset:8
	global_load_dword v136, v[132:133], off offset:16
	global_load_dword v6, v[132:133], off offset:24
	s_waitcnt vmcnt(0) lgkmcnt(0)
	v_pk_mul_f32 v[132:133], v[18:19], v[36:37] op_sel_hi:[1,0]
	v_pk_mul_f32 v[134:135], v[16:17], v[134:135] op_sel_hi:[1,0]
	v_pk_mul_f32 v[36:37], v[34:35], v[136:137] op_sel_hi:[1,0]
	ds_write2_b32 v64, v132, v133 offset1:1
	ds_write2_b32 v65, v134, v135 offset1:1
	s_cbranch_execnz .LBB0_332

.LBB0_332:
	s_waitcnt vmcnt(0) lgkmcnt(0)
	v_add_u32_e32 v18, v5, v93
	v_pk_mul_f32 v[16:17], v[38:39], v[6:7] op_sel_hi:[1,0]
	v_cndmask_b32_e64 v6, 0, 1, s[54:55]
	ds_write2_b32 v18, v36, v37 offset1:1
	ds_write2_b32 v18, v16, v17 offset0:130 offset1:131
	v_cmp_ne_u32_e64 s[4:5], 1, v6
	s_andn2_b64 vcc, exec, s[54:55]
	v_add_u32_e32 v18, v5, v94
	s_cbranch_vccnz .LBB0_353
	v_lshl_add_u64 v[16:17], v[10:11], 0, v[2:3]
	v_lshl_add_u64 v[16:17], v[16:17], 2, s[52:53]
	global_load_dword v34, v[16:17], off offset:32
	global_load_dword v36, v[16:17], off offset:40
	global_load_dword v38, v[16:17], off offset:48
	global_load_dword v6, v[16:17], off offset:56
	s_waitcnt vmcnt(0) lgkmcnt(0)
	v_pk_mul_f32 v[34:35], v[12:13], v[34:35] op_sel_hi:[1,0]
	v_pk_mul_f32 v[36:37], v[26:27], v[36:37] op_sel_hi:[1,0]
	v_pk_mul_f32 v[16:17], v[42:43], v[38:39] op_sel_hi:[1,0]
	ds_write2_b32 v18, v34, v35 offset1:1
	ds_write2_b32 v18, v36, v37 offset0:130 offset1:131
	s_cbranch_execnz .LBB0_335

.LBB0_335:
	v_add_u32_e32 v18, v5, v95
	ds_write2_b32 v18, v16, v17 offset1:1
	v_pk_mul_f32 v[12:13], v[44:45], v[6:7] op_sel_hi:[1,0]
	s_and_b64 vcc, exec, s[4:5]
	v_add_u32_e32 v16, v5, v96
	ds_write2_b32 v18, v12, v13 offset0:130 offset1:131
	s_cbranch_vccnz .LBB0_354
	v_lshl_add_u64 v[12:13], v[10:11], 0, v[2:3]
	v_lshl_add_u64 v[12:13], v[12:13], 2, s[52:53]
	global_load_dword v18, v[12:13], off offset:64
	global_load_dword v26, v[12:13], off offset:72
	global_load_dword v34, v[12:13], off offset:80
	global_load_dword v6, v[12:13], off offset:88
	s_waitcnt vmcnt(0) lgkmcnt(0)
	v_pk_mul_f32 v[18:19], v[14:15], v[18:19] op_sel_hi:[1,0]
	v_pk_mul_f32 v[26:27], v[32:33], v[26:27] op_sel_hi:[1,0]
	v_pk_mul_f32 v[12:13], v[48:49], v[34:35] op_sel_hi:[1,0]
	ds_write2_b32 v16, v18, v19 offset1:1
	ds_write2_b32 v16, v26, v27 offset0:130 offset1:131
	s_cbranch_execnz .LBB0_338

.LBB0_338:
	v_add_u32_e32 v14, v5, v97
	ds_write2_b32 v14, v12, v13 offset1:1
	v_pk_mul_f32 v[12:13], v[50:51], v[6:7] op_sel_hi:[1,0]
	ds_write2_b32 v14, v12, v13 offset0:130 offset1:131
	s_and_b64 vcc, exec, s[4:5]
	v_add_u32_e32 v14, v5, v98
	s_cbranch_vccnz .LBB0_355
	v_lshl_add_u64 v[12:13], v[10:11], 0, v[2:3]
	v_lshl_add_u64 v[12:13], v[12:13], 2, s[52:53]
	global_load_dword v16, v[12:13], off offset:96
	global_load_dword v18, v[12:13], off offset:104
	global_load_dword v26, v[12:13], off offset:112
	global_load_dword v6, v[12:13], off offset:120
	s_waitcnt vmcnt(0) lgkmcnt(0)
	v_pk_mul_f32 v[16:17], v[20:21], v[16:17] op_sel_hi:[1,0]
	v_pk_mul_f32 v[18:19], v[40:41], v[18:19] op_sel_hi:[1,0]
	v_pk_mul_f32 v[12:13], v[54:55], v[26:27] op_sel_hi:[1,0]
	ds_write2_b32 v14, v16, v17 offset1:1
	ds_write2_b32 v14, v18, v19 offset0:130 offset1:131
	s_cbranch_execnz .LBB0_341

.LBB0_341:
	v_add_u32_e32 v14, v5, v99
	ds_write2_b32 v14, v12, v13 offset1:1
	v_pk_mul_f32 v[12:13], v[56:57], v[6:7] op_sel_hi:[1,0]
	ds_write2_b32 v14, v12, v13 offset0:130 offset1:131
	s_and_b64 vcc, exec, s[4:5]
	v_add_u32_e32 v14, v5, v100
	s_cbranch_vccnz .LBB0_356
	v_lshl_add_u64 v[12:13], v[10:11], 0, v[2:3]
	v_lshl_add_u64 v[12:13], v[12:13], 2, s[52:53]
	global_load_dword v16, v[12:13], off offset:128
	global_load_dword v18, v[12:13], off offset:136
	global_load_dword v20, v[12:13], off offset:144
	global_load_dword v6, v[12:13], off offset:152
	s_waitcnt vmcnt(0) lgkmcnt(0)
	v_pk_mul_f32 v[16:17], v[22:23], v[16:17] op_sel_hi:[1,0]
	v_pk_mul_f32 v[18:19], v[46:47], v[18:19] op_sel_hi:[1,0]
	v_pk_mul_f32 v[12:13], v[62:63], v[20:21] op_sel_hi:[1,0]
	ds_write2_b32 v14, v16, v17 offset1:1
	ds_write2_b32 v14, v18, v19 offset0:130 offset1:131
	s_cbranch_execnz .LBB0_344

.LBB0_344:
	v_add_u32_e32 v14, v5, v101
	ds_write2_b32 v14, v12, v13 offset1:1
	v_pk_mul_f32 v[12:13], v[66:67], v[6:7] op_sel_hi:[1,0]
	ds_write2_b32 v14, v12, v13 offset0:130 offset1:131
	s_and_b64 vcc, exec, s[4:5]
	v_add_u32_e32 v14, v5, v102
	s_cbranch_vccnz .LBB0_357
	v_lshl_add_u64 v[12:13], v[10:11], 0, v[2:3]
	v_lshl_add_u64 v[12:13], v[12:13], 2, s[52:53]
	global_load_dword v16, v[12:13], off offset:160
	global_load_dword v18, v[12:13], off offset:168
	global_load_dword v20, v[12:13], off offset:176
	global_load_dword v6, v[12:13], off offset:184
	s_waitcnt vmcnt(0) lgkmcnt(0)
	v_pk_mul_f32 v[16:17], v[24:25], v[16:17] op_sel_hi:[1,0]
	v_pk_mul_f32 v[18:19], v[52:53], v[18:19] op_sel_hi:[1,0]
	v_pk_mul_f32 v[12:13], v[68:69], v[20:21] op_sel_hi:[1,0]
	ds_write2_b32 v14, v16, v17 offset1:1
	ds_write2_b32 v14, v18, v19 offset0:130 offset1:131
	s_cbranch_execnz .LBB0_347

.LBB0_347:
	v_add_u32_e32 v15, 0x410, v14
	ds_write2_b32 v15, v12, v13 offset1:1
	v_pk_mul_f32 v[12:13], v[70:71], v[6:7] op_sel_hi:[1,0]
	v_add_u32_e32 v6, 0x618, v14
	s_and_b64 vcc, exec, s[4:5]
	v_add_u32_e32 v15, 0x820, v14
	v_add_u32_e32 v16, 0xa28, v14
	ds_write2_b32 v6, v12, v13 offset1:1
	s_cbranch_vccnz .LBB0_358
	v_lshl_add_u64 v[12:13], v[10:11], 0, v[2:3]
	v_lshl_add_u64 v[12:13], v[12:13], 2, s[52:53]
	global_load_dword v18, v[12:13], off offset:192
	global_load_dword v20, v[12:13], off offset:200
	global_load_dword v22, v[12:13], off offset:208
	global_load_dword v6, v[12:13], off offset:216
	s_waitcnt vmcnt(0) lgkmcnt(0)
	v_pk_mul_f32 v[18:19], v[28:29], v[18:19] op_sel_hi:[1,0]
	v_pk_mul_f32 v[20:21], v[58:59], v[20:21] op_sel_hi:[1,0]
	v_pk_mul_f32 v[12:13], v[76:77], v[22:23] op_sel_hi:[1,0]
	ds_write2_b32 v15, v18, v19 offset1:1
	ds_write2_b32 v16, v20, v21 offset1:1
	s_cbranch_execnz .LBB0_350

.LBB0_350:
	v_add_u32_e32 v15, 0xc30, v14
	ds_write2_b32 v15, v12, v13 offset1:1
	v_pk_mul_f32 v[12:13], v[78:79], v[6:7] op_sel_hi:[1,0]
	v_add_u32_e32 v6, 0xe38, v14
	s_and_b64 vcc, exec, s[4:5]
	v_add_u32_e32 v15, 0x1040, v14
	v_add_u32_e32 v16, 0x1248, v14
	ds_write2_b32 v6, v12, v13 offset1:1
	s_cbranch_vccnz .LBB0_359
	v_lshl_add_u64 v[12:13], v[10:11], 0, v[2:3]
	v_lshl_add_u64 v[12:13], v[12:13], 2, s[52:53]
	global_load_dword v18, v[12:13], off offset:224
	global_load_dword v20, v[12:13], off offset:232
	global_load_dword v22, v[12:13], off offset:240
	global_load_dword v6, v[12:13], off offset:248
	s_waitcnt vmcnt(0) lgkmcnt(0)
	v_pk_mul_f32 v[18:19], v[30:31], v[18:19] op_sel_hi:[1,0]
	v_pk_mul_f32 v[20:21], v[60:61], v[20:21] op_sel_hi:[1,0]
	v_pk_mul_f32 v[12:13], v[74:75], v[22:23] op_sel_hi:[1,0]
	ds_write2_b32 v15, v18, v19 offset1:1
	ds_write2_b32 v16, v20, v21 offset1:1
	s_cbranch_execnz .LBB0_27
	s_branch .LBB0_26

.LBB0_372:
	global_load_dwordx4 v[16:19], v[6:7], off
	global_load_dwordx4 v[20:23], v[6:7], off offset:1024
	global_load_dwordx4 v[24:27], v[6:7], off offset:2048
	global_load_dwordx4 v[28:31], v[6:7], off offset:3072
	s_waitcnt vmcnt(0) lgkmcnt(0)
	v_mul_f32_e32 v1, v17, v17
	v_mul_f32_e32 v15, v19, v19
	v_mul_f32_e32 v32, v21, v21
	v_mul_f32_e32 v33, v23, v23
	v_mul_f32_e32 v34, v25, v25
	v_mul_f32_e32 v35, v27, v27
	v_fmac_f32_e32 v1, v16, v16
	v_fmac_f32_e32 v15, v18, v18
	v_fmac_f32_e32 v32, v20, v20
	v_fmac_f32_e32 v33, v22, v22
	v_mul_f32_e32 v36, v29, v29
	v_mul_f32_e32 v37, v31, v31
	v_fmac_f32_e32 v34, v24, v24
	v_fmac_f32_e32 v35, v26, v26
	v_add_f32_e32 v1, v1, v15
	v_add_f32_e32 v15, v32, v33
	v_fmac_f32_e32 v36, v28, v28
	v_fmac_f32_e32 v37, v30, v30
	v_add_f32_e32 v32, v34, v35
	v_add_f32_e32 v1, v1, v15
	v_add_f32_e32 v33, v36, v37
	v_add_f32_e32 v1, v1, v32
	v_add_f32_e32 v1, v1, v33
	ds_bpermute_b32 v15, v8, v1
	v_cvt_pk_bf16_f32 v16, v16, v17
	v_cvt_pk_bf16_f32 v17, v18, v19
	v_cvt_pk_bf16_f32 v18, v20, v21
	v_cvt_pk_bf16_f32 v19, v22, v23
	s_waitcnt lgkmcnt(0)
	v_add_f32_e32 v1, v1, v15
	ds_bpermute_b32 v15, v10, v1
	v_cvt_pk_bf16_f32 v20, v24, v25
	global_store_dwordx2 v[4:5], v[16:17], off
	global_store_dwordx2 v[4:5], v[18:19], off offset:512
	v_cvt_pk_bf16_f32 v21, v26, v27
	v_cvt_pk_bf16_f32 v16, v28, v29
	s_waitcnt lgkmcnt(0)
	v_add_f32_e32 v1, v1, v15
	ds_bpermute_b32 v15, v11, v1
	v_cvt_pk_bf16_f32 v17, v30, v31
	global_store_dwordx2 v[4:5], v[20:21], off offset:1024
	global_store_dwordx2 v[4:5], v[16:17], off offset:1536
	s_waitcnt lgkmcnt(0)
	v_add_f32_e32 v1, v1, v15
	ds_bpermute_b32 v15, v12, v1
	s_waitcnt lgkmcnt(0)
	v_add_f32_e32 v1, v1, v15
	ds_bpermute_b32 v15, v13, v1
	s_waitcnt lgkmcnt(0)
	v_add_f32_e32 v1, v1, v15
	ds_bpermute_b32 v15, v14, v1
	s_and_saveexec_b64 s[6:7], vcc
	s_cbranch_execz .LBB0_371
	s_waitcnt lgkmcnt(0)
	v_add_f32_e32 v1, v1, v15
	v_cndmask_b32_e64 v1, 0, v1, s[4:5]
	global_store_dword v[2:3], v1, off
	s_branch .LBB0_371
.LBB0_374:
	s_or_b64 exec, exec, s[8:9]
	v_readlane_b32 s4, v252, 0
	s_cmp_eq_u32 s4, 0
	s_cselect_b64 s[4:5], -1, 0
	v_cmp_gt_i32_e32 vcc, 4, v9
	s_and_b64 s[6:7], s[4:5], vcc
	s_and_saveexec_b64 s[4:5], s[6:7]
	s_cbranch_execz .LBB0_376
	v_lshlrev_b32_e32 v0, 6, v9
	s_mov_b64 s[6:7], s[22:23]
	v_ashrrev_i32_e32 v1, 31, v0
	v_mov_b32_e32 v2, 0
	v_lshl_add_u64 v[0:1], v[0:1], 2, s[6:7]
	v_add_co_u32_e32 v0, vcc, 0x15800000, v0
	s_nop 1
	v_addc_co_u32_e32 v1, vcc, 0, v1, vcc
	global_store_dword v[0:1], v2, off

.LBB0_379:
	s_or_b64 exec, exec, s[24:25]
	v_cmp_eq_u32_e64 s[4:5], 2, v1
	v_add_u32_e32 v0, s63, v0
	s_nop 0
	v_cndmask_b32_e64 v3, v26, v24, s[4:5]
	v_cndmask_b32_e64 v30, -v27, -v25, s[4:5]
	v_cmp_eq_u32_e64 s[4:5], 1, v1
	s_nop 1
	v_cndmask_b32_e64 v1, v3, v26, s[4:5]
	v_cndmask_b32_e64 v3, v30, v27, s[4:5]
	v_cndmask_b32_e32 v25, v3, v25, vcc
	v_ashrrev_i32_e32 v3, 31, v2
	s_mov_b64 s[4:5], s[22:23]
	v_lshlrev_b64 v[26:27], 2, v[2:3]
	v_cndmask_b32_e32 v24, v1, v24, vcc
	v_cvt_f32_f64_e32 v1, v[28:29]
	v_add_u32_e32 v2, s28, v2
	v_lshl_add_u64 v[28:29], s[4:5], 0, v[26:27]
	v_add_co_u32_e32 v28, vcc, s30, v28
	s_mov_b64 s[4:5], s[22:23]
	s_nop 0
	v_addc_co_u32_e32 v29, vcc, 0, v29, vcc
	global_store_dword v[28:29], v1, off
	v_cvt_f32_f64_e32 v1, v[24:25]
	s_nop 0
	v_lshl_add_u64 v[24:25], s[4:5], 0, v[26:27]
	v_add_co_u32_e32 v24, vcc, 0x13400000, v24
	s_nop 1
	v_addc_co_u32_e32 v25, vcc, 0, v25, vcc
	v_cmp_lt_i32_e32 vcc, s31, v0
	s_or_b64 s[8:9], vcc, s[8:9]
	global_store_dword v[24:25], v1, off offset:4
	s_andn2_b64 exec, exec, s[8:9]
	s_cbranch_execz .LBB0_383

.LBB0_460:
	v_lshl_add_u32 v140, s27, 8, v146
	v_ashrrev_i32_e32 v141, 31, v140
	v_lshlrev_b64 v[144:145], 6, v[140:141]
	v_lshl_add_u64 v[142:143], s[42:43], 0, v[144:145]
	global_load_dwordx4 v[150:153], v[142:143], off
	global_load_dwordx4 v[154:157], v[142:143], off offset:32
	global_load_dwordx4 v[158:161], v[142:143], off offset:16
	global_load_dwordx4 v[168:171], v[142:143], off offset:48
	s_mov_b32 s4, 0xf800000
	v_mov_b64_e32 v[164:165], s[36:37]
	v_lshl_or_b32 v142, s26, 8, v148
	s_movk_i32 s33, 0xac7
	s_waitcnt vmcnt(0) lgkmcnt(0)
	v_mov_b32_e32 v166, v150
	v_mov_b32_e32 v167, v154
	v_mov_b32_e32 v154, v151
	v_mov_b32_e32 v150, v152
	v_mov_b32_e32 v151, v156
	v_mov_b32_e32 v156, v153
	v_mov_b32_e32 v152, v158
	v_mov_b32_e32 v153, v168
	v_mov_b32_e32 v168, v159
	v_mov_b32_e32 v158, v160
	v_mov_b32_e32 v159, v170
	v_mov_b32_e32 v170, v161
	v_pk_add_f32 v[154:155], v[166:167], v[154:155]
	v_pk_add_f32 v[150:151], v[150:151], v[156:157]
	v_pk_add_f32 v[152:153], v[152:153], v[168:169]
	v_pk_add_f32 v[156:157], v[158:159], v[170:171]
	v_pk_add_f32 v[150:151], v[154:155], v[150:151]
	v_pk_add_f32 v[152:153], v[152:153], v[156:157]
	s_nop 0
	v_pk_add_f32 v[150:151], v[150:151], v[152:153]
	s_nop 0
	v_add_f32_e32 v141, v150, v151
	v_fmamk_f32 v141, v141, 0x3a800000, v194
	v_mul_f32_e32 v143, 0x4f800000, v141
	v_cmp_gt_f32_e32 vcc, s4, v141
	s_movk_i32 s4, 0x1600
	v_mad_i64_i32 v[150:151], s[4:5], v140, s4, v[164:165]
	v_cndmask_b32_e32 v141, v141, v143, vcc
	v_sqrt_f32_e32 v152, v141
	v_ashrrev_i32_e32 v143, 31, v142
	v_lshl_add_u64 v[150:151], v[142:143], 1, v[150:151]
	v_add_u32_e32 v153, -1, v152
	v_add_u32_e32 v154, 1, v152
	v_fma_f32 v155, -v153, v152, v141
	v_fma_f32 v156, -v154, v152, v141
	v_cmp_ge_f32_e64 s[4:5], 0, v155
	s_nop 1
	v_cndmask_b32_e64 v152, v152, v153, s[4:5]
	v_cmp_lt_f32_e64 s[4:5], 0, v156
	s_nop 1
	v_cndmask_b32_e64 v152, v152, v154, s[4:5]
	v_mul_f32_e32 v153, 0x37800000, v152
	v_cndmask_b32_e32 v152, v152, v153, vcc
	v_cmp_class_f32_e32 vcc, v141, v195
	s_nop 1
	v_cndmask_b32_e32 v141, v152, v141, vcc
	v_div_scale_f32 v152, s[4:5], v141, v141, 1.0
	v_rcp_f32_e32 v153, v152
	v_div_scale_f32 v154, vcc, 1.0, v141, 1.0
	s_mov_b64 s[4:5], 0
	v_fma_f32 v155, -v152, v153, 1.0
	v_fmac_f32_e32 v153, v155, v153
	v_mul_f32_e32 v155, v154, v153
	v_fma_f32 v156, -v152, v155, v154
	v_fmac_f32_e32 v155, v156, v153
	v_fma_f32 v152, -v152, v155, v154
	v_div_fmas_f32 v152, v152, v153, v155
	v_div_fixup_f32 v152, v152, v141, 1.0
	v_pk_mul_f32 v[128:129], v[128:129], v[152:153] op_sel_hi:[1,0]
	v_pk_mul_f32 v[126:127], v[126:127], v[152:153] op_sel_hi:[1,0]
	v_pk_mul_f32 v[154:155], v[124:125], v[152:153] op_sel_hi:[1,0]
	v_pk_mul_f32 v[124:125], v[122:123], v[152:153] op_sel_hi:[1,0]
	v_pk_mul_f32 v[114:115], v[114:115], v[152:153] op_sel_hi:[1,0]
	v_pk_mul_f32 v[120:121], v[120:121], v[152:153] op_sel_hi:[1,0]
	v_pk_mul_f32 v[118:119], v[118:119], v[152:153] op_sel_hi:[1,0]
	v_pk_mul_f32 v[116:117], v[116:117], v[152:153] op_sel_hi:[1,0]
	v_cvt_pk_bf16_f32 v122, v126, v127
	v_cvt_pk_bf16_f32 v123, v128, v129
	v_cvt_pk_bf16_f32 v124, v124, v125
	v_cvt_pk_bf16_f32 v125, v154, v155
	v_cvt_pk_bf16_f32 v128, v114, v115
	v_cvt_pk_bf16_f32 v126, v118, v119
	v_cvt_pk_bf16_f32 v127, v120, v121
	v_cvt_pk_bf16_f32 v129, v116, v117
	global_store_dwordx4 v[150:151], v[122:125], off
	global_store_dwordx4 v[150:151], v[126:129], off offset:256
	s_nop 1
	v_or_b32_e32 v128, 0x80, v142
	v_cmp_lt_i32_e32 vcc, s33, v128
	s_and_saveexec_b64 s[26:27], vcc
	s_xor_b64 s[30:31], exec, s[26:27]
	s_movk_i32 s4, 0xac8
	v_cmp_eq_u32_e32 vcc, s4, v128
	s_and_b64 s[4:5], vcc, exec
	s_or_saveexec_b64 s[30:31], s[30:31]
	v_lshl_add_u64 v[122:123], s[38:39], 0, v[144:145]
	v_mov_b64_e32 v[124:125], 40
	v_mov_b64_e32 v[126:127], 44
	s_xor_b64 exec, exec, s[30:31]
	s_cbranch_execz .LBB0_466
	s_movk_i32 s26, 0xac0
	v_cmp_eq_u32_e32 vcc, s26, v128
	s_mov_b64 s[54:55], s[4:5]
	s_and_saveexec_b64 s[56:57], vcc
	s_cbranch_execz .LBB0_465
	global_store_dwordx4 v[122:123], v[118:121], off
	global_store_dwordx2 v[122:123], v[114:115], off offset:16
	s_or_b64 s[54:55], s[4:5], exec
	v_mov_b32_e32 v119, v117
	v_mov_b32_e32 v118, v116

.LBB0_466:
	s_or_b64 exec, exec, s[30:31]
	s_and_saveexec_b64 s[30:31], s[4:5]
	s_cbranch_execz .LBB0_468
	v_lshl_add_u64 v[114:115], v[122:123], 0, v[124:125]
	global_store_dword v[114:115], v118, off
	v_lshl_add_u64 v[114:115], v[122:123], 0, v[126:127]
	global_store_dword v[114:115], v119, off
.LBB0_468:
	s_or_b64 exec, exec, s[30:31]
	v_or_b32_e32 v144, 16, v140
	v_ashrrev_i32_e32 v145, 31, v144
	v_lshlrev_b64 v[114:115], 6, v[144:145]
	v_lshl_add_u64 v[150:151], s[42:43], 0, v[114:115]
	global_load_dwordx4 v[116:119], v[150:151], off
	global_load_dwordx4 v[120:123], v[150:151], off offset:32
	global_load_dwordx4 v[124:127], v[150:151], off offset:16
	s_nop 0
	global_load_dwordx4 v[150:153], v[150:151], off offset:48
	s_mov_b32 s4, 0xf800000
	s_waitcnt vmcnt(0) lgkmcnt(0)
	v_mov_b32_e32 v154, v116
	v_mov_b32_e32 v155, v120
	v_mov_b32_e32 v120, v117
	v_mov_b32_e32 v116, v118
	v_mov_b32_e32 v117, v122
	v_mov_b32_e32 v122, v119
	v_mov_b32_e32 v118, v124
	v_mov_b32_e32 v119, v150
	v_mov_b32_e32 v150, v125
	v_mov_b32_e32 v124, v126
	v_mov_b32_e32 v125, v152
	v_mov_b32_e32 v152, v127
	v_pk_add_f32 v[120:121], v[154:155], v[120:121]
	v_pk_add_f32 v[116:117], v[116:117], v[122:123]
	v_pk_add_f32 v[118:119], v[118:119], v[150:151]
	v_pk_add_f32 v[122:123], v[124:125], v[152:153]
	v_pk_add_f32 v[116:117], v[120:121], v[116:117]
	v_pk_add_f32 v[118:119], v[118:119], v[122:123]
	s_nop 0
	v_pk_add_f32 v[116:117], v[116:117], v[118:119]
	s_nop 0
	v_add_f32_e32 v116, v116, v117
	v_fmamk_f32 v116, v116, 0x3a800000, v194
	v_mul_f32_e32 v117, 0x4f800000, v116
	v_cmp_gt_f32_e32 vcc, s4, v116
	s_movk_i32 s4, 0x1600
	s_nop 0
	v_cndmask_b32_e32 v118, v116, v117, vcc
	v_sqrt_f32_e32 v119, v118
	v_mov_b64_e32 v[116:117], s[36:37]
	v_mad_i64_i32 v[116:117], s[4:5], v144, s4, v[116:117]
	v_add_u32_e32 v120, -1, v119
	v_add_u32_e32 v121, 1, v119
	v_fma_f32 v122, -v120, v119, v118
	v_fma_f32 v123, -v121, v119, v118
	v_cmp_ge_f32_e64 s[4:5], 0, v122
	v_lshl_add_u64 v[116:117], v[142:143], 1, v[116:117]
	s_nop 0
	v_cndmask_b32_e64 v119, v119, v120, s[4:5]
	v_cmp_lt_f32_e64 s[4:5], 0, v123
	s_nop 1
	v_cndmask_b32_e64 v119, v119, v121, s[4:5]
	v_mul_f32_e32 v120, 0x37800000, v119
	v_cndmask_b32_e32 v119, v119, v120, vcc
	v_cmp_class_f32_e32 vcc, v118, v195
	s_nop 1
	v_cndmask_b32_e32 v118, v119, v118, vcc
	v_div_scale_f32 v119, s[4:5], v118, v118, 1.0
	v_rcp_f32_e32 v120, v119
	v_div_scale_f32 v121, vcc, 1.0, v118, 1.0
	s_mov_b64 s[4:5], 0
	v_fma_f32 v122, -v119, v120, 1.0
	v_fmac_f32_e32 v120, v122, v120
	v_mul_f32_e32 v122, v121, v120
	v_fma_f32 v123, -v119, v122, v121
	v_fmac_f32_e32 v122, v123, v120
	v_fma_f32 v119, -v119, v122, v121
	v_div_fmas_f32 v119, v119, v120, v122
	v_div_fixup_f32 v118, v119, v118, 1.0
	v_pk_mul_f32 v[112:113], v[112:113], v[118:119] op_sel_hi:[1,0]
	v_pk_mul_f32 v[110:111], v[110:111], v[118:119] op_sel_hi:[1,0]
	v_pk_mul_f32 v[120:121], v[108:109], v[118:119] op_sel_hi:[1,0]
	v_pk_mul_f32 v[108:109], v[106:107], v[118:119] op_sel_hi:[1,0]
	v_pk_mul_f32 v[104:105], v[104:105], v[118:119] op_sel_hi:[1,0]
	v_pk_mul_f32 v[102:103], v[102:103], v[118:119] op_sel_hi:[1,0]
	v_pk_mul_f32 v[100:101], v[100:101], v[118:119] op_sel_hi:[1,0]
	v_pk_mul_f32 v[98:99], v[98:99], v[118:119] op_sel_hi:[1,0]
	v_cvt_pk_bf16_f32 v106, v110, v111
	v_cvt_pk_bf16_f32 v107, v112, v113
	v_cvt_pk_bf16_f32 v108, v108, v109
	v_cvt_pk_bf16_f32 v109, v120, v121
	v_cmp_lt_i32_e32 vcc, s33, v128
	v_cvt_pk_bf16_f32 v110, v102, v103
	v_cvt_pk_bf16_f32 v111, v104, v105
	v_cvt_pk_bf16_f32 v112, v98, v99
	v_cvt_pk_bf16_f32 v113, v100, v101
	global_store_dwordx4 v[116:117], v[106:109], off
	global_store_dwordx4 v[116:117], v[110:113], off offset:256
	s_and_saveexec_b64 s[26:27], vcc
	s_xor_b64 s[30:31], exec, s[26:27]
	s_movk_i32 s4, 0xac8
	v_cmp_eq_u32_e32 vcc, s4, v128
	s_and_b64 s[4:5], vcc, exec
	s_or_saveexec_b64 s[30:31], s[30:31]
	v_lshl_add_u64 v[106:107], s[38:39], 0, v[114:115]
	v_mov_b64_e32 v[108:109], 40
	v_mov_b64_e32 v[110:111], 44
	s_xor_b64 exec, exec, s[30:31]
	s_cbranch_execz .LBB0_474
	s_movk_i32 s26, 0xac0
	v_cmp_eq_u32_e32 vcc, s26, v128
	s_mov_b64 s[54:55], s[4:5]
	s_and_saveexec_b64 s[56:57], vcc
	s_cbranch_execz .LBB0_473
	global_store_dwordx4 v[106:107], v[102:105], off
	global_store_dwordx2 v[106:107], v[98:99], off offset:16
	s_or_b64 s[54:55], s[4:5], exec
	v_mov_b32_e32 v103, v101
	v_mov_b32_e32 v102, v100

.LBB0_474:
	s_or_b64 exec, exec, s[30:31]
	s_and_saveexec_b64 s[30:31], s[4:5]
	s_cbranch_execz .LBB0_476
	v_lshl_add_u64 v[98:99], v[106:107], 0, v[108:109]
	global_store_dword v[98:99], v102, off
	v_lshl_add_u64 v[98:99], v[106:107], 0, v[110:111]
	global_store_dword v[98:99], v103, off
.LBB0_476:
	s_or_b64 exec, exec, s[30:31]
	v_or_b32_e32 v116, 32, v140
	v_ashrrev_i32_e32 v117, 31, v116
	v_lshlrev_b64 v[98:99], 6, v[116:117]
	v_lshl_add_u64 v[112:113], s[42:43], 0, v[98:99]
	global_load_dwordx4 v[100:103], v[112:113], off
	global_load_dwordx4 v[104:107], v[112:113], off offset:32
	global_load_dwordx4 v[108:111], v[112:113], off offset:16
	s_nop 0
	global_load_dwordx4 v[112:115], v[112:113], off offset:48
	s_mov_b32 s4, 0xf800000
	s_waitcnt vmcnt(0) lgkmcnt(0)
	v_mov_b32_e32 v118, v100
	v_mov_b32_e32 v119, v104
	v_mov_b32_e32 v104, v101
	v_mov_b32_e32 v100, v102
	v_mov_b32_e32 v101, v106
	v_mov_b32_e32 v106, v103
	v_mov_b32_e32 v102, v108
	v_mov_b32_e32 v103, v112
	v_mov_b32_e32 v112, v109
	v_mov_b32_e32 v108, v110
	v_mov_b32_e32 v109, v114
	v_mov_b32_e32 v114, v111
	v_pk_add_f32 v[104:105], v[118:119], v[104:105]
	v_pk_add_f32 v[100:101], v[100:101], v[106:107]
	v_pk_add_f32 v[102:103], v[102:103], v[112:113]
	v_pk_add_f32 v[106:107], v[108:109], v[114:115]
	v_pk_add_f32 v[100:101], v[104:105], v[100:101]
	v_pk_add_f32 v[102:103], v[102:103], v[106:107]
	s_nop 0
	v_pk_add_f32 v[100:101], v[100:101], v[102:103]
	s_nop 0
	v_add_f32_e32 v100, v100, v101
	v_fmamk_f32 v100, v100, 0x3a800000, v194
	v_mul_f32_e32 v101, 0x4f800000, v100
	v_cmp_gt_f32_e32 vcc, s4, v100
	s_movk_i32 s4, 0x1600
	s_nop 0
	v_cndmask_b32_e32 v102, v100, v101, vcc
	v_sqrt_f32_e32 v103, v102
	v_mov_b64_e32 v[100:101], s[36:37]
	v_mad_i64_i32 v[100:101], s[4:5], v116, s4, v[100:101]
	v_add_u32_e32 v104, -1, v103
	v_add_u32_e32 v105, 1, v103
	v_fma_f32 v106, -v104, v103, v102
	v_fma_f32 v107, -v105, v103, v102
	v_cmp_ge_f32_e64 s[4:5], 0, v106
	v_lshl_add_u64 v[100:101], v[142:143], 1, v[100:101]
	s_nop 0
	v_cndmask_b32_e64 v103, v103, v104, s[4:5]
	v_cmp_lt_f32_e64 s[4:5], 0, v107
	s_nop 1
	v_cndmask_b32_e64 v103, v103, v105, s[4:5]
	v_mul_f32_e32 v104, 0x37800000, v103
	v_cndmask_b32_e32 v103, v103, v104, vcc
	v_cmp_class_f32_e32 vcc, v102, v195
	s_nop 1
	v_cndmask_b32_e32 v102, v103, v102, vcc
	v_div_scale_f32 v103, s[4:5], v102, v102, 1.0
	v_rcp_f32_e32 v104, v103
	v_div_scale_f32 v105, vcc, 1.0, v102, 1.0
	s_mov_b64 s[4:5], 0
	v_fma_f32 v106, -v103, v104, 1.0
	v_fmac_f32_e32 v104, v106, v104
	v_mul_f32_e32 v106, v105, v104
	v_fma_f32 v107, -v103, v106, v105
	v_fmac_f32_e32 v106, v107, v104
	v_fma_f32 v103, -v103, v106, v105
	v_div_fmas_f32 v103, v103, v104, v106
	v_div_fixup_f32 v102, v103, v102, 1.0
	v_pk_mul_f32 v[96:97], v[96:97], v[102:103] op_sel_hi:[1,0]
	v_pk_mul_f32 v[94:95], v[94:95], v[102:103] op_sel_hi:[1,0]
	v_pk_mul_f32 v[104:105], v[92:93], v[102:103] op_sel_hi:[1,0]
	v_pk_mul_f32 v[92:93], v[90:91], v[102:103] op_sel_hi:[1,0]
	v_pk_mul_f32 v[88:89], v[88:89], v[102:103] op_sel_hi:[1,0]
	v_pk_mul_f32 v[86:87], v[86:87], v[102:103] op_sel_hi:[1,0]
	v_pk_mul_f32 v[84:85], v[84:85], v[102:103] op_sel_hi:[1,0]
	v_pk_mul_f32 v[82:83], v[82:83], v[102:103] op_sel_hi:[1,0]
	v_cvt_pk_bf16_f32 v90, v94, v95
	v_cvt_pk_bf16_f32 v91, v96, v97
	v_cvt_pk_bf16_f32 v92, v92, v93
	v_cvt_pk_bf16_f32 v93, v104, v105
	v_cmp_lt_i32_e32 vcc, s33, v128
	v_cvt_pk_bf16_f32 v94, v86, v87
	v_cvt_pk_bf16_f32 v95, v88, v89
	v_cvt_pk_bf16_f32 v96, v82, v83
	v_cvt_pk_bf16_f32 v97, v84, v85
	global_store_dwordx4 v[100:101], v[90:93], off
	global_store_dwordx4 v[100:101], v[94:97], off offset:256
	s_and_saveexec_b64 s[26:27], vcc
	s_xor_b64 s[30:31], exec, s[26:27]
	s_movk_i32 s4, 0xac8
	v_cmp_eq_u32_e32 vcc, s4, v128
	s_and_b64 s[4:5], vcc, exec
	s_or_saveexec_b64 s[30:31], s[30:31]
	v_lshl_add_u64 v[90:91], s[38:39], 0, v[98:99]
	v_mov_b64_e32 v[92:93], 40
	v_mov_b64_e32 v[94:95], 44
	s_xor_b64 exec, exec, s[30:31]
	s_cbranch_execz .LBB0_482
	s_movk_i32 s26, 0xac0
	v_cmp_eq_u32_e32 vcc, s26, v128
	s_mov_b64 s[54:55], s[4:5]
	s_and_saveexec_b64 s[56:57], vcc
	s_cbranch_execz .LBB0_481
	global_store_dwordx4 v[90:91], v[86:89], off
	global_store_dwordx2 v[90:91], v[82:83], off offset:16
	s_or_b64 s[54:55], s[4:5], exec
	v_mov_b32_e32 v87, v85
	v_mov_b32_e32 v86, v84

.LBB0_482:
	s_or_b64 exec, exec, s[30:31]
	s_and_saveexec_b64 s[30:31], s[4:5]
	s_cbranch_execz .LBB0_484
	v_lshl_add_u64 v[82:83], v[90:91], 0, v[92:93]
	global_store_dword v[82:83], v86, off
	v_lshl_add_u64 v[82:83], v[90:91], 0, v[94:95]
	global_store_dword v[82:83], v87, off
.LBB0_484:
	s_or_b64 exec, exec, s[30:31]
	v_or_b32_e32 v100, 48, v140
	v_ashrrev_i32_e32 v101, 31, v100
	v_lshlrev_b64 v[82:83], 6, v[100:101]
	v_lshl_add_u64 v[96:97], s[42:43], 0, v[82:83]
	global_load_dwordx4 v[84:87], v[96:97], off
	global_load_dwordx4 v[88:91], v[96:97], off offset:32
	global_load_dwordx4 v[92:95], v[96:97], off offset:16
	s_nop 0
	global_load_dwordx4 v[96:99], v[96:97], off offset:48
	s_mov_b32 s4, 0xf800000
	s_waitcnt vmcnt(0) lgkmcnt(0)
	v_mov_b32_e32 v102, v84
	v_mov_b32_e32 v103, v88
	v_mov_b32_e32 v88, v85
	v_mov_b32_e32 v84, v86
	v_mov_b32_e32 v85, v90
	v_mov_b32_e32 v90, v87
	v_mov_b32_e32 v86, v92
	v_mov_b32_e32 v87, v96
	v_mov_b32_e32 v96, v93
	v_mov_b32_e32 v92, v94
	v_mov_b32_e32 v93, v98
	v_mov_b32_e32 v98, v95
	v_pk_add_f32 v[88:89], v[102:103], v[88:89]
	v_pk_add_f32 v[84:85], v[84:85], v[90:91]
	v_pk_add_f32 v[86:87], v[86:87], v[96:97]
	v_pk_add_f32 v[90:91], v[92:93], v[98:99]
	v_pk_add_f32 v[84:85], v[88:89], v[84:85]
	v_pk_add_f32 v[86:87], v[86:87], v[90:91]
	s_nop 0
	v_pk_add_f32 v[84:85], v[84:85], v[86:87]
	s_nop 0
	v_add_f32_e32 v84, v84, v85
	v_fmamk_f32 v84, v84, 0x3a800000, v194
	v_mul_f32_e32 v85, 0x4f800000, v84
	v_cmp_gt_f32_e32 vcc, s4, v84
	s_movk_i32 s4, 0x1600
	s_nop 0
	v_cndmask_b32_e32 v86, v84, v85, vcc
	v_sqrt_f32_e32 v87, v86
	v_mov_b64_e32 v[84:85], s[36:37]
	v_mad_i64_i32 v[84:85], s[4:5], v100, s4, v[84:85]
	v_add_u32_e32 v88, -1, v87
	v_add_u32_e32 v89, 1, v87
	v_fma_f32 v90, -v88, v87, v86
	v_fma_f32 v91, -v89, v87, v86
	v_cmp_ge_f32_e64 s[4:5], 0, v90
	v_lshl_add_u64 v[84:85], v[142:143], 1, v[84:85]
	s_nop 0
	v_cndmask_b32_e64 v87, v87, v88, s[4:5]
	v_cmp_lt_f32_e64 s[4:5], 0, v91
	s_nop 1
	v_cndmask_b32_e64 v87, v87, v89, s[4:5]
	v_mul_f32_e32 v88, 0x37800000, v87
	v_cndmask_b32_e32 v87, v87, v88, vcc
	v_cmp_class_f32_e32 vcc, v86, v195
	s_nop 1
	v_cndmask_b32_e32 v86, v87, v86, vcc
	v_div_scale_f32 v87, s[4:5], v86, v86, 1.0
	v_rcp_f32_e32 v88, v87
	v_div_scale_f32 v89, vcc, 1.0, v86, 1.0
	s_mov_b64 s[4:5], 0
	v_fma_f32 v90, -v87, v88, 1.0
	v_fmac_f32_e32 v88, v90, v88
	v_mul_f32_e32 v90, v89, v88
	v_fma_f32 v91, -v87, v90, v89
	v_fmac_f32_e32 v90, v91, v88
	v_fma_f32 v87, -v87, v90, v89
	v_div_fmas_f32 v87, v87, v88, v90
	v_div_fixup_f32 v86, v87, v86, 1.0
	v_pk_mul_f32 v[80:81], v[80:81], v[86:87] op_sel_hi:[1,0]
	v_pk_mul_f32 v[78:79], v[78:79], v[86:87] op_sel_hi:[1,0]
	v_pk_mul_f32 v[88:89], v[76:77], v[86:87] op_sel_hi:[1,0]
	v_pk_mul_f32 v[76:77], v[74:75], v[86:87] op_sel_hi:[1,0]
	v_pk_mul_f32 v[72:73], v[72:73], v[86:87] op_sel_hi:[1,0]
	v_pk_mul_f32 v[70:71], v[70:71], v[86:87] op_sel_hi:[1,0]
	v_pk_mul_f32 v[68:69], v[68:69], v[86:87] op_sel_hi:[1,0]
	v_pk_mul_f32 v[66:67], v[66:67], v[86:87] op_sel_hi:[1,0]
	v_cvt_pk_bf16_f32 v74, v78, v79
	v_cvt_pk_bf16_f32 v75, v80, v81
	v_cvt_pk_bf16_f32 v76, v76, v77
	v_cvt_pk_bf16_f32 v77, v88, v89
	v_cmp_lt_i32_e32 vcc, s33, v128
	v_cvt_pk_bf16_f32 v78, v70, v71
	v_cvt_pk_bf16_f32 v79, v72, v73
	v_cvt_pk_bf16_f32 v80, v66, v67
	v_cvt_pk_bf16_f32 v81, v68, v69
	global_store_dwordx4 v[84:85], v[74:77], off
	global_store_dwordx4 v[84:85], v[78:81], off offset:256
	s_and_saveexec_b64 s[26:27], vcc
	s_xor_b64 s[30:31], exec, s[26:27]
	s_movk_i32 s4, 0xac8
	v_cmp_eq_u32_e32 vcc, s4, v128
	s_and_b64 s[4:5], vcc, exec
	s_or_saveexec_b64 s[30:31], s[30:31]
	v_lshl_add_u64 v[74:75], s[38:39], 0, v[82:83]
	v_mov_b64_e32 v[76:77], 40
	v_mov_b64_e32 v[78:79], 44
	s_xor_b64 exec, exec, s[30:31]
	s_cbranch_execz .LBB0_490
	s_movk_i32 s26, 0xac0
	v_cmp_eq_u32_e32 vcc, s26, v128
	s_mov_b64 s[54:55], s[4:5]
	s_and_saveexec_b64 s[56:57], vcc
	s_cbranch_execz .LBB0_489
	global_store_dwordx4 v[74:75], v[70:73], off
	global_store_dwordx2 v[74:75], v[66:67], off offset:16
	s_or_b64 s[54:55], s[4:5], exec
	v_mov_b32_e32 v71, v69
	v_mov_b32_e32 v70, v68

.LBB0_490:
	s_or_b64 exec, exec, s[30:31]
	s_and_saveexec_b64 s[30:31], s[4:5]
	s_cbranch_execz .LBB0_492
	v_lshl_add_u64 v[66:67], v[74:75], 0, v[76:77]
	global_store_dword v[66:67], v70, off
	v_lshl_add_u64 v[66:67], v[74:75], 0, v[78:79]
	global_store_dword v[66:67], v71, off
.LBB0_492:
	s_or_b64 exec, exec, s[30:31]
	v_add_u32_e32 v84, 0x80, v140
	v_ashrrev_i32_e32 v85, 31, v84
	v_lshlrev_b64 v[66:67], 6, v[84:85]
	v_lshl_add_u64 v[80:81], s[42:43], 0, v[66:67]
	global_load_dwordx4 v[68:71], v[80:81], off
	global_load_dwordx4 v[72:75], v[80:81], off offset:32
	global_load_dwordx4 v[76:79], v[80:81], off offset:16
	s_nop 0
	global_load_dwordx4 v[80:83], v[80:81], off offset:48
	s_mov_b32 s4, 0xf800000
	s_waitcnt vmcnt(0) lgkmcnt(0)
	v_mov_b32_e32 v86, v68
	v_mov_b32_e32 v87, v72
	v_mov_b32_e32 v72, v69
	v_mov_b32_e32 v68, v70
	v_mov_b32_e32 v69, v74
	v_mov_b32_e32 v74, v71
	v_mov_b32_e32 v70, v76
	v_mov_b32_e32 v71, v80
	v_mov_b32_e32 v80, v77
	v_mov_b32_e32 v76, v78
	v_mov_b32_e32 v77, v82
	v_mov_b32_e32 v82, v79
	v_pk_add_f32 v[72:73], v[86:87], v[72:73]
	v_pk_add_f32 v[68:69], v[68:69], v[74:75]
	v_pk_add_f32 v[70:71], v[70:71], v[80:81]
	v_pk_add_f32 v[74:75], v[76:77], v[82:83]
	v_pk_add_f32 v[68:69], v[72:73], v[68:69]
	v_pk_add_f32 v[70:71], v[70:71], v[74:75]
	s_nop 0
	v_pk_add_f32 v[68:69], v[68:69], v[70:71]
	s_nop 0
	v_add_f32_e32 v68, v68, v69
	v_fmamk_f32 v68, v68, 0x3a800000, v194
	v_mul_f32_e32 v69, 0x4f800000, v68
	v_cmp_gt_f32_e32 vcc, s4, v68
	s_movk_i32 s4, 0x1600
	s_nop 0
	v_cndmask_b32_e32 v70, v68, v69, vcc
	v_sqrt_f32_e32 v71, v70
	v_mov_b64_e32 v[68:69], s[36:37]
	v_mad_i64_i32 v[68:69], s[4:5], v84, s4, v[68:69]
	v_add_u32_e32 v72, -1, v71
	v_add_u32_e32 v73, 1, v71
	v_fma_f32 v74, -v72, v71, v70
	v_fma_f32 v75, -v73, v71, v70
	v_cmp_ge_f32_e64 s[4:5], 0, v74
	v_lshl_add_u64 v[68:69], v[142:143], 1, v[68:69]
	s_nop 0
	v_cndmask_b32_e64 v71, v71, v72, s[4:5]
	v_cmp_lt_f32_e64 s[4:5], 0, v75
	s_nop 1
	v_cndmask_b32_e64 v71, v71, v73, s[4:5]
	v_mul_f32_e32 v72, 0x37800000, v71
	v_cndmask_b32_e32 v71, v71, v72, vcc
	v_cmp_class_f32_e32 vcc, v70, v195
	s_nop 1
	v_cndmask_b32_e32 v70, v71, v70, vcc
	v_div_scale_f32 v71, s[4:5], v70, v70, 1.0
	v_rcp_f32_e32 v72, v71
	v_div_scale_f32 v73, vcc, 1.0, v70, 1.0
	s_mov_b64 s[4:5], 0
	v_fma_f32 v74, -v71, v72, 1.0
	v_fmac_f32_e32 v72, v74, v72
	v_mul_f32_e32 v74, v73, v72
	v_fma_f32 v75, -v71, v74, v73
	v_fmac_f32_e32 v74, v75, v72
	v_fma_f32 v71, -v71, v74, v73
	v_div_fmas_f32 v71, v71, v72, v74
	v_div_fixup_f32 v70, v71, v70, 1.0
	v_pk_mul_f32 v[62:63], v[62:63], v[70:71] op_sel_hi:[1,0]
	v_pk_mul_f32 v[60:61], v[60:61], v[70:71] op_sel_hi:[1,0]
	v_pk_mul_f32 v[72:73], v[58:59], v[70:71] op_sel_hi:[1,0]
	v_pk_mul_f32 v[58:59], v[56:57], v[70:71] op_sel_hi:[1,0]
	v_pk_mul_f32 v[54:55], v[54:55], v[70:71] op_sel_hi:[1,0]
	v_pk_mul_f32 v[52:53], v[52:53], v[70:71] op_sel_hi:[1,0]
	v_pk_mul_f32 v[50:51], v[50:51], v[70:71] op_sel_hi:[1,0]
	v_pk_mul_f32 v[48:49], v[48:49], v[70:71] op_sel_hi:[1,0]
	v_cvt_pk_bf16_f32 v56, v60, v61
	v_cvt_pk_bf16_f32 v57, v62, v63
	v_cvt_pk_bf16_f32 v58, v58, v59
	v_cvt_pk_bf16_f32 v59, v72, v73
	v_cmp_lt_i32_e32 vcc, s33, v128
	v_cvt_pk_bf16_f32 v60, v52, v53
	v_cvt_pk_bf16_f32 v61, v54, v55
	v_cvt_pk_bf16_f32 v62, v48, v49
	v_cvt_pk_bf16_f32 v63, v50, v51
	global_store_dwordx4 v[68:69], v[56:59], off
	global_store_dwordx4 v[68:69], v[60:63], off offset:256
	s_and_saveexec_b64 s[26:27], vcc
	s_xor_b64 s[30:31], exec, s[26:27]
	s_movk_i32 s4, 0xac8
	v_cmp_eq_u32_e32 vcc, s4, v128
	s_and_b64 s[4:5], vcc, exec
	s_or_saveexec_b64 s[30:31], s[30:31]
	v_lshl_add_u64 v[56:57], s[38:39], 0, v[66:67]
	v_mov_b64_e32 v[58:59], 40
	v_mov_b64_e32 v[60:61], 44
	s_xor_b64 exec, exec, s[30:31]
	s_cbranch_execz .LBB0_498
	s_movk_i32 s26, 0xac0
	v_cmp_eq_u32_e32 vcc, s26, v128
	s_mov_b64 s[54:55], s[4:5]
	s_and_saveexec_b64 s[56:57], vcc
	s_cbranch_execz .LBB0_497
	global_store_dwordx4 v[56:57], v[52:55], off
	global_store_dwordx2 v[56:57], v[48:49], off offset:16
	s_or_b64 s[54:55], s[4:5], exec
	v_mov_b32_e32 v53, v51
	v_mov_b32_e32 v52, v50

.LBB0_498:
	s_or_b64 exec, exec, s[30:31]
	s_and_saveexec_b64 s[30:31], s[4:5]
	s_cbranch_execz .LBB0_500
	v_lshl_add_u64 v[48:49], v[56:57], 0, v[58:59]
	global_store_dword v[48:49], v52, off
	v_lshl_add_u64 v[48:49], v[56:57], 0, v[60:61]
	global_store_dword v[48:49], v53, off
.LBB0_500:
	s_or_b64 exec, exec, s[30:31]
	v_add_u32_e32 v62, 0x90, v140
	v_ashrrev_i32_e32 v63, 31, v62
	v_lshlrev_b64 v[48:49], 6, v[62:63]
	v_lshl_add_u64 v[66:67], s[42:43], 0, v[48:49]
	global_load_dwordx4 v[50:53], v[66:67], off
	global_load_dwordx4 v[54:57], v[66:67], off offset:32
	global_load_dwordx4 v[58:61], v[66:67], off offset:16
	s_nop 0
	global_load_dwordx4 v[66:69], v[66:67], off offset:48
	s_mov_b32 s4, 0xf800000
	s_waitcnt vmcnt(0) lgkmcnt(0)
	v_mov_b32_e32 v70, v50
	v_mov_b32_e32 v71, v54
	v_mov_b32_e32 v54, v51
	v_mov_b32_e32 v50, v52
	v_mov_b32_e32 v51, v56
	v_mov_b32_e32 v56, v53
	v_mov_b32_e32 v52, v58
	v_mov_b32_e32 v53, v66
	v_mov_b32_e32 v66, v59
	v_mov_b32_e32 v58, v60
	v_mov_b32_e32 v59, v68
	v_mov_b32_e32 v68, v61
	v_pk_add_f32 v[54:55], v[70:71], v[54:55]
	v_pk_add_f32 v[50:51], v[50:51], v[56:57]
	v_pk_add_f32 v[52:53], v[52:53], v[66:67]
	v_pk_add_f32 v[56:57], v[58:59], v[68:69]
	v_pk_add_f32 v[50:51], v[54:55], v[50:51]
	v_pk_add_f32 v[52:53], v[52:53], v[56:57]
	s_nop 0
	v_pk_add_f32 v[50:51], v[50:51], v[52:53]
	s_nop 0
	v_add_f32_e32 v50, v50, v51
	v_fmamk_f32 v50, v50, 0x3a800000, v194
	v_mul_f32_e32 v51, 0x4f800000, v50
	v_cmp_gt_f32_e32 vcc, s4, v50
	s_movk_i32 s4, 0x1600
	s_nop 0
	v_cndmask_b32_e32 v52, v50, v51, vcc
	v_sqrt_f32_e32 v53, v52
	v_mov_b64_e32 v[50:51], s[36:37]
	v_mad_i64_i32 v[50:51], s[4:5], v62, s4, v[50:51]
	v_add_u32_e32 v54, -1, v53
	v_add_u32_e32 v55, 1, v53
	v_fma_f32 v56, -v54, v53, v52
	v_fma_f32 v57, -v55, v53, v52
	v_cmp_ge_f32_e64 s[4:5], 0, v56
	v_lshl_add_u64 v[50:51], v[142:143], 1, v[50:51]
	s_nop 0
	v_cndmask_b32_e64 v53, v53, v54, s[4:5]
	v_cmp_lt_f32_e64 s[4:5], 0, v57
	s_nop 1
	v_cndmask_b32_e64 v53, v53, v55, s[4:5]
	v_mul_f32_e32 v54, 0x37800000, v53
	v_cndmask_b32_e32 v53, v53, v54, vcc
	v_cmp_class_f32_e32 vcc, v52, v195
	s_nop 1
	v_cndmask_b32_e32 v52, v53, v52, vcc
	v_div_scale_f32 v53, s[4:5], v52, v52, 1.0
	v_rcp_f32_e32 v54, v53
	v_div_scale_f32 v55, vcc, 1.0, v52, 1.0
	s_mov_b64 s[4:5], 0
	v_fma_f32 v56, -v53, v54, 1.0
	v_fmac_f32_e32 v54, v56, v54
	v_mul_f32_e32 v56, v55, v54
	v_fma_f32 v57, -v53, v56, v55
	v_fmac_f32_e32 v56, v57, v54
	v_fma_f32 v53, -v53, v56, v55
	v_div_fmas_f32 v53, v53, v54, v56
	v_div_fixup_f32 v52, v53, v52, 1.0
	v_pk_mul_f32 v[46:47], v[46:47], v[52:53] op_sel_hi:[1,0]
	v_pk_mul_f32 v[44:45], v[44:45], v[52:53] op_sel_hi:[1,0]
	v_pk_mul_f32 v[54:55], v[42:43], v[52:53] op_sel_hi:[1,0]
	v_pk_mul_f32 v[42:43], v[40:41], v[52:53] op_sel_hi:[1,0]
	v_pk_mul_f32 v[38:39], v[38:39], v[52:53] op_sel_hi:[1,0]
	v_pk_mul_f32 v[36:37], v[36:37], v[52:53] op_sel_hi:[1,0]
	v_pk_mul_f32 v[34:35], v[34:35], v[52:53] op_sel_hi:[1,0]
	v_pk_mul_f32 v[32:33], v[32:33], v[52:53] op_sel_hi:[1,0]
	v_cvt_pk_bf16_f32 v40, v44, v45
	v_cvt_pk_bf16_f32 v41, v46, v47
	v_cvt_pk_bf16_f32 v42, v42, v43
	v_cvt_pk_bf16_f32 v43, v54, v55
	v_cmp_lt_i32_e32 vcc, s33, v128
	v_cvt_pk_bf16_f32 v44, v36, v37
	v_cvt_pk_bf16_f32 v45, v38, v39
	v_cvt_pk_bf16_f32 v46, v32, v33
	v_cvt_pk_bf16_f32 v47, v34, v35
	global_store_dwordx4 v[50:51], v[40:43], off
	global_store_dwordx4 v[50:51], v[44:47], off offset:256
	s_and_saveexec_b64 s[26:27], vcc
	s_xor_b64 s[30:31], exec, s[26:27]
	s_movk_i32 s4, 0xac8
	v_cmp_eq_u32_e32 vcc, s4, v128
	s_and_b64 s[4:5], vcc, exec
	s_or_saveexec_b64 s[30:31], s[30:31]
	v_lshl_add_u64 v[40:41], s[38:39], 0, v[48:49]
	v_mov_b64_e32 v[42:43], 40
	v_mov_b64_e32 v[44:45], 44
	s_xor_b64 exec, exec, s[30:31]
	s_cbranch_execz .LBB0_506
	s_movk_i32 s26, 0xac0
	v_cmp_eq_u32_e32 vcc, s26, v128
	s_mov_b64 s[54:55], s[4:5]
	s_and_saveexec_b64 s[56:57], vcc
	s_cbranch_execz .LBB0_505
	global_store_dwordx4 v[40:41], v[36:39], off
	global_store_dwordx2 v[40:41], v[32:33], off offset:16
	s_or_b64 s[54:55], s[4:5], exec
	v_mov_b32_e32 v37, v35
	v_mov_b32_e32 v36, v34

.LBB0_506:
	s_or_b64 exec, exec, s[30:31]
	s_and_saveexec_b64 s[30:31], s[4:5]
	s_cbranch_execz .LBB0_508
	v_lshl_add_u64 v[32:33], v[40:41], 0, v[42:43]
	global_store_dword v[32:33], v36, off
	v_lshl_add_u64 v[32:33], v[40:41], 0, v[44:45]
	global_store_dword v[32:33], v37, off
.LBB0_508:
	s_or_b64 exec, exec, s[30:31]
	v_add_u32_e32 v50, 0xa0, v140
	v_ashrrev_i32_e32 v51, 31, v50
	v_lshlrev_b64 v[32:33], 6, v[50:51]
	v_lshl_add_u64 v[46:47], s[42:43], 0, v[32:33]
	global_load_dwordx4 v[34:37], v[46:47], off
	global_load_dwordx4 v[38:41], v[46:47], off offset:32
	global_load_dwordx4 v[42:45], v[46:47], off offset:16
	s_nop 0
	global_load_dwordx4 v[46:49], v[46:47], off offset:48
	s_mov_b32 s4, 0xf800000
	s_waitcnt vmcnt(0) lgkmcnt(0)
	v_mov_b32_e32 v52, v34
	v_mov_b32_e32 v53, v38
	v_mov_b32_e32 v38, v35
	v_mov_b32_e32 v34, v36
	v_mov_b32_e32 v35, v40
	v_mov_b32_e32 v40, v37
	v_mov_b32_e32 v36, v42
	v_mov_b32_e32 v37, v46
	v_mov_b32_e32 v46, v43
	v_mov_b32_e32 v42, v44
	v_mov_b32_e32 v43, v48
	v_mov_b32_e32 v48, v45
	v_pk_add_f32 v[38:39], v[52:53], v[38:39]
	v_pk_add_f32 v[34:35], v[34:35], v[40:41]
	v_pk_add_f32 v[36:37], v[36:37], v[46:47]
	v_pk_add_f32 v[40:41], v[42:43], v[48:49]
	v_pk_add_f32 v[34:35], v[38:39], v[34:35]
	v_pk_add_f32 v[36:37], v[36:37], v[40:41]
	s_nop 0
	v_pk_add_f32 v[34:35], v[34:35], v[36:37]
	s_nop 0
	v_add_f32_e32 v34, v34, v35
	v_fmamk_f32 v34, v34, 0x3a800000, v194
	v_mul_f32_e32 v35, 0x4f800000, v34
	v_cmp_gt_f32_e32 vcc, s4, v34
	s_movk_i32 s4, 0x1600
	s_nop 0
	v_cndmask_b32_e32 v36, v34, v35, vcc
	v_sqrt_f32_e32 v37, v36
	v_mov_b64_e32 v[34:35], s[36:37]
	v_mad_i64_i32 v[34:35], s[4:5], v50, s4, v[34:35]
	v_add_u32_e32 v38, -1, v37
	v_add_u32_e32 v39, 1, v37
	v_fma_f32 v40, -v38, v37, v36
	v_fma_f32 v41, -v39, v37, v36
	v_cmp_ge_f32_e64 s[4:5], 0, v40
	v_lshl_add_u64 v[34:35], v[142:143], 1, v[34:35]
	s_nop 0
	v_cndmask_b32_e64 v37, v37, v38, s[4:5]
	v_cmp_lt_f32_e64 s[4:5], 0, v41
	s_nop 1
	v_cndmask_b32_e64 v37, v37, v39, s[4:5]
	v_mul_f32_e32 v38, 0x37800000, v37
	v_cndmask_b32_e32 v37, v37, v38, vcc
	v_cmp_class_f32_e32 vcc, v36, v195
	s_nop 1
	v_cndmask_b32_e32 v36, v37, v36, vcc
	v_div_scale_f32 v37, s[4:5], v36, v36, 1.0
	v_rcp_f32_e32 v38, v37
	v_div_scale_f32 v39, vcc, 1.0, v36, 1.0
	s_mov_b64 s[4:5], 0
	v_fma_f32 v40, -v37, v38, 1.0
	v_fmac_f32_e32 v38, v40, v38
	v_mul_f32_e32 v40, v39, v38
	v_fma_f32 v41, -v37, v40, v39
	v_fmac_f32_e32 v40, v41, v38
	v_fma_f32 v37, -v37, v40, v39
	v_div_fmas_f32 v37, v37, v38, v40
	v_div_fixup_f32 v36, v37, v36, 1.0
	v_pk_mul_f32 v[30:31], v[30:31], v[36:37] op_sel_hi:[1,0]
	v_pk_mul_f32 v[28:29], v[28:29], v[36:37] op_sel_hi:[1,0]
	v_pk_mul_f32 v[38:39], v[26:27], v[36:37] op_sel_hi:[1,0]
	v_pk_mul_f32 v[26:27], v[24:25], v[36:37] op_sel_hi:[1,0]
	v_pk_mul_f32 v[22:23], v[22:23], v[36:37] op_sel_hi:[1,0]
	v_pk_mul_f32 v[20:21], v[20:21], v[36:37] op_sel_hi:[1,0]
	v_pk_mul_f32 v[18:19], v[18:19], v[36:37] op_sel_hi:[1,0]
	v_pk_mul_f32 v[16:17], v[16:17], v[36:37] op_sel_hi:[1,0]
	v_cvt_pk_bf16_f32 v24, v28, v29
	v_cvt_pk_bf16_f32 v25, v30, v31
	v_cvt_pk_bf16_f32 v26, v26, v27
	v_cvt_pk_bf16_f32 v27, v38, v39
	v_cmp_lt_i32_e32 vcc, s33, v128
	v_cvt_pk_bf16_f32 v28, v20, v21
	v_cvt_pk_bf16_f32 v29, v22, v23
	v_cvt_pk_bf16_f32 v30, v16, v17
	v_cvt_pk_bf16_f32 v31, v18, v19
	global_store_dwordx4 v[34:35], v[24:27], off
	global_store_dwordx4 v[34:35], v[28:31], off offset:256
	s_and_saveexec_b64 s[26:27], vcc
	s_xor_b64 s[30:31], exec, s[26:27]
	s_movk_i32 s4, 0xac8
	v_cmp_eq_u32_e32 vcc, s4, v128
	s_and_b64 s[4:5], vcc, exec
	s_or_saveexec_b64 s[30:31], s[30:31]
	v_lshl_add_u64 v[24:25], s[38:39], 0, v[32:33]
	v_mov_b64_e32 v[26:27], 40
	v_mov_b64_e32 v[28:29], 44
	s_xor_b64 exec, exec, s[30:31]
	s_cbranch_execz .LBB0_514
	s_movk_i32 s26, 0xac0
	v_cmp_eq_u32_e32 vcc, s26, v128
	s_mov_b64 s[54:55], s[4:5]
	s_and_saveexec_b64 s[56:57], vcc
	s_cbranch_execz .LBB0_513
	global_store_dwordx4 v[24:25], v[20:23], off
	global_store_dwordx2 v[24:25], v[16:17], off offset:16
	s_or_b64 s[54:55], s[4:5], exec
	v_mov_b32_e32 v21, v19
	v_mov_b32_e32 v20, v18

.LBB0_514:
	s_or_b64 exec, exec, s[30:31]
	s_and_saveexec_b64 s[30:31], s[4:5]
	s_cbranch_execz .LBB0_516
	v_lshl_add_u64 v[16:17], v[24:25], 0, v[26:27]
	global_store_dword v[16:17], v20, off
	v_lshl_add_u64 v[16:17], v[24:25], 0, v[28:29]
	global_store_dword v[16:17], v21, off
.LBB0_516:
	s_or_b64 exec, exec, s[30:31]
	v_add_u32_e32 v16, 0xb0, v140
	v_ashrrev_i32_e32 v17, 31, v16
	v_mov_b64_e32 v[18:19], s[36:37]
	s_movk_i32 s4, 0x1600
	v_mad_i64_i32 v[18:19], s[4:5], v16, s4, v[18:19]
	v_lshlrev_b64 v[16:17], 6, v[16:17]
	v_lshl_add_u64 v[32:33], s[42:43], 0, v[16:17]
	global_load_dwordx4 v[20:23], v[32:33], off
	global_load_dwordx4 v[24:27], v[32:33], off offset:16
	global_load_dwordx4 v[28:31], v[32:33], off offset:32
	s_nop 0
	global_load_dwordx4 v[32:35], v[32:33], off offset:48
	s_mov_b32 s4, 0xf800000
	v_lshl_add_u64 v[18:19], v[142:143], 1, v[18:19]
	s_waitcnt vmcnt(0) lgkmcnt(0)
	v_mov_b32_e32 v36, v20
	v_mov_b32_e32 v37, v28
	v_mov_b32_e32 v28, v21
	v_pk_add_f32 v[20:21], v[36:37], v[28:29]
	v_mov_b32_e32 v28, v22
	v_mov_b32_e32 v29, v30
	v_mov_b32_e32 v30, v23
	v_pk_add_f32 v[22:23], v[28:29], v[30:31]
	s_nop 0
	v_pk_add_f32 v[20:21], v[20:21], v[22:23]
	v_mov_b32_e32 v22, v24
	v_mov_b32_e32 v23, v32
	v_mov_b32_e32 v32, v25
	v_mov_b32_e32 v24, v26
	v_mov_b32_e32 v25, v34
	v_mov_b32_e32 v34, v27
	v_pk_add_f32 v[22:23], v[22:23], v[32:33]
	v_pk_add_f32 v[24:25], v[24:25], v[34:35]
	s_nop 0
	v_pk_add_f32 v[22:23], v[22:23], v[24:25]
	s_nop 0
	v_pk_add_f32 v[20:21], v[20:21], v[22:23]
	s_nop 0
	v_add_f32_e32 v20, v20, v21
	v_fmamk_f32 v20, v20, 0x3a800000, v194
	v_cmp_gt_f32_e32 vcc, s4, v20
	v_mul_f32_e32 v21, 0x4f800000, v20
	s_nop 0
	v_cndmask_b32_e32 v20, v20, v21, vcc
	v_sqrt_f32_e32 v21, v20
	s_nop 0
	v_add_u32_e32 v22, -1, v21
	v_fma_f32 v23, -v22, v21, v20
	v_cmp_ge_f32_e64 s[4:5], 0, v23
	v_add_u32_e32 v23, 1, v21
	s_nop 0
	v_cndmask_b32_e64 v22, v21, v22, s[4:5]
	v_fma_f32 v21, -v23, v21, v20
	v_cmp_lt_f32_e64 s[4:5], 0, v21
	s_nop 1
	v_cndmask_b32_e64 v21, v22, v23, s[4:5]
	v_mul_f32_e32 v22, 0x37800000, v21
	v_cndmask_b32_e32 v21, v21, v22, vcc
	v_cmp_class_f32_e32 vcc, v20, v195
	s_nop 1
	v_cndmask_b32_e32 v20, v21, v20, vcc
	v_div_scale_f32 v21, s[4:5], v20, v20, 1.0
	v_rcp_f32_e32 v22, v21
	s_mov_b64 s[4:5], 0
	v_fma_f32 v23, -v21, v22, 1.0
	v_fmac_f32_e32 v22, v23, v22
	v_div_scale_f32 v23, vcc, 1.0, v20, 1.0
	v_mul_f32_e32 v24, v23, v22
	v_fma_f32 v25, -v21, v24, v23
	v_fmac_f32_e32 v24, v25, v22
	v_fma_f32 v21, -v21, v24, v23
	v_div_fmas_f32 v21, v21, v22, v24
	v_div_fixup_f32 v20, v21, v20, 1.0
	v_pk_mul_f32 v[14:15], v[14:15], v[20:21] op_sel_hi:[1,0]
	v_pk_mul_f32 v[12:13], v[12:13], v[20:21] op_sel_hi:[1,0]
	v_pk_mul_f32 v[22:23], v[10:11], v[20:21] op_sel_hi:[1,0]
	v_pk_mul_f32 v[10:11], v[8:9], v[20:21] op_sel_hi:[1,0]
	v_cvt_pk_bf16_f32 v8, v12, v13
	v_cvt_pk_bf16_f32 v9, v14, v15
	v_cvt_pk_bf16_f32 v10, v10, v11
	v_cvt_pk_bf16_f32 v11, v22, v23
	v_pk_mul_f32 v[6:7], v[6:7], v[20:21] op_sel_hi:[1,0]
	v_pk_mul_f32 v[4:5], v[4:5], v[20:21] op_sel_hi:[1,0]
	v_pk_mul_f32 v[2:3], v[2:3], v[20:21] op_sel_hi:[1,0]
	v_pk_mul_f32 v[0:1], v[0:1], v[20:21] op_sel_hi:[1,0]
	global_store_dwordx4 v[18:19], v[8:11], off
	v_cmp_lt_i32_e32 vcc, s33, v128
	s_nop 0
	v_cvt_pk_bf16_f32 v8, v4, v5
	v_cvt_pk_bf16_f32 v9, v6, v7
	v_cvt_pk_bf16_f32 v10, v0, v1
	v_cvt_pk_bf16_f32 v11, v2, v3
	global_store_dwordx4 v[18:19], v[8:11], off offset:256
	s_and_saveexec_b64 s[26:27], vcc
	s_xor_b64 s[30:31], exec, s[26:27]
	s_movk_i32 s4, 0xac8
	v_cmp_eq_u32_e32 vcc, s4, v128
	s_and_b64 s[4:5], vcc, exec
	s_or_saveexec_b64 s[30:31], s[30:31]
	v_lshl_add_u64 v[8:9], s[38:39], 0, v[16:17]
	v_mov_b64_e32 v[10:11], 40
	v_mov_b64_e32 v[12:13], 44
	s_xor_b64 exec, exec, s[30:31]
	s_cbranch_execz .LBB0_523
	s_movk_i32 s26, 0xac0
	v_cmp_eq_u32_e32 vcc, s26, v128
	s_mov_b64 s[54:55], s[4:5]
	s_and_saveexec_b64 s[56:57], vcc
	s_cbranch_execz .LBB0_521
	global_store_dwordx4 v[8:9], v[4:7], off
	global_store_dwordx2 v[8:9], v[0:1], off offset:16
	s_or_b64 s[54:55], s[4:5], exec
	v_mov_b32_e32 v5, v3
	v_mov_b32_e32 v4, v2

.LBB0_524:
	v_lshl_add_u64 v[0:1], v[8:9], 0, v[10:11]
	global_store_dword v[0:1], v4, off
	v_lshl_add_u64 v[0:1], v[8:9], 0, v[12:13]
	global_store_dword v[0:1], v5, off
	s_or_b64 exec, exec, s[30:31]
	s_andn2_b64 vcc, exec, s[0:1]
	s_mov_b64 s[0:1], -1
	s_cbranch_vccnz .LBB0_453

.LBB0_586:
	s_andn2_b64 vcc, exec, s[0:1]
	s_cbranch_vccnz .LBB0_803
	v_readlane_b32 s0, v254, 43
	v_readlane_b32 s1, v254, 44
	s_lshl_b32 s0, s96, 6
	v_writelane_b32 v254, s0, 43
	s_mov_b64 s[4:5], s[40:41]
	s_movk_i32 s6, 0x6000
	v_writelane_b32 v254, s1, 44
	s_mov_b32 s0, -1
	v_readlane_b32 s44, v254, 53
	v_mbcnt_lo_u32_b32 v0, s0, 0
	v_mbcnt_hi_u32_b32 v0, s0, v0
	v_readlane_b32 s0, v252, 5
	v_readlane_b32 s52, v254, 61
	v_readlane_b32 s53, v254, 62
	v_add_u32_e32 v120, s0, v0
	v_readlane_b32 s0, v254, 27
	v_ashrrev_i32_e32 v118, 6, v120
	v_readlane_b32 s54, v254, 63
	v_add_u32_e32 v115, s0, v118
	s_mov_b64 s[0:1], s[40:41]
	v_readlane_b32 s55, v255, 0
	v_lshlrev_b32_e32 v0, 3, v120
	v_and_b32_e32 v119, 63, v120
	s_mov_b64 s[36:37], s[52:53]
	v_and_b32_e32 v48, 56, v0
	s_mov_b64 s[0:1], s[54:55]
	v_cmp_gt_i32_e32 vcc, s6, v115
	v_readlane_b32 s45, v254, 54
	v_readlane_b32 s46, v254, 55
	v_readlane_b32 s47, v254, 56
	v_readlane_b32 s48, v254, 57
	v_readlane_b32 s49, v254, 58
	v_readlane_b32 s50, v254, 59
	v_readlane_b32 s51, v254, 60
	v_readlane_b32 s56, v255, 1
	v_readlane_b32 s57, v255, 2
	v_readlane_b32 s58, v255, 3
	v_readlane_b32 s59, v255, 4
	s_and_saveexec_b64 s[6:7], vcc
	s_cbranch_execz .LBB0_618
	s_add_u32 s30, s4, 0x8000000
	s_addc_u32 s31, s5, 0
	v_readlane_b32 s4, v254, 43
	v_readlane_b32 s5, v254, 44
	s_lshl_b64 s[4:5], s[4:5], 2
	s_add_u32 s26, s36, s4
	s_addc_u32 s27, s37, s5
	s_add_u32 s0, s0, s4
	v_lshlrev_b32_e32 v64, 2, v48
	s_addc_u32 s1, s1, s5
	v_lshl_add_u64 v[4:5], s[26:27], 0, v[64:65]
	s_waitcnt lgkmcnt(0)
	v_lshl_add_u64 v[12:13], s[0:1], 0, v[64:65]
	global_load_dwordx4 v[0:3], v[4:5], off
	s_nop 0
	global_load_dwordx4 v[4:7], v[4:5], off offset:16
	s_nop 0
	global_load_dwordx4 v[8:11], v[12:13], off
	s_nop 0
	global_load_dwordx4 v[12:15], v[12:13], off offset:16
	v_lshlrev_b32_e32 v51, 9, v118
	v_readlane_b32 s0, v254, 15
	v_lshrrev_b32_e32 v50, 3, v119
	v_mov_b32_e32 v16, 0
	v_add_u32_e32 v52, s0, v51
	v_readlane_b32 s0, v254, 19
	v_lshlrev_b32_e32 v49, 3, v115
	s_mov_b64 s[42:43], 0
	v_lshl_add_u32 v53, v50, 6, s0
	v_readlane_b32 s0, v254, 6
	v_lshlrev_b32_e32 v64, 1, v48
	v_mov_b32_e32 v17, v16
	v_add_u32_e32 v54, s0, v50
	v_readlane_b32 s0, v254, 17
	v_mov_b32_e32 v18, v16
	v_mov_b32_e32 v19, v16
	v_add_u32_e32 v55, s0, v51
	v_readlane_b32 s0, v254, 8
	v_mov_b32_e32 v20, v16
	v_mov_b32_e32 v21, v16
	v_add_u32_e32 v56, s0, v50
	v_readlane_b32 s0, v253, 24
	v_mov_b32_e32 v22, v16
	v_mov_b32_e32 v23, v16
	v_add_u32_e32 v57, s0, v50
	v_readlane_b32 s0, v254, 20
	v_mov_b32_e32 v24, v16
	v_mov_b32_e32 v25, v16
	v_add_u32_e32 v58, s0, v51
	v_mov_b32_e32 v26, v16
	v_mov_b32_e32 v27, v16
	s_branch .LBB0_591
.LBB0_589:
	s_or_b64 exec, exec, s[0:1]
	v_ashrrev_i32_e32 v37, 31, v39
	v_lshrrev_b32_e32 v37, 21, v37
	v_add_u32_e32 v37, v39, v37
	v_lshlrev_b32_e32 v70, 16, v24
	v_and_b32_e32 v71, 0xffff0000, v24
	v_and_b32_e32 v37, 0xfffff800, v37
	v_lshlrev_b32_e32 v66, 16, v25
	v_and_b32_e32 v67, 0xffff0000, v25
	v_pk_mul_f32 v[72:73], v[70:71], v[70:71]
	v_sub_u32_e32 v42, v39, v37
	v_ashrrev_i32_e32 v39, 31, v38
	v_pk_mul_f32 v[68:69], v[66:67], v[66:67]
	v_add_f32_e32 v37, v72, v73
	v_ashrrev_i32_e32 v43, 31, v42
	v_lshlrev_b64 v[38:39], 18, v[38:39]
	v_lshlrev_b32_e32 v60, 16, v26
	v_and_b32_e32 v61, 0xffff0000, v26
	v_add_f32_e32 v37, v68, v37
	v_lshl_add_u64 v[38:39], v[40:41], 0, v[38:39]
	v_lshlrev_b64 v[40:41], 7, v[42:43]
	v_pk_mul_f32 v[62:63], v[60:61], v[60:61]
	v_add_f32_e32 v37, v69, v37
	v_lshl_add_u64 v[38:39], v[38:39], 0, v[40:41]
	v_lshlrev_b32_e32 v40, 16, v27
	v_and_b32_e32 v41, 0xffff0000, v27
	v_add_f32_e32 v37, v62, v37
	v_pk_mul_f32 v[42:43], v[40:41], v[40:41]
	v_add_f32_e32 v37, v63, v37
	v_add_f32_e32 v37, v42, v37
	v_add_f32_e32 v37, v43, v37
	ds_bpermute_b32 v42, v44, v37
	s_mov_b32 s0, 0xf800000
	s_waitcnt lgkmcnt(0)
	v_add_f32_e32 v37, v37, v42
	ds_bpermute_b32 v42, v46, v37
	s_waitcnt lgkmcnt(0)
	v_add_f32_e32 v37, v37, v42
	ds_bpermute_b32 v42, v45, v37
	s_waitcnt lgkmcnt(0)
	v_add_f32_e32 v37, v37, v42
	v_fmamk_f32 v37, v37, 0x3c800000, v194
	v_cmp_gt_f32_e32 vcc, s0, v37
	v_mul_f32_e32 v42, 0x4f800000, v37
	s_nop 0
	v_cndmask_b32_e32 v37, v37, v42, vcc
	v_sqrt_f32_e32 v42, v37
	s_nop 0
	v_add_u32_e32 v43, -1, v42
	v_fma_f32 v44, -v43, v42, v37
	v_cmp_ge_f32_e64 s[0:1], 0, v44
	v_add_u32_e32 v44, 1, v42
	s_nop 0
	v_cndmask_b32_e64 v43, v42, v43, s[0:1]
	v_fma_f32 v42, -v44, v42, v37
	v_cmp_lt_f32_e64 s[0:1], 0, v42
	s_nop 1
	v_cndmask_b32_e64 v42, v43, v44, s[0:1]
	v_mul_f32_e32 v43, 0x37800000, v42
	v_cndmask_b32_e32 v42, v42, v43, vcc
	v_cmp_class_f32_e32 vcc, v37, v195
	s_nop 1
	v_cndmask_b32_e32 v37, v42, v37, vcc
	v_div_scale_f32 v42, s[0:1], v37, v37, 1.0
	v_rcp_f32_e32 v43, v42
	s_nop 0
	v_fma_f32 v44, -v42, v43, 1.0
	v_fmac_f32_e32 v43, v44, v43
	v_div_scale_f32 v44, vcc, 1.0, v37, 1.0
	v_mul_f32_e32 v45, v44, v43
	v_fma_f32 v46, -v42, v45, v44
	v_fmac_f32_e32 v45, v46, v43
	v_fma_f32 v42, -v42, v45, v44
	v_div_fmas_f32 v42, v42, v43, v45
	v_div_fixup_f32 v42, v42, v37, 1.0
	v_pk_mul_f32 v[28:29], v[28:29], v[42:43] op_sel_hi:[1,0]
	v_pk_mul_f32 v[32:33], v[32:33], v[42:43] op_sel_hi:[1,0]
	v_pk_mul_f32 v[44:45], v[28:29], v[60:61]
	v_pk_mul_f32 v[28:29], v[34:35], v[42:43] op_sel_hi:[1,0]
	v_pk_mul_f32 v[32:33], v[32:33], v[70:71]
	v_pk_mul_f32 v[34:35], v[28:29], v[66:67]
	v_pk_mul_f32 v[28:29], v[30:31], v[42:43] op_sel_hi:[1,0]
	v_pk_mul_f32 v[30:31], v[36:37], v[34:35] op_sel_hi:[0,1]
	v_pk_mul_f32 v[40:41], v[28:29], v[40:41]
	v_pk_mul_f32 v[28:29], v[36:37], v[32:33] op_sel_hi:[0,1]
	v_cvt_pk_bf16_f32 v28, v28, v29
	v_cvt_pk_bf16_f32 v29, v30, v31
	v_pk_mul_f32 v[30:31], v[36:37], v[44:45] op_sel_hi:[0,1]
	v_pk_mul_f32 v[32:33], v[36:37], v[40:41] op_sel_hi:[0,1]
	v_cvt_pk_bf16_f32 v30, v30, v31
	v_cvt_pk_bf16_f32 v31, v32, v33
	v_lshl_add_u64 v[32:33], v[38:39], 0, v[64:65]
	global_store_dwordx4 v[32:33], v[28:31], off

.LBB0_591:
	v_add_u32_e32 v42, v50, v49
	v_mul_hi_i32 v32, v42, s95
	v_lshrrev_b32_e32 v33, 31, v32
	v_ashrrev_i32_e32 v28, 1, v32
	v_add_u32_e32 v41, v28, v33
	s_movk_i32 s0, 0xfd00
	v_mul_lo_u32 v28, v41, s0
	v_add3_u32 v28, v51, v53, v28
	v_mov_b64_e32 v[30:31], s[30:31]
	s_movk_i32 s0, 0x1600
	v_mad_i64_i32 v[30:31], s[0:1], v41, s0, v[30:31]
	v_ashrrev_i32_e32 v29, 31, v28
	v_lshl_add_u64 v[28:29], v[28:29], 1, v[30:31]
	v_lshl_add_u64 v[28:29], v[28:29], 0, v[64:65]
	global_load_dwordx4 v[28:31], v[28:29], off nt
	v_readlane_b32 s0, v253, 24
	s_nop 1
	v_add_u32_e32 v59, s0, v49
	s_mov_b32 s0, 0x30000
	v_cmp_gt_i32_e64 s[38:39], s0, v59
	s_and_saveexec_b64 s[0:1], s[38:39]
	s_cbranch_execz .LBB0_593
	v_add_u32_e32 v16, v57, v49
	v_mul_hi_i32 v16, v16, s95
	v_lshrrev_b32_e32 v17, 31, v16
	v_ashrrev_i32_e32 v16, 1, v16
	v_add_u32_e32 v17, v16, v17
	s_movk_i32 s4, 0xfd00
	v_mul_lo_u32 v16, v17, s4
	v_add3_u32 v16, v58, v53, v16
	v_mov_b64_e32 v[18:19], s[30:31]
	s_movk_i32 s4, 0x1600
	v_mad_i64_i32 v[18:19], s[4:5], v17, s4, v[18:19]
	v_ashrrev_i32_e32 v17, 31, v16
	v_lshl_add_u64 v[16:17], v[16:17], 1, v[18:19]
	v_lshl_add_u64 v[16:17], v[16:17], 0, v[64:65]
	global_load_dwordx4 v[16:19], v[16:17], off nt
.LBB0_593:
	s_or_b64 exec, exec, s[0:1]
	v_readlane_b32 s0, v254, 6
	s_nop 1
	v_add_u32_e32 v34, s0, v49
	s_mov_b32 s0, 0x30000
	v_cmp_gt_i32_e64 s[36:37], s0, v34
	s_and_saveexec_b64 s[0:1], s[36:37]
	s_cbranch_execz .LBB0_595
	v_add_u32_e32 v20, v54, v49
	v_mul_hi_i32 v20, v20, s95
	v_lshrrev_b32_e32 v21, 31, v20
	v_ashrrev_i32_e32 v20, 1, v20
	v_add_u32_e32 v21, v20, v21
	s_movk_i32 s4, 0xfd00
	v_mul_lo_u32 v20, v21, s4
	v_add3_u32 v20, v52, v53, v20
	v_mov_b64_e32 v[22:23], s[30:31]
	s_movk_i32 s4, 0x1600
	v_mad_i64_i32 v[22:23], s[4:5], v21, s4, v[22:23]
	v_ashrrev_i32_e32 v21, 31, v20
	v_lshl_add_u64 v[20:21], v[20:21], 1, v[22:23]
	v_lshl_add_u64 v[20:21], v[20:21], 0, v[64:65]
	global_load_dwordx4 v[20:23], v[20:21], off nt
.LBB0_595:
	s_or_b64 exec, exec, s[0:1]
	v_readlane_b32 s0, v254, 8
	s_nop 1
	v_add_u32_e32 v34, s0, v49
	s_mov_b32 s0, 0x30000
	v_cmp_gt_i32_e64 s[0:1], s0, v34
	s_and_saveexec_b64 s[4:5], s[0:1]
	s_cbranch_execz .LBB0_597
	v_add_u32_e32 v24, v56, v49
	v_mul_hi_i32 v24, v24, s95
	v_lshrrev_b32_e32 v25, 31, v24
	v_ashrrev_i32_e32 v24, 1, v24
	v_add_u32_e32 v25, v24, v25
	s_movk_i32 s26, 0xfd00
	v_mul_lo_u32 v24, v25, s26
	v_add3_u32 v24, v55, v53, v24
	v_mov_b64_e32 v[26:27], s[30:31]
	s_movk_i32 s26, 0x1600
	v_mad_i64_i32 v[26:27], s[26:27], v25, s26, v[26:27]
	v_ashrrev_i32_e32 v25, 31, v24
	v_lshl_add_u64 v[24:25], v[24:25], 1, v[26:27]
	v_lshl_add_u64 v[24:25], v[24:25], 0, v[64:65]
	global_load_dwordx4 v[24:27], v[24:25], off nt

.LBB0_601:
	s_or_b64 exec, exec, s[4:5]
	v_ashrrev_i32_e32 v42, 31, v41
	v_lshrrev_b32_e32 v42, 21, v42
	v_add_u32_e32 v42, v41, v42
	v_and_b32_e32 v42, 0xfffff800, v42
	v_lshlrev_b32_e32 v72, 16, v28
	v_and_b32_e32 v73, 0xffff0000, v28
	v_sub_u32_e32 v42, v41, v42
	v_ashrrev_i32_e32 v45, 31, v44
	v_lshlrev_b32_e32 v68, 16, v29
	v_and_b32_e32 v69, 0xffff0000, v29
	v_pk_mul_f32 v[28:29], v[72:73], v[72:73]
	v_ashrrev_i32_e32 v43, 31, v42
	v_lshlrev_b64 v[44:45], 18, v[44:45]
	v_pk_mul_f32 v[70:71], v[68:69], v[68:69]
	v_add_f32_e32 v28, v28, v29
	v_lshl_add_u64 v[44:45], v[46:47], 0, v[44:45]
	v_lshlrev_b64 v[42:43], 7, v[42:43]
	v_lshlrev_b32_e32 v66, 16, v30
	v_and_b32_e32 v67, 0xffff0000, v30
	v_add_f32_e32 v28, v70, v28
	v_lshl_add_u64 v[42:43], v[44:45], 0, v[42:43]
	v_and_b32_e32 v44, 64, v197
	v_lshlrev_b32_e32 v60, 16, v31
	v_and_b32_e32 v61, 0xffff0000, v31
	v_pk_mul_f32 v[30:31], v[66:67], v[66:67]
	v_add_f32_e32 v28, v71, v28
	v_xor_b32_e32 v41, 1, v197
	v_add_u32_e32 v45, 64, v44
	v_add_f32_e32 v28, v30, v28
	v_cmp_lt_i32_e32 vcc, v41, v45
	v_pk_mul_f32 v[62:63], v[60:61], v[60:61]
	v_add_f32_e32 v28, v31, v28
	v_cndmask_b32_e32 v41, v197, v41, vcc
	v_add_f32_e32 v28, v62, v28
	v_lshlrev_b32_e32 v44, 2, v41
	v_add_f32_e32 v28, v63, v28
	ds_bpermute_b32 v29, v44, v28
	v_xor_b32_e32 v41, 2, v197
	v_cmp_lt_i32_e32 vcc, v41, v45
	s_mov_b32 s4, 0xf800000
	s_waitcnt lgkmcnt(0)
	v_add_f32_e32 v28, v28, v29
	v_cndmask_b32_e32 v41, v197, v41, vcc
	v_lshlrev_b32_e32 v46, 2, v41
	ds_bpermute_b32 v29, v46, v28
	v_xor_b32_e32 v41, 4, v197
	v_cmp_lt_i32_e32 vcc, v41, v45
	s_waitcnt lgkmcnt(0)
	v_add_f32_e32 v28, v28, v29
	v_cndmask_b32_e32 v41, v197, v41, vcc
	v_lshlrev_b32_e32 v45, 2, v41
	ds_bpermute_b32 v29, v45, v28
	s_waitcnt lgkmcnt(0)
	v_add_f32_e32 v28, v28, v29
	v_fmamk_f32 v28, v28, 0x3c800000, v194
	v_cmp_gt_f32_e32 vcc, s4, v28
	v_mul_f32_e32 v29, 0x4f800000, v28
	s_nop 0
	v_cndmask_b32_e32 v28, v28, v29, vcc
	v_sqrt_f32_e32 v29, v28
	s_nop 0
	v_add_u32_e32 v30, -1, v29
	v_fma_f32 v31, -v30, v29, v28
	v_cmp_ge_f32_e64 s[4:5], 0, v31
	v_add_u32_e32 v31, 1, v29
	s_nop 0
	v_cndmask_b32_e64 v30, v29, v30, s[4:5]
	v_fma_f32 v29, -v31, v29, v28
	v_cmp_lt_f32_e64 s[4:5], 0, v29
	s_nop 1
	v_cndmask_b32_e64 v29, v30, v31, s[4:5]
	v_mul_f32_e32 v30, 0x37800000, v29
	v_cndmask_b32_e32 v29, v29, v30, vcc
	v_cmp_class_f32_e32 vcc, v28, v195
	s_nop 1
	v_cndmask_b32_e32 v28, v29, v28, vcc
	v_div_scale_f32 v29, s[4:5], v28, v28, 1.0
	v_rcp_f32_e32 v30, v29
	s_nop 0
	v_fma_f32 v31, -v29, v30, 1.0
	v_fmac_f32_e32 v30, v31, v30
	v_div_scale_f32 v31, vcc, 1.0, v28, 1.0
	v_mul_f32_e32 v41, v31, v30
	v_fma_f32 v47, -v29, v41, v31
	v_fmac_f32_e32 v41, v47, v30
	v_fma_f32 v29, -v29, v41, v31
	v_div_fmas_f32 v29, v29, v30, v41
	v_div_fixup_f32 v28, v29, v28, 1.0
	v_pk_mul_f32 v[30:31], v[36:37], v[28:29] op_sel_hi:[1,0]
	v_pk_mul_f32 v[36:37], v[38:39], v[28:29] op_sel_hi:[1,0]
	v_pk_mul_f32 v[30:31], v[30:31], v[72:73]
	v_pk_mul_f32 v[32:33], v[32:33], v[28:29] op_sel_hi:[1,0]
	v_pk_mul_f32 v[36:37], v[36:37], v[68:69]
	v_pk_mul_f32 v[28:29], v[34:35], v[28:29] op_sel_hi:[1,0]
	v_pk_mul_f32 v[32:33], v[32:33], v[66:67]
	v_pk_mul_f32 v[34:35], v[28:29], v[60:61]
	v_pk_mul_f32 v[28:29], v[40:41], v[30:31] op_sel_hi:[0,1]
	v_pk_mul_f32 v[30:31], v[40:41], v[36:37] op_sel_hi:[0,1]
	v_cvt_pk_bf16_f32 v28, v28, v29
	v_cvt_pk_bf16_f32 v29, v30, v31
	v_pk_mul_f32 v[30:31], v[40:41], v[32:33] op_sel_hi:[0,1]
	v_pk_mul_f32 v[32:33], v[40:41], v[34:35] op_sel_hi:[0,1]
	v_cvt_pk_bf16_f32 v30, v30, v31
	v_cvt_pk_bf16_f32 v31, v32, v33
	v_lshl_add_u64 v[32:33], v[42:43], 0, v[64:65]
	global_store_dwordx4 v[32:33], v[28:31], off
	s_and_saveexec_b64 s[44:45], s[38:39]
	s_cbranch_execz .LBB0_607
	v_add_u32_e32 v42, v57, v49
	v_mul_hi_i32 v29, v42, s95
	v_ashrrev_i32_e32 v28, 1, v29
	v_lshrrev_b32_e32 v30, 31, v29
	v_add_u32_e32 v37, v28, v30
	v_mul_lo_u32 v28, v37, -12
	v_ashrrev_i32_e32 v29, 12, v29
	v_add_u32_e32 v31, v42, v28
	v_add_u32_e32 v29, v29, v30
	v_cmp_lt_i32_e32 vcc, 5, v31
	v_mul_i32_i24_e32 v39, 6, v29
	s_and_saveexec_b64 s[4:5], vcc
	s_xor_b64 s[4:5], exec, s[4:5]
	s_cbranch_execz .LBB0_604
	v_or_b32_e32 v29, v59, v50
	s_mov_b64 s[26:27], s[40:41]
	v_add_u32_e32 v28, v28, v29
	s_add_u32 s38, s26, 0xe400000
	s_addc_u32 s39, s27, 0
	v_add3_u32 v38, v28, v39, -6

.LBB0_606:
	s_or_b64 exec, exec, s[4:5]
	v_ashrrev_i32_e32 v39, 31, v37
	v_lshrrev_b32_e32 v39, 21, v39
	v_add_u32_e32 v39, v37, v39
	v_lshlrev_b32_e32 v70, 16, v16
	v_and_b32_e32 v71, 0xffff0000, v16
	v_and_b32_e32 v39, 0xfffff800, v39
	v_lshlrev_b32_e32 v66, 16, v17
	v_and_b32_e32 v67, 0xffff0000, v17
	v_pk_mul_f32 v[72:73], v[70:71], v[70:71]
	v_sub_u32_e32 v42, v37, v39
	v_ashrrev_i32_e32 v39, 31, v38
	v_pk_mul_f32 v[68:69], v[66:67], v[66:67]
	v_add_f32_e32 v37, v72, v73
	v_ashrrev_i32_e32 v43, 31, v42
	v_lshlrev_b64 v[38:39], 18, v[38:39]
	v_lshlrev_b32_e32 v60, 16, v18
	v_and_b32_e32 v61, 0xffff0000, v18
	v_add_f32_e32 v37, v68, v37
	v_lshl_add_u64 v[38:39], v[40:41], 0, v[38:39]
	v_lshlrev_b64 v[40:41], 7, v[42:43]
	v_pk_mul_f32 v[62:63], v[60:61], v[60:61]
	v_add_f32_e32 v37, v69, v37
	v_lshl_add_u64 v[38:39], v[38:39], 0, v[40:41]
	v_lshlrev_b32_e32 v40, 16, v19
	v_and_b32_e32 v41, 0xffff0000, v19
	v_add_f32_e32 v37, v62, v37
	v_pk_mul_f32 v[42:43], v[40:41], v[40:41]
	v_add_f32_e32 v37, v63, v37
	v_add_f32_e32 v37, v42, v37
	v_add_f32_e32 v37, v43, v37
	ds_bpermute_b32 v42, v44, v37
	s_mov_b32 s4, 0xf800000
	s_waitcnt lgkmcnt(0)
	v_add_f32_e32 v37, v37, v42
	ds_bpermute_b32 v42, v46, v37
	s_waitcnt lgkmcnt(0)
	v_add_f32_e32 v37, v37, v42
	ds_bpermute_b32 v42, v45, v37
	s_waitcnt lgkmcnt(0)
	v_add_f32_e32 v37, v37, v42
	v_fmamk_f32 v37, v37, 0x3c800000, v194
	v_cmp_gt_f32_e32 vcc, s4, v37
	v_mul_f32_e32 v42, 0x4f800000, v37
	s_nop 0
	v_cndmask_b32_e32 v37, v37, v42, vcc
	v_sqrt_f32_e32 v42, v37
	s_nop 0
	v_add_u32_e32 v43, -1, v42
	v_fma_f32 v47, -v43, v42, v37
	v_cmp_ge_f32_e64 s[4:5], 0, v47
	v_add_u32_e32 v47, 1, v42
	s_nop 0
	v_cndmask_b32_e64 v43, v42, v43, s[4:5]
	v_fma_f32 v42, -v47, v42, v37
	v_cmp_lt_f32_e64 s[4:5], 0, v42
	s_nop 1
	v_cndmask_b32_e64 v42, v43, v47, s[4:5]
	v_mul_f32_e32 v43, 0x37800000, v42
	v_cndmask_b32_e32 v42, v42, v43, vcc
	v_cmp_class_f32_e32 vcc, v37, v195
	s_nop 1
	v_cndmask_b32_e32 v37, v42, v37, vcc
	v_div_scale_f32 v42, s[4:5], v37, v37, 1.0
	v_rcp_f32_e32 v43, v42
	s_nop 0
	v_fma_f32 v47, -v42, v43, 1.0
	v_fmac_f32_e32 v43, v47, v43
	v_div_scale_f32 v47, vcc, 1.0, v37, 1.0
	v_mul_f32_e32 v62, v47, v43
	v_fma_f32 v63, -v42, v62, v47
	v_fmac_f32_e32 v62, v63, v43
	v_fma_f32 v42, -v42, v62, v47
	v_div_fmas_f32 v42, v42, v43, v62
	v_div_fixup_f32 v42, v42, v37, 1.0
	v_pk_mul_f32 v[28:29], v[28:29], v[42:43] op_sel_hi:[1,0]
	v_pk_mul_f32 v[32:33], v[32:33], v[42:43] op_sel_hi:[1,0]
	v_pk_mul_f32 v[60:61], v[28:29], v[60:61]
	v_pk_mul_f32 v[28:29], v[34:35], v[42:43] op_sel_hi:[1,0]
	v_pk_mul_f32 v[32:33], v[32:33], v[70:71]
	v_pk_mul_f32 v[34:35], v[28:29], v[66:67]
	v_pk_mul_f32 v[28:29], v[30:31], v[42:43] op_sel_hi:[1,0]
	v_pk_mul_f32 v[30:31], v[36:37], v[34:35] op_sel_hi:[0,1]
	v_pk_mul_f32 v[40:41], v[28:29], v[40:41]
	v_pk_mul_f32 v[28:29], v[36:37], v[32:33] op_sel_hi:[0,1]
	v_cvt_pk_bf16_f32 v28, v28, v29
	v_cvt_pk_bf16_f32 v29, v30, v31
	v_pk_mul_f32 v[30:31], v[36:37], v[60:61] op_sel_hi:[0,1]
	v_pk_mul_f32 v[32:33], v[36:37], v[40:41] op_sel_hi:[0,1]
	v_cvt_pk_bf16_f32 v30, v30, v31
	v_cvt_pk_bf16_f32 v31, v32, v33
	v_lshl_add_u64 v[32:33], v[38:39], 0, v[64:65]
	global_store_dwordx4 v[32:33], v[28:31], off

.LBB0_612:
	s_or_b64 exec, exec, s[4:5]
	v_ashrrev_i32_e32 v42, 31, v39
	v_lshrrev_b32_e32 v42, 21, v42
	v_add_u32_e32 v42, v39, v42
	v_lshlrev_b32_e32 v70, 16, v20
	v_and_b32_e32 v71, 0xffff0000, v20
	v_and_b32_e32 v42, 0xfffff800, v42
	v_lshlrev_b32_e32 v66, 16, v21
	v_and_b32_e32 v67, 0xffff0000, v21
	v_pk_mul_f32 v[72:73], v[70:71], v[70:71]
	v_sub_u32_e32 v42, v39, v42
	v_ashrrev_i32_e32 v39, 31, v38
	v_pk_mul_f32 v[68:69], v[66:67], v[66:67]
	v_add_f32_e32 v47, v72, v73
	v_ashrrev_i32_e32 v43, 31, v42
	v_lshlrev_b64 v[38:39], 18, v[38:39]
	v_lshlrev_b32_e32 v60, 16, v22
	v_and_b32_e32 v61, 0xffff0000, v22
	v_add_f32_e32 v47, v68, v47
	v_lshl_add_u64 v[38:39], v[40:41], 0, v[38:39]
	v_lshlrev_b64 v[40:41], 7, v[42:43]
	v_pk_mul_f32 v[62:63], v[60:61], v[60:61]
	v_add_f32_e32 v47, v69, v47
	v_lshl_add_u64 v[38:39], v[38:39], 0, v[40:41]
	v_lshlrev_b32_e32 v40, 16, v23
	v_and_b32_e32 v41, 0xffff0000, v23
	v_add_f32_e32 v47, v62, v47
	v_pk_mul_f32 v[42:43], v[40:41], v[40:41]
	v_add_f32_e32 v47, v63, v47
	v_add_f32_e32 v42, v42, v47
	v_add_f32_e32 v42, v43, v42
	ds_bpermute_b32 v43, v44, v42
	s_mov_b32 s4, 0xf800000
	s_waitcnt lgkmcnt(0)
	v_add_f32_e32 v42, v42, v43
	ds_bpermute_b32 v43, v46, v42
	s_waitcnt lgkmcnt(0)
	v_add_f32_e32 v42, v42, v43
	ds_bpermute_b32 v43, v45, v42
	s_waitcnt lgkmcnt(0)
	v_add_f32_e32 v42, v42, v43
	v_fmamk_f32 v42, v42, 0x3c800000, v194
	v_cmp_gt_f32_e32 vcc, s4, v42
	v_mul_f32_e32 v43, 0x4f800000, v42
	s_nop 0
	v_cndmask_b32_e32 v42, v42, v43, vcc
	v_sqrt_f32_e32 v43, v42
	s_nop 0
	v_add_u32_e32 v47, -1, v43
	v_fma_f32 v59, -v47, v43, v42
	v_cmp_ge_f32_e64 s[4:5], 0, v59
	v_add_u32_e32 v59, 1, v43
	s_nop 0
	v_cndmask_b32_e64 v47, v43, v47, s[4:5]
	v_fma_f32 v43, -v59, v43, v42
	v_cmp_lt_f32_e64 s[4:5], 0, v43
	s_nop 1
	v_cndmask_b32_e64 v43, v47, v59, s[4:5]
	v_mul_f32_e32 v47, 0x37800000, v43
	v_cndmask_b32_e32 v43, v43, v47, vcc
	v_cmp_class_f32_e32 vcc, v42, v195
	s_nop 1
	v_cndmask_b32_e32 v42, v43, v42, vcc
	v_div_scale_f32 v43, s[4:5], v42, v42, 1.0
	v_rcp_f32_e32 v47, v43
	s_nop 0
	v_fma_f32 v59, -v43, v47, 1.0
	v_fmac_f32_e32 v47, v59, v47
	v_div_scale_f32 v59, vcc, 1.0, v42, 1.0
	v_mul_f32_e32 v62, v59, v47
	v_fma_f32 v63, -v43, v62, v59
	v_fmac_f32_e32 v62, v63, v47
	v_fma_f32 v43, -v43, v62, v59
	v_div_fmas_f32 v43, v43, v47, v62
	v_div_fixup_f32 v42, v43, v42, 1.0
	v_pk_mul_f32 v[28:29], v[28:29], v[42:43] op_sel_hi:[1,0]
	v_pk_mul_f32 v[32:33], v[32:33], v[42:43] op_sel_hi:[1,0]
	v_pk_mul_f32 v[60:61], v[28:29], v[60:61]
	v_pk_mul_f32 v[28:29], v[34:35], v[42:43] op_sel_hi:[1,0]
	v_pk_mul_f32 v[32:33], v[32:33], v[70:71]
	v_pk_mul_f32 v[34:35], v[28:29], v[66:67]
	v_pk_mul_f32 v[28:29], v[30:31], v[42:43] op_sel_hi:[1,0]
	v_pk_mul_f32 v[30:31], v[36:37], v[34:35] op_sel_hi:[0,1]
	v_pk_mul_f32 v[40:41], v[28:29], v[40:41]
	v_pk_mul_f32 v[28:29], v[36:37], v[32:33] op_sel_hi:[0,1]
	v_cvt_pk_bf16_f32 v28, v28, v29
	v_cvt_pk_bf16_f32 v29, v30, v31
	v_pk_mul_f32 v[30:31], v[36:37], v[60:61] op_sel_hi:[0,1]
	v_pk_mul_f32 v[32:33], v[36:37], v[40:41] op_sel_hi:[0,1]
	v_cvt_pk_bf16_f32 v30, v30, v31
	v_cvt_pk_bf16_f32 v31, v32, v33
	v_lshl_add_u64 v[32:33], v[38:39], 0, v[64:65]
	global_store_dwordx4 v[32:33], v[28:31], off

.LBB0_618:
	s_or_b64 exec, exec, s[6:7]
	v_readlane_b32 s44, v254, 53
	v_readlane_b32 s56, v255, 1
	v_readlane_b32 s57, v255, 2
	v_readlane_b32 s58, v255, 3
	v_readlane_b32 s59, v255, 4
	s_movk_i32 s6, 0x4000
	s_mov_b64 s[30:31], s[40:41]
	s_mov_b64 s[36:37], s[40:41]
	s_mov_b64 s[4:5], s[56:57]
	s_mov_b64 s[0:1], s[58:59]
	v_cmp_gt_i32_e32 vcc, s6, v115
	v_readlane_b32 s45, v254, 54
	v_readlane_b32 s46, v254, 55
	v_readlane_b32 s47, v254, 56
	v_readlane_b32 s48, v254, 57
	v_readlane_b32 s49, v254, 58
	v_readlane_b32 s50, v254, 59
	v_readlane_b32 s51, v254, 60
	v_readlane_b32 s52, v254, 61
	v_readlane_b32 s53, v254, 62
	v_readlane_b32 s54, v254, 63
	v_readlane_b32 s55, v255, 0
	s_and_saveexec_b64 s[6:7], vcc
	s_cbranch_execz .LBB0_657
	s_lshl_b32 s26, s96, 5
	v_readlane_b32 s28, v254, 43
	s_add_u32 s30, s30, 0x8000000
	v_readlane_b32 s29, v254, 44
	s_addc_u32 s31, s31, 0
	s_mov_b32 s27, s29
	s_add_u32 s44, s36, 0x13400000
	s_addc_u32 s45, s37, 0
	s_lshl_b64 s[26:27], s[26:27], 2
	s_add_u32 s4, s4, s26
	s_addc_u32 s5, s5, s27
	v_and_b32_e32 v16, 3, v120
	s_add_u32 s0, s0, s26
	v_lshlrev_b32_e32 v64, 5, v16
	s_addc_u32 s1, s1, s27
	v_lshl_add_u64 v[4:5], s[4:5], 0, v[64:65]
	s_waitcnt lgkmcnt(0)
	v_lshl_add_u64 v[12:13], s[0:1], 0, v[64:65]
	global_load_dwordx4 v[0:3], v[4:5], off
	s_nop 0
	global_load_dwordx4 v[4:7], v[4:5], off offset:16
	s_nop 0
	global_load_dwordx4 v[8:11], v[12:13], off
	s_nop 0
	global_load_dwordx4 v[12:15], v[12:13], off offset:16
	v_cmp_eq_u32_e64 s[0:1], 0, v16
	v_lshlrev_b32_e32 v16, 9, v118
	v_readlane_b32 s4, v254, 9
	v_lshrrev_b32_e32 v82, 3, v119
	s_waitcnt vmcnt(0)
	v_lshlrev_b32_e32 v79, 3, v115
	v_add_u32_e32 v83, s4, v16
	v_readlane_b32 s4, v254, 19
	v_add_u32_e32 v90, 0x480, v16
	s_mov_b64 s[46:47], 0
	v_lshl_add_u32 v84, v82, 6, s4
	v_readlane_b32 s4, v254, 6
	v_lshlrev_b32_e32 v64, 1, v48
	s_nop 0
	v_add_u32_e32 v85, s4, v82
	v_readlane_b32 s4, v254, 10
	s_nop 1
	v_add_u32_e32 v86, s4, v16
	v_readlane_b32 s4, v254, 8
	s_nop 1
	v_add_u32_e32 v87, s4, v82
	v_readlane_b32 s4, v253, 24
	s_nop 1
	v_add_u32_e32 v88, s4, v82
	v_readlane_b32 s4, v254, 11
	s_nop 1
	v_add_u32_e32 v89, s4, v16
	s_branch .LBB0_622
.LBB0_620:
	s_or_b64 exec, exec, s[4:5]
	v_ashrrev_i32_e32 v55, 3, v61
	v_ashrrev_i32_e32 v57, 31, v55
	v_lshrrev_b32_e32 v57, 21, v57
	v_add_u32_e32 v57, v55, v57
	v_and_b32_e32 v57, 0xfffff800, v57
	v_sub_u32_e32 v70, v55, v57
	v_ashrrev_i32_e32 v61, 31, v60
	v_ashrrev_i32_e32 v71, 31, v70
	v_lshlrev_b64 v[60:61], 18, v[60:61]
	v_lshl_add_u64 v[60:61], v[66:67], 0, v[60:61]
	v_lshlrev_b64 v[66:67], 7, v[70:71]
	v_mov_b32_e32 v57, v59
	v_pk_mul_f32 v[52:53], v[62:63], v[52:53] op_sel_hi:[0,1]
	v_mov_b32_e32 v55, v58
	v_lshl_add_u64 v[60:61], v[60:61], 0, v[66:67]
	v_pk_mul_f32 v[66:67], v[62:63], v[68:69] op_sel_hi:[0,1]
	v_pk_mul_f32 v[56:57], v[62:63], v[56:57] op_sel_hi:[0,1]
	v_cvt_pk_bf16_f32 v68, v52, v53
	v_pk_mul_f32 v[52:53], v[62:63], v[54:55] op_sel_hi:[0,1]
	v_cvt_pk_bf16_f32 v66, v66, v67
	v_cvt_pk_bf16_f32 v67, v56, v57
	v_cvt_pk_bf16_f32 v69, v52, v53
	v_lshl_add_u64 v[52:53], v[60:61], 0, v[64:65]
	global_store_dwordx4 v[52:53], v[66:69], off

.LBB0_622:
	v_add_u32_e32 v75, v82, v79
	v_ashrrev_i32_e32 v66, 31, v75
	v_lshrrev_b32_e32 v52, 29, v66
	v_add_u32_e32 v52, v75, v52
	v_ashrrev_i32_e32 v67, 3, v52
	v_ashrrev_i32_e32 v52, 31, v52
	v_lshrrev_b32_e32 v52, 21, v52
	v_add_u32_e32 v52, v67, v52
	v_and_b32_e32 v52, 0xfffff800, v52
	v_sub_u32_e32 v74, v67, v52
	v_add_u32_e32 v52, v90, v84
	v_lshlrev_b32_e32 v53, 9, v67
	v_sub_u32_e32 v52, v52, v53
	v_mov_b64_e32 v[54:55], s[30:31]
	s_movk_i32 s4, 0x1600
	v_mad_i64_i32 v[54:55], s[4:5], v67, s4, v[54:55]
	v_ashrrev_i32_e32 v53, 31, v52
	v_lshl_add_u64 v[52:53], v[52:53], 1, v[54:55]
	v_lshl_add_u64 v[52:53], v[52:53], 0, v[64:65]
	global_load_dwordx4 v[60:63], v[52:53], off nt
	v_mul_i32_i24_e32 v52, 24, v74
	v_ashrrev_i32_e32 v53, 31, v52
	v_lshl_add_u64 v[52:53], v[52:53], 2, s[44:45]
	global_load_dwordx4 v[56:59], v[52:53], off offset:64
	s_nop 0
	global_load_dwordx4 v[52:55], v[52:53], off offset:80
	v_readlane_b32 s4, v253, 24
	s_nop 1
	v_add_u32_e32 v93, s4, v79
	s_mov_b32 s4, 0x20000
	v_cmp_gt_i32_e64 s[42:43], s4, v93
	s_and_saveexec_b64 s[4:5], s[42:43]
	s_cbranch_execz .LBB0_624
	v_add_u32_e32 v16, v88, v79
	v_ashrrev_i32_e32 v17, 31, v16
	v_lshrrev_b32_e32 v17, 29, v17
	v_add_u32_e32 v16, v16, v17
	v_ashrrev_i32_e32 v17, 3, v16
	v_ashrrev_i32_e32 v16, 31, v16
	v_lshrrev_b32_e32 v16, 21, v16
	v_add_u32_e32 v16, v17, v16
	v_and_b32_e32 v16, 0xfff800, v16
	v_sub_u32_e32 v36, v17, v16
	v_add_u32_e32 v16, v89, v84
	v_lshlrev_b32_e32 v18, 9, v17
	v_sub_u32_e32 v16, v16, v18
	v_mov_b64_e32 v[18:19], s[30:31]
	s_movk_i32 s26, 0x1600
	v_mad_i64_i32 v[18:19], s[26:27], v17, s26, v[18:19]
	v_ashrrev_i32_e32 v17, 31, v16
	v_mul_i32_i24_e32 v36, 24, v36
	v_lshl_add_u64 v[16:17], v[16:17], 1, v[18:19]
	v_ashrrev_i32_e32 v37, 31, v36
	v_lshl_add_u64 v[16:17], v[16:17], 0, v[64:65]
	v_lshl_add_u64 v[36:37], v[36:37], 2, s[44:45]
	global_load_dwordx4 v[16:19], v[16:17], off nt
	s_nop 0
	global_load_dwordx4 v[40:43], v[36:37], off offset:64
	s_nop 0
	global_load_dwordx4 v[36:39], v[36:37], off offset:80
.LBB0_624:
	s_or_b64 exec, exec, s[4:5]
	v_readlane_b32 s4, v254, 6
	s_nop 1
	v_add_u32_e32 v68, s4, v79
	s_mov_b32 s4, 0x20000
	v_cmp_gt_i32_e64 s[38:39], s4, v68
	s_and_saveexec_b64 s[4:5], s[38:39]
	s_cbranch_execz .LBB0_626
	v_add_u32_e32 v24, v85, v79
	v_ashrrev_i32_e32 v25, 31, v24
	v_lshrrev_b32_e32 v25, 29, v25
	v_add_u32_e32 v24, v24, v25
	v_ashrrev_i32_e32 v25, 3, v24
	v_ashrrev_i32_e32 v24, 31, v24
	v_lshrrev_b32_e32 v24, 21, v24
	v_add_u32_e32 v24, v25, v24
	v_and_b32_e32 v24, 0xfff800, v24
	v_sub_u32_e32 v44, v25, v24
	v_add_u32_e32 v24, v83, v84
	v_lshlrev_b32_e32 v26, 9, v25
	v_sub_u32_e32 v24, v24, v26
	v_mov_b64_e32 v[26:27], s[30:31]
	s_movk_i32 s26, 0x1600
	v_mad_i64_i32 v[26:27], s[26:27], v25, s26, v[26:27]
	v_ashrrev_i32_e32 v25, 31, v24
	v_mul_i32_i24_e32 v44, 24, v44
	v_lshl_add_u64 v[24:25], v[24:25], 1, v[26:27]
	v_ashrrev_i32_e32 v45, 31, v44
	v_lshl_add_u64 v[24:25], v[24:25], 0, v[64:65]
	v_lshl_add_u64 v[44:45], v[44:45], 2, s[44:45]
	global_load_dwordx4 v[24:27], v[24:25], off nt
	s_nop 0
	global_load_dwordx4 v[48:51], v[44:45], off offset:64
	s_nop 0
	global_load_dwordx4 v[44:47], v[44:45], off offset:80
.LBB0_626:
	s_or_b64 exec, exec, s[4:5]
	v_readlane_b32 s4, v254, 8
	s_nop 1
	v_add_u32_e32 v68, s4, v79
	s_mov_b32 s4, 0x20000
	v_cmp_gt_i32_e64 s[36:37], s4, v68
	s_and_saveexec_b64 s[4:5], s[36:37]
	s_cbranch_execz .LBB0_628
	v_add_u32_e32 v20, v87, v79
	v_ashrrev_i32_e32 v21, 31, v20
	v_lshrrev_b32_e32 v21, 29, v21
	v_add_u32_e32 v20, v20, v21
	v_ashrrev_i32_e32 v21, 3, v20
	v_ashrrev_i32_e32 v20, 31, v20
	v_lshrrev_b32_e32 v20, 21, v20
	v_add_u32_e32 v20, v21, v20
	v_and_b32_e32 v20, 0xfff800, v20
	v_sub_u32_e32 v28, v21, v20
	v_add_u32_e32 v20, v86, v84
	v_lshlrev_b32_e32 v22, 9, v21
	v_sub_u32_e32 v20, v20, v22
	v_mov_b64_e32 v[22:23], s[30:31]
	s_movk_i32 s26, 0x1600
	v_mad_i64_i32 v[22:23], s[26:27], v21, s26, v[22:23]
	v_ashrrev_i32_e32 v21, 31, v20
	v_mul_i32_i24_e32 v28, 24, v28
	v_lshl_add_u64 v[20:21], v[20:21], 1, v[22:23]
	v_ashrrev_i32_e32 v29, 31, v28
	v_lshl_add_u64 v[20:21], v[20:21], 0, v[64:65]
	v_lshl_add_u64 v[28:29], v[28:29], 2, s[44:45]
	global_load_dwordx4 v[20:23], v[20:21], off nt
	s_nop 0
	global_load_dwordx4 v[32:35], v[28:29], off offset:64
	s_nop 0
	global_load_dwordx4 v[28:31], v[28:29], off offset:80

.LBB0_634:
	s_or_b64 exec, exec, s[4:5]
	v_ashrrev_i32_e32 v77, 31, v76
	v_ashrrev_i32_e32 v75, 31, v74
	v_lshlrev_b64 v[52:53], 18, v[76:77]
	v_lshl_add_u64 v[52:53], v[80:81], 0, v[52:53]
	v_lshlrev_b64 v[54:55], 7, v[74:75]
	v_mov_b32_e32 v63, v69
	v_lshl_add_u64 v[56:57], v[52:53], 0, v[54:55]
	v_pk_mul_f32 v[52:53], v[78:79], v[70:71] op_sel_hi:[0,1]
	v_pk_mul_f32 v[54:55], v[78:79], v[62:63] op_sel_hi:[0,1]
	v_mov_b32_e32 v67, v68
	v_cvt_pk_bf16_f32 v52, v52, v53
	v_cvt_pk_bf16_f32 v53, v54, v55
	v_pk_mul_f32 v[54:55], v[78:79], v[60:61] op_sel_hi:[0,1]
	v_pk_mul_f32 v[58:59], v[78:79], v[66:67] op_sel_hi:[0,1]
	v_cvt_pk_bf16_f32 v54, v54, v55
	v_cvt_pk_bf16_f32 v55, v58, v59
	v_lshl_add_u64 v[56:57], v[56:57], 0, v[64:65]
	global_store_dwordx4 v[56:57], v[52:55], off
	s_and_saveexec_b64 s[48:49], s[42:43]
	s_cbranch_execz .LBB0_642
	v_add_u32_e32 v68, v88, v79
	v_ashrrev_i32_e32 v52, 31, v68
	v_lshrrev_b32_e32 v53, 29, v52
	v_add_u32_e32 v61, v68, v53
	v_lshrrev_b32_e32 v52, 18, v52
	v_and_b32_e32 v69, -8, v61
	v_add_u32_e32 v52, v68, v52
	v_sub_u32_e32 v53, v68, v69
	v_ashrrev_i32_e32 v52, 14, v52
	v_cmp_lt_i32_e32 vcc, 3, v53
	v_lshlrev_b32_e32 v63, 2, v52
	s_and_saveexec_b64 s[4:5], vcc
	s_xor_b64 s[4:5], exec, s[4:5]
	s_cbranch_execz .LBB0_637
	v_or_b32_e32 v52, v93, v82
	s_mov_b64 s[26:27], s[40:41]
	v_sub_u32_e32 v52, v52, v69
	s_add_u32 s42, s26, 0xf800000
	s_addc_u32 s43, s27, 0
	v_add3_u32 v60, v52, v63, -4

.LBB0_657:
	s_or_b64 exec, exec, s[6:7]
	v_and_b32_e32 v122, 7, v120
	s_movk_i32 s6, 0x3800
	s_mov_b64 s[30:31], s[40:41]
	s_mov_b64 s[36:37], s[40:41]
	s_waitcnt lgkmcnt(0)
	s_mov_b64 s[4:5], s[18:19]
	v_lshlrev_b32_e32 v121, 3, v122
	s_mov_b64 s[0:1], s[20:21]
	v_cmp_gt_i32_e32 vcc, s6, v115
	s_and_saveexec_b64 s[6:7], vcc
	s_cbranch_execz .LBB0_696
	s_add_u32 s30, s30, 0x8000000
	s_addc_u32 s31, s31, 0
	v_readlane_b32 s26, v254, 43
	s_add_u32 s44, s36, 0x13400000
	v_readlane_b32 s27, v254, 44
	s_addc_u32 s45, s37, 0
	s_lshl_b64 s[26:27], s[26:27], 2
	s_add_u32 s4, s4, s26
	s_addc_u32 s5, s5, s27
	s_add_u32 s0, s0, s26
	v_lshlrev_b32_e32 v64, 2, v121
	s_addc_u32 s1, s1, s27
	v_lshl_add_u64 v[4:5], s[4:5], 0, v[64:65]
	v_lshl_add_u64 v[12:13], s[0:1], 0, v[64:65]
	global_load_dwordx4 v[0:3], v[4:5], off
	s_nop 0
	global_load_dwordx4 v[4:7], v[4:5], off offset:16
	s_nop 0
	global_load_dwordx4 v[8:11], v[12:13], off
	s_nop 0
	global_load_dwordx4 v[12:15], v[12:13], off offset:16
	v_lshlrev_b32_e32 v17, 9, v118
	v_readlane_b32 s4, v254, 12
	v_lshrrev_b32_e32 v124, 3, v119
	v_cmp_eq_u32_e32 vcc, 0, v122
	v_add_u32_e32 v125, s4, v17
	v_readlane_b32 s4, v254, 19
	v_mov_b32_e32 v16, 0
	s_waitcnt vmcnt(0)
	v_cndmask_b32_e64 v106, 1.0, -1.0, vcc
	v_lshl_add_u32 v126, v124, 6, s4
	v_readlane_b32 s4, v254, 6
	v_lshlrev_b32_e32 v123, 3, v115
	v_cmp_gt_u32_e64 s[0:1], 2, v122
	v_add_u32_e32 v127, s4, v124
	v_readlane_b32 s4, v254, 13
	v_mov_b32_e32 v107, v106
	v_add_u32_e32 v132, 0x780, v17
	v_add_u32_e32 v128, s4, v17
	v_readlane_b32 s4, v254, 8
	s_mov_b64 s[46:47], 0
	v_mov_b32_e32 v18, v16
	v_add_u32_e32 v129, s4, v124
	v_readlane_b32 s4, v253, 24
	v_mov_b32_e32 v19, v16
	v_mov_b32_e32 v70, v16
	v_add_u32_e32 v130, s4, v124
	v_readlane_b32 s4, v254, 14
	v_mov_b32_e32 v71, v16
	v_mov_b32_e32 v72, v16
	v_add_u32_e32 v131, s4, v17
	v_mov_b32_e32 v17, v16
	v_mov_b32_e32 v73, v16
	v_mov_b32_e32 v74, v16
	v_mov_b32_e32 v75, v16
	v_mov_b32_e32 v76, v16
	v_mov_b32_e32 v77, v16
	s_branch .LBB0_661
.LBB0_659:
	s_or_b64 exec, exec, s[4:5]
	s_waitcnt lgkmcnt(0)
	v_ashrrev_i32_e32 v87, 31, v86
	v_lshlrev_b64 v[80:81], 7, v[86:87]
	v_lshl_add_u64 v[86:87], v[90:91], 0, v[80:81]
	v_pk_mul_f32 v[80:81], v[88:89], v[92:93] op_sel_hi:[0,1]
	v_pk_mul_f32 v[84:85], v[88:89], v[84:85] op_sel_hi:[0,1]
	v_pk_mul_f32 v[82:83], v[88:89], v[82:83] op_sel_hi:[0,1]
	v_pk_mul_f32 v[78:79], v[88:89], v[78:79] op_sel_hi:[0,1]
	v_cvt_pk_bf16_f32 v80, v80, v81
	v_cvt_pk_bf16_f32 v81, v84, v85
	v_cvt_pk_bf16_f32 v82, v82, v83
	v_cvt_pk_bf16_f32 v83, v78, v79
	v_lshl_add_u64 v[78:79], v[86:87], 0, v[64:65]
	global_store_dwordx4 v[78:79], v[80:83], off

.LBB0_661:
	s_waitcnt lgkmcnt(0)
	v_add_u32_e32 v110, v124, v123
	s_mov_b32 s4, 0x92492493
	v_mul_hi_i32 v64, v110, s4
	v_add_u32_e32 v111, v64, v110
	v_lshrrev_b32_e32 v113, 31, v111
	v_ashrrev_i32_e32 v64, 2, v111
	v_add_u32_e32 v108, v64, v113
	v_ashrrev_i32_e32 v109, 31, v108
	v_lshrrev_b32_e32 v64, 21, v109
	v_add_u32_e32 v64, v108, v64
	v_and_b32_e32 v64, 0xfffff800, v64
	s_movk_i32 s26, 0xfe40
	v_mad_u64_u32 v[78:79], s[4:5], v108, -7, v[110:111]
	v_sub_u32_e32 v112, v108, v64
	v_mul_lo_u32 v64, v108, s26
	v_cmp_gt_i32_e64 s[4:5], 6, v78
	v_add3_u32 v64, v132, v126, v64
	v_cmp_lt_i32_e32 vcc, 5, v78
	v_cndmask_b32_e64 v78, v201, v64, s[4:5]
	v_mov_b64_e32 v[80:81], s[30:31]
	s_movk_i32 s4, 0x1600
	v_ashrrev_i32_e32 v79, 31, v78
	v_mad_i64_i32 v[80:81], s[4:5], v108, s4, v[80:81]
	v_lshl_add_u64 v[78:79], v[78:79], 1, v[80:81]
	v_lshlrev_b32_e32 v64, 1, v121
	v_lshl_add_u64 v[78:79], v[78:79], 0, v[64:65]
	global_load_dwordx4 v[94:97], v[78:79], off nt
	v_mul_i32_i24_e32 v78, 24, v112
	v_ashrrev_i32_e32 v79, 31, v78
	v_lshl_add_u64 v[90:91], v[78:79], 2, s[44:45]
	global_load_dwordx4 v[78:81], v[90:91], off
	global_load_dwordx4 v[82:85], v[90:91], off offset:16
	global_load_dwordx4 v[86:89], v[90:91], off offset:32
	s_nop 0
	global_load_dwordx4 v[90:93], v[90:91], off offset:48
	v_readlane_b32 s4, v253, 24
	s_nop 1
	v_add_u32_e32 v98, s4, v123
	s_mov_b32 s4, 0x1c000
	v_cmp_gt_i32_e64 s[42:43], s4, v98
	s_and_saveexec_b64 s[36:37], s[42:43]
	s_cbranch_execz .LBB0_663
	v_add_u32_e32 v16, v130, v123
	s_mov_b32 s4, 0x92492493
	v_mul_hi_i32 v17, v16, s4
	v_add_u32_e32 v17, v17, v16
	v_lshrrev_b32_e32 v18, 31, v17
	v_ashrrev_i32_e32 v17, 2, v17
	v_add_u32_e32 v52, v17, v18
	v_mad_u64_u32 v[16:17], s[4:5], v52, -7, v[16:17]
	v_ashrrev_i32_e32 v17, 31, v52
	v_lshrrev_b32_e32 v17, 21, v17
	v_add_u32_e32 v17, v52, v17
	v_and_b32_e32 v17, 0xfff800, v17
	s_movk_i32 s4, 0xfe40
	v_sub_u32_e32 v53, v52, v17
	v_mul_lo_u32 v17, v52, s4
	v_add3_u32 v17, v131, v126, v17
	v_cmp_gt_i32_e64 s[4:5], 6, v16
	v_mov_b64_e32 v[18:19], s[30:31]
	s_nop 0
	v_cndmask_b32_e64 v16, v201, v17, s[4:5]
	s_movk_i32 s4, 0x1600
	v_ashrrev_i32_e32 v17, 31, v16
	v_mad_i64_i32 v[18:19], s[4:5], v52, s4, v[18:19]
	v_mul_i32_i24_e32 v52, 24, v53
	v_lshl_add_u64 v[16:17], v[16:17], 1, v[18:19]
	v_ashrrev_i32_e32 v53, 31, v52
	v_lshl_add_u64 v[16:17], v[16:17], 0, v[64:65]
	v_lshl_add_u64 v[52:53], v[52:53], 2, s[44:45]
	global_load_dwordx4 v[16:19], v[16:17], off nt
	s_nop 0
	global_load_dwordx4 v[66:69], v[52:53], off
	global_load_dwordx4 v[60:63], v[52:53], off offset:16
	global_load_dwordx4 v[56:59], v[52:53], off offset:32
	s_nop 0
	global_load_dwordx4 v[52:55], v[52:53], off offset:48
.LBB0_663:
	s_or_b64 exec, exec, s[36:37]
	v_readlane_b32 s4, v254, 6
	s_nop 1
	v_add_u32_e32 v98, s4, v123
	s_mov_b32 s4, 0x1c000
	v_cmp_gt_i32_e64 s[38:39], s4, v98
	s_and_saveexec_b64 s[36:37], s[38:39]
	s_cbranch_execz .LBB0_665
	v_add_u32_e32 v36, v127, v123
	s_mov_b32 s4, 0x92492493
	v_mul_hi_i32 v37, v36, s4
	v_add_u32_e32 v37, v37, v36
	v_lshrrev_b32_e32 v38, 31, v37
	v_ashrrev_i32_e32 v37, 2, v37
	v_add_u32_e32 v40, v37, v38
	v_mad_u64_u32 v[36:37], s[4:5], v40, -7, v[36:37]
	v_ashrrev_i32_e32 v37, 31, v40
	v_lshrrev_b32_e32 v37, 21, v37
	v_add_u32_e32 v37, v40, v37
	v_and_b32_e32 v37, 0xfff800, v37
	s_movk_i32 s4, 0xfe40
	v_sub_u32_e32 v41, v40, v37
	v_mul_lo_u32 v37, v40, s4
	v_add3_u32 v37, v125, v126, v37
	v_cmp_gt_i32_e64 s[4:5], 6, v36
	v_mov_b64_e32 v[38:39], s[30:31]
	s_nop 0
	v_cndmask_b32_e64 v36, v201, v37, s[4:5]
	s_movk_i32 s4, 0x1600
	v_ashrrev_i32_e32 v37, 31, v36
	v_mad_i64_i32 v[38:39], s[4:5], v40, s4, v[38:39]
	v_lshl_add_u64 v[36:37], v[36:37], 1, v[38:39]
	v_lshl_add_u64 v[36:37], v[36:37], 0, v[64:65]
	global_load_dwordx4 v[70:73], v[36:37], off nt
	v_mul_i32_i24_e32 v36, 24, v41
	v_ashrrev_i32_e32 v37, 31, v36
	v_lshl_add_u64 v[36:37], v[36:37], 2, s[44:45]
	global_load_dwordx4 v[48:51], v[36:37], off
	global_load_dwordx4 v[44:47], v[36:37], off offset:16
	global_load_dwordx4 v[40:43], v[36:37], off offset:32
	s_nop 0
	global_load_dwordx4 v[36:39], v[36:37], off offset:48
.LBB0_665:
	s_or_b64 exec, exec, s[36:37]
	v_readlane_b32 s4, v254, 8
	s_nop 1
	v_add_u32_e32 v98, s4, v123
	s_mov_b32 s4, 0x1c000
	v_cmp_gt_i32_e64 s[36:37], s4, v98
	s_and_saveexec_b64 s[48:49], s[36:37]
	s_cbranch_execz .LBB0_667
	v_add_u32_e32 v20, v129, v123
	s_mov_b32 s4, 0x92492493
	v_mul_hi_i32 v21, v20, s4
	v_add_u32_e32 v21, v21, v20
	v_lshrrev_b32_e32 v22, 31, v21
	v_ashrrev_i32_e32 v21, 2, v21
	v_add_u32_e32 v24, v21, v22
	v_mad_u64_u32 v[20:21], s[4:5], v24, -7, v[20:21]
	v_ashrrev_i32_e32 v21, 31, v24
	v_lshrrev_b32_e32 v21, 21, v21
	v_add_u32_e32 v21, v24, v21
	v_and_b32_e32 v21, 0xfff800, v21
	s_movk_i32 s4, 0xfe40
	v_sub_u32_e32 v25, v24, v21
	v_mul_lo_u32 v21, v24, s4
	v_add3_u32 v21, v128, v126, v21
	v_cmp_gt_i32_e64 s[4:5], 6, v20
	v_mov_b64_e32 v[22:23], s[30:31]
	s_nop 0
	v_cndmask_b32_e64 v20, v201, v21, s[4:5]
	s_movk_i32 s4, 0x1600
	v_ashrrev_i32_e32 v21, 31, v20
	v_mad_i64_i32 v[22:23], s[4:5], v24, s4, v[22:23]
	v_lshl_add_u64 v[20:21], v[20:21], 1, v[22:23]
	v_lshl_add_u64 v[20:21], v[20:21], 0, v[64:65]
	global_load_dwordx4 v[74:77], v[20:21], off nt
	v_mul_i32_i24_e32 v20, 24, v25
	v_ashrrev_i32_e32 v21, 31, v20
	v_lshl_add_u64 v[20:21], v[20:21], 2, s[44:45]
	global_load_dwordx4 v[32:35], v[20:21], off
	global_load_dwordx4 v[28:31], v[20:21], off offset:16
	global_load_dwordx4 v[24:27], v[20:21], off offset:32
	s_nop 0
	global_load_dwordx4 v[20:23], v[20:21], off offset:48

.LBB0_673:
	s_or_b64 exec, exec, s[4:5]
	v_lshlrev_b64 v[78:79], 7, v[108:109]
	v_lshl_add_u64 v[82:83], v[116:117], 0, v[78:79]
	v_pk_mul_f32 v[78:79], v[114:115], v[102:103] op_sel_hi:[0,1]
	v_pk_mul_f32 v[80:81], v[114:115], v[98:99] op_sel_hi:[0,1]
	v_cvt_pk_bf16_f32 v78, v78, v79
	v_cvt_pk_bf16_f32 v79, v80, v81
	v_pk_mul_f32 v[80:81], v[114:115], v[96:97] op_sel_hi:[0,1]
	v_pk_mul_f32 v[84:85], v[114:115], v[94:95] op_sel_hi:[0,1]
	v_cvt_pk_bf16_f32 v80, v80, v81
	v_cvt_pk_bf16_f32 v81, v84, v85
	v_lshl_add_u64 v[82:83], v[82:83], 0, v[64:65]
	global_store_dwordx4 v[82:83], v[78:81], off
	s_and_saveexec_b64 s[48:49], s[42:43]
	s_cbranch_execz .LBB0_682
	v_add_u32_e32 v92, v130, v123
	s_mov_b32 s4, 0x92492493
	v_mul_hi_i32 v78, v92, s4
	v_add_u32_e32 v87, v78, v92
	v_lshrrev_b32_e32 v89, 31, v87
	v_ashrrev_i32_e32 v78, 2, v87
	v_add_u32_e32 v86, v78, v89
	v_mad_u64_u32 v[78:79], s[4:5], v86, -7, v[92:93]
	v_cmp_lt_i32_e32 vcc, 5, v78
	s_and_saveexec_b64 s[4:5], vcc
	s_xor_b64 s[4:5], exec, s[4:5]
	s_cbranch_execz .LBB0_676
	s_mov_b64 s[26:27], s[40:41]
	s_add_u32 s42, s26, 0x10c00000
	s_addc_u32 s43, s27, 0

.LBB0_680:
	s_or_b64 exec, exec, s[4:5]
	s_waitcnt lgkmcnt(0)
	v_ashrrev_i32_e32 v87, 31, v86
	v_lshlrev_b64 v[80:81], 7, v[86:87]
	v_lshl_add_u64 v[86:87], v[90:91], 0, v[80:81]
	v_pk_mul_f32 v[80:81], v[88:89], v[92:93] op_sel_hi:[0,1]
	v_pk_mul_f32 v[84:85], v[88:89], v[84:85] op_sel_hi:[0,1]
	v_pk_mul_f32 v[82:83], v[88:89], v[82:83] op_sel_hi:[0,1]
	v_pk_mul_f32 v[78:79], v[88:89], v[78:79] op_sel_hi:[0,1]
	v_cvt_pk_bf16_f32 v80, v80, v81
	v_cvt_pk_bf16_f32 v81, v84, v85
	v_cvt_pk_bf16_f32 v82, v82, v83
	v_cvt_pk_bf16_f32 v83, v78, v79
	v_lshl_add_u64 v[78:79], v[86:87], 0, v[64:65]
	global_store_dwordx4 v[78:79], v[80:83], off
	s_or_b64 exec, exec, s[48:49]
	s_and_saveexec_b64 s[42:43], s[38:39]
	s_cbranch_execnz .LBB0_683

.LBB0_689:
	s_or_b64 exec, exec, s[4:5]
	s_waitcnt lgkmcnt(0)
	v_ashrrev_i32_e32 v87, 31, v86
	v_lshlrev_b64 v[80:81], 7, v[86:87]
	v_lshl_add_u64 v[86:87], v[90:91], 0, v[80:81]
	v_pk_mul_f32 v[80:81], v[88:89], v[92:93] op_sel_hi:[0,1]
	v_pk_mul_f32 v[84:85], v[88:89], v[84:85] op_sel_hi:[0,1]
	v_pk_mul_f32 v[82:83], v[88:89], v[82:83] op_sel_hi:[0,1]
	v_pk_mul_f32 v[78:79], v[88:89], v[78:79] op_sel_hi:[0,1]
	v_cvt_pk_bf16_f32 v80, v80, v81
	v_cvt_pk_bf16_f32 v81, v84, v85
	v_cvt_pk_bf16_f32 v82, v82, v83
	v_cvt_pk_bf16_f32 v83, v78, v79
	v_lshl_add_u64 v[78:79], v[86:87], 0, v[64:65]
	global_store_dwordx4 v[78:79], v[80:83], off
	s_or_b64 exec, exec, s[42:43]
	s_and_saveexec_b64 s[38:39], s[36:37]
	s_cbranch_execz .LBB0_660

.LBB0_698:
	s_or_b64 exec, exec, s[0:1]
	s_waitcnt lgkmcnt(0)
	v_cvt_pk_bf16_f32 v74, v62, v63
	v_cvt_pk_bf16_f32 v75, v66, v67
	v_cvt_pk_bf16_f32 v76, v68, v69
	v_cvt_pk_bf16_f32 v77, v70, v72
	v_lshl_add_u64 v[60:61], v[60:61], 0, v[64:65]
	global_store_dwordx4 v[60:61], v[74:77], off

.LBB0_700:
	v_add_u32_e32 v60, v99, v98
	s_mov_b32 s0, 0x66666667
	v_mul_hi_i32 v61, v60, s0
	v_lshrrev_b32_e32 v62, 31, v61
	v_ashrrev_i32_e32 v61, 1, v61
	v_add_u32_e32 v84, v61, v62
	v_mad_u64_u32 v[60:61], s[0:1], v84, -5, v[60:61]
	v_ashrrev_i32_e32 v85, 31, v84
	v_lshrrev_b32_e32 v61, 21, v85
	s_movk_i32 s4, 0xfec0
	v_add_u32_e32 v61, v84, v61
	v_cmp_lt_i32_e64 s[42:43], 3, v60
	v_cmp_gt_i32_e64 s[0:1], 4, v60
	v_mul_lo_u32 v60, v84, s4
	v_and_b32_e32 v61, 0xfff800, v61
	v_add3_u32 v86, v100, v107, v60
	v_sub_u32_e32 v66, v84, v61
	v_add_u32_e32 v60, 0x980, v86
	v_mov_b32_e32 v61, 0xa80
	v_cndmask_b32_e64 v60, v61, v60, s[0:1]
	v_mov_b64_e32 v[62:63], s[30:31]
	s_movk_i32 s0, 0x1600
	v_ashrrev_i32_e32 v61, 31, v60
	v_mad_i64_i32 v[62:63], s[0:1], v84, s0, v[62:63]
	v_lshl_add_u64 v[60:61], v[60:61], 1, v[62:63]
	v_lshlrev_b32_e32 v64, 1, v121
	v_lshl_add_u64 v[60:61], v[60:61], 0, v[64:65]
	s_waitcnt lgkmcnt(0)
	global_load_dwordx4 v[78:81], v[60:61], off nt
	v_mul_i32_i24_e32 v60, 24, v66
	v_ashrrev_i32_e32 v61, 31, v60
	v_lshl_add_u64 v[60:61], v[60:61], 2, s[44:45]
	global_load_dwordx4 v[74:77], v[60:61], off
	global_load_dwordx4 v[70:73], v[60:61], off offset:16
	global_load_dwordx4 v[66:69], v[60:61], off offset:32
	s_nop 0
	global_load_dwordx4 v[60:63], v[60:61], off offset:48
	v_readlane_b32 s0, v253, 24
	s_nop 1
	v_add_u32_e32 v87, s0, v98
	s_mov_b32 s0, 0x14000
	v_cmp_gt_i32_e64 s[38:39], s0, v87
	s_and_saveexec_b64 s[4:5], s[38:39]
	s_cbranch_execz .LBB0_702
	v_add_u32_e32 v0, v106, v98
	s_mov_b32 s0, 0x66666667
	v_mul_hi_i32 v1, v0, s0
	v_lshrrev_b32_e32 v2, 31, v1
	v_ashrrev_i32_e32 v1, 1, v1
	v_add_u32_e32 v36, v1, v2
	v_mad_u64_u32 v[0:1], s[0:1], v36, -5, v[0:1]
	v_ashrrev_i32_e32 v1, 31, v36
	v_lshrrev_b32_e32 v1, 21, v1
	v_add_u32_e32 v1, v36, v1
	v_and_b32_e32 v1, 0xfff800, v1
	s_movk_i32 s0, 0xfec0
	v_sub_u32_e32 v37, v36, v1
	v_mul_lo_u32 v1, v36, s0
	v_add_u32_e32 v2, v100, v105
	s_movk_i32 s0, 0x980
	v_add3_u32 v1, v2, v1, s0
	v_cmp_gt_i32_e64 s[0:1], 4, v0
	v_mov_b32_e32 v0, 0xa80
	v_mov_b64_e32 v[2:3], s[30:31]
	v_cndmask_b32_e64 v0, v0, v1, s[0:1]
	s_movk_i32 s0, 0x1600
	v_ashrrev_i32_e32 v1, 31, v0
	v_mad_i64_i32 v[2:3], s[0:1], v36, s0, v[2:3]
	v_mul_i32_i24_e32 v36, 24, v37
	v_lshl_add_u64 v[0:1], v[0:1], 1, v[2:3]
	v_ashrrev_i32_e32 v37, 31, v36
	v_lshl_add_u64 v[0:1], v[0:1], 0, v[64:65]
	v_lshl_add_u64 v[36:37], v[36:37], 2, s[44:45]
	global_load_dwordx4 v[0:3], v[0:1], off nt
	s_nop 0
	global_load_dwordx4 v[48:51], v[36:37], off
	global_load_dwordx4 v[44:47], v[36:37], off offset:16
	global_load_dwordx4 v[40:43], v[36:37], off offset:32
	s_nop 0
	global_load_dwordx4 v[36:39], v[36:37], off offset:48
.LBB0_702:
	s_or_b64 exec, exec, s[4:5]
	v_readlane_b32 s0, v254, 6
	s_nop 1
	v_add_u32_e32 v87, s0, v98
	s_mov_b32 s0, 0x14000
	v_cmp_gt_i32_e64 s[36:37], s0, v87
	s_and_saveexec_b64 s[4:5], s[36:37]
	s_cbranch_execz .LBB0_704
	v_add_u32_e32 v20, v102, v98
	s_mov_b32 s0, 0x66666667
	v_mul_hi_i32 v21, v20, s0
	v_lshrrev_b32_e32 v22, 31, v21
	v_ashrrev_i32_e32 v21, 1, v21
	v_add_u32_e32 v24, v21, v22
	v_mad_u64_u32 v[20:21], s[0:1], v24, -5, v[20:21]
	v_ashrrev_i32_e32 v21, 31, v24
	v_lshrrev_b32_e32 v21, 21, v21
	v_add_u32_e32 v21, v24, v21
	v_and_b32_e32 v21, 0xfff800, v21
	s_movk_i32 s0, 0xfec0
	v_sub_u32_e32 v25, v24, v21
	v_mul_lo_u32 v21, v24, s0
	v_add_u32_e32 v22, v100, v101
	s_movk_i32 s0, 0x980
	v_add3_u32 v21, v22, v21, s0
	v_cmp_gt_i32_e64 s[0:1], 4, v20
	v_mov_b32_e32 v20, 0xa80
	v_mov_b64_e32 v[22:23], s[30:31]
	v_cndmask_b32_e64 v20, v20, v21, s[0:1]
	s_movk_i32 s0, 0x1600
	v_ashrrev_i32_e32 v21, 31, v20
	v_mad_i64_i32 v[22:23], s[0:1], v24, s0, v[22:23]
	v_lshl_add_u64 v[20:21], v[20:21], 1, v[22:23]
	v_lshl_add_u64 v[20:21], v[20:21], 0, v[64:65]
	global_load_dwordx4 v[52:55], v[20:21], off nt
	v_mul_i32_i24_e32 v20, 24, v25
	v_ashrrev_i32_e32 v21, 31, v20
	v_lshl_add_u64 v[20:21], v[20:21], 2, s[44:45]
	global_load_dwordx4 v[32:35], v[20:21], off
	global_load_dwordx4 v[28:31], v[20:21], off offset:16
	global_load_dwordx4 v[24:27], v[20:21], off offset:32
	s_nop 0
	global_load_dwordx4 v[20:23], v[20:21], off offset:48
.LBB0_704:
	s_or_b64 exec, exec, s[4:5]
	v_readlane_b32 s0, v254, 8
	s_mov_b32 s4, 0x14000
	s_nop 0
	v_add_u32_e32 v87, s0, v98
	s_mov_b32 s0, 0x13fff
	v_cmp_lt_i32_e64 s[0:1], s0, v87
	v_cmp_gt_i32_e64 s[4:5], s4, v87
	s_and_saveexec_b64 s[48:49], s[4:5]
	s_cbranch_execz .LBB0_706
	v_add_u32_e32 v4, v104, v98
	s_mov_b32 s4, 0x66666667
	v_mul_hi_i32 v5, v4, s4
	v_lshrrev_b32_e32 v6, 31, v5
	v_ashrrev_i32_e32 v5, 1, v5
	v_add_u32_e32 v8, v5, v6
	v_mad_u64_u32 v[4:5], s[4:5], v8, -5, v[4:5]
	v_ashrrev_i32_e32 v5, 31, v8
	v_lshrrev_b32_e32 v5, 21, v5
	v_add_u32_e32 v5, v8, v5
	v_and_b32_e32 v5, 0xfff800, v5
	s_movk_i32 s4, 0xfec0
	v_sub_u32_e32 v9, v8, v5
	v_mul_lo_u32 v5, v8, s4
	v_add_u32_e32 v6, v100, v103
	s_movk_i32 s4, 0x980
	v_add3_u32 v5, v6, v5, s4
	v_cmp_gt_i32_e64 s[4:5], 4, v4
	v_mov_b32_e32 v4, 0xa80
	v_mov_b64_e32 v[6:7], s[30:31]
	v_cndmask_b32_e64 v4, v4, v5, s[4:5]
	s_movk_i32 s4, 0x1600
	v_ashrrev_i32_e32 v5, 31, v4
	v_mad_i64_i32 v[6:7], s[4:5], v8, s4, v[6:7]
	v_lshl_add_u64 v[4:5], v[4:5], 1, v[6:7]
	v_lshl_add_u64 v[4:5], v[4:5], 0, v[64:65]
	global_load_dwordx4 v[56:59], v[4:5], off nt
	v_mul_i32_i24_e32 v4, 24, v9
	v_ashrrev_i32_e32 v5, 31, v4
	v_lshl_add_u64 v[4:5], v[4:5], 2, s[44:45]
	global_load_dwordx4 v[16:19], v[4:5], off
	global_load_dwordx4 v[12:15], v[4:5], off offset:16
	global_load_dwordx4 v[8:11], v[4:5], off offset:32
	s_nop 0
	global_load_dwordx4 v[4:7], v[4:5], off offset:48

.LBB0_712:
	s_or_b64 exec, exec, s[4:5]
	v_cvt_pk_bf16_f32 v60, v84, v85
	v_cvt_pk_bf16_f32 v61, v78, v79
	v_cvt_pk_bf16_f32 v62, v86, v87
	v_cvt_pk_bf16_f32 v63, v80, v90
	v_lshl_add_u64 v[66:67], v[88:89], 0, v[64:65]
	global_store_dwordx4 v[66:67], v[60:63], off
	s_and_saveexec_b64 s[42:43], s[38:39]
	s_cbranch_execz .LBB0_722
	v_add_u32_e32 v60, v106, v98
	s_mov_b32 s4, 0x66666667
	v_mul_hi_i32 v61, v60, s4
	v_lshrrev_b32_e32 v62, 31, v61
	v_ashrrev_i32_e32 v61, 1, v61
	v_add_u32_e32 v62, v61, v62
	v_mad_u64_u32 v[60:61], s[4:5], v62, -5, v[60:61]
	v_cmp_lt_i32_e64 s[4:5], 3, v60
	v_ashrrev_i32_e32 v63, 31, v62
	s_and_saveexec_b64 s[26:27], s[4:5]
	s_xor_b64 s[4:5], exec, s[26:27]
	s_cbranch_execz .LBB0_715
	s_mov_b64 s[26:27], s[40:41]
	v_lshlrev_b64 v[60:61], 7, v[62:63]
	v_lshl_add_u64 v[60:61], s[26:27], 0, v[60:61]
	s_mov_b64 s[26:27], 0x11600000
	v_lshl_add_u64 v[60:61], v[60:61], 0, s[26:27]

.LBB0_719:
	s_or_b64 exec, exec, s[4:5]
	s_waitcnt lgkmcnt(0)
	v_cvt_pk_bf16_f32 v74, v62, v63
	v_cvt_pk_bf16_f32 v75, v66, v67
	v_cvt_pk_bf16_f32 v76, v68, v69
	v_cvt_pk_bf16_f32 v77, v70, v72
	v_lshl_add_u64 v[60:61], v[60:61], 0, v[64:65]
	global_store_dwordx4 v[60:61], v[74:77], off
	s_or_b64 exec, exec, s[42:43]
	s_and_saveexec_b64 s[38:39], s[36:37]
	s_cbranch_execnz .LBB0_723

.LBB0_729:
	s_or_b64 exec, exec, s[4:5]
	s_waitcnt lgkmcnt(0)
	v_cvt_pk_bf16_f32 v74, v62, v63
	v_cvt_pk_bf16_f32 v75, v66, v67
	v_cvt_pk_bf16_f32 v76, v68, v69
	v_cvt_pk_bf16_f32 v77, v70, v72
	v_lshl_add_u64 v[60:61], v[60:61], 0, v[64:65]
	global_store_dwordx4 v[60:61], v[74:77], off
	s_or_b64 exec, exec, s[38:39]
	s_and_saveexec_b64 s[4:5], s[0:1]
	s_xor_b64 s[0:1], exec, s[4:5]
	s_cbranch_execnz .LBB0_721

.LBB0_739:
	v_ashrrev_i32_e32 v1, 31, v0
	v_lshrrev_b32_e32 v2, 21, v1
	v_add_u32_e32 v2, v0, v2
	v_ashrrev_i32_e32 v2, 11, v2
	v_mul_hi_i32 v4, v2, s95
	v_lshrrev_b32_e32 v5, 31, v4
	v_add_u32_e32 v4, v4, v5
	v_mul_lo_u32 v4, v4, 6
	v_mul_i32_i24_e32 v3, 0x800, v2
	v_sub_u32_e32 v2, v2, v4
	v_mul_hi_i32 v4, v0, s95
	v_lshrrev_b32_e32 v5, 31, v4
	v_lshrrev_b32_e32 v4, 11, v4
	v_add_lshl_u32 v4, v4, v5, 11
	v_sub_u32_e32 v3, v4, v3
	v_add_u32_e32 v4, v0, v3
	v_ashrrev_i32_e32 v5, 31, v4
	s_mov_b64 s[6:7], s[40:41]
	v_lshlrev_b64 v[4:5], 6, v[4:5]
	v_ashrrev_i32_e32 v3, 31, v2
	v_lshl_add_u64 v[4:5], s[6:7], 0, v[4:5]
	v_lshl_add_u64 v[4:5], v[2:3], 2, v[4:5]
	s_mov_b32 s6, 0x12e00000
	s_mul_i32 s26, s96, 6
	v_add_co_u32_e32 v4, vcc, s6, v4
	v_add_u32_e32 v2, s26, v2
	s_nop 0
	v_addc_co_u32_e32 v5, vcc, 0, v5, vcc
	s_mov_b64 s[6:7], s[50:51]
	v_ashrrev_i32_e32 v3, 31, v2
	global_load_dword v4, v[4:5], off
	s_nop 0
	v_lshl_add_u64 v[2:3], v[2:3], 2, s[6:7]
	global_load_dword v2, v[2:3], off
	s_mov_b32 s6, 0xbfb8aa3b
	s_waitcnt vmcnt(0) lgkmcnt(0)
	v_add_f32_e32 v2, v4, v2
	v_min_f32_e32 v16, 0, v2
	v_mul_f32_e64 v2, |v2|, s6
	v_exp_f32_e32 v17, v2
	s_mov_b32 s6, 0x3f2aaaab
	v_add_f32_e32 v4, 1.0, v17
	v_add_f32_e32 v2, -1.0, v4
	v_sub_f32_e32 v3, v2, v4
	v_add_f32_e32 v3, 1.0, v3
	v_sub_f32_e32 v2, v17, v2
	v_add_f32_e32 v5, v2, v3
	v_frexp_mant_f32_e32 v2, v4
	v_cmp_gt_f32_e32 vcc, s6, v2
	v_cvt_f64_f32_e32 v[2:3], v4
	v_frexp_exp_i32_f64_e32 v2, v[2:3]
	v_subbrev_co_u32_e32 v10, vcc, 0, v2, vcc
	v_sub_u32_e32 v2, 0, v10
	v_ldexp_f32 v3, v4, v2
	v_add_f32_e32 v4, -1.0, v3
	v_add_f32_e32 v6, 1.0, v3
	v_ldexp_f32 v2, v5, v2
	v_add_f32_e32 v5, 1.0, v4
	v_add_f32_e32 v7, -1.0, v6
	v_sub_f32_e32 v5, v3, v5
	v_sub_f32_e32 v3, v3, v7
	v_add_f32_e32 v5, v2, v5
	v_add_f32_e32 v2, v2, v3
	v_add_f32_e32 v11, v6, v2
	v_rcp_f32_e32 v13, v11
	v_sub_f32_e32 v3, v11, v6
	v_sub_f32_e32 v12, v2, v3
	v_add_f32_e32 v3, v4, v5
	v_mul_f32_e32 v15, v3, v13
	v_sub_f32_e32 v2, v3, v4
	v_mul_f32_e32 v4, v11, v15
	v_fma_f32 v6, v15, v11, -v4
	v_fmac_f32_e32 v6, v15, v12
	v_sub_f32_e32 v14, v5, v2
	v_add_f32_e32 v2, v4, v6
	v_sub_f32_e32 v5, v3, v2
	v_pk_add_f32 v[8:9], v[2:3], v[4:5] neg_lo:[0,1] neg_hi:[0,1]
	v_mov_b32_e32 v7, v2
	v_pk_add_f32 v[2:3], v[8:9], v[6:7] neg_lo:[0,1] neg_hi:[0,1]
	s_mov_b32 s6, 0x3f317218
	v_add_f32_e32 v3, v14, v3
	v_add_f32_e32 v2, v2, v3
	v_add_f32_e32 v3, v5, v2
	v_mul_f32_e32 v14, v13, v3
	v_mul_f32_e32 v4, v11, v14
	v_fma_f32 v6, v14, v11, -v4
	v_fmac_f32_e32 v6, v14, v12
	v_sub_f32_e32 v5, v5, v3
	v_add_f32_e32 v11, v2, v5
	v_add_f32_e32 v2, v4, v6
	v_sub_f32_e32 v5, v3, v2
	v_pk_add_f32 v[8:9], v[2:3], v[4:5] neg_lo:[0,1] neg_hi:[0,1]
	v_mov_b32_e32 v7, v2
	v_pk_add_f32 v[2:3], v[8:9], v[6:7] neg_lo:[0,1] neg_hi:[0,1]
	s_nop 0
	v_add_f32_e32 v3, v11, v3
	v_add_f32_e32 v2, v2, v3
	v_add_f32_e32 v3, v15, v14
	v_add_f32_e32 v2, v5, v2
	v_sub_f32_e32 v4, v3, v15
	v_mul_f32_e32 v2, v13, v2
	v_sub_f32_e32 v4, v14, v4
	v_add_f32_e32 v4, v4, v2
	v_add_f32_e32 v6, v3, v4
	v_mul_f32_e32 v7, v6, v6
	v_mov_b32_e32 v2, 0x3ecc95a3
	v_fmamk_f32 v2, v7, 0x3e9b6dac, v2
	v_fmaak_f32 v201, v7, v2, 0x3f2aaada
	v_cvt_f32_i32_e32 v2, v10
	v_sub_f32_e32 v3, v6, v3
	v_sub_f32_e32 v3, v4, v3
	v_ldexp_f32 v8, v3, 1
	v_mul_f32_e32 v3, v6, v7
	v_ldexp_f32 v5, v6, 1
	v_pk_mul_f32 v[6:7], v[2:3], v[200:201]
	s_nop 0
	v_fma_f32 v4, v2, s6, -v6
	v_fmac_f32_e32 v4, 0xb102e308, v2
	v_pk_add_f32 v[2:3], v[6:7], v[4:5]
	s_mov_b32 s6, 0x7f800000
	v_sub_f32_e32 v5, v3, v5
	v_sub_f32_e32 v5, v7, v5
	v_add_f32_e32 v9, v8, v5
	v_mov_b32_e32 v8, v6
	v_pk_add_f32 v[6:7], v[2:3], v[6:7] neg_lo:[0,1] neg_hi:[0,1]
	v_pk_add_f32 v[10:11], v[2:3], v[8:9]
	v_mov_b32_e32 v5, v2
	v_mov_b32_e32 v7, v11
	v_pk_add_f32 v[12:13], v[4:5], v[6:7] neg_lo:[0,1] neg_hi:[0,1]
	v_pk_add_f32 v[4:5], v[4:5], v[6:7]
	v_mov_b32_e32 v8, v9
	v_pk_add_f32 v[6:7], v[4:5], v[2:3] op_sel:[1,0] op_sel_hi:[0,1] neg_lo:[0,1] neg_hi:[0,1]
	v_pk_add_f32 v[14:15], v[10:11], v[6:7] op_sel_hi:[1,0] neg_lo:[0,1] neg_hi:[0,1]
	v_mov_b32_e32 v10, v11
	v_mov_b32_e32 v11, v5
	v_pk_mov_b32 v[6:7], v[2:3], v[6:7] op_sel:[1,0]
	v_mov_b32_e32 v9, v2
	v_pk_add_f32 v[6:7], v[10:11], v[6:7] neg_lo:[0,1] neg_hi:[0,1]
	v_mov_b32_e32 v14, v12
	v_pk_add_f32 v[2:3], v[8:9], v[6:7] neg_lo:[0,1] neg_hi:[0,1]
	v_mov_b32_e32 v13, v5
	v_pk_add_f32 v[6:7], v[14:15], v[2:3]
	v_cmp_neq_f32_e32 vcc, s6, v17
	v_pk_add_f32 v[8:9], v[6:7], v[6:7] op_sel:[0,1] op_sel_hi:[1,0]
	s_mov_b32 s6, 0x33800000
	v_pk_add_f32 v[4:5], v[4:5], v[8:9] op_sel:[1,0] op_sel_hi:[0,1]
	v_mov_b32_e32 v7, v4
	v_pk_add_f32 v[10:11], v[6:7], v[12:13] neg_lo:[0,1] neg_hi:[0,1]
	v_mov_b32_e32 v3, v8
	v_sub_f32_e32 v5, v6, v10
	v_pk_add_f32 v[2:3], v[2:3], v[10:11] neg_lo:[0,1] neg_hi:[0,1]
	v_sub_f32_e32 v5, v12, v5
	v_add_f32_e32 v2, v2, v5
	v_add_f32_e32 v2, v2, v3
	v_add_f32_e32 v2, v4, v2
	v_cndmask_b32_e32 v2, v202, v2, vcc
	v_cmp_ngt_f32_e32 vcc, -1.0, v17
	v_mov_b32_e32 v3, 0x7fc00000
	s_nop 0
	v_cndmask_b32_e32 v2, v3, v2, vcc
	v_cmp_neq_f32_e32 vcc, -1.0, v17
	v_mov_b32_e32 v3, 0xff800000
	s_nop 0
	v_cndmask_b32_e32 v2, v3, v2, vcc
	v_cmp_lt_f32_e64 vcc, |v17|, s6
	s_mov_b64 s[6:7], s[40:41]
	s_nop 0
	v_lshl_add_u64 v[4:5], v[0:1], 2, s[6:7]
	v_cndmask_b32_e32 v2, v2, v17, vcc
	v_add_co_u32_e32 v4, vcc, 0x12f00000, v4
	v_add_u32_e32 v0, s33, v0
	s_nop 0
	v_addc_co_u32_e32 v5, vcc, 0, v5, vcc
	s_mov_b32 s6, 0x17fff
	v_cmp_lt_i32_e32 vcc, s6, v0
	v_sub_f32_e32 v2, v16, v2
	s_or_b64 s[4:5], vcc, s[4:5]
	global_store_dword v[4:5], v2, off
	s_andn2_b64 exec, exec, s[4:5]
	s_cbranch_execnz .LBB0_739

.LBB0_742:
	s_or_b64 exec, exec, s[6:7]
	v_mul_hi_i32 v1, v115, s94
	v_lshrrev_b32_e32 v2, 31, v1
	v_ashrrev_i32_e32 v1, 6, v1
	s_mov_b64 s[6:7], s[40:41]
	v_lshlrev_b32_e32 v0, 11, v0
	v_add_u32_e32 v29, v1, v2
	v_sub_u32_e32 v28, v31, v0
	v_lshl_add_u32 v2, v29, 11, v28
	v_mov_b64_e32 v[0:1], s[6:7]
	s_movk_i32 s6, 0x1600
	v_mad_i64_i32 v[0:1], s[6:7], v2, s6, v[0:1]
	v_lshl_add_u64 v[0:1], v[64:65], 1, v[0:1]
	v_lshlrev_b32_e32 v64, 1, v121
	v_lshl_add_u64 v[0:1], v[0:1], 0, v[64:65]
	s_mov_b64 s[6:7], 0x8000000
	v_lshl_add_u64 v[46:47], v[0:1], 0, s[6:7]
	v_mov_b32_e32 v17, v65
	v_lshl_add_u64 v[12:13], v[46:47], 0, v[16:17]
	s_mov_b32 s6, 0xb000
	v_add_co_u32_e32 v4, vcc, s6, v12
	s_mov_b32 s6, 0x16000
	s_nop 0
	v_addc_co_u32_e32 v5, vcc, 0, v13, vcc
	v_add_co_u32_e32 v8, vcc, s6, v12
	v_mov_b32_e32 v19, v65
	s_nop 0
	v_addc_co_u32_e32 v9, vcc, 0, v13, vcc
	s_mov_b32 s6, 0x21000
	v_lshl_add_u64 v[34:35], v[46:47], 0, v[18:19]
	global_load_dwordx4 v[0:3], v[12:13], off nt
	v_mov_b32_e32 v21, v65
	global_load_dwordx4 v[34:37], v[34:35], off nt
	v_add_co_u32_e32 v12, vcc, s6, v12
	global_load_dwordx4 v[4:7], v[4:5], off nt
	s_nop 0
	v_addc_co_u32_e32 v13, vcc, 0, v13, vcc
	global_load_dwordx4 v[8:11], v[8:9], off nt
	v_lshl_add_u64 v[38:39], v[46:47], 0, v[20:21]
	global_load_dwordx4 v[12:15], v[12:13], off nt
	v_mov_b32_e32 v23, v65
	global_load_dwordx4 v[38:41], v[38:39], off nt
	v_lshl_add_u64 v[42:43], v[46:47], 0, v[22:23]
	v_mov_b32_e32 v25, v65
	global_load_dwordx4 v[42:45], v[42:43], off nt
	v_lshl_add_u64 v[46:47], v[46:47], 0, v[24:25]
	global_load_dwordx4 v[46:49], v[46:47], off nt
	v_mad_i32_i24 v50, v29, 11, v27
	v_ashrrev_i32_e32 v51, 31, v50
	s_mov_b64 s[6:7], s[40:41]
	v_lshlrev_b64 v[50:51], 18, v[50:51]
	v_mov_b32_e32 v27, v65
	v_ashrrev_i32_e32 v29, 31, v28
	v_add_u32_e32 v31, s26, v31
	s_waitcnt vmcnt(0) lgkmcnt(0)
	ds_write2_b64 v32, v[0:1], v[2:3] offset1:1
	ds_write2_b64 v32, v[4:5], v[6:7] offset0:136 offset1:137
	v_add_u32_e32 v0, 0x880, v32
	ds_write2_b64 v0, v[8:9], v[10:11] offset1:1
	v_add_u32_e32 v0, 0xcc0, v32
	ds_write2_b64 v0, v[12:13], v[14:15] offset1:1
	v_add_u32_e32 v0, 0x1100, v32
	ds_write2_b64 v0, v[34:35], v[36:37] offset1:1
	v_add_u32_e32 v0, 0x1540, v32
	ds_write2_b64 v0, v[38:39], v[40:41] offset1:1
	v_add_u32_e32 v0, 0x1980, v32
	ds_write2_b64 v0, v[42:43], v[44:45] offset1:1
	v_add_u32_e32 v0, 0x1dc0, v32
	ds_write2_b64 v0, v[46:47], v[48:49] offset1:1
	s_waitcnt lgkmcnt(0)
	ds_read_u16 v0, v30
	ds_read_u16 v1, v30 offset:136
	s_waitcnt lgkmcnt(0)
	v_lshl_or_b32 v0, v1, 16, v0
	ds_read_u16 v1, v30 offset:272
	ds_read_u16 v2, v30 offset:408
	s_waitcnt lgkmcnt(0)
	v_lshl_or_b32 v1, v2, 16, v1
	ds_read_u16 v2, v30 offset:544
	ds_read_u16 v3, v30 offset:680
	s_waitcnt lgkmcnt(0)
	v_lshl_or_b32 v4, v3, 16, v2
	ds_read_u16 v2, v30 offset:816
	ds_read_u16 v3, v30 offset:952
	s_waitcnt lgkmcnt(0)
	v_lshl_or_b32 v5, v3, 16, v2
	ds_read_u16 v2, v30 offset:1088
	ds_read_u16 v3, v30 offset:1224
	s_waitcnt lgkmcnt(0)
	v_lshl_or_b32 v2, v3, 16, v2
	ds_read_u16 v3, v30 offset:1360
	ds_read_u16 v6, v30 offset:1496
	s_waitcnt lgkmcnt(0)
	v_lshl_or_b32 v3, v6, 16, v3
	ds_read_u16 v6, v30 offset:1632
	ds_read_u16 v7, v30 offset:1768
	s_waitcnt lgkmcnt(0)
	v_lshl_or_b32 v6, v7, 16, v6
	ds_read_u16 v7, v30 offset:1904
	ds_read_u16 v8, v30 offset:2040
	s_waitcnt lgkmcnt(0)
	v_lshl_or_b32 v7, v8, 16, v7
	ds_read_u16 v8, v30 offset:2176
	ds_read_u16 v9, v30 offset:2312
	s_waitcnt lgkmcnt(0)
	v_lshl_or_b32 v8, v9, 16, v8
	ds_read_u16 v9, v30 offset:2448
	ds_read_u16 v10, v30 offset:2584
	s_waitcnt lgkmcnt(0)
	v_lshl_or_b32 v9, v10, 16, v9
	ds_read_u16 v10, v30 offset:2720
	ds_read_u16 v11, v30 offset:2856
	s_waitcnt lgkmcnt(0)
	v_lshl_or_b32 v12, v11, 16, v10
	ds_read_u16 v10, v30 offset:2992
	ds_read_u16 v11, v30 offset:3128
	s_waitcnt lgkmcnt(0)
	v_lshl_or_b32 v13, v11, 16, v10
	ds_read_u16 v10, v30 offset:3264
	ds_read_u16 v11, v30 offset:3400
	s_waitcnt lgkmcnt(0)
	v_lshl_or_b32 v10, v11, 16, v10
	ds_read_u16 v11, v30 offset:3536
	ds_read_u16 v14, v30 offset:3672
	s_waitcnt lgkmcnt(0)
	v_lshl_or_b32 v11, v14, 16, v11
	ds_read_u16 v14, v30 offset:3808
	ds_read_u16 v15, v30 offset:3944
	s_waitcnt lgkmcnt(0)
	v_lshl_or_b32 v14, v15, 16, v14
	ds_read_u16 v15, v30 offset:4080
	ds_read_u16 v17, v30 offset:4216
	s_waitcnt lgkmcnt(0)
	v_lshl_or_b32 v15, v17, 16, v15
	ds_read_u16 v17, v30 offset:4352
	ds_read_u16 v19, v30 offset:4488
	s_waitcnt lgkmcnt(0)
	v_lshl_or_b32 v34, v19, 16, v17
	ds_read_u16 v17, v30 offset:4624
	ds_read_u16 v19, v30 offset:4760
	s_waitcnt lgkmcnt(0)
	v_lshl_or_b32 v35, v19, 16, v17
	ds_read_u16 v17, v30 offset:4896
	ds_read_u16 v19, v30 offset:5032
	s_waitcnt lgkmcnt(0)
	v_lshl_or_b32 v38, v19, 16, v17
	ds_read_u16 v17, v30 offset:5168
	ds_read_u16 v19, v30 offset:5304
	s_waitcnt lgkmcnt(0)
	v_lshl_or_b32 v39, v19, 16, v17
	ds_read_u16 v17, v30 offset:5440
	ds_read_u16 v19, v30 offset:5576
	s_waitcnt lgkmcnt(0)
	v_lshl_or_b32 v36, v19, 16, v17
	ds_read_u16 v17, v30 offset:5712
	ds_read_u16 v19, v30 offset:5848
	s_waitcnt lgkmcnt(0)
	v_lshl_or_b32 v37, v19, 16, v17
	ds_read_u16 v17, v30 offset:5984
	ds_read_u16 v19, v30 offset:6120
	s_waitcnt lgkmcnt(0)
	v_lshl_or_b32 v40, v19, 16, v17
	ds_read_u16 v17, v30 offset:6256
	ds_read_u16 v19, v30 offset:6392
	s_waitcnt lgkmcnt(0)
	v_lshl_or_b32 v41, v19, 16, v17
	ds_read_u16 v17, v30 offset:6528
	ds_read_u16 v19, v30 offset:6664
	s_waitcnt lgkmcnt(0)
	v_lshl_or_b32 v42, v19, 16, v17
	ds_read_u16 v17, v30 offset:6800
	ds_read_u16 v19, v30 offset:6936
	s_waitcnt lgkmcnt(0)
	v_lshl_or_b32 v43, v19, 16, v17
	ds_read_u16 v17, v30 offset:7072
	ds_read_u16 v19, v30 offset:7208
	s_waitcnt lgkmcnt(0)
	v_lshl_or_b32 v46, v19, 16, v17
	ds_read_u16 v17, v30 offset:7344
	ds_read_u16 v19, v30 offset:7480
	s_waitcnt lgkmcnt(0)
	v_lshl_or_b32 v47, v19, 16, v17
	ds_read_u16 v17, v30 offset:7616
	ds_read_u16 v19, v30 offset:7752
	s_waitcnt lgkmcnt(0)
	v_lshl_or_b32 v44, v19, 16, v17
	ds_read_u16 v17, v30 offset:7888
	ds_read_u16 v19, v30 offset:8024
	s_waitcnt lgkmcnt(0)
	v_lshl_or_b32 v45, v19, 16, v17
	ds_read_u16 v17, v30 offset:8160
	ds_read_u16 v19, v30 offset:8296
	s_waitcnt lgkmcnt(0)
	v_lshl_or_b32 v48, v19, 16, v17
	ds_read_u16 v17, v30 offset:8432
	ds_read_u16 v19, v30 offset:8568
	s_waitcnt lgkmcnt(0)
	v_lshl_or_b32 v49, v19, 16, v17
	v_lshl_add_u64 v[50:51], s[6:7], 0, v[50:51]
	v_lshl_add_u64 v[50:51], v[50:51], 0, v[26:27]
	v_lshl_add_u64 v[28:29], v[28:29], 1, v[50:51]
	s_mov_b64 s[6:7], 0x11800000
	v_lshl_add_u64 v[50:51], v[28:29], 0, s[6:7]
	s_mov_b32 s6, 0x11800000
	v_add_co_u32_e32 v28, vcc, s6, v28
	v_readlane_b32 s6, v253, 23
	s_nop 0
	v_addc_co_u32_e32 v29, vcc, 0, v29, vcc
	global_store_dwordx4 v[28:29], v[0:3], off
	global_store_dwordx4 v[50:51], v[8:11], off offset:16
	global_store_dwordx4 v[50:51], v[4:7], off offset:32
	global_store_dwordx4 v[50:51], v[12:15], off offset:48
	global_store_dwordx4 v[50:51], v[34:37], off offset:64
	global_store_dwordx4 v[50:51], v[42:45], off offset:80
	global_store_dwordx4 v[50:51], v[38:41], off offset:96
	global_store_dwordx4 v[50:51], v[46:49], off offset:112
	s_waitcnt lgkmcnt(0)
	v_add_u32_e32 v115, s6, v115
	s_movk_i32 s6, 0xaff
	v_cmp_lt_i32_e32 vcc, s6, v115
	s_or_b64 s[4:5], vcc, s[4:5]
	s_andn2_b64 exec, exec, s[4:5]
	s_cbranch_execz .LBB0_747

.LBB0_810:
	v_readlane_b32 s0, v252, 1
	v_readlane_b32 s1, v252, 2
	s_bitcmp0_b32 s34, 0
	v_readlane_b32 s1, v252, 0
	v_readlane_b32 s4, v253, 26
	s_mul_i32 s0, s34, s0
	s_cselect_b32 s1, s1, s4
	s_add_i32 s0, s1, s0
	s_cmpk_gt_i32 s0, 0x3ff
	s_cbranch_scc1 .LBB0_809
	s_ashr_i32 s1, s0, 31
	s_lshr_b32 s1, s1, 29
	s_add_i32 s1, s0, s1
	s_and_b32 s4, s1, 0x1ffff8
	s_sub_i32 s5, s0, s4
	s_ashr_i32 s0, s1, 3
	s_sub_i32 s4, 0x7f, s0
	s_mov_b32 s0, -1
	s_lshl_b32 s33, s4, 4
	v_mbcnt_lo_u32_b32 v0, s0, 0
	v_mbcnt_hi_u32_b32 v0, s0, v0
	v_readlane_b32 s0, v252, 5
	s_lshl_b32 s28, s5, 11
	s_add_i32 s5, s33, s28
	v_add_u32_e32 v88, s0, v0
	s_mov_b64 s[0:1], s[40:41]
	v_and_b32_e32 v36, 15, v88
	v_or_b32_e32 v32, s5, v36
	v_ashrrev_i32_e32 v33, 31, v32
	v_lshrrev_b32_e32 v2, 1, v88
	s_waitcnt lgkmcnt(0)
	v_lshlrev_b64 v[0:1], 9, v[32:33]
	v_and_b32_e32 v2, 24, v2
	v_lshlrev_b32_e32 v64, 1, v2
	v_lshl_add_u64 v[0:1], s[0:1], 0, v[0:1]
	v_lshl_add_u64 v[0:1], v[0:1], 0, v[64:65]
	s_mov_b64 s[0:1], 0x10e00000
	v_lshl_add_u64 v[28:29], v[0:1], 0, s[0:1]
	s_mov_b32 s0, 0x10e00000
	v_add_co_u32_e32 v24, vcc, s0, v0
	s_mov_b64 s[0:1], s[40:41]
	s_nop 0
	v_addc_co_u32_e32 v25, vcc, 0, v1, vcc
	global_load_dwordx4 v[0:3], v[28:29], off offset:64
	global_load_dwordx4 v[4:7], v[28:29], off offset:128
	global_load_dwordx4 v[8:11], v[28:29], off offset:192
	global_load_dwordx4 v[12:15], v[28:29], off offset:256
	global_load_dwordx4 v[16:19], v[28:29], off offset:320
	global_load_dwordx4 v[20:23], v[28:29], off offset:384
	s_nop 0
	global_load_dwordx4 v[24:27], v[24:25], off
	s_nop 0
	global_load_dwordx4 v[28:31], v[28:29], off offset:448
	v_lshlrev_b64 v[32:33], 6, v[32:33]
	s_nop 0
	v_lshl_add_u64 v[32:33], s[0:1], 0, v[32:33]
	v_add_co_u32_e32 v32, vcc, 0x12e00000, v32
	v_readfirstlane_b32 s0, v88
	s_nop 0
	v_addc_co_u32_e32 v33, vcc, 0, v33, vcc
	global_load_dwordx4 v[32:35], v[32:33], off offset:32
	s_ashr_i32 s5, s0, 6
	s_lshl_b32 s6, s5, 2
	s_mov_b64 s[0:1], s[40:41]
	s_cmp_gt_i32 s6, s4
	s_cbranch_scc1 .LBB0_820
	v_or_b32_e32 v38, s28, v36
	v_ashrrev_i32_e32 v39, 31, v38
	v_lshlrev_b64 v[38:39], 7, v[38:39]
	v_lshl_add_u64 v[38:39], s[0:1], 0, v[38:39]
	v_lshl_add_u64 v[38:39], v[38:39], 0, v[64:65]
	s_mov_b64 s[0:1], 0x11600000
	v_lshl_add_u64 v[60:61], v[38:39], 0, s[0:1]
	s_lshl_b32 s0, s5, 8
	v_mov_b32_e32 v38, s0
	s_movk_i32 s0, 0x2010
	v_and_b32_e32 v37, 48, v88
	v_mad_u32_u24 v36, v36, s0, v38
	s_waitcnt vmcnt(0) lgkmcnt(0)
	v_mov_b32_e32 v62, v32
	v_mov_b32_e32 v63, v32
	v_mov_b32_e32 v66, v32
	v_mov_b32_e32 v67, v32
	v_mov_b32_e32 v68, v33
	v_mov_b32_e32 v69, v33
	v_mov_b32_e32 v32, v33
	v_mov_b32_e32 v70, v34
	v_mov_b32_e32 v71, v34
	v_mov_b32_e32 v72, v34
	v_mov_b32_e32 v73, v34
	v_mov_b32_e32 v74, v35
	v_mov_b32_e32 v75, v35
	v_mov_b32_e32 v34, v35
	v_add3_u32 v64, v36, v37, 0
	s_branch .LBB0_814

.LBB0_814:
	s_add_i32 s0, s6, 1
	s_min_i32 s0, s0, s4
	s_ashr_i32 s1, s0, 31
	s_lshl_b64 s[0:1], s[0:1], 11
	v_lshl_add_u64 v[36:37], v[60:61], 0, s[0:1]
	s_add_i32 s1, s6, 2
	s_min_i32 s26, s1, s4
	s_ashr_i32 s27, s26, 31
	s_lshl_b64 s[26:27], s[26:27], 11
	s_add_i32 s0, s6, 3
	global_load_dwordx4 v[56:59], v[36:37], off
	global_load_dwordx4 v[52:55], v[36:37], off offset:64
	v_lshl_add_u64 v[36:37], v[60:61], 0, s[26:27]
	s_min_i32 s26, s0, s4
	s_ashr_i32 s27, s26, 31
	s_lshl_b64 s[26:27], s[26:27], 11
	global_load_dwordx4 v[48:51], v[36:37], off
	global_load_dwordx4 v[44:47], v[36:37], off offset:64
	v_lshl_add_u64 v[36:37], v[60:61], 0, s[26:27]
	s_min_i32 s26, s6, s4
	s_ashr_i32 s27, s26, 31
	s_lshl_b64 s[26:27], s[26:27], 11
	v_lshl_add_u64 v[76:77], v[60:61], 0, s[26:27]
	global_load_dwordx4 v[40:43], v[36:37], off
	s_nop 0
	global_load_dwordx4 v[36:39], v[36:37], off offset:64
	s_nop 0
	global_load_dwordx4 v[90:93], v[76:77], off offset:64
	global_load_dwordx4 v[94:97], v[76:77], off
	s_cmp_ge_i32 s6, s4
	s_waitcnt vmcnt(0) lgkmcnt(0)
	v_mfma_f32_16x16x32_bf16 v[76:79], v[94:97], v[24:27], 0
	v_mfma_f32_16x16x32_bf16 v[78:81], v[90:93], v[0:3], v[76:79]
	v_mfma_f32_16x16x32_bf16 v[84:87], v[94:97], v[12:15], 0
	v_mfma_f32_16x16x32_bf16 v[98:101], v[90:93], v[16:19], v[84:87]
	s_nop 5
	v_max_f32_e32 v76, v78, v78
	v_max_f32_e32 v78, 0, v76
	v_max_f32_e32 v76, v79, v79
	v_max_f32_e32 v79, 0, v76
	v_max_f32_e32 v76, v80, v80
	v_max_f32_e32 v77, v81, v81
	v_mfma_f32_16x16x32_bf16 v[80:83], v[94:97], v[4:7], 0
	v_max_f32_e32 v84, v98, v98
	v_max_f32_e32 v76, 0, v76
	v_max_f32_e32 v77, 0, v77
	v_mfma_f32_16x16x32_bf16 v[94:97], v[94:97], v[20:23], 0
	v_max_f32_e32 v86, 0, v84
	v_max_f32_e32 v84, v99, v99
	v_max_f32_e32 v87, 0, v84
	v_mfma_f32_16x16x32_bf16 v[80:83], v[90:93], v[8:11], v[80:83]
	v_max_f32_e32 v84, v100, v100
	v_max_f32_e32 v85, v101, v101
	v_pk_fma_f32 v[78:79], v[62:63], v[78:79], 0 op_sel_hi:[1,1,0]
	v_mfma_f32_16x16x32_bf16 v[90:93], v[90:93], v[28:31], v[94:97]
	v_fma_f32 v76, v66, v76, 0
	v_fma_f32 v77, v67, v77, 0
	s_nop 1
	v_max_f32_e32 v80, v80, v80
	v_max_f32_e32 v81, v81, v81
	v_max_f32_e32 v82, v82, v82
	v_max_f32_e32 v83, v83, v83
	v_max_f32_e32 v89, v90, v90
	v_max_f32_e32 v90, 0, v89
	v_max_f32_e32 v89, v91, v91
	v_max_f32_e32 v80, 0, v80
	v_max_f32_e32 v81, 0, v81
	v_max_f32_e32 v82, 0, v82
	v_max_f32_e32 v83, 0, v83
	v_max_f32_e32 v91, 0, v89
	v_max_f32_e32 v89, v92, v92
	v_max_f32_e32 v84, 0, v84
	v_max_f32_e32 v85, 0, v85
	v_max_f32_e32 v92, 0, v89
	v_max_f32_e32 v89, v93, v93
	v_pk_fma_f32 v[76:77], v[32:33], v[82:83], v[76:77]
	v_pk_fma_f32 v[78:79], v[68:69], v[80:81], v[78:79]
	v_max_f32_e32 v93, 0, v89
	v_pk_fma_f32 v[80:81], v[70:71], v[86:87], v[78:79]
	v_pk_fma_f32 v[76:77], v[72:73], v[84:85], v[76:77]
	s_nop 0
	v_pk_fma_f32 v[78:79], v[34:35], v[92:93], v[76:77]
	v_pk_fma_f32 v[76:77], v[74:75], v[90:91], v[80:81]
	ds_write_b128 v64, v[76:79]
	s_cbranch_scc1 .LBB0_817
	v_mfma_f32_16x16x32_bf16 v[76:79], v[56:59], v[24:27], 0
	v_mfma_f32_16x16x32_bf16 v[76:79], v[52:55], v[0:3], v[76:79]
	s_nop 7
	v_max_f32_e32 v76, v76, v76
	v_max_f32_e32 v80, 0, v76
	v_max_f32_e32 v76, v77, v77
	v_max_f32_e32 v81, 0, v76
	v_max_f32_e32 v76, v78, v78
	v_max_f32_e32 v82, 0, v76
	v_max_f32_e32 v76, v79, v79
	v_max_f32_e32 v83, 0, v76
	v_mfma_f32_16x16x32_bf16 v[76:79], v[56:59], v[4:7], 0
	v_mfma_f32_16x16x32_bf16 v[76:79], v[52:55], v[8:11], v[76:79]
	s_nop 7
	v_max_f32_e32 v76, v76, v76
	v_max_f32_e32 v84, 0, v76
	v_max_f32_e32 v76, v77, v77
	v_max_f32_e32 v85, 0, v76
	v_max_f32_e32 v76, v78, v78
	v_max_f32_e32 v86, 0, v76
	v_max_f32_e32 v76, v79, v79
	v_max_f32_e32 v87, 0, v76
	v_mfma_f32_16x16x32_bf16 v[76:79], v[56:59], v[12:15], 0
	v_mfma_f32_16x16x32_bf16 v[56:59], v[56:59], v[20:23], 0
	v_mfma_f32_16x16x32_bf16 v[76:79], v[52:55], v[16:19], v[76:79]
	v_mfma_f32_16x16x32_bf16 v[52:55], v[52:55], v[28:31], v[56:59]
	s_nop 5
	v_fma_f32 v56, v62, v80, 0
	v_fma_f32 v57, v63, v81, 0
	v_max_f32_e32 v76, v76, v76
	v_max_f32_e32 v77, v77, v77
	v_max_f32_e32 v78, v78, v78
	v_max_f32_e32 v79, v79, v79
	v_pk_fma_f32 v[58:59], v[66:67], v[82:83], 0 op_sel_hi:[1,1,0]
	v_max_f32_e32 v76, 0, v76
	v_max_f32_e32 v77, 0, v77
	v_max_f32_e32 v78, 0, v78
	v_max_f32_e32 v79, 0, v79
	v_max_f32_e32 v52, v52, v52
	v_max_f32_e32 v53, v53, v53
	v_max_f32_e32 v54, v54, v54
	v_max_f32_e32 v55, v55, v55
	v_pk_fma_f32 v[58:59], v[32:33], v[86:87], v[58:59]
	v_pk_fma_f32 v[56:57], v[68:69], v[84:85], v[56:57]
	v_max_f32_e32 v52, 0, v52
	v_max_f32_e32 v53, 0, v53
	v_max_f32_e32 v54, 0, v54
	v_max_f32_e32 v55, 0, v55
	v_pk_fma_f32 v[56:57], v[70:71], v[76:77], v[56:57]
	v_pk_fma_f32 v[58:59], v[72:73], v[78:79], v[58:59]
	v_pk_fma_f32 v[52:53], v[74:75], v[52:53], v[56:57]
	v_pk_fma_f32 v[54:55], v[34:35], v[54:55], v[58:59]
	ds_write_b128 v64, v[52:55] offset:64
	s_cmp_gt_i32 s1, s4
	s_cbranch_scc0 .LBB0_818

.LBB0_898:
	v_readlane_b32 s92, v252, 6
	v_cvt_pk_bf16_f32 v1, v2, v3
	v_readlane_b32 s93, v252, 7
	s_waitcnt vmcnt(0)
	global_store_dwordx2 v[66:67], v[0:1], off offset:112

.LBB0_900:
	v_readlane_b32 s0, v252, 1
	v_readlane_b32 s1, v252, 2
	s_bitcmp0_b32 s30, 0
	v_readlane_b32 s1, v252, 0
	v_readlane_b32 s4, v253, 26
	s_mul_i32 s0, s30, s0
	s_cselect_b32 s1, s1, s4
	s_add_i32 s0, s1, s0
	s_cmpk_gt_i32 s0, 0x3ff
	s_cbranch_scc1 .LBB0_899
	s_ashr_i32 s1, s0, 31
	s_lshr_b32 s1, s1, 25
	s_add_i32 s1, s0, s1
	s_ashr_i32 s4, s1, 7
	s_and_b32 s1, s1, 0xffffff80
	s_sub_i32 s75, 0, s4
	s_sub_i32 s66, 7, s4
	s_sub_i32 s67, s0, s1
	s_cmp_gt_i32 s67, 31
	s_mov_b64 s[0:1], -1
	s_cbranch_scc0 .LBB0_955
	s_cmpk_gt_u32 s67, 0x4f
	s_cbranch_scc0 .LBB0_918
	s_add_i32 s0, s67, 0xffb0
	s_and_b32 s31, s0, 0xff
	s_mul_i32 s1, s31, 0xab
	s_bfe_u32 s7, s1, 0x6000a
	s_mul_i32 s4, s7, 6
	s_sub_i32 s0, s0, s4
	s_and_b32 s6, s0, 0xff
	s_mov_b32 s0, -1
	s_add_i32 s4, s4, s6
	v_mbcnt_lo_u32_b32 v0, s0, 0
	v_mbcnt_hi_u32_b32 v0, s0, v0
	v_readlane_b32 s0, v252, 5
	s_lshl_b32 s4, s4, 18
	s_mul_i32 s33, s7, 0x2c0000
	v_add_u32_e32 v12, s0, v0
	s_mov_b64 s[0:1], s[40:41]
	s_add_u32 s26, s0, s4
	s_addc_u32 s27, s1, 0
	s_mov_b64 s[0:1], s[40:41]
	s_lshl_b32 s4, s7, 18
	v_ashrrev_i32_e32 v0, 3, v12
	s_add_u32 s28, s0, s4
	v_ashrrev_i32_e32 v1, 31, v0
	s_addc_u32 s29, s1, 0
	s_mov_b64 s[4:5], s[40:41]
	v_lshlrev_b64 v[2:3], 7, v[0:1]
	v_lshlrev_b32_e32 v6, 4, v12
	s_add_u32 s34, s4, s33
	v_lshl_add_u64 v[4:5], s[28:29], 0, v[2:3]
	v_and_b32_e32 v64, 0x70, v6
	s_addc_u32 s35, s5, 0
	v_lshl_add_u64 v[4:5], v[4:5], 0, v[64:65]
	v_lshlrev_b64 v[6:7], 12, v[0:1]
	s_mov_b32 s28, 0x10c00000
	v_lshl_add_u64 v[8:9], s[34:35], 0, v[6:7]
	v_add_co_u32_e32 v10, vcc, s28, v4
	v_lshl_add_u64 v[8:9], v[8:9], 0, v[64:65]
	s_nop 0
	v_addc_co_u32_e32 v11, vcc, 0, v5, vcc
	s_mov_b32 s28, 0x11a80000
	s_waitcnt vmcnt(0)
	global_load_dwordx4 v[66:69], v[10:11], off
	v_add_co_u32_e32 v10, vcc, s28, v8
	v_readfirstlane_b32 s28, v12
	s_ashr_i32 s33, s28, 1
	s_lshl_b32 s29, s66, 8
	s_and_b32 s28, s33, 0xffffffe0
	v_addc_co_u32_e32 v11, vcc, 0, v9, vcc
	v_and_b32_e32 v14, 31, v12
	s_add_i32 s28, s28, s29
	global_load_dwordx4 v[70:73], v[10:11], off
	v_or_b32_e32 v10, s28, v14
	s_mov_b64 s[28:29], 0x11a80000
	v_lshl_add_u64 v[8:9], v[8:9], 0, s[28:29]
	s_mov_b32 s28, 0x10c02000
	v_add_co_u32_e32 v4, vcc, s28, v4
	v_ashrrev_i32_e32 v11, 31, v10
	s_nop 0
	v_addc_co_u32_e32 v5, vcc, 0, v5, vcc
	v_bfe_u32 v15, v12, 5, 1
	global_load_dwordx4 v[74:77], v[4:5], off
	s_waitcnt lgkmcnt(0)
	global_load_dwordx4 v[78:81], v[8:9], off offset:128
	v_lshlrev_b64 v[4:5], 7, v[10:11]
	v_lshl_add_u64 v[4:5], s[26:27], 0, v[4:5]
	v_lshlrev_b32_e32 v8, 4, v15
	v_mov_b32_e32 v9, v65
	v_lshl_add_u64 v[4:5], v[4:5], 0, v[8:9]
	s_mov_b64 s[26:27], 0x10000000
	v_lshl_add_u64 v[12:13], v[4:5], 0, s[26:27]
	s_brev_b32 s26, 8
	v_add_co_u32_e32 v4, vcc, s26, v4
	v_lshl_add_u32 v132, s7, 11, v10
	s_nop 0
	v_addc_co_u32_e32 v5, vcc, 0, v5, vcc
	v_ashrrev_i32_e32 v133, 31, v132
	global_load_dwordx4 v[82:85], v[12:13], off offset:32
	global_load_dwordx4 v[86:89], v[12:13], off offset:64
	global_load_dwordx4 v[90:93], v[4:5], off
	global_load_dwordx4 v[94:97], v[12:13], off offset:96
	s_mov_b64 s[26:27], s[40:41]
	v_lshlrev_b64 v[4:5], 8, v[132:133]
	s_mov_b32 s7, 0x13000000
	v_lshl_add_u64 v[4:5], s[26:27], 0, v[4:5]
	v_lshl_add_u64 v[4:5], v[4:5], 0, v[8:9]
	s_mov_b64 s[26:27], 0x13000000
	v_lshl_add_u64 v[10:11], v[4:5], 0, s[26:27]
	v_add_co_u32_e32 v4, vcc, s7, v4
	s_movk_i32 s35, 0x90
	s_nop 0
	v_addc_co_u32_e32 v5, vcc, 0, v5, vcc
	global_load_dwordx4 v[98:101], v[10:11], off offset:32
	global_load_dwordx4 v[102:105], v[10:11], off offset:64
	global_load_dwordx4 v[106:109], v[10:11], off offset:160
	global_load_dwordx4 v[110:113], v[10:11], off offset:192
	global_load_dwordx4 v[114:117], v[10:11], off offset:128
	global_load_dwordx4 v[118:121], v[10:11], off offset:96
	global_load_dwordx4 v[122:125], v[4:5], off
	global_load_dwordx4 v[126:129], v[10:11], off offset:224
	v_mad_u64_u32 v[0:1], s[28:29], v0, s35, v[64:65]
	s_lshl_b32 s34, s66, 2
	s_mul_hi_u32 s29, s31, 0x2aaaaaab
	s_add_i32 s26, s34, 4
	s_or_b32 s27, s33, 31
	s_or_b32 s28, s34, 3
	s_lshl_b32 s31, s29, 18
	s_add_u32 s0, s0, s31
	s_addc_u32 s1, s1, 0
	s_mul_i32 s29, s29, 0x2c0000
	v_lshl_add_u64 v[134:135], s[0:1], 0, v[2:3]
	s_add_u32 s0, s4, s29
	s_addc_u32 s1, s5, 0
	v_add_u32_e32 v142, 0, v0
	v_mul_u32_u24_e32 v0, 0x90, v14
	v_mad_u32_u24 v1, v14, s35, 0
	v_lshl_add_u32 v4, v15, 5, 0
	v_lshl_add_u64 v[136:137], s[0:1], 0, v[6:7]
	s_lshl_b32 s0, s75, 8
	s_lshl_b32 s1, s75, 2
	v_mov_b32_e32 v131, 0
	s_mov_b32 s7, 3
	v_lshlrev_b32_e32 v130, 2, v15
	v_readlane_b32 s33, v255, 5
	s_sub_i32 s0, 0xfffff900, s0
	s_sub_i32 s1, 0, s1
	v_add_u32_e32 v143, v1, v8
	v_add_u32_e32 v144, v4, v0
	v_mov_b32_e32 v16, 0
	v_mov_b32_e32 v17, v131
	v_mov_b32_e32 v18, v131
	v_mov_b32_e32 v19, v131
	v_mov_b32_e32 v20, v131
	v_mov_b32_e32 v21, v131
	v_mov_b32_e32 v22, v131
	v_mov_b32_e32 v23, v131
	v_mov_b32_e32 v24, v131
	v_mov_b32_e32 v25, v131
	v_mov_b32_e32 v26, v131
	v_mov_b32_e32 v27, v131
	v_mov_b32_e32 v28, v131
	v_mov_b32_e32 v29, v131
	v_mov_b32_e32 v30, v131
	v_mov_b32_e32 v31, v131
	v_mov_b32_e32 v0, v131
	v_mov_b32_e32 v1, v131
	v_mov_b32_e32 v2, v131
	v_mov_b32_e32 v3, v131
	v_mov_b32_e32 v4, v131
	v_mov_b32_e32 v5, v131
	v_mov_b32_e32 v6, v131
	v_mov_b32_e32 v7, v131
	v_mov_b32_e32 v8, v131
	v_mov_b32_e32 v9, v131
	v_mov_b32_e32 v10, v131
	v_mov_b32_e32 v11, v131
	v_mov_b32_e32 v12, v131
	v_mov_b32_e32 v13, v131
	v_mov_b32_e32 v14, v131
	v_mov_b32_e32 v15, v131
	s_waitcnt vmcnt(0)
	ds_write_b128 v142, v[66:69]
	ds_write_b128 v142, v[70:73] offset:18432
	s_waitcnt lgkmcnt(0)
	s_barrier
	s_branch .LBB0_905

.LBB0_905:
	s_add_i32 s4, s7, -1
	s_cmp_ge_u32 s4, s26
	v_lshl_add_u64 v[140:141], v[134:135], 0, v[64:65]
	v_lshl_add_u64 v[138:139], v[136:137], 0, v[64:65]
	s_cbranch_scc1 .LBB0_907
	v_add_co_u32_e32 v32, vcc, 0x10c04000, v140
	s_nop 1
	v_addc_co_u32_e32 v33, vcc, 0, v141, vcc
	s_waitcnt vmcnt(0)
	global_load_dwordx4 v[66:69], v[32:33], off
	v_add_co_u32_e32 v32, vcc, 0x11a80000, v138
	s_nop 1
	v_addc_co_u32_e32 v33, vcc, 0, v139, vcc
	global_load_dwordx4 v[70:73], v[32:33], off offset:256

.LBB0_911:
	s_cmp_ge_u32 s7, s26
	s_waitcnt lgkmcnt(0)
	s_barrier
	s_cbranch_scc1 .LBB0_913
	v_add_co_u32_e32 v32, vcc, 0x10c06000, v140
	s_nop 1
	v_addc_co_u32_e32 v33, vcc, 0, v141, vcc
	s_waitcnt vmcnt(0)
	global_load_dwordx4 v[74:77], v[32:33], off
	v_add_co_u32_e32 v32, vcc, 0x11a80000, v138
	s_nop 1
	v_addc_co_u32_e32 v33, vcc, 0, v139, vcc
	global_load_dwordx4 v[78:81], v[32:33], off offset:384

.LBB0_917:
	v_and_b32_e32 v35, 64, v197
	v_xor_b32_e32 v34, 32, v197
	v_add_u32_e32 v35, 64, v35
	v_cmp_lt_i32_e32 vcc, v34, v35
	s_mov_b64 s[0:1], s[40:41]
	v_lshlrev_b64 v[32:33], 11, v[132:133]
	v_cndmask_b32_e32 v34, v197, v34, vcc
	v_lshlrev_b32_e32 v34, 2, v34
	ds_bpermute_b32 v34, v34, v131
	v_lshl_add_u64 v[32:33], s[0:1], 0, v[32:33]
	v_readlane_b32 s0, v254, 43
	v_readlane_b32 s1, v254, 44
	s_mov_b32 s5, s1
	v_writelane_b32 v254, s0, 43
	s_waitcnt lgkmcnt(0)
	v_add_f32_e32 v34, v131, v34
	s_lshl_b32 s4, s6, 7
	v_writelane_b32 v254, s1, 44
	v_div_scale_f32 v35, s[0:1], v34, v34, 1.0
	v_rcp_f32_e32 v36, v35
	v_lshl_add_u64 v[32:33], v[32:33], 0, s[4:5]
	v_lshlrev_b32_e32 v64, 1, v130
	v_lshl_add_u64 v[32:33], v[32:33], 0, v[64:65]
	v_fma_f32 v37, -v35, v36, 1.0
	v_fmac_f32_e32 v36, v37, v36
	v_div_scale_f32 v37, vcc, 1.0, v34, 1.0
	v_mul_f32_e32 v38, v37, v36
	v_fma_f32 v39, -v35, v38, v37
	v_fmac_f32_e32 v38, v39, v36
	v_fma_f32 v35, -v35, v38, v37
	v_div_fmas_f32 v35, v35, v36, v38
	v_div_fixup_f32 v34, v35, v34, 1.0
	s_mov_b64 s[0:1], 0x6000500
	s_waitcnt vmcnt(0)
	v_lshl_add_u64 v[66:67], v[32:33], 0, s[0:1]
	v_pk_mul_f32 v[16:17], v[16:17], v[34:35] op_sel_hi:[1,0]
	v_pk_mul_f32 v[18:19], v[18:19], v[34:35] op_sel_hi:[1,0]
	s_mov_b32 s0, 0x6000000
	v_cvt_pk_bf16_f32 v16, v16, v17
	v_cvt_pk_bf16_f32 v17, v18, v19
	v_add_co_u32_e32 v18, vcc, s0, v32
	v_pk_mul_f32 v[0:1], v[0:1], v[34:35] op_sel_hi:[1,0]
	s_nop 0
	v_addc_co_u32_e32 v19, vcc, 0, v33, vcc
	v_pk_mul_f32 v[2:3], v[2:3], v[34:35] op_sel_hi:[1,0]
	global_store_dwordx2 v[18:19], v[16:17], off offset:1280
	v_pk_mul_f32 v[16:17], v[20:21], v[34:35] op_sel_hi:[1,0]
	v_pk_mul_f32 v[18:19], v[22:23], v[34:35] op_sel_hi:[1,0]
	v_cvt_pk_bf16_f32 v0, v0, v1
	v_cvt_pk_bf16_f32 v1, v2, v3
	v_cvt_pk_bf16_f32 v16, v16, v17
	v_cvt_pk_bf16_f32 v17, v18, v19
	global_store_dwordx2 v[66:67], v[0:1], off offset:64
	v_pk_mul_f32 v[0:1], v[4:5], v[34:35] op_sel_hi:[1,0]
	v_pk_mul_f32 v[2:3], v[6:7], v[34:35] op_sel_hi:[1,0]
	global_store_dwordx2 v[66:67], v[16:17], off offset:16
	v_pk_mul_f32 v[16:17], v[24:25], v[34:35] op_sel_hi:[1,0]
	v_pk_mul_f32 v[18:19], v[26:27], v[34:35] op_sel_hi:[1,0]
	v_cvt_pk_bf16_f32 v0, v0, v1
	v_cvt_pk_bf16_f32 v1, v2, v3
	v_cvt_pk_bf16_f32 v16, v16, v17
	v_cvt_pk_bf16_f32 v17, v18, v19
	global_store_dwordx2 v[66:67], v[0:1], off offset:80
	v_pk_mul_f32 v[0:1], v[8:9], v[34:35] op_sel_hi:[1,0]
	v_pk_mul_f32 v[2:3], v[10:11], v[34:35] op_sel_hi:[1,0]
	global_store_dwordx2 v[66:67], v[16:17], off offset:32
	v_pk_mul_f32 v[16:17], v[28:29], v[34:35] op_sel_hi:[1,0]
	v_pk_mul_f32 v[18:19], v[30:31], v[34:35] op_sel_hi:[1,0]
	v_cvt_pk_bf16_f32 v0, v0, v1
	v_cvt_pk_bf16_f32 v1, v2, v3
	v_cvt_pk_bf16_f32 v16, v16, v17
	v_cvt_pk_bf16_f32 v17, v18, v19
	global_store_dwordx2 v[66:67], v[0:1], off offset:96
	v_pk_mul_f32 v[0:1], v[12:13], v[34:35] op_sel_hi:[1,0]
	global_store_dwordx2 v[66:67], v[16:17], off offset:48
	v_cvt_pk_bf16_f32 v0, v0, v1
	v_pk_mul_f32 v[2:3], v[14:15], v[34:35] op_sel_hi:[1,0]
	s_mov_b64 s[0:1], 0
.LBB0_918:
	s_and_b64 vcc, exec, s[0:1]
	s_cbranch_vccz .LBB0_954
	s_add_i32 s0, s67, 0xffe0
	s_and_b32 s26, s0, 0xff
	s_mul_i32 s1, s26, 0xab
	s_bfe_u32 s69, s1, 0x6000a
	s_mul_i32 s4, s69, 6
	s_sub_i32 s0, s0, s4
	s_and_b32 s68, s0, 0xff
	s_mov_b32 s0, -1
	s_add_i32 s31, s4, s68
	v_mbcnt_lo_u32_b32 v0, s0, 0
	v_mbcnt_hi_u32_b32 v0, s0, v0
	v_readlane_b32 s0, v252, 5
	s_lshl_b32 s4, s31, 18
	s_mul_i32 s27, s69, 5
	v_add_u32_e32 v17, s0, v0
	v_mov_b32_e32 v9, v65
	v_readfirstlane_b32 s0, v17
	s_ashr_i32 s29, s0, 6
	s_mov_b64 s[0:1], s[40:41]
	s_add_u32 s6, s0, s4
	s_addc_u32 s7, s1, 0
	s_mov_b64 s[0:1], s[40:41]
	s_add_u32 s34, s0, s4
	s_addc_u32 s35, s1, 0
	s_add_i32 s28, s31, s27
	s_mov_b64 s[4:5], s[40:41]
	s_lshl_b32 s27, s28, 17
	s_lshl_b32 s28, s28, 18
	v_ashrrev_i32_e32 v10, 3, v17
	s_add_u32 s36, s4, s28
	v_ashrrev_i32_e32 v11, 31, v10
	s_addc_u32 s37, s5, 0
	s_lshl_b32 s33, s66, 8
	s_lshl_b32 s28, s29, 5
	v_lshlrev_b64 v[4:5], 7, v[10:11]
	v_and_b32_e32 v2, 7, v17
	v_and_b32_e32 v16, 31, v17
	s_add_i32 s33, s28, s33
	v_lshl_add_u64 v[0:1], s[34:35], 0, v[4:5]
	v_lshlrev_b32_e32 v64, 4, v2
	v_or_b32_e32 v130, s33, v16
	v_lshl_add_u64 v[0:1], v[0:1], 0, v[64:65]
	v_ashrrev_i32_e32 v12, 4, v17
	s_mov_b32 s33, 0xe400000
	v_ashrrev_i32_e32 v13, 31, v12
	v_add_co_u32_e32 v14, vcc, s33, v0
	v_lshlrev_b64 v[6:7], 12, v[12:13]
	v_and_b32_e32 v8, 15, v17
	v_addc_co_u32_e32 v15, vcc, 0, v1, vcc
	s_mov_b32 s33, 0xe402000
	v_lshl_add_u64 v[2:3], s[36:37], 0, v[6:7]
	v_lshlrev_b32_e32 v8, 4, v8
	v_add_co_u32_e32 v0, vcc, s33, v0
	v_lshl_add_u64 v[2:3], v[2:3], 0, v[8:9]
	s_nop 0
	v_addc_co_u32_e32 v1, vcc, 0, v1, vcc
	s_mov_b32 s33, 0x11800000
	s_waitcnt vmcnt(0) lgkmcnt(0)
	global_load_dwordx4 v[98:101], v[14:15], off
	global_load_dwordx4 v[102:105], v[0:1], off
	v_add_co_u32_e32 v0, vcc, s33, v2
	s_mov_b32 s33, 0x11820000
	s_nop 0
	v_addc_co_u32_e32 v1, vcc, 0, v3, vcc
	v_add_co_u32_e32 v2, vcc, s33, v2
	v_ashrrev_i32_e32 v131, 31, v130
	v_bfe_u32 v18, v17, 5, 1
	v_addc_co_u32_e32 v3, vcc, 0, v3, vcc
	global_load_dwordx4 v[106:109], v[0:1], off
	global_load_dwordx4 v[126:129], v[2:3], off
	v_lshlrev_b64 v[0:1], 7, v[130:131]
	v_lshl_add_u64 v[0:1], s[6:7], 0, v[0:1]
	v_lshlrev_b32_e32 v132, 4, v18
	v_mov_b32_e32 v133, v65
	v_lshl_add_u64 v[0:1], v[0:1], 0, v[132:133]
	s_mov_b64 s[6:7], 0xd800000
	v_lshl_add_u64 v[2:3], v[0:1], 0, s[6:7]
	s_mov_b32 s6, 0xd800000
	v_add_co_u32_e32 v0, vcc, s6, v0
	s_mov_b64 s[6:7], s[40:41]
	s_nop 0
	v_addc_co_u32_e32 v1, vcc, 0, v1, vcc
	global_load_dwordx4 v[110:113], v[2:3], off offset:32
	global_load_dwordx4 v[114:117], v[2:3], off offset:64
	global_load_dwordx4 v[118:121], v[0:1], off
	global_load_dwordx4 v[122:125], v[2:3], off offset:96
	s_lshl_b32 s31, s31, 13
	s_add_u32 s6, s6, s31
	v_lshlrev_b32_e32 v14, 2, v17
	s_addc_u32 s7, s7, 0
	v_ashrrev_i32_e32 v15, 31, v14
	v_lshl_add_u64 v[0:1], v[14:15], 2, s[6:7]
	s_mov_b32 s6, 0x12f00000
	v_add_co_u32_e32 v0, vcc, s6, v0
	v_and_b32_e32 v131, 64, v197
	s_nop 0
	v_addc_co_u32_e32 v1, vcc, 0, v1, vcc
	global_load_dwordx4 v[0:3], v[0:1], off
	v_and_b32_e32 v11, 63, v17
	s_mov_b32 s6, 1
	s_waitcnt vmcnt(0) lgkmcnt(0)
	v_add_f32_e32 v1, v0, v1
	v_add_f32_e32 v2, v2, v1
	v_add_f32_e32 v3, v3, v2
	v_mov_b32_e32 v9, v3

.LBB0_939:
	s_add_i32 s34, s0, 1
	s_cmp_lt_u32 s34, s71
	s_cselect_b64 s[62:63], -1, 0
	s_cmp_ge_u32 s34, s71
	s_cbranch_scc1 .LBB0_941
	v_add_co_u32_e32 v32, vcc, 0x2000, v134
	s_waitcnt vmcnt(0)
	global_load_dwordx4 v[98:101], v[134:135], off
	v_addc_co_u32_e32 v33, vcc, 0, v135, vcc
	global_load_dwordx4 v[102:105], v[32:33], off
	v_add_co_u32_e32 v32, vcc, 0x20000, v136
	s_nop 1
	v_addc_co_u32_e32 v33, vcc, 0, v137, vcc
	global_load_dwordx4 v[106:109], v[136:137], off
	global_load_dwordx4 v[126:129], v[32:33], off

.LBB0_953:
	v_xor_b32_e32 v2, 32, v197
	v_add_u32_e32 v3, 64, v131
	v_cmp_lt_i32_e32 vcc, v2, v3
	v_lshl_add_u32 v0, s69, 11, v130
	s_mov_b64 s[0:1], s[40:41]
	v_cndmask_b32_e32 v2, v197, v2, vcc
	v_lshlrev_b32_e32 v2, 2, v2
	ds_bpermute_b32 v2, v2, v140
	v_ashrrev_i32_e32 v1, 31, v0
	v_lshlrev_b64 v[0:1], 11, v[0:1]
	v_lshl_add_u64 v[0:1], s[0:1], 0, v[0:1]
	s_mov_b32 s1, s29
	v_writelane_b32 v254, s0, 43
	s_waitcnt lgkmcnt(0)
	v_add_f32_e32 v2, v140, v2
	s_lshl_b32 s28, s68, 7
	v_writelane_b32 v254, s1, 44
	v_div_scale_f32 v3, s[0:1], v2, v2, 1.0
	v_rcp_f32_e32 v4, v3
	v_lshl_add_u64 v[0:1], v[0:1], 0, s[28:29]
	v_lshlrev_b32_e32 v64, 1, v133
	v_lshl_add_u64 v[0:1], v[0:1], 0, v[64:65]
	v_fma_f32 v5, -v3, v4, 1.0
	v_fmac_f32_e32 v4, v5, v4
	v_div_scale_f32 v5, vcc, 1.0, v2, 1.0
	v_mul_f32_e32 v6, v5, v4
	v_fma_f32 v7, -v3, v6, v5
	v_fmac_f32_e32 v6, v7, v4
	v_fma_f32 v3, -v3, v6, v5
	v_div_fmas_f32 v3, v3, v4, v6
	s_mov_b64 s[0:1], 0x6000000
	v_div_fixup_f32 v2, v3, v2, 1.0
	v_lshl_add_u64 v[66:67], v[0:1], 0, s[0:1]
	s_mov_b32 s0, 0x6000000
	v_pk_mul_f32 v[4:5], v[32:33], v[2:3] op_sel_hi:[1,0]
	v_pk_mul_f32 v[6:7], v[34:35], v[2:3] op_sel_hi:[1,0]
	v_add_co_u32_e32 v0, vcc, s0, v0
	v_cvt_pk_bf16_f32 v4, v4, v5
	v_cvt_pk_bf16_f32 v5, v6, v7
	v_addc_co_u32_e32 v1, vcc, 0, v1, vcc
	global_store_dwordx2 v[0:1], v[4:5], off
	v_pk_mul_f32 v[0:1], v[36:37], v[2:3] op_sel_hi:[1,0]
	v_pk_mul_f32 v[4:5], v[38:39], v[2:3] op_sel_hi:[1,0]
	v_cvt_pk_bf16_f32 v0, v0, v1
	v_cvt_pk_bf16_f32 v1, v4, v5
	global_store_dwordx2 v[66:67], v[0:1], off offset:16
	v_pk_mul_f32 v[0:1], v[40:41], v[2:3] op_sel_hi:[1,0]
	v_pk_mul_f32 v[4:5], v[42:43], v[2:3] op_sel_hi:[1,0]
	v_cvt_pk_bf16_f32 v0, v0, v1
	v_cvt_pk_bf16_f32 v1, v4, v5
	global_store_dwordx2 v[66:67], v[0:1], off offset:32
	v_pk_mul_f32 v[0:1], v[44:45], v[2:3] op_sel_hi:[1,0]
	v_pk_mul_f32 v[4:5], v[46:47], v[2:3] op_sel_hi:[1,0]
	v_cvt_pk_bf16_f32 v0, v0, v1
	v_cvt_pk_bf16_f32 v1, v4, v5
	global_store_dwordx2 v[66:67], v[0:1], off offset:48
	v_pk_mul_f32 v[0:1], v[48:49], v[2:3] op_sel_hi:[1,0]
	v_pk_mul_f32 v[4:5], v[50:51], v[2:3] op_sel_hi:[1,0]
	v_cvt_pk_bf16_f32 v0, v0, v1
	v_cvt_pk_bf16_f32 v1, v4, v5
	global_store_dwordx2 v[66:67], v[0:1], off offset:64
	v_pk_mul_f32 v[0:1], v[52:53], v[2:3] op_sel_hi:[1,0]
	v_pk_mul_f32 v[4:5], v[54:55], v[2:3] op_sel_hi:[1,0]
	v_cvt_pk_bf16_f32 v0, v0, v1
	v_cvt_pk_bf16_f32 v1, v4, v5
	global_store_dwordx2 v[66:67], v[0:1], off offset:80
	v_pk_mul_f32 v[0:1], v[56:57], v[2:3] op_sel_hi:[1,0]
	v_pk_mul_f32 v[4:5], v[58:59], v[2:3] op_sel_hi:[1,0]
	v_cvt_pk_bf16_f32 v0, v0, v1
	v_cvt_pk_bf16_f32 v1, v4, v5
	global_store_dwordx2 v[66:67], v[0:1], off offset:96
	v_pk_mul_f32 v[0:1], v[60:61], v[2:3] op_sel_hi:[1,0]
	v_pk_mul_f32 v[2:3], v[62:63], v[2:3] op_sel_hi:[1,0]
	v_cvt_pk_bf16_f32 v0, v0, v1

.LBB0_955:
	s_andn2_b64 vcc, exec, s[0:1]
	s_cbranch_vccnz .LBB0_898
	s_bfe_i32 s0, s67, 0x80000
	s_bfe_u32 s0, s0, 0x2000d
	s_add_i32 s0, s67, s0
	s_bfe_i32 s1, s0, 0x80000
	s_and_b32 s0, s0, 0xfc
	s_sub_i32 s0, s67, s0
	s_sext_i32_i16 s4, s1
	s_sext_i32_i8 s29, s0
	s_mov_b32 s0, -1
	s_ashr_i32 s28, s4, 2
	s_and_b32 s4, s4, -4
	v_mbcnt_lo_u32_b32 v0, s0, 0
	v_mbcnt_hi_u32_b32 v0, s0, v0
	v_readlane_b32 s0, v252, 5
	s_add_i32 s4, s4, s29
	s_ashr_i32 s5, s4, 31
	v_add_u32_e32 v8, s0, v0
	s_mov_b64 s[0:1], s[40:41]
	s_lshl_b64 s[4:5], s[4:5], 18
	s_add_u32 s0, s0, s4
	v_writelane_b32 v255, s28, 12
	s_mul_i32 s28, s28, 11
	v_readfirstlane_b32 s31, v8
	s_addc_u32 s1, s1, s5
	s_add_i32 s28, s29, s28
	s_add_i32 s28, s28, 6
	s_ashr_i32 s31, s31, 1
	v_writelane_b32 v255, s29, 13
	s_ashr_i32 s29, s28, 31
	s_lshl_b32 s33, s66, 8
	s_and_b32 s34, s31, 0xffffffe0
	s_mov_b64 s[6:7], s[40:41]
	s_lshl_b64 s[28:29], s[28:29], 18
	s_add_i32 s34, s34, s33
	s_lshl_b32 s35, s66, 2
	v_ashrrev_i32_e32 v0, 3, v8
	v_ashrrev_i32_e32 v1, 31, v0
	s_add_u32 s4, s6, s4
	s_mov_b64 s[26:27], s[40:41]
	v_lshlrev_b64 v[2:3], 7, v[0:1]
	s_addc_u32 s5, s7, s5
	v_lshlrev_b32_e32 v4, 4, v8
	v_lshl_add_u64 v[174:175], s[4:5], 0, v[2:3]
	s_add_u32 s4, s26, s28
	v_and_b32_e32 v172, 0x70, v4
	v_mov_b32_e32 v173, v65
	v_lshlrev_b64 v[4:5], 12, v[0:1]
	s_addc_u32 s5, s27, s29
	v_lshl_add_u64 v[2:3], v[174:175], 0, v[172:173]
	v_lshl_add_u64 v[176:177], s[4:5], 0, v[4:5]
	s_mov_b32 s4, 0xf800000
	v_add_co_u32_e32 v6, vcc, s4, v2
	v_lshl_add_u64 v[4:5], v[176:177], 0, v[172:173]
	s_nop 0
	v_addc_co_u32_e32 v7, vcc, 0, v3, vcc
	s_mov_b32 s4, 0x11800000
	s_waitcnt vmcnt(0) lgkmcnt(0)
	global_load_dwordx4 v[98:101], v[6:7], off
	v_add_co_u32_e32 v6, vcc, s4, v4
	s_mov_b64 s[4:5], 0x11800000
	s_nop 0
	v_addc_co_u32_e32 v7, vcc, 0, v5, vcc
	v_and_b32_e32 v1, 31, v8
	v_lshl_add_u64 v[4:5], v[4:5], 0, s[4:5]
	s_mov_b32 s4, 0xf802000
	v_or_b32_e32 v170, s34, v1
	v_add_co_u32_e32 v2, vcc, s4, v2
	v_ashrrev_i32_e32 v171, 31, v170
	s_nop 0
	v_addc_co_u32_e32 v3, vcc, 0, v3, vcc
	v_bfe_u32 v8, v8, 5, 1
	global_load_dwordx4 v[106:109], v[2:3], off
	v_lshlrev_b64 v[2:3], 7, v[170:171]
	v_lshl_add_u64 v[2:3], s[0:1], 0, v[2:3]
	v_lshlrev_b32_e32 v64, 4, v8
	v_lshl_add_u64 v[2:3], v[2:3], 0, v[64:65]
	s_mov_b64 s[0:1], 0xf000000
	global_load_dwordx4 v[102:105], v[6:7], off
	v_lshl_add_u64 v[6:7], v[2:3], 0, s[0:1]
	s_mov_b32 s0, 0xf000000
	v_add_co_u32_e32 v2, vcc, s0, v2
	s_movk_i32 s0, 0x90
	s_nop 0
	v_addc_co_u32_e32 v3, vcc, 0, v3, vcc
	global_load_dwordx4 v[110:113], v[6:7], off offset:32
	global_load_dwordx4 v[114:117], v[6:7], off offset:64
	global_load_dwordx4 v[118:121], v[2:3], off
	global_load_dwordx4 v[122:125], v[6:7], off offset:96
	global_load_dwordx4 v[126:129], v[4:5], off offset:128
	v_mul_u32_u24_e32 v183, 0x90, v1
	v_mad_u32_u24 v16, v1, s0, 0
	v_mad_u64_u32 v[0:1], s[0:1], v0, s0, v[172:173]
	s_lshl_b32 s0, s75, 8
	v_mov_b32_e32 v14, v65
	v_mov_b32_e32 v15, v65
	v_lshl_add_u32 v184, v8, 5, 0
	v_add_u32_e32 v185, 0, v0
	v_lshlrev_b32_e32 v171, 2, v8
	s_sub_i32 s34, 0xfffff900, s0
	s_lshl_b32 s0, s75, 2
	v_mov_b32_e32 v0, v65
	v_mov_b32_e32 v1, v65
	v_mov_b32_e32 v2, v65
	v_mov_b32_e32 v3, v65
	v_mov_b32_e32 v4, v65
	v_mov_b32_e32 v5, v65
	v_mov_b32_e32 v6, v65
	v_mov_b32_e32 v7, v65
	v_mov_b32_e32 v8, v65
	v_mov_b32_e32 v9, v65
	v_mov_b32_e32 v10, v65
	v_mov_b32_e32 v11, v65
	v_mov_b32_e32 v12, v65
	v_mov_b32_e32 v13, v65
	v_add_u32_e32 v187, v16, v64
	v_mov_b64_e32 v[46:47], v[14:15]
	v_mov_b64_e32 v[30:31], v[14:15]
	v_mov_b64_e32 v[62:63], v[14:15]
	s_mov_b32 s28, 3
	s_add_i32 s29, s35, 4
	s_or_b32 s33, s31, 31
	s_or_b32 s31, s35, 3
	v_sub_u32_e32 v186, v170, v171
	s_sub_i32 s35, 0, s0
	v_mov_b32_e32 v169, 0
	v_mov_b32_e32 v182, 0
	v_mov_b64_e32 v[44:45], v[12:13]
	v_mov_b64_e32 v[42:43], v[10:11]
	v_mov_b64_e32 v[40:41], v[8:9]
	v_mov_b64_e32 v[38:39], v[6:7]
	v_mov_b64_e32 v[36:37], v[4:5]
	v_mov_b64_e32 v[34:35], v[2:3]
	v_mov_b64_e32 v[32:33], v[0:1]
	v_mov_b64_e32 v[28:29], v[12:13]
	v_mov_b64_e32 v[26:27], v[10:11]
	v_mov_b64_e32 v[24:25], v[8:9]
	v_mov_b64_e32 v[22:23], v[6:7]
	v_mov_b64_e32 v[20:21], v[4:5]
	v_mov_b64_e32 v[18:19], v[2:3]
	v_mov_b64_e32 v[16:17], v[0:1]
	v_mov_b64_e32 v[60:61], v[12:13]
	v_mov_b64_e32 v[58:59], v[10:11]
	v_mov_b64_e32 v[56:57], v[8:9]
	v_mov_b64_e32 v[54:55], v[6:7]
	v_mov_b64_e32 v[52:53], v[4:5]
	v_mov_b64_e32 v[50:51], v[2:3]
	v_mov_b64_e32 v[48:49], v[0:1]
	s_waitcnt vmcnt(0) lgkmcnt(0)
	ds_write_b128 v185, v[98:101]
	ds_write_b128 v185, v[102:105] offset:18432
	s_waitcnt lgkmcnt(0)
	s_barrier
	s_branch .LBB0_958

.LBB0_958:
	s_add_i32 s27, s28, -1
	s_cmp_lt_u32 s27, s29
	v_lshl_add_u64 v[180:181], v[174:175], 0, v[172:173]
	v_lshl_add_u64 v[178:179], v[176:177], 0, v[172:173]
	s_cbranch_scc0 .LBB0_960
	v_add_co_u32_e32 v66, vcc, 0xf804000, v180
	s_nop 1
	v_addc_co_u32_e32 v67, vcc, 0, v181, vcc
	s_waitcnt vmcnt(0)
	global_load_dwordx4 v[98:101], v[66:67], off
	v_add_co_u32_e32 v66, vcc, 0x11800000, v178
	s_nop 1
	v_addc_co_u32_e32 v67, vcc, 0, v179, vcc
	global_load_dwordx4 v[102:105], v[66:67], off offset:256

.LBB0_968:
	s_cmp_ge_u32 s28, s29
	s_waitcnt lgkmcnt(0)
	s_barrier
	s_cbranch_scc1 .LBB0_970
	v_add_co_u32_e32 v66, vcc, 0xf806000, v180
	s_nop 1
	v_addc_co_u32_e32 v67, vcc, 0, v181, vcc
	s_waitcnt vmcnt(0)
	global_load_dwordx4 v[106:109], v[66:67], off
	v_add_co_u32_e32 v66, vcc, 0x11800000, v178
	s_nop 1
	v_addc_co_u32_e32 v67, vcc, 0, v179, vcc
	global_load_dwordx4 v[126:129], v[66:67], off offset:384

.LBB0_979:
	s_mov_b64 s[6:7], s[8:9]
	s_add_u32 s6, s6, s2
	s_addc_u32 s7, s7, s3
	s_add_u32 s6, s6, s4
	s_addc_u32 s7, s7, s5
	v_mov_b64_e32 v[66:67], s[6:7]
	s_mov_b64 s[6:7], s[10:11]
	global_load_dword v67, v[66:67], off
	s_add_u32 s6, s6, s2
	s_addc_u32 s7, s7, s3
	s_add_u32 s6, s6, s4
	s_addc_u32 s7, s7, s5
	v_mov_b64_e32 v[70:71], s[6:7]
	s_mov_b64 s[6:7], s[12:13]
	global_load_dword v71, v[70:71], off
	s_add_u32 s6, s6, s2
	s_addc_u32 s7, s7, s3
	s_add_u32 s6, s6, s4
	s_addc_u32 s7, s7, s5
	v_mov_b64_e32 v[72:73], s[6:7]
	s_mov_b64 s[6:7], s[14:15]
	global_load_dword v66, v[72:73], off
	s_add_u32 s6, s6, s2
	s_addc_u32 s7, s7, s3
	s_add_u32 s6, s6, s4
	s_addc_u32 s7, s7, s5
	v_mov_b64_e32 v[72:73], s[6:7]
	global_load_dword v70, v[72:73], off
	s_mov_b64 s[6:7], s[8:9]
	s_add_u32 s6, s6, s2
	s_addc_u32 s7, s7, s3
	s_add_u32 s6, s6, s4
	s_addc_u32 s7, s7, s5
	s_waitcnt vmcnt(0) lgkmcnt(0)
	v_pk_fma_f32 v[66:67], v[66:67], v[70:71], v[68:69]
	v_mov_b64_e32 v[68:69], s[6:7]
	s_mov_b64 s[6:7], s[10:11]
	global_load_dword v69, v[68:69], off offset:4
	s_add_u32 s6, s6, s2
	s_addc_u32 s7, s7, s3
	s_add_u32 s6, s6, s4
	s_addc_u32 s7, s7, s5
	v_mov_b64_e32 v[70:71], s[6:7]
	s_mov_b64 s[6:7], s[12:13]
	global_load_dword v71, v[70:71], off offset:4
	s_add_u32 s6, s6, s2
	s_addc_u32 s7, s7, s3
	s_add_u32 s6, s6, s4
	s_addc_u32 s7, s7, s5
	v_mov_b64_e32 v[72:73], s[6:7]
	s_mov_b64 s[6:7], s[14:15]
	global_load_dword v68, v[72:73], off offset:4
	s_add_u32 s6, s6, s2
	s_addc_u32 s7, s7, s3
	s_add_u32 s6, s6, s4
	s_addc_u32 s7, s7, s5
	v_mov_b64_e32 v[72:73], s[6:7]
	global_load_dword v70, v[72:73], off offset:4
	s_mov_b64 s[6:7], s[8:9]
	s_add_u32 s6, s6, s2
	s_addc_u32 s7, s7, s3
	s_add_u32 s6, s6, s4
	s_addc_u32 s7, s7, s5
	s_waitcnt vmcnt(0) lgkmcnt(0)
	v_pk_fma_f32 v[66:67], v[68:69], v[70:71], v[66:67]
	v_mov_b64_e32 v[68:69], s[6:7]
	s_mov_b64 s[6:7], s[10:11]
	global_load_dword v69, v[68:69], off offset:8
	s_add_u32 s6, s6, s2
	s_addc_u32 s7, s7, s3
	s_add_u32 s6, s6, s4
	s_addc_u32 s7, s7, s5
	v_mov_b64_e32 v[70:71], s[6:7]
	s_mov_b64 s[6:7], s[12:13]
	global_load_dword v71, v[70:71], off offset:8
	s_add_u32 s6, s6, s2
	s_addc_u32 s7, s7, s3
	s_add_u32 s6, s6, s4
	s_addc_u32 s7, s7, s5
	v_mov_b64_e32 v[72:73], s[6:7]
	s_mov_b64 s[6:7], s[14:15]
	global_load_dword v68, v[72:73], off offset:8
	s_add_u32 s6, s6, s2
	s_addc_u32 s7, s7, s3
	s_add_u32 s6, s6, s4
	s_addc_u32 s7, s7, s5
	v_mov_b64_e32 v[72:73], s[6:7]
	global_load_dword v70, v[72:73], off offset:8
	s_mov_b64 s[6:7], s[8:9]
	s_add_u32 s6, s6, s2
	s_addc_u32 s7, s7, s3
	s_add_u32 s6, s6, s4
	s_addc_u32 s7, s7, s5
	s_waitcnt vmcnt(0) lgkmcnt(0)
	v_pk_fma_f32 v[66:67], v[68:69], v[70:71], v[66:67]
	v_mov_b64_e32 v[68:69], s[6:7]
	s_mov_b64 s[6:7], s[10:11]
	global_load_dword v69, v[68:69], off offset:12
	s_add_u32 s6, s6, s2
	s_addc_u32 s7, s7, s3
	s_add_u32 s6, s6, s4
	s_addc_u32 s7, s7, s5
	v_mov_b64_e32 v[70:71], s[6:7]
	s_mov_b64 s[6:7], s[12:13]
	global_load_dword v71, v[70:71], off offset:12
	s_add_u32 s6, s6, s2
	s_addc_u32 s7, s7, s3
	s_add_u32 s6, s6, s4
	s_addc_u32 s7, s7, s5
	v_mov_b64_e32 v[72:73], s[6:7]
	s_mov_b64 s[6:7], s[14:15]
	global_load_dword v68, v[72:73], off offset:12
	s_add_u32 s6, s6, s2
	s_addc_u32 s7, s7, s3
	s_add_u32 s6, s6, s4
	s_addc_u32 s7, s7, s5
	v_mov_b64_e32 v[72:73], s[6:7]
	global_load_dword v70, v[72:73], off offset:12
	s_add_u32 s4, s4, 16
	s_addc_u32 s5, s5, 0
	s_cmpk_lg_i32 s4, 0x80
	s_waitcnt vmcnt(0) lgkmcnt(0)
	v_pk_fma_f32 v[68:69], v[68:69], v[70:71], v[66:67]
	s_cbranch_scc1 .LBB0_979
	v_readlane_b32 s4, v255, 12
	v_mul_f32_e32 v64, 0x3fb8aa3b, v69
	v_rndne_f32_e32 v70, v64
	v_lshl_add_u32 v66, s4, 11, v170
	s_mov_b32 s4, 0x3fb8aa3b
	v_sub_f32_e32 v71, v64, v70
	v_fma_f32 v64, v69, s4, -v64
	v_ashrrev_i32_e32 v67, 31, v66
	v_fmac_f32_e32 v64, 0x32a5705f, v69
	v_lshlrev_b64 v[66:67], 11, v[66:67]
	v_add_f32_e32 v64, v71, v64
	v_lshl_add_u64 v[66:67], s[0:1], 0, v[66:67]
	v_readlane_b32 s0, v255, 13
	v_exp_f32_e32 v64, v64
	v_cvt_i32_f32_e32 v70, v70
	s_lshl_b32 s0, s0, 6
	s_ashr_i32 s1, s0, 31
	v_lshl_add_u64 v[66:67], s[0:1], 1, v[66:67]
	s_mov_b32 s0, 0xc2ce8ed0
	v_ldexp_f32 v64, v64, v70
	v_cmp_ngt_f32_e32 vcc, s0, v69
	s_mov_b32 s1, 0x42b17218
	v_mov_b32_e32 v72, 0x7f800000
	v_cndmask_b32_e32 v64, 0, v64, vcc
	v_cmp_nlt_f32_e32 vcc, s1, v69
	v_mul_f32_e32 v69, 0x3fb8aa3b, v68
	v_rndne_f32_e32 v70, v69
	v_sub_f32_e32 v71, v69, v70
	v_fma_f32 v69, v68, s4, -v69
	v_fmac_f32_e32 v69, 0x32a5705f, v68
	v_add_f32_e32 v69, v71, v69
	v_exp_f32_e32 v69, v69
	v_cvt_i32_f32_e32 v70, v70
	v_cndmask_b32_e32 v64, v72, v64, vcc
	v_cmp_ngt_f32_e32 vcc, s0, v68
	v_readlane_b32 s4, v255, 10
	v_ldexp_f32 v69, v69, v70
	v_cndmask_b32_e32 v69, 0, v69, vcc
	v_cmp_nlt_f32_e32 vcc, s1, v68
	v_readlane_b32 s5, v255, 11
	s_lshl_b64 s[4:5], s[4:5], 2
	v_cndmask_b32_e32 v68, v72, v69, vcc
	v_and_b32_e32 v69, 64, v197
	v_sub_f32_e32 v68, v64, v68
	v_xor_b32_e32 v64, 32, v197
	v_add_u32_e32 v69, 64, v69
	v_cmp_lt_i32_e32 vcc, v64, v69
	v_readlane_b32 s33, v255, 5
	s_nop 0
	v_cndmask_b32_e32 v64, v197, v64, vcc
	v_lshlrev_b32_e32 v73, 2, v64
	ds_bpermute_b32 v64, v73, v182
	s_waitcnt lgkmcnt(0)
	v_add_f32_e32 v64, v182, v64
	v_div_scale_f32 v69, s[0:1], v64, v64, 1.0
	v_rcp_f32_e32 v70, v69
	s_nop 0
	v_fma_f32 v71, -v69, v70, 1.0
	v_fmac_f32_e32 v70, v71, v70
	v_div_scale_f32 v71, vcc, 1.0, v64, 1.0
	v_mul_f32_e32 v72, v71, v70
	v_fma_f32 v74, -v69, v72, v71
	v_fmac_f32_e32 v72, v74, v70
	v_fma_f32 v69, -v69, v72, v71
	v_div_fmas_f32 v69, v69, v70, v72
	v_div_fixup_f32 v72, v69, v64, 1.0
	ds_bpermute_b32 v69, v73, v169
	s_waitcnt lgkmcnt(0)
	v_pk_add_f32 v[68:69], v[168:169], v[68:69]
	s_nop 0
	v_div_scale_f32 v64, s[0:1], v69, v69, v68
	v_rcp_f32_e32 v70, v64
	s_mov_b64 s[0:1], s[16:17]
	s_add_u32 s0, s0, s4
	v_fma_f32 v71, -v64, v70, 1.0
	v_fmac_f32_e32 v70, v71, v70
	v_div_scale_f32 v71, vcc, v68, v69, v68
	v_mul_f32_e32 v74, v71, v70
	v_fma_f32 v75, -v64, v74, v71
	v_fmac_f32_e32 v74, v75, v70
	v_fma_f32 v64, -v64, v74, v71
	v_div_fmas_f32 v64, v64, v70, v74
	v_div_fixup_f32 v74, v64, v69, v68
	v_pk_mul_f32 v[10:11], v[10:11], v[74:75] op_sel_hi:[1,0]
	s_addc_u32 s1, s1, s5
	v_lshlrev_b32_e32 v64, 2, v171
	v_pk_fma_f32 v[26:27], v[26:27], v[72:73], v[10:11] op_sel_hi:[1,0,1] neg_lo:[0,0,1] neg_hi:[0,0,1]
	v_pk_mul_f32 v[10:11], v[12:13], v[74:75] op_sel_hi:[1,0]
	v_lshl_add_u64 v[12:13], s[0:1], 0, v[64:65]
	global_load_dwordx4 v[68:71], v[12:13], off
	v_pk_mul_f32 v[32:33], v[32:33], v[74:75] op_sel_hi:[1,0]
	v_pk_mul_f32 v[34:35], v[34:35], v[74:75] op_sel_hi:[1,0]
	v_pk_fma_f32 v[32:33], v[48:49], v[72:73], v[32:33] op_sel_hi:[1,0,1] neg_lo:[0,0,1] neg_hi:[0,0,1]
	v_pk_fma_f32 v[34:35], v[50:51], v[72:73], v[34:35] op_sel_hi:[1,0,1] neg_lo:[0,0,1] neg_hi:[0,0,1]
	v_pk_mul_f32 v[48:49], v[32:33], v[32:33]
	v_pk_mul_f32 v[50:51], v[34:35], v[34:35]
	v_pk_mul_f32 v[36:37], v[36:37], v[74:75] op_sel_hi:[1,0]
	v_add_f32_e32 v48, v48, v49
	v_pk_fma_f32 v[36:37], v[52:53], v[72:73], v[36:37] op_sel_hi:[1,0,1] neg_lo:[0,0,1] neg_hi:[0,0,1]
	v_add_f32_e32 v48, v50, v48
	v_pk_mul_f32 v[38:39], v[38:39], v[74:75] op_sel_hi:[1,0]
	v_pk_mul_f32 v[52:53], v[36:37], v[36:37]
	v_add_f32_e32 v48, v51, v48
	v_pk_fma_f32 v[38:39], v[54:55], v[72:73], v[38:39] op_sel_hi:[1,0,1] neg_lo:[0,0,1] neg_hi:[0,0,1]
	v_add_f32_e32 v48, v52, v48
	v_pk_mul_f32 v[54:55], v[38:39], v[38:39]
	v_pk_mul_f32 v[40:41], v[40:41], v[74:75] op_sel_hi:[1,0]
	v_add_f32_e32 v48, v53, v48
	v_pk_fma_f32 v[40:41], v[56:57], v[72:73], v[40:41] op_sel_hi:[1,0,1] neg_lo:[0,0,1] neg_hi:[0,0,1]
	v_add_f32_e32 v48, v54, v48
	v_pk_mul_f32 v[42:43], v[42:43], v[74:75] op_sel_hi:[1,0]
	v_pk_mul_f32 v[56:57], v[40:41], v[40:41]
	v_add_f32_e32 v48, v55, v48
	v_pk_fma_f32 v[42:43], v[58:59], v[72:73], v[42:43] op_sel_hi:[1,0,1] neg_lo:[0,0,1] neg_hi:[0,0,1]
	v_add_f32_e32 v48, v56, v48
	v_pk_mul_f32 v[58:59], v[42:43], v[42:43]
	v_pk_mul_f32 v[44:45], v[44:45], v[74:75] op_sel_hi:[1,0]
	v_add_f32_e32 v48, v57, v48
	v_pk_fma_f32 v[44:45], v[60:61], v[72:73], v[44:45] op_sel_hi:[1,0,1] neg_lo:[0,0,1] neg_hi:[0,0,1]
	v_add_f32_e32 v48, v58, v48
	v_pk_mul_f32 v[46:47], v[46:47], v[74:75] op_sel_hi:[1,0]
	v_pk_mul_f32 v[60:61], v[44:45], v[44:45]
	v_add_f32_e32 v48, v59, v48
	v_pk_fma_f32 v[46:47], v[62:63], v[72:73], v[46:47] op_sel_hi:[1,0,1] neg_lo:[0,0,1] neg_hi:[0,0,1]
	v_add_f32_e32 v48, v60, v48
	v_pk_mul_f32 v[62:63], v[46:47], v[46:47]
	v_pk_mul_f32 v[0:1], v[0:1], v[74:75] op_sel_hi:[1,0]
	v_add_f32_e32 v48, v61, v48
	v_pk_fma_f32 v[16:17], v[16:17], v[72:73], v[0:1] op_sel_hi:[1,0,1] neg_lo:[0,0,1] neg_hi:[0,0,1]
	v_add_f32_e32 v48, v62, v48
	v_pk_mul_f32 v[2:3], v[2:3], v[74:75] op_sel_hi:[1,0]
	v_pk_mul_f32 v[0:1], v[16:17], v[16:17]
	v_add_f32_e32 v48, v63, v48
	v_pk_fma_f32 v[18:19], v[18:19], v[72:73], v[2:3] op_sel_hi:[1,0,1] neg_lo:[0,0,1] neg_hi:[0,0,1]
	v_add_f32_e32 v0, v0, v48
	v_pk_mul_f32 v[2:3], v[18:19], v[18:19]
	v_pk_mul_f32 v[4:5], v[4:5], v[74:75] op_sel_hi:[1,0]
	v_add_f32_e32 v0, v1, v0
	v_pk_fma_f32 v[4:5], v[20:21], v[72:73], v[4:5] op_sel_hi:[1,0,1] neg_lo:[0,0,1] neg_hi:[0,0,1]
	v_add_f32_e32 v0, v2, v0
	v_pk_mul_f32 v[6:7], v[6:7], v[74:75] op_sel_hi:[1,0]
	v_pk_mul_f32 v[20:21], v[4:5], v[4:5]
	v_add_f32_e32 v0, v3, v0
	v_pk_fma_f32 v[6:7], v[22:23], v[72:73], v[6:7] op_sel_hi:[1,0,1] neg_lo:[0,0,1] neg_hi:[0,0,1]
	v_add_f32_e32 v0, v20, v0
	v_pk_mul_f32 v[22:23], v[6:7], v[6:7]
	v_pk_mul_f32 v[8:9], v[8:9], v[74:75] op_sel_hi:[1,0]
	v_add_f32_e32 v0, v21, v0
	v_pk_fma_f32 v[8:9], v[24:25], v[72:73], v[8:9] op_sel_hi:[1,0,1] neg_lo:[0,0,1] neg_hi:[0,0,1]
	v_add_f32_e32 v0, v22, v0
	v_pk_mul_f32 v[24:25], v[8:9], v[8:9]
	v_add_f32_e32 v0, v23, v0
	v_add_f32_e32 v0, v24, v0
	v_pk_mul_f32 v[76:77], v[26:27], v[26:27]
	v_add_f32_e32 v0, v25, v0
	v_pk_fma_f32 v[10:11], v[28:29], v[72:73], v[10:11] op_sel_hi:[1,0,1] neg_lo:[0,0,1] neg_hi:[0,0,1]
	v_add_f32_e32 v0, v76, v0
	v_pk_mul_f32 v[28:29], v[10:11], v[10:11]
	v_pk_mul_f32 v[14:15], v[14:15], v[74:75] op_sel_hi:[1,0]
	v_add_f32_e32 v0, v77, v0
	v_pk_fma_f32 v[14:15], v[30:31], v[72:73], v[14:15] op_sel_hi:[1,0,1] neg_lo:[0,0,1] neg_hi:[0,0,1]
	v_add_f32_e32 v0, v28, v0
	v_pk_mul_f32 v[30:31], v[14:15], v[14:15]
	v_add_f32_e32 v0, v29, v0
	v_add_f32_e32 v0, v30, v0
	v_add_f32_e32 v0, v31, v0
	ds_bpermute_b32 v1, v73, v0
	v_lshlrev_b32_e32 v64, 1, v171
	v_lshl_add_u64 v[78:79], v[66:67], 0, v[64:65]
	s_mov_b64 s[0:1], 0x6000300
	v_lshl_add_u64 v[66:67], v[78:79], 0, s[0:1]
	s_waitcnt lgkmcnt(0)
	v_add_f32_e32 v0, v0, v1
	v_fmamk_f32 v0, v0, 0x3c800000, v194
	s_mov_b32 s0, 0xf800000
	v_cmp_gt_f32_e32 vcc, s0, v0
	v_mul_f32_e32 v1, 0x4f800000, v0
	s_nop 0
	v_cndmask_b32_e32 v0, v0, v1, vcc
	v_sqrt_f32_e32 v1, v0
	s_nop 0
	v_add_u32_e32 v2, -1, v1
	v_fma_f32 v3, -v2, v1, v0
	v_cmp_ge_f32_e64 s[0:1], 0, v3
	v_add_u32_e32 v3, 1, v1
	s_nop 0
	v_cndmask_b32_e64 v2, v1, v2, s[0:1]
	v_fma_f32 v1, -v3, v1, v0
	v_cmp_lt_f32_e64 s[0:1], 0, v1
	s_nop 1
	v_cndmask_b32_e64 v1, v2, v3, s[0:1]
	v_mul_f32_e32 v2, 0x37800000, v1
	v_cndmask_b32_e32 v1, v1, v2, vcc
	v_cmp_class_f32_e32 vcc, v0, v195
	s_nop 1
	v_cndmask_b32_e32 v0, v1, v0, vcc
	v_div_scale_f32 v1, s[0:1], v0, v0, v163
	v_rcp_f32_e32 v2, v1
	s_mov_b32 s0, 0x6000000
	v_fma_f32 v3, -v1, v2, 1.0
	v_fmac_f32_e32 v2, v3, v2
	v_div_scale_f32 v3, vcc, v163, v0, v163
	v_mul_f32_e32 v20, v3, v2
	v_fma_f32 v21, -v1, v20, v3
	v_fmac_f32_e32 v20, v21, v2
	v_fma_f32 v1, -v1, v20, v3
	v_div_fmas_f32 v1, v1, v2, v20
	v_div_fixup_f32 v20, v1, v0, v163
	v_pk_mul_f32 v[0:1], v[32:33], v[20:21] op_sel_hi:[1,0]
	v_pk_mul_f32 v[2:3], v[34:35], v[20:21] op_sel_hi:[1,0]
	s_waitcnt vmcnt(0)
	v_pk_mul_f32 v[0:1], v[68:69], v[0:1]
	v_pk_mul_f32 v[2:3], v[70:71], v[2:3]
	v_cvt_pk_bf16_f32 v0, v0, v1
	v_cvt_pk_bf16_f32 v1, v2, v3
	v_add_co_u32_e32 v2, vcc, s0, v78
	v_pk_mul_f32 v[22:23], v[36:37], v[20:21] op_sel_hi:[1,0]
	s_nop 0
	v_addc_co_u32_e32 v3, vcc, 0, v79, vcc
	global_store_dwordx2 v[2:3], v[0:1], off offset:768
	global_load_dwordx4 v[0:3], v[12:13], off offset:32
	v_pk_mul_f32 v[16:17], v[16:17], v[20:21] op_sel_hi:[1,0]
	v_pk_mul_f32 v[4:5], v[4:5], v[20:21] op_sel_hi:[1,0]
	s_waitcnt vmcnt(0) lgkmcnt(0)
	v_pk_mul_f32 v[0:1], v[0:1], v[22:23]
	v_pk_mul_f32 v[22:23], v[38:39], v[20:21] op_sel_hi:[1,0]
	v_cvt_pk_bf16_f32 v0, v0, v1
	v_pk_mul_f32 v[2:3], v[2:3], v[22:23]
	v_pk_mul_f32 v[22:23], v[40:41], v[20:21] op_sel_hi:[1,0]
	v_cvt_pk_bf16_f32 v1, v2, v3
	global_store_dwordx2 v[66:67], v[0:1], off offset:16
	global_load_dwordx4 v[0:3], v[12:13], off offset:64
	s_waitcnt vmcnt(0) lgkmcnt(0)
	v_pk_mul_f32 v[0:1], v[0:1], v[22:23]
	v_pk_mul_f32 v[22:23], v[42:43], v[20:21] op_sel_hi:[1,0]
	v_cvt_pk_bf16_f32 v0, v0, v1
	v_pk_mul_f32 v[2:3], v[2:3], v[22:23]
	v_pk_mul_f32 v[22:23], v[44:45], v[20:21] op_sel_hi:[1,0]
	v_cvt_pk_bf16_f32 v1, v2, v3
	global_store_dwordx2 v[66:67], v[0:1], off offset:32
	global_load_dwordx4 v[0:3], v[12:13], off offset:96
	s_waitcnt vmcnt(0) lgkmcnt(0)
	v_pk_mul_f32 v[0:1], v[0:1], v[22:23]
	v_pk_mul_f32 v[22:23], v[46:47], v[20:21] op_sel_hi:[1,0]
	v_cvt_pk_bf16_f32 v0, v0, v1
	v_pk_mul_f32 v[2:3], v[2:3], v[22:23]
	s_nop 0
	v_cvt_pk_bf16_f32 v1, v2, v3
	global_store_dwordx2 v[66:67], v[0:1], off offset:48
	global_load_dwordx4 v[0:3], v[12:13], off offset:128
	s_waitcnt vmcnt(0) lgkmcnt(0)
	v_pk_mul_f32 v[0:1], v[0:1], v[16:17]
	v_pk_mul_f32 v[16:17], v[18:19], v[20:21] op_sel_hi:[1,0]
	v_cvt_pk_bf16_f32 v0, v0, v1
	v_pk_mul_f32 v[2:3], v[2:3], v[16:17]
	s_nop 0
	v_cvt_pk_bf16_f32 v1, v2, v3
	global_store_dwordx2 v[66:67], v[0:1], off offset:64
	global_load_dwordx4 v[0:3], v[12:13], off offset:160
	s_waitcnt vmcnt(0) lgkmcnt(0)
	v_pk_mul_f32 v[0:1], v[0:1], v[4:5]
	v_pk_mul_f32 v[4:5], v[6:7], v[20:21] op_sel_hi:[1,0]
	v_cvt_pk_bf16_f32 v0, v0, v1
	v_pk_mul_f32 v[2:3], v[2:3], v[4:5]
	v_pk_mul_f32 v[4:5], v[8:9], v[20:21] op_sel_hi:[1,0]
	v_cvt_pk_bf16_f32 v1, v2, v3
	global_store_dwordx2 v[66:67], v[0:1], off offset:80
	global_load_dwordx4 v[0:3], v[12:13], off offset:192
	s_waitcnt vmcnt(0) lgkmcnt(0)
	v_pk_mul_f32 v[0:1], v[0:1], v[4:5]
	v_pk_mul_f32 v[4:5], v[26:27], v[20:21] op_sel_hi:[1,0]
	v_cvt_pk_bf16_f32 v0, v0, v1
	v_pk_mul_f32 v[2:3], v[2:3], v[4:5]
	v_pk_mul_f32 v[4:5], v[10:11], v[20:21] op_sel_hi:[1,0]
	v_cvt_pk_bf16_f32 v1, v2, v3
	global_store_dwordx2 v[66:67], v[0:1], off offset:96
	global_load_dwordx4 v[0:3], v[12:13], off offset:224
	s_waitcnt vmcnt(0) lgkmcnt(0)
	v_pk_mul_f32 v[0:1], v[0:1], v[4:5]
	v_pk_mul_f32 v[4:5], v[14:15], v[20:21] op_sel_hi:[1,0]
	v_cvt_pk_bf16_f32 v0, v0, v1
	v_pk_mul_f32 v[2:3], v[2:3], v[4:5]
	s_branch .LBB0_898

.LBB0_1006:
	s_mov_b32 s0, -1
	v_readlane_b32 s4, v254, 3
	v_mbcnt_lo_u32_b32 v0, s0, 0
	v_mbcnt_hi_u32_b32 v0, s0, v0
	v_readlane_b32 s0, v252, 5
	s_mov_b32 s31, s7
	v_readlane_b32 s36, v254, 24
	v_add_u32_e32 v4, s0, v0
	s_mov_b64 s[0:1], s[40:41]
	s_add_u32 s26, s0, s4
	s_addc_u32 s27, s1, 0
	s_mov_b64 s[0:1], s[40:41]
	s_add_u32 s28, s0, s4
	s_addc_u32 s29, s1, 0
	s_mov_b64 s[4:5], s[40:41]
	v_readfirstlane_b32 s6, v4
	s_add_u32 s34, s4, s7
	v_ashrrev_i32_e32 v6, 3, v4
	s_addc_u32 s35, s5, 0
	s_ashr_i32 s6, s6, 1
	v_ashrrev_i32_e32 v7, 31, v6
	s_and_b32 s7, s6, 0xffffffe0
	v_lshlrev_b64 v[0:1], 7, v[6:7]
	v_lshlrev_b32_e32 v8, 4, v4
	v_and_b32_e32 v5, 31, v4
	s_add_i32 s7, s7, s36
	v_lshl_add_u64 v[2:3], s[28:29], 0, v[0:1]
	v_and_b32_e32 v64, 0x70, v8
	v_or_b32_e32 v172, s7, v5
	v_lshl_add_u64 v[8:9], v[2:3], 0, v[64:65]
	v_lshlrev_b64 v[2:3], 12, v[6:7]
	s_mov_b32 s7, 0xf800000
	v_lshl_add_u64 v[10:11], s[34:35], 0, v[2:3]
	v_add_co_u32_e32 v14, vcc, s7, v8
	v_lshl_add_u64 v[10:11], v[10:11], 0, v[64:65]
	s_mov_b64 s[28:29], 0x11800000
	v_addc_co_u32_e32 v15, vcc, 0, v9, vcc
	s_mov_b32 s7, 0x11800000
	v_lshl_add_u64 v[12:13], v[10:11], 0, s[28:29]
	v_add_co_u32_e32 v10, vcc, s7, v10
	s_mov_b32 s7, 0xf802000
	s_nop 0
	v_addc_co_u32_e32 v11, vcc, 0, v11, vcc
	v_add_co_u32_e32 v8, vcc, s7, v8
	v_ashrrev_i32_e32 v173, 31, v172
	s_nop 0
	v_addc_co_u32_e32 v9, vcc, 0, v9, vcc
	v_bfe_u32 v184, v4, 5, 1
	s_waitcnt vmcnt(0) lgkmcnt(0)
	global_load_dwordx4 v[98:101], v[14:15], off
	global_load_dwordx4 v[106:109], v[10:11], off
	global_load_dwordx4 v[102:105], v[8:9], off
	global_load_dwordx4 v[110:113], v[12:13], off offset:128
	v_lshlrev_b64 v[8:9], 7, v[172:173]
	v_lshl_add_u64 v[8:9], s[26:27], 0, v[8:9]
	v_lshlrev_b32_e32 v170, 4, v184
	v_mov_b32_e32 v171, v65
	v_lshl_add_u64 v[8:9], v[8:9], 0, v[170:171]
	s_mov_b64 s[26:27], 0xf000000
	s_mov_b32 s7, 0xf000000
	v_lshl_add_u64 v[10:11], v[8:9], 0, s[26:27]
	v_add_co_u32_e32 v8, vcc, s7, v8
	s_movk_i32 s7, 0x90
	s_nop 0
	v_addc_co_u32_e32 v9, vcc, 0, v9, vcc
	global_load_dwordx4 v[114:117], v[10:11], off offset:32
	global_load_dwordx4 v[118:121], v[10:11], off offset:64
	global_load_dwordx4 v[122:125], v[8:9], off
	global_load_dwordx4 v[126:129], v[10:11], off offset:96
	v_mad_u64_u32 v[6:7], s[26:27], v6, s7, v[64:65]
	v_readlane_b32 s26, v253, 33
	v_readlane_b32 s27, v253, 34
	v_add_u32_e32 v173, 0, v6
	s_andn2_b64 vcc, exec, s[26:27]
	s_waitcnt vmcnt(0) lgkmcnt(0)
	ds_write_b128 v173, v[98:101]
	ds_write_b128 v173, v[106:109] offset:18432
	s_waitcnt lgkmcnt(0)
	s_barrier
	s_cbranch_vccnz .LBB0_1031
	s_or_b32 s28, s6, 31
	v_readlane_b32 s6, v254, 23
	s_add_u32 s0, s0, s6
	s_addc_u32 s1, s1, 0
	v_lshl_add_u64 v[176:177], s[0:1], 0, v[0:1]
	s_add_u32 s0, s4, s31
	v_mul_u32_u24_e32 v185, 0x90, v5
	v_mad_u32_u24 v5, v5, s7, 0
	v_lshlrev_b32_e32 v6, 2, v184
	v_and_b32_e32 v4, 7, v4
	s_addc_u32 s1, s5, 0
	v_mov_b32_e32 v64, v65
	v_sub_u32_e32 v187, v172, v6
	v_lshlrev_b32_e32 v174, 4, v4
	v_lshl_add_u64 v[178:179], s[0:1], 0, v[2:3]
	v_mov_b32_e32 v66, v65
	v_mov_b32_e32 v67, v65
	v_mov_b32_e32 v68, v65
	v_mov_b32_e32 v69, v65
	v_mov_b32_e32 v70, v65
	v_mov_b32_e32 v71, v65
	v_mov_b32_e32 v72, v65
	v_mov_b32_e32 v73, v65
	v_mov_b32_e32 v74, v65
	v_mov_b32_e32 v75, v65
	v_mov_b32_e32 v76, v65
	v_mov_b32_e32 v77, v65
	v_mov_b32_e32 v78, v65
	v_mov_b32_e32 v79, v65
	v_add_u32_e32 v188, v5, v170
	v_mov_b64_e32 v[32:33], v[64:65]
	v_mov_b64_e32 v[48:49], v[64:65]
	v_mov_b64_e32 v[0:1], v[64:65]
	v_mov_b64_e32 v[16:17], v[64:65]
	v_lshl_add_u32 v186, v184, 5, 0
	v_mov_b32_e32 v175, v65
	v_mov_b32_e32 v169, 0
	s_mov_b32 s29, 3
	v_readlane_b32 s31, v254, 25
	v_mov_b32_e32 v171, 0
	v_mov_b64_e32 v[34:35], v[66:67]
	v_mov_b64_e32 v[36:37], v[68:69]
	v_mov_b64_e32 v[38:39], v[70:71]
	v_mov_b64_e32 v[40:41], v[72:73]
	v_mov_b64_e32 v[42:43], v[74:75]
	v_mov_b64_e32 v[44:45], v[76:77]
	v_mov_b64_e32 v[46:47], v[78:79]
	v_mov_b64_e32 v[50:51], v[66:67]
	v_mov_b64_e32 v[52:53], v[68:69]
	v_mov_b64_e32 v[54:55], v[70:71]
	v_mov_b64_e32 v[56:57], v[72:73]
	v_mov_b64_e32 v[58:59], v[74:75]
	v_mov_b64_e32 v[60:61], v[76:77]
	v_mov_b64_e32 v[62:63], v[78:79]
	v_mov_b64_e32 v[2:3], v[66:67]
	v_mov_b64_e32 v[4:5], v[68:69]
	v_mov_b64_e32 v[6:7], v[70:71]
	v_mov_b64_e32 v[8:9], v[72:73]
	v_mov_b64_e32 v[10:11], v[74:75]
	v_mov_b64_e32 v[12:13], v[76:77]
	v_mov_b64_e32 v[14:15], v[78:79]
	v_mov_b64_e32 v[18:19], v[66:67]
	v_mov_b64_e32 v[20:21], v[68:69]
	v_mov_b64_e32 v[22:23], v[70:71]
	v_mov_b64_e32 v[24:25], v[72:73]
	v_mov_b64_e32 v[26:27], v[74:75]
	v_mov_b64_e32 v[28:29], v[76:77]
	v_mov_b64_e32 v[30:31], v[78:79]
	v_readlane_b32 s6, v253, 31
	s_branch .LBB0_1009

.LBB0_1009:
	s_add_i32 s26, s29, -1
	s_cmp_lt_i32 s26, s6
	v_lshl_add_u64 v[182:183], v[176:177], 0, v[174:175]
	v_lshl_add_u64 v[180:181], v[178:179], 0, v[174:175]
	s_cbranch_scc0 .LBB0_1011
	v_add_co_u32_e32 v66, vcc, 0xf804000, v182
	s_nop 1
	v_addc_co_u32_e32 v67, vcc, 0, v183, vcc
	global_load_dwordx4 v[98:101], v[66:67], off
	v_add_co_u32_e32 v66, vcc, 0x11800000, v180
	s_nop 1
	v_addc_co_u32_e32 v67, vcc, 0, v181, vcc
	global_load_dwordx4 v[106:109], v[66:67], off offset:256

.LBB0_1017:
	s_add_i32 s0, s29, -3
	v_readlane_b32 s1, v253, 36
	s_cmp_ge_i32 s0, s1
	s_cbranch_scc1 .LBB0_1019
	s_add_i32 s0, s29, -1
	s_cmp_ge_i32 s0, s6
	s_cbranch_scc1 .Lvm0_dif_a
	s_waitcnt vmcnt(2)
	s_branch .Lvm1_dif_a

.Lvm1_dif_a:
	ds_write_b128 v173, v[102:105] offset:9216
	ds_write_b128 v173, v[110:113] offset:27648
.LBB0_1019:
	s_cmp_ge_i32 s29, s6
	s_waitcnt lgkmcnt(0)
	s_barrier
	s_cbranch_scc1 .LBB0_1021
	v_add_co_u32_e32 v66, vcc, 0xf806000, v182
	s_nop 1
	v_addc_co_u32_e32 v67, vcc, 0, v183, vcc
	global_load_dwordx4 v[102:105], v[66:67], off
	v_add_co_u32_e32 v66, vcc, 0x11800000, v180
	s_nop 1
	v_addc_co_u32_e32 v67, vcc, 0, v181, vcc
	global_load_dwordx4 v[110:113], v[66:67], off offset:384

.LBB0_1027:
	s_add_i32 s0, s29, -2
	v_readlane_b32 s1, v253, 36
	s_cmp_ge_i32 s0, s1
	s_cbranch_scc1 .LBB0_1008
	s_cmp_ge_i32 s29, s6
	s_cbranch_scc1 .Lvm0_dif_b
	s_waitcnt vmcnt(2)
	s_branch .Lvm1_dif_b

.Lvm1_dif_b:
	ds_write_b128 v173, v[98:101]
	ds_write_b128 v173, v[106:109] offset:18432
	s_branch .LBB0_1008

.LBB0_1033:
	s_mov_b64 s[6:7], s[8:9]
	s_add_u32 s6, s6, s2
	s_addc_u32 s7, s7, s3
	s_add_u32 s6, s6, s4
	s_addc_u32 s7, s7, s5
	v_mov_b64_e32 v[68:69], s[6:7]
	s_mov_b64 s[6:7], s[10:11]
	global_load_dword v69, v[68:69], off
	s_add_u32 s6, s6, s2
	s_addc_u32 s7, s7, s3
	s_add_u32 s6, s6, s4
	s_addc_u32 s7, s7, s5
	v_mov_b64_e32 v[70:71], s[6:7]
	s_mov_b64 s[6:7], s[12:13]
	global_load_dword v71, v[70:71], off
	s_add_u32 s6, s6, s2
	s_addc_u32 s7, s7, s3
	s_add_u32 s6, s6, s4
	s_addc_u32 s7, s7, s5
	v_mov_b64_e32 v[72:73], s[6:7]
	s_mov_b64 s[6:7], s[14:15]
	global_load_dword v68, v[72:73], off
	s_add_u32 s6, s6, s2
	s_addc_u32 s7, s7, s3
	s_add_u32 s6, s6, s4
	s_addc_u32 s7, s7, s5
	v_mov_b64_e32 v[72:73], s[6:7]
	global_load_dword v70, v[72:73], off
	s_mov_b64 s[6:7], s[8:9]
	s_add_u32 s6, s6, s2
	s_addc_u32 s7, s7, s3
	s_add_u32 s6, s6, s4
	s_addc_u32 s7, s7, s5
	s_waitcnt vmcnt(0) lgkmcnt(0)
	v_pk_fma_f32 v[66:67], v[68:69], v[70:71], v[66:67]
	v_mov_b64_e32 v[68:69], s[6:7]
	s_mov_b64 s[6:7], s[10:11]
	global_load_dword v69, v[68:69], off offset:4
	s_add_u32 s6, s6, s2
	s_addc_u32 s7, s7, s3
	s_add_u32 s6, s6, s4
	s_addc_u32 s7, s7, s5
	v_mov_b64_e32 v[70:71], s[6:7]
	s_mov_b64 s[6:7], s[12:13]
	global_load_dword v71, v[70:71], off offset:4
	s_add_u32 s6, s6, s2
	s_addc_u32 s7, s7, s3
	s_add_u32 s6, s6, s4
	s_addc_u32 s7, s7, s5
	v_mov_b64_e32 v[72:73], s[6:7]
	s_mov_b64 s[6:7], s[14:15]
	global_load_dword v68, v[72:73], off offset:4
	s_add_u32 s6, s6, s2
	s_addc_u32 s7, s7, s3
	s_add_u32 s6, s6, s4
	s_addc_u32 s7, s7, s5
	v_mov_b64_e32 v[72:73], s[6:7]
	global_load_dword v70, v[72:73], off offset:4
	s_mov_b64 s[6:7], s[8:9]
	s_add_u32 s6, s6, s2
	s_addc_u32 s7, s7, s3
	s_add_u32 s6, s6, s4
	s_addc_u32 s7, s7, s5
	s_waitcnt vmcnt(0) lgkmcnt(0)
	v_pk_fma_f32 v[66:67], v[68:69], v[70:71], v[66:67]
	v_mov_b64_e32 v[68:69], s[6:7]
	s_mov_b64 s[6:7], s[10:11]
	global_load_dword v69, v[68:69], off offset:8
	s_add_u32 s6, s6, s2
	s_addc_u32 s7, s7, s3
	s_add_u32 s6, s6, s4
	s_addc_u32 s7, s7, s5
	v_mov_b64_e32 v[70:71], s[6:7]
	s_mov_b64 s[6:7], s[12:13]
	global_load_dword v71, v[70:71], off offset:8
	s_add_u32 s6, s6, s2
	s_addc_u32 s7, s7, s3
	s_add_u32 s6, s6, s4
	s_addc_u32 s7, s7, s5
	v_mov_b64_e32 v[72:73], s[6:7]
	s_mov_b64 s[6:7], s[14:15]
	global_load_dword v68, v[72:73], off offset:8
	s_add_u32 s6, s6, s2
	s_addc_u32 s7, s7, s3
	s_add_u32 s6, s6, s4
	s_addc_u32 s7, s7, s5
	v_mov_b64_e32 v[72:73], s[6:7]
	global_load_dword v70, v[72:73], off offset:8
	s_mov_b64 s[6:7], s[8:9]
	s_add_u32 s6, s6, s2
	s_addc_u32 s7, s7, s3
	s_add_u32 s6, s6, s4
	s_addc_u32 s7, s7, s5
	s_waitcnt vmcnt(0) lgkmcnt(0)
	v_pk_fma_f32 v[66:67], v[68:69], v[70:71], v[66:67]
	v_mov_b64_e32 v[68:69], s[6:7]
	s_mov_b64 s[6:7], s[10:11]
	global_load_dword v69, v[68:69], off offset:12
	s_add_u32 s6, s6, s2
	s_addc_u32 s7, s7, s3
	s_add_u32 s6, s6, s4
	s_addc_u32 s7, s7, s5
	v_mov_b64_e32 v[70:71], s[6:7]
	s_mov_b64 s[6:7], s[12:13]
	global_load_dword v71, v[70:71], off offset:12
	s_add_u32 s6, s6, s2
	s_addc_u32 s7, s7, s3
	s_add_u32 s6, s6, s4
	s_addc_u32 s7, s7, s5
	v_mov_b64_e32 v[72:73], s[6:7]
	s_mov_b64 s[6:7], s[14:15]
	global_load_dword v68, v[72:73], off offset:12
	s_add_u32 s6, s6, s2
	s_addc_u32 s7, s7, s3
	s_add_u32 s6, s6, s4
	s_addc_u32 s7, s7, s5
	v_mov_b64_e32 v[72:73], s[6:7]
	global_load_dword v70, v[72:73], off offset:12
	s_add_u32 s4, s4, 16
	s_addc_u32 s5, s5, 0
	s_cmpk_lg_i32 s4, 0x80
	s_waitcnt vmcnt(0) lgkmcnt(0)
	v_pk_fma_f32 v[66:67], v[68:69], v[70:71], v[66:67]
	s_cbranch_scc1 .LBB0_1033
	v_readlane_b32 s4, v253, 35
	v_mul_f32_e32 v64, 0x3fb8aa3b, v67
	v_rndne_f32_e32 v70, v64
	v_add_u32_e32 v68, s4, v172
	v_ashrrev_i32_e32 v69, 31, v68
	v_lshlrev_b64 v[68:69], 11, v[68:69]
	v_lshl_add_u64 v[68:69], s[0:1], 0, v[68:69]
	v_readlane_b32 s0, v254, 41
	v_readlane_b32 s1, v254, 42
	s_mov_b32 s4, s0
	v_readlane_b32 s0, v254, 43
	v_readlane_b32 s1, v254, 44
	s_mov_b32 s5, s1
	s_mov_b32 s0, s4
	v_lshl_add_u64 v[68:69], v[68:69], 0, s[4:5]
	s_mov_b32 s4, 0x3fb8aa3b
	v_sub_f32_e32 v71, v64, v70
	v_fma_f32 v64, v67, s4, -v64
	v_fmac_f32_e32 v64, 0x32a5705f, v67
	v_add_f32_e32 v64, v71, v64
	v_exp_f32_e32 v64, v64
	v_cvt_i32_f32_e32 v70, v70
	v_writelane_b32 v254, s0, 41
	v_mov_b32_e32 v72, 0x7f800000
	v_and_b32_e32 v192, 64, v197
	v_writelane_b32 v254, s1, 42
	s_mov_b32 s0, 0xc2ce8ed0
	v_ldexp_f32 v64, v64, v70
	v_cmp_ngt_f32_e32 vcc, s0, v67
	s_mov_b32 s1, 0x42b17218
	s_mov_b32 s31, 2
	v_cndmask_b32_e32 v64, 0, v64, vcc
	v_cmp_nlt_f32_e32 vcc, s1, v67
	v_mul_f32_e32 v67, 0x3fb8aa3b, v66
	v_rndne_f32_e32 v70, v67
	v_sub_f32_e32 v71, v67, v70
	v_fma_f32 v67, v66, s4, -v67
	v_fmac_f32_e32 v67, 0x32a5705f, v66
	v_add_f32_e32 v67, v71, v67
	v_exp_f32_e32 v67, v67
	v_cvt_i32_f32_e32 v70, v70
	v_cndmask_b32_e32 v64, v72, v64, vcc
	v_cmp_ngt_f32_e32 vcc, s0, v66
	v_readlane_b32 s4, v255, 10
	v_ldexp_f32 v67, v67, v70
	v_cndmask_b32_e32 v67, 0, v67, vcc
	v_cmp_nlt_f32_e32 vcc, s1, v66
	v_readlane_b32 s5, v255, 11
	s_lshl_b64 s[4:5], s[4:5], 2
	v_cndmask_b32_e32 v66, v72, v67, vcc
	v_sub_f32_e32 v66, v64, v66
	v_xor_b32_e32 v64, 32, v197
	v_add_u32_e32 v67, 64, v192
	v_cmp_lt_i32_e32 vcc, v64, v67
	s_nop 1
	v_cndmask_b32_e32 v64, v197, v64, vcc
	v_lshlrev_b32_e32 v193, 2, v64
	ds_bpermute_b32 v64, v193, v171
	s_waitcnt lgkmcnt(0)
	v_add_f32_e32 v64, v171, v64
	v_div_scale_f32 v67, s[0:1], v64, v64, 1.0
	v_rcp_f32_e32 v70, v67
	v_mov_b32_e32 v171, v65
	v_fma_f32 v71, -v67, v70, 1.0
	v_fmac_f32_e32 v70, v71, v70
	v_div_scale_f32 v71, vcc, 1.0, v64, 1.0
	v_mul_f32_e32 v72, v71, v70
	v_fma_f32 v73, -v67, v72, v71
	v_fmac_f32_e32 v72, v73, v70
	v_fma_f32 v67, -v67, v72, v71
	v_div_fmas_f32 v67, v67, v70, v72
	v_div_fixup_f32 v70, v67, v64, 1.0
	ds_bpermute_b32 v67, v193, v169
	s_waitcnt lgkmcnt(0)
	v_pk_add_f32 v[66:67], v[168:169], v[66:67]
	s_nop 0
	v_div_scale_f32 v64, s[0:1], v67, v67, v66
	v_rcp_f32_e32 v71, v64
	s_mov_b64 s[0:1], s[16:17]
	s_add_u32 s0, s0, s4
	v_fma_f32 v72, -v64, v71, 1.0
	v_fmac_f32_e32 v71, v72, v71
	v_div_scale_f32 v72, vcc, v66, v67, v66
	v_mul_f32_e32 v73, v72, v71
	v_fma_f32 v74, -v64, v73, v72
	v_fmac_f32_e32 v73, v74, v71
	v_fma_f32 v64, -v64, v73, v72
	v_div_fmas_f32 v64, v64, v71, v73
	v_div_fixup_f32 v72, v64, v67, v66
	v_pk_mul_f32 v[42:43], v[42:43], v[72:73] op_sel_hi:[1,0]
	s_addc_u32 s1, s1, s5
	v_pk_fma_f32 v[66:67], v[10:11], v[70:71], v[42:43] op_sel_hi:[1,0,1] neg_lo:[0,0,1] neg_hi:[0,0,1]
	v_pk_mul_f32 v[10:11], v[44:45], v[72:73] op_sel_hi:[1,0]
	v_pk_mul_f32 v[48:49], v[48:49], v[72:73] op_sel_hi:[1,0]
	v_pk_fma_f32 v[42:43], v[12:13], v[70:71], v[10:11] op_sel_hi:[1,0,1] neg_lo:[0,0,1] neg_hi:[0,0,1]
	v_pk_mul_f32 v[10:11], v[46:47], v[72:73] op_sel_hi:[1,0]
	v_pk_mul_f32 v[50:51], v[50:51], v[72:73] op_sel_hi:[1,0]
	v_pk_fma_f32 v[10:11], v[14:15], v[70:71], v[10:11] op_sel_hi:[1,0,1] neg_lo:[0,0,1] neg_hi:[0,0,1]
	v_lshl_add_u64 v[14:15], s[0:1], 0, v[170:171]
	global_load_dwordx4 v[44:47], v[14:15], off
	v_pk_fma_f32 v[16:17], v[16:17], v[70:71], v[48:49] op_sel_hi:[1,0,1] neg_lo:[0,0,1] neg_hi:[0,0,1]
	v_pk_fma_f32 v[18:19], v[18:19], v[70:71], v[50:51] op_sel_hi:[1,0,1] neg_lo:[0,0,1] neg_hi:[0,0,1]
	v_pk_mul_f32 v[48:49], v[16:17], v[16:17]
	v_pk_mul_f32 v[50:51], v[18:19], v[18:19]
	v_pk_mul_f32 v[52:53], v[52:53], v[72:73] op_sel_hi:[1,0]
	v_add_f32_e32 v48, v48, v49
	v_pk_fma_f32 v[20:21], v[20:21], v[70:71], v[52:53] op_sel_hi:[1,0,1] neg_lo:[0,0,1] neg_hi:[0,0,1]
	v_add_f32_e32 v48, v50, v48
	v_pk_mul_f32 v[54:55], v[54:55], v[72:73] op_sel_hi:[1,0]
	v_pk_mul_f32 v[52:53], v[20:21], v[20:21]
	v_add_f32_e32 v48, v51, v48
	v_pk_fma_f32 v[22:23], v[22:23], v[70:71], v[54:55] op_sel_hi:[1,0,1] neg_lo:[0,0,1] neg_hi:[0,0,1]
	v_add_f32_e32 v48, v52, v48
	v_pk_mul_f32 v[54:55], v[22:23], v[22:23]
	v_pk_mul_f32 v[56:57], v[56:57], v[72:73] op_sel_hi:[1,0]
	v_add_f32_e32 v48, v53, v48
	v_pk_fma_f32 v[24:25], v[24:25], v[70:71], v[56:57] op_sel_hi:[1,0,1] neg_lo:[0,0,1] neg_hi:[0,0,1]
	v_add_f32_e32 v48, v54, v48
	v_pk_mul_f32 v[58:59], v[58:59], v[72:73] op_sel_hi:[1,0]
	v_pk_mul_f32 v[56:57], v[24:25], v[24:25]
	v_add_f32_e32 v48, v55, v48
	v_pk_fma_f32 v[26:27], v[26:27], v[70:71], v[58:59] op_sel_hi:[1,0,1] neg_lo:[0,0,1] neg_hi:[0,0,1]
	v_add_f32_e32 v48, v56, v48
	v_pk_mul_f32 v[58:59], v[26:27], v[26:27]
	v_pk_mul_f32 v[60:61], v[60:61], v[72:73] op_sel_hi:[1,0]
	v_add_f32_e32 v48, v57, v48
	v_pk_fma_f32 v[28:29], v[28:29], v[70:71], v[60:61] op_sel_hi:[1,0,1] neg_lo:[0,0,1] neg_hi:[0,0,1]
	v_add_f32_e32 v48, v58, v48
	v_pk_mul_f32 v[62:63], v[62:63], v[72:73] op_sel_hi:[1,0]
	v_pk_mul_f32 v[60:61], v[28:29], v[28:29]
	v_add_f32_e32 v48, v59, v48
	v_pk_fma_f32 v[30:31], v[30:31], v[70:71], v[62:63] op_sel_hi:[1,0,1] neg_lo:[0,0,1] neg_hi:[0,0,1]
	v_add_f32_e32 v48, v60, v48
	v_pk_mul_f32 v[62:63], v[30:31], v[30:31]
	v_pk_mul_f32 v[32:33], v[32:33], v[72:73] op_sel_hi:[1,0]
	v_add_f32_e32 v48, v61, v48
	v_pk_fma_f32 v[32:33], v[0:1], v[70:71], v[32:33] op_sel_hi:[1,0,1] neg_lo:[0,0,1] neg_hi:[0,0,1]
	v_add_f32_e32 v48, v62, v48
	v_pk_mul_f32 v[34:35], v[34:35], v[72:73] op_sel_hi:[1,0]
	v_pk_mul_f32 v[0:1], v[32:33], v[32:33]
	v_add_f32_e32 v48, v63, v48
	v_pk_fma_f32 v[34:35], v[2:3], v[70:71], v[34:35] op_sel_hi:[1,0,1] neg_lo:[0,0,1] neg_hi:[0,0,1]
	v_add_f32_e32 v0, v0, v48
	v_pk_mul_f32 v[2:3], v[34:35], v[34:35]
	v_pk_mul_f32 v[36:37], v[36:37], v[72:73] op_sel_hi:[1,0]
	v_add_f32_e32 v0, v1, v0
	v_pk_fma_f32 v[4:5], v[4:5], v[70:71], v[36:37] op_sel_hi:[1,0,1] neg_lo:[0,0,1] neg_hi:[0,0,1]
	v_add_f32_e32 v0, v2, v0
	v_pk_mul_f32 v[38:39], v[38:39], v[72:73] op_sel_hi:[1,0]
	v_pk_mul_f32 v[36:37], v[4:5], v[4:5]
	v_add_f32_e32 v0, v3, v0
	v_pk_fma_f32 v[6:7], v[6:7], v[70:71], v[38:39] op_sel_hi:[1,0,1] neg_lo:[0,0,1] neg_hi:[0,0,1]
	v_add_f32_e32 v0, v36, v0
	v_pk_mul_f32 v[38:39], v[6:7], v[6:7]
	v_pk_mul_f32 v[40:41], v[40:41], v[72:73] op_sel_hi:[1,0]
	v_add_f32_e32 v0, v37, v0
	v_pk_fma_f32 v[8:9], v[8:9], v[70:71], v[40:41] op_sel_hi:[1,0,1] neg_lo:[0,0,1] neg_hi:[0,0,1]
	v_add_f32_e32 v0, v38, v0
	v_pk_mul_f32 v[40:41], v[8:9], v[8:9]
	v_add_f32_e32 v0, v39, v0
	v_add_f32_e32 v0, v40, v0
	v_pk_mul_f32 v[74:75], v[66:67], v[66:67]
	v_add_f32_e32 v0, v41, v0
	v_add_f32_e32 v0, v74, v0
	v_pk_mul_f32 v[76:77], v[42:43], v[42:43]
	v_add_f32_e32 v0, v75, v0
	v_add_f32_e32 v0, v76, v0
	v_pk_mul_f32 v[78:79], v[10:11], v[10:11]
	v_add_f32_e32 v0, v77, v0
	v_add_f32_e32 v0, v78, v0
	v_add_f32_e32 v0, v79, v0
	ds_bpermute_b32 v1, v193, v0
	v_lshlrev_b32_e32 v64, 3, v184
	v_lshl_add_u64 v[68:69], v[68:69], 0, v[64:65]
	s_mov_b64 s[0:1], 0x6000300
	v_lshl_add_u64 v[12:13], v[68:69], 0, s[0:1]
	s_waitcnt lgkmcnt(0)
	v_add_f32_e32 v0, v0, v1
	v_fmamk_f32 v0, v0, 0x3c800000, v194
	s_mov_b32 s0, 0xf800000
	v_cmp_gt_f32_e32 vcc, s0, v0
	v_mul_f32_e32 v1, 0x4f800000, v0
	s_nop 0
	v_cndmask_b32_e32 v0, v0, v1, vcc
	v_sqrt_f32_e32 v1, v0
	s_nop 0
	v_add_u32_e32 v2, -1, v1
	v_fma_f32 v3, -v2, v1, v0
	v_cmp_ge_f32_e64 s[0:1], 0, v3
	v_add_u32_e32 v3, 1, v1
	s_nop 0
	v_cndmask_b32_e64 v2, v1, v2, s[0:1]
	v_fma_f32 v1, -v3, v1, v0
	v_cmp_lt_f32_e64 s[0:1], 0, v1
	s_nop 1
	v_cndmask_b32_e64 v1, v2, v3, s[0:1]
	v_mul_f32_e32 v2, 0x37800000, v1
	v_cndmask_b32_e32 v1, v1, v2, vcc
	v_cmp_class_f32_e32 vcc, v0, v195
	s_nop 1
	v_cndmask_b32_e32 v0, v1, v0, vcc
	v_div_scale_f32 v1, s[0:1], v0, v0, v163
	v_rcp_f32_e32 v2, v1
	s_mov_b32 s0, 0x6000000
	v_fma_f32 v3, -v1, v2, 1.0
	v_fmac_f32_e32 v2, v3, v2
	v_div_scale_f32 v3, vcc, v163, v0, v163
	v_mul_f32_e32 v36, v3, v2
	v_fma_f32 v37, -v1, v36, v3
	v_fmac_f32_e32 v36, v37, v2
	v_fma_f32 v1, -v1, v36, v3
	v_div_fmas_f32 v1, v1, v2, v36
	v_div_fixup_f32 v36, v1, v0, v163
	v_pk_mul_f32 v[0:1], v[16:17], v[36:37] op_sel_hi:[1,0]
	v_pk_mul_f32 v[2:3], v[18:19], v[36:37] op_sel_hi:[1,0]
	s_waitcnt vmcnt(0)
	v_pk_mul_f32 v[0:1], v[44:45], v[0:1]
	v_pk_mul_f32 v[2:3], v[46:47], v[2:3]
	v_cvt_pk_bf16_f32 v0, v0, v1
	v_cvt_pk_bf16_f32 v1, v2, v3
	v_add_co_u32_e32 v2, vcc, s0, v68
	v_pk_mul_f32 v[16:17], v[20:21], v[36:37] op_sel_hi:[1,0]
	s_nop 0
	v_addc_co_u32_e32 v3, vcc, 0, v69, vcc
	global_store_dwordx2 v[2:3], v[0:1], off offset:768
	global_load_dwordx4 v[0:3], v[14:15], off offset:32
	v_pk_mul_f32 v[4:5], v[4:5], v[36:37] op_sel_hi:[1,0]
	s_waitcnt vmcnt(0) lgkmcnt(0)
	v_pk_mul_f32 v[0:1], v[0:1], v[16:17]
	v_pk_mul_f32 v[16:17], v[22:23], v[36:37] op_sel_hi:[1,0]
	v_cvt_pk_bf16_f32 v0, v0, v1
	v_pk_mul_f32 v[2:3], v[2:3], v[16:17]
	v_pk_mul_f32 v[16:17], v[24:25], v[36:37] op_sel_hi:[1,0]
	v_cvt_pk_bf16_f32 v1, v2, v3
	global_store_dwordx2 v[12:13], v[0:1], off offset:16
	global_load_dwordx4 v[0:3], v[14:15], off offset:64
	s_waitcnt vmcnt(0) lgkmcnt(0)
	v_pk_mul_f32 v[0:1], v[0:1], v[16:17]
	v_pk_mul_f32 v[16:17], v[26:27], v[36:37] op_sel_hi:[1,0]
	v_cvt_pk_bf16_f32 v0, v0, v1
	v_pk_mul_f32 v[2:3], v[2:3], v[16:17]
	v_pk_mul_f32 v[16:17], v[28:29], v[36:37] op_sel_hi:[1,0]
	v_cvt_pk_bf16_f32 v1, v2, v3
	global_store_dwordx2 v[12:13], v[0:1], off offset:32
	global_load_dwordx4 v[0:3], v[14:15], off offset:96
	s_waitcnt vmcnt(0) lgkmcnt(0)
	v_pk_mul_f32 v[0:1], v[0:1], v[16:17]
	v_pk_mul_f32 v[16:17], v[30:31], v[36:37] op_sel_hi:[1,0]
	v_cvt_pk_bf16_f32 v0, v0, v1
	v_pk_mul_f32 v[2:3], v[2:3], v[16:17]
	v_pk_mul_f32 v[16:17], v[32:33], v[36:37] op_sel_hi:[1,0]
	v_cvt_pk_bf16_f32 v1, v2, v3
	global_store_dwordx2 v[12:13], v[0:1], off offset:48
	global_load_dwordx4 v[0:3], v[14:15], off offset:128
	s_waitcnt vmcnt(0) lgkmcnt(0)
	v_pk_mul_f32 v[0:1], v[0:1], v[16:17]
	v_pk_mul_f32 v[16:17], v[34:35], v[36:37] op_sel_hi:[1,0]
	v_cvt_pk_bf16_f32 v0, v0, v1
	v_pk_mul_f32 v[2:3], v[2:3], v[16:17]
	s_nop 0
	v_cvt_pk_bf16_f32 v1, v2, v3
	global_store_dwordx2 v[12:13], v[0:1], off offset:64
	global_load_dwordx4 v[0:3], v[14:15], off offset:160
	s_waitcnt vmcnt(0) lgkmcnt(0)
	v_pk_mul_f32 v[0:1], v[0:1], v[4:5]
	v_pk_mul_f32 v[4:5], v[6:7], v[36:37] op_sel_hi:[1,0]
	v_cvt_pk_bf16_f32 v0, v0, v1
	v_pk_mul_f32 v[2:3], v[2:3], v[4:5]
	v_pk_mul_f32 v[4:5], v[8:9], v[36:37] op_sel_hi:[1,0]
	v_cvt_pk_bf16_f32 v1, v2, v3
	global_store_dwordx2 v[12:13], v[0:1], off offset:80
	global_load_dwordx4 v[0:3], v[14:15], off offset:192
	s_waitcnt vmcnt(0) lgkmcnt(0)
	v_pk_mul_f32 v[0:1], v[0:1], v[4:5]
	v_pk_mul_f32 v[4:5], v[66:67], v[36:37] op_sel_hi:[1,0]
	v_cvt_pk_bf16_f32 v0, v0, v1
	v_pk_mul_f32 v[2:3], v[2:3], v[4:5]
	v_pk_mul_f32 v[4:5], v[42:43], v[36:37] op_sel_hi:[1,0]
	v_cvt_pk_bf16_f32 v1, v2, v3
	global_store_dwordx2 v[12:13], v[0:1], off offset:96
	global_load_dwordx4 v[0:3], v[14:15], off offset:224
	s_waitcnt vmcnt(0) lgkmcnt(0)
	v_pk_mul_f32 v[0:1], v[0:1], v[4:5]
	v_pk_mul_f32 v[4:5], v[10:11], v[36:37] op_sel_hi:[1,0]
	v_cvt_pk_bf16_f32 v0, v0, v1
	v_pk_mul_f32 v[2:3], v[2:3], v[4:5]
	s_nop 0
	v_cvt_pk_bf16_f32 v1, v2, v3
	global_store_dwordx2 v[12:13], v[0:1], off offset:112
	s_branch .LBB0_1037
.LBB0_1035:
	v_lshl_add_u32 v32, s67, 11, v130
	v_ashrrev_i32_e32 v33, 31, v32
	s_mov_b64 s[0:1], s[40:41]
	v_lshlrev_b64 v[32:33], 11, v[32:33]
	s_lshl_b32 s26, s66, 7
	v_lshl_add_u64 v[32:33], s[0:1], 0, v[32:33]
	v_lshl_add_u64 v[34:35], v[32:33], 0, s[26:27]
	ds_bpermute_b32 v32, v193, v140
	s_mov_b32 s1, s27
	v_writelane_b32 v254, s0, 43
	v_lshlrev_b32_e32 v64, 1, v131
	v_readlane_b32 s92, v252, 6
	s_waitcnt lgkmcnt(0)
	v_add_f32_e32 v32, v140, v32
	v_writelane_b32 v254, s1, 44
	v_div_scale_f32 v33, s[0:1], v32, v32, 1.0
	v_rcp_f32_e32 v36, v33
	s_mov_b64 s[0:1], 0x6000000
	v_readlane_b32 s93, v252, 7
	v_fma_f32 v37, -v33, v36, 1.0
	v_fmac_f32_e32 v36, v37, v36
	v_div_scale_f32 v37, vcc, 1.0, v32, 1.0
	v_mul_f32_e32 v38, v37, v36
	v_fma_f32 v39, -v33, v38, v37
	v_fmac_f32_e32 v38, v39, v36
	v_fma_f32 v33, -v33, v38, v37
	v_div_fmas_f32 v33, v33, v36, v38
	v_div_fixup_f32 v32, v33, v32, 1.0
	v_lshl_add_u64 v[36:37], v[34:35], 0, v[64:65]
	v_lshl_add_u64 v[34:35], v[36:37], 0, s[0:1]
	v_pk_mul_f32 v[0:1], v[0:1], v[32:33] op_sel_hi:[1,0]
	v_pk_mul_f32 v[2:3], v[2:3], v[32:33] op_sel_hi:[1,0]
	s_mov_b32 s0, 0x6000000
	v_cvt_pk_bf16_f32 v0, v0, v1
	v_cvt_pk_bf16_f32 v1, v2, v3
	v_add_co_u32_e32 v2, vcc, s0, v36
	s_nop 1
	v_addc_co_u32_e32 v3, vcc, 0, v37, vcc
	global_store_dwordx2 v[2:3], v[0:1], off
	v_pk_mul_f32 v[0:1], v[4:5], v[32:33] op_sel_hi:[1,0]
	v_pk_mul_f32 v[2:3], v[6:7], v[32:33] op_sel_hi:[1,0]
	v_cvt_pk_bf16_f32 v0, v0, v1
	v_cvt_pk_bf16_f32 v1, v2, v3
	global_store_dwordx2 v[34:35], v[0:1], off offset:16
	v_pk_mul_f32 v[0:1], v[8:9], v[32:33] op_sel_hi:[1,0]
	v_pk_mul_f32 v[2:3], v[10:11], v[32:33] op_sel_hi:[1,0]
	v_cvt_pk_bf16_f32 v0, v0, v1
	v_cvt_pk_bf16_f32 v1, v2, v3
	global_store_dwordx2 v[34:35], v[0:1], off offset:32
	v_pk_mul_f32 v[0:1], v[12:13], v[32:33] op_sel_hi:[1,0]
	v_pk_mul_f32 v[36:37], v[14:15], v[32:33] op_sel_hi:[1,0]
	v_cvt_pk_bf16_f32 v0, v0, v1
.LBB0_1036:
	v_mov_b32_e32 v33, v32
	v_cvt_pk_bf16_f32 v1, v36, v37
	global_store_dwordx2 v[34:35], v[0:1], off offset:48
	v_pk_mul_f32 v[0:1], v[16:17], v[32:33]
	v_pk_mul_f32 v[2:3], v[18:19], v[32:33]
	v_cvt_pk_bf16_f32 v0, v0, v1
	v_cvt_pk_bf16_f32 v1, v2, v3
	global_store_dwordx2 v[34:35], v[0:1], off offset:64
	v_pk_mul_f32 v[0:1], v[20:21], v[32:33]
	v_pk_mul_f32 v[2:3], v[22:23], v[32:33]
	v_cvt_pk_bf16_f32 v0, v0, v1
	v_cvt_pk_bf16_f32 v1, v2, v3
	global_store_dwordx2 v[34:35], v[0:1], off offset:80
	v_pk_mul_f32 v[0:1], v[24:25], v[32:33]
	v_pk_mul_f32 v[2:3], v[26:27], v[32:33]
	v_cvt_pk_bf16_f32 v0, v0, v1
	v_cvt_pk_bf16_f32 v1, v2, v3
	global_store_dwordx2 v[34:35], v[0:1], off offset:96
	v_pk_mul_f32 v[0:1], v[28:29], v[32:33]
	v_pk_mul_f32 v[2:3], v[30:31], v[32:33]
	v_cvt_pk_bf16_f32 v0, v0, v1
	v_cvt_pk_bf16_f32 v1, v2, v3
	global_store_dwordx2 v[34:35], v[0:1], off offset:112
	v_sub_co_u32_e64 v0, s[0:1], s31, 1
	s_nop 0
	v_readfirstlane_b32 s31, v0
	s_and_b64 vcc, exec, s[0:1]
	s_cbranch_vccnz .LBB0_1089
.LBB0_1037:
	s_mul_i32 s0, s31, 5
	s_lshr_b32 s0, s30, s0
	s_bfe_u32 s26, s0, 0x30002
	s_lshl_b32 s0, s0, 5
	s_and_b32 s0, s0, 0x60
	v_readlane_b32 s1, v254, 22
	s_or_b32 s4, s0, s1
	s_cmp_gt_u32 s4, 47
	s_mov_b64 s[0:1], -1
	s_cbranch_scc0 .LBB0_1053
	s_mov_b32 s5, -1
	s_sub_i32 s0, s4, 48
	v_mbcnt_lo_u32_b32 v0, s5, 0
	v_mbcnt_hi_u32_b32 v0, s5, v0
	v_readlane_b32 s5, v252, 5
	s_mul_hi_u32 s1, s0, 0xaaaaaaab
	s_mov_b64 s[6:7], s[40:41]
	v_add_u32_e32 v8, s5, v0
	s_lshr_b32 s1, s1, 2
	s_lshl_b32 s27, s0, 18
	v_readlane_b32 s34, v254, 43
	s_add_u32 s6, s6, s27
	v_readlane_b32 s35, v254, 44
	s_addc_u32 s7, s7, 0
	s_mov_b32 s39, s35
	s_lshl_b32 s38, s1, 17
	s_mov_b64 s[28:29], s[40:41]
	s_lshl_b64 s[34:35], s[38:39], 1
	s_mov_b64 s[36:37], s[40:41]
	s_mul_i32 s38, s1, 0x160000
	s_mov_b32 s43, s39
	s_lshl_b64 s[38:39], s[38:39], 1
	v_readfirstlane_b32 s5, v8
	s_add_u32 s36, s36, s38
	s_addc_u32 s37, s37, s39
	s_ashr_i32 s27, s5, 1
	s_lshl_b32 s33, s26, 8
	s_and_b32 s5, s27, 0xffffffe0
	s_add_i32 s5, s5, s33
	s_lshl_b32 s38, s26, 2
	v_ashrrev_i32_e32 v0, 3, v8
	v_ashrrev_i32_e32 v1, 31, v0
	s_add_u32 s28, s28, s34
	v_lshlrev_b64 v[2:3], 7, v[0:1]
	v_lshlrev_b32_e32 v4, 4, v8
	s_addc_u32 s29, s29, s35
	v_and_b32_e32 v64, 0x70, v4
	v_lshl_add_u64 v[132:133], s[28:29], 0, v[2:3]
	v_lshl_add_u64 v[2:3], v[132:133], 0, v[64:65]
	v_lshlrev_b64 v[4:5], 12, v[0:1]
	s_mov_b32 s28, 0x10c00000
	v_lshl_add_u64 v[134:135], s[36:37], 0, v[4:5]
	v_add_co_u32_e32 v6, vcc, s28, v2
	v_lshl_add_u64 v[4:5], v[134:135], 0, v[64:65]
	s_nop 0
	v_addc_co_u32_e32 v7, vcc, 0, v3, vcc
	s_mov_b32 s28, 0x11a80000
	s_waitcnt vmcnt(0)
	global_load_dwordx4 v[66:69], v[6:7], off
	v_add_co_u32_e32 v6, vcc, s28, v4
	v_and_b32_e32 v9, 31, v8
	s_nop 0
	v_addc_co_u32_e32 v7, vcc, 0, v5, vcc
	global_load_dwordx4 v[70:73], v[6:7], off
	v_or_b32_e32 v6, s5, v9
	s_mov_b32 s5, 0x10c02000
	v_add_co_u32_e32 v2, vcc, s5, v2
	s_mov_b64 s[28:29], 0x11a80000
	s_nop 0
	v_addc_co_u32_e32 v3, vcc, 0, v3, vcc
	v_ashrrev_i32_e32 v7, 31, v6
	v_bfe_u32 v8, v8, 5, 1
	v_lshl_add_u64 v[4:5], v[4:5], 0, s[28:29]
	global_load_dwordx4 v[74:77], v[2:3], off
	global_load_dwordx4 v[78:81], v[4:5], off offset:128
	v_lshlrev_b64 v[2:3], 7, v[6:7]
	v_lshl_add_u64 v[2:3], s[6:7], 0, v[2:3]
	v_lshlrev_b32_e32 v136, 4, v8
	v_mov_b32_e32 v137, v65
	v_lshl_add_u64 v[2:3], v[2:3], 0, v[136:137]
	s_mov_b64 s[6:7], 0x10000000
	s_brev_b32 s5, 8
	v_lshl_add_u64 v[4:5], v[2:3], 0, s[6:7]
	v_add_co_u32_e32 v2, vcc, s5, v2
	v_lshl_add_u32 v138, s1, 11, v6
	s_nop 0
	v_addc_co_u32_e32 v3, vcc, 0, v3, vcc
	v_ashrrev_i32_e32 v139, 31, v138
	global_load_dwordx4 v[82:85], v[4:5], off offset:32
	global_load_dwordx4 v[86:89], v[4:5], off offset:64
	global_load_dwordx4 v[90:93], v[2:3], off
	global_load_dwordx4 v[94:97], v[4:5], off offset:96
	s_mov_b64 s[6:7], s[40:41]
	v_lshlrev_b64 v[2:3], 8, v[138:139]
	s_mov_b32 s5, 0x13000000
	v_lshl_add_u64 v[2:3], s[6:7], 0, v[2:3]
	v_lshl_add_u64 v[2:3], v[2:3], 0, v[136:137]
	s_mov_b64 s[6:7], 0x13000000
	v_lshl_add_u64 v[4:5], v[2:3], 0, s[6:7]
	v_add_co_u32_e32 v2, vcc, s5, v2
	s_movk_i32 s34, 0x90
	s_nop 0
	v_addc_co_u32_e32 v3, vcc, 0, v3, vcc
	global_load_dwordx4 v[98:101], v[4:5], off offset:32
	global_load_dwordx4 v[102:105], v[4:5], off offset:64
	global_load_dwordx4 v[106:109], v[4:5], off offset:160
	global_load_dwordx4 v[110:113], v[4:5], off offset:192
	global_load_dwordx4 v[114:117], v[4:5], off offset:128
	global_load_dwordx4 v[118:121], v[4:5], off offset:96
	global_load_dwordx4 v[122:125], v[2:3], off
	global_load_dwordx4 v[126:129], v[4:5], off offset:224
	v_mad_u64_u32 v[0:1], s[28:29], v0, s34, v[64:65]
	v_mov_b32_e32 v131, 0
	s_mov_b32 s5, 3
	s_add_i32 s6, s38, 4
	v_lshlrev_b32_e32 v130, 2, v8
	v_add_u32_e32 v137, 0, v0
	s_or_b32 s7, s27, 31
	s_or_b32 s27, s38, 3
	v_mul_u32_u24_e32 v140, 0x90, v9
	v_mad_u32_u24 v141, v9, s34, 0
	v_lshl_add_u32 v142, v8, 5, 0
	s_sub_i32 s28, 0, s33
	s_sub_i32 s29, 0, s38
	v_mov_b32_e32 v0, 0
	v_mov_b32_e32 v1, v131
	v_mov_b32_e32 v2, v131
	v_mov_b32_e32 v3, v131
	v_mov_b32_e32 v4, v131
	v_mov_b32_e32 v5, v131
	v_mov_b32_e32 v6, v131
	v_mov_b32_e32 v7, v131
	v_mov_b32_e32 v8, v131
	v_mov_b32_e32 v9, v131
	v_mov_b32_e32 v10, v131
	v_mov_b32_e32 v11, v131
	v_mov_b32_e32 v12, v131
	v_mov_b32_e32 v13, v131
	v_mov_b32_e32 v14, v131
	v_mov_b32_e32 v15, v131
	v_mov_b32_e32 v16, v131
	v_mov_b32_e32 v17, v131
	v_mov_b32_e32 v18, v131
	v_mov_b32_e32 v19, v131
	v_mov_b32_e32 v20, v131
	v_mov_b32_e32 v21, v131
	v_mov_b32_e32 v22, v131
	v_mov_b32_e32 v23, v131
	v_mov_b32_e32 v24, v131
	v_mov_b32_e32 v25, v131
	v_mov_b32_e32 v26, v131
	v_mov_b32_e32 v27, v131
	v_mov_b32_e32 v28, v131
	v_mov_b32_e32 v29, v131
	v_mov_b32_e32 v30, v131
	v_mov_b32_e32 v31, v131
	s_waitcnt vmcnt(0) lgkmcnt(0)
	ds_write_b128 v137, v[66:69]
	ds_write_b128 v137, v[70:73] offset:18432
	s_waitcnt lgkmcnt(0)
	s_barrier
	s_branch .LBB0_1040

.LBB0_1040:
	s_add_i32 s33, s5, -1
	s_cmp_ge_u32 s33, s6
	s_cbranch_scc1 .LBB0_1042
	v_lshl_add_u64 v[32:33], v[132:133], 0, v[64:65]
	v_add_co_u32_e32 v32, vcc, 0x10c04000, v32
	v_lshl_add_u64 v[34:35], v[134:135], 0, v[64:65]
	s_nop 0
	v_addc_co_u32_e32 v33, vcc, 0, v33, vcc
	global_load_dwordx4 v[66:69], v[32:33], off
	v_add_co_u32_e32 v32, vcc, 0x11a80000, v34
	s_nop 1
	v_addc_co_u32_e32 v33, vcc, 0, v35, vcc
	global_load_dwordx4 v[70:73], v[32:33], off offset:256
.LBB0_1042:
	s_add_i32 s34, s29, s5
	s_add_i32 s35, s5, -3
	s_add_i32 s36, s34, -3
	s_cmp_gt_i32 s36, -1
	s_cselect_b64 s[36:37], -1, 0
	s_cmp_gt_i32 s28, s7
	s_cselect_b64 s[38:39], -1, 0
	s_and_b64 s[36:37], s[36:37], s[38:39]
	s_and_b64 vcc, exec, s[36:37]
	s_cbranch_vccnz .LBB0_1044
	v_add_u32_e32 v159, v141, v136
	v_add_u32_e32 v160, v142, v140
	ds_read_b128 v[166:169], v159
	ds_read_b128 v[170:173], v159 offset:4608
	ds_read_b128 v[174:177], v159 offset:32
	ds_read_b128 v[178:181], v159 offset:4640
	ds_read_b128 v[182:185], v159 offset:64
	ds_read_b128 v[186:189], v159 offset:4672
	ds_read_b128 v[226:229], v159 offset:96
	ds_read_b128 v[230:233], v159 offset:4704
	v_bfe_i32 v234, v122, s35, 1
	v_bfe_i32 v235, v123, s35, 1
	v_bfe_i32 v236, v124, s35, 1
	v_bfe_i32 v237, v125, s35, 1
	s_waitcnt lgkmcnt(7)
	v_mfma_f32_32x32x16_bf16 v[32:47], v[166:169], v[90:93], 0
	ds_read_b128 v[166:169], v160 offset:18432
	v_bfe_i32 v238, v98, s35, 1
	v_bfe_i32 v239, v99, s35, 1
	v_bfe_i32 v240, v100, s35, 1
	s_waitcnt lgkmcnt(7)
	v_mfma_f32_32x32x16_bf16 v[48:63], v[170:173], v[90:93], 0
	ds_read_b128 v[170:173], v160 offset:23040
	v_bfe_i32 v241, v101, s35, 1
	v_bfe_i32 v242, v102, s35, 1
	v_bfe_i32 v243, v103, s35, 1
	s_waitcnt lgkmcnt(7)
	v_mfma_f32_32x32x16_bf16 v[32:47], v[174:177], v[82:85], v[32:47]
	ds_read_b128 v[174:177], v160 offset:18448
	v_bfe_i32 v244, v104, s35, 1
	v_bfe_i32 v245, v105, s35, 1
	v_bfe_i32 v246, v118, s35, 1
	s_waitcnt lgkmcnt(7)
	v_mfma_f32_32x32x16_bf16 v[48:63], v[178:181], v[82:85], v[48:63]
	ds_read_b128 v[178:181], v160 offset:23056
	v_bfe_i32 v247, v119, s35, 1
	v_bfe_i32 v248, v120, s35, 1
	v_bfe_i32 v249, v121, s35, 1
	s_waitcnt lgkmcnt(7)
	v_mfma_f32_32x32x16_bf16 v[32:47], v[182:185], v[86:89], v[32:47]
	ds_read_b128 v[182:185], v160 offset:18496
	v_bfe_i32 v143, v114, s35, 1
	v_bfe_i32 v144, v115, s35, 1
	v_bfe_i32 v145, v116, s35, 1
	s_waitcnt lgkmcnt(7)
	v_mfma_f32_32x32x16_bf16 v[48:63], v[186:189], v[86:89], v[48:63]
	ds_read_b128 v[186:189], v160 offset:23104
	v_bfe_i32 v146, v117, s35, 1
	v_bfe_i32 v147, v106, s35, 1
	v_bfe_i32 v148, v107, s35, 1
	s_waitcnt lgkmcnt(7)
	v_mfma_f32_32x32x16_bf16 v[32:47], v[226:229], v[94:97], v[32:47]
	ds_read_b128 v[226:229], v160 offset:18512
	v_bfe_i32 v149, v108, s35, 1
	v_bfe_i32 v150, v109, s35, 1
	v_bfe_i32 v151, v110, s35, 1
	s_waitcnt lgkmcnt(7)
	v_mfma_f32_32x32x16_bf16 v[48:63], v[230:233], v[94:97], v[48:63]
	ds_read_b128 v[230:233], v160 offset:23120
	v_bfe_i32 v152, v111, s35, 1
	v_bfe_i32 v153, v112, s35, 1
	v_bfe_i32 v154, v113, s35, 1
	v_bfe_i32 v155, v126, s35, 1
	v_bfe_i32 v156, v127, s35, 1
	v_bfe_i32 v157, v128, s35, 1
	v_bfe_i32 v158, v129, s35, 1
	v_exp_f32_e32 v32, v32
	v_exp_f32_e32 v33, v33
	v_exp_f32_e32 v34, v34
	v_exp_f32_e32 v35, v35
	v_and_b32_e32 v32, v234, v32
	v_and_b32_e32 v33, v235, v33
	v_and_b32_e32 v34, v236, v34
	v_and_b32_e32 v35, v237, v35
	v_add_f32_e32 v161, 0, v32
	v_add_f32_e32 v163, 0, v33
	v_add_f32_e32 v164, 0, v34
	v_add_f32_e32 v165, 0, v35
	v_cvt_pk_bf16_f32 v32, v32, v33
	v_cvt_pk_bf16_f32 v33, v34, v35
	v_exp_f32_e32 v36, v36
	v_exp_f32_e32 v37, v37
	v_exp_f32_e32 v38, v38
	v_exp_f32_e32 v39, v39
	v_and_b32_e32 v36, v238, v36
	v_and_b32_e32 v37, v239, v37
	v_and_b32_e32 v38, v240, v38
	v_and_b32_e32 v39, v241, v39
	v_add_f32_e32 v161, v161, v36
	v_add_f32_e32 v163, v163, v37
	v_add_f32_e32 v164, v164, v38
	v_add_f32_e32 v165, v165, v39
	v_cvt_pk_bf16_f32 v34, v36, v37
	v_cvt_pk_bf16_f32 v35, v38, v39
	s_waitcnt lgkmcnt(7)
	s_nop 0
	v_mfma_f32_32x32x16_bf16 v[0:15], v[166:169], v[32:35], v[0:15]
	v_exp_f32_e32 v40, v40
	v_exp_f32_e32 v41, v41
	v_exp_f32_e32 v42, v42
	v_exp_f32_e32 v43, v43
	v_and_b32_e32 v40, v242, v40
	v_and_b32_e32 v41, v243, v41
	v_and_b32_e32 v42, v244, v42
	v_and_b32_e32 v43, v245, v43
	v_add_f32_e32 v161, v161, v40
	v_add_f32_e32 v163, v163, v41
	v_add_f32_e32 v164, v164, v42
	v_add_f32_e32 v165, v165, v43
	v_cvt_pk_bf16_f32 v36, v40, v41
	v_cvt_pk_bf16_f32 v37, v42, v43
	s_waitcnt lgkmcnt(6)
	v_mfma_f32_32x32x16_bf16 v[16:31], v[170:173], v[32:35], v[16:31]
	v_exp_f32_e32 v44, v44
	v_exp_f32_e32 v45, v45
	v_exp_f32_e32 v46, v46
	v_exp_f32_e32 v47, v47
	v_and_b32_e32 v44, v246, v44
	v_and_b32_e32 v45, v247, v45
	v_and_b32_e32 v46, v248, v46
	v_and_b32_e32 v47, v249, v47
	v_add_f32_e32 v161, v161, v44
	v_add_f32_e32 v163, v163, v45
	v_add_f32_e32 v164, v164, v46
	v_add_f32_e32 v165, v165, v47
	v_cvt_pk_bf16_f32 v38, v44, v45
	v_cvt_pk_bf16_f32 v39, v46, v47
	s_waitcnt lgkmcnt(5)
	s_nop 0
	v_mfma_f32_32x32x16_bf16 v[0:15], v[174:177], v[36:39], v[0:15]
	v_exp_f32_e32 v48, v48
	v_exp_f32_e32 v49, v49
	v_exp_f32_e32 v50, v50
	v_exp_f32_e32 v51, v51
	v_and_b32_e32 v48, v143, v48
	v_and_b32_e32 v49, v144, v49
	v_and_b32_e32 v50, v145, v50
	v_and_b32_e32 v51, v146, v51
	v_add_f32_e32 v161, v161, v48
	v_add_f32_e32 v163, v163, v49
	v_add_f32_e32 v164, v164, v50
	v_add_f32_e32 v165, v165, v51
	v_cvt_pk_bf16_f32 v48, v48, v49
	v_cvt_pk_bf16_f32 v49, v50, v51
	s_waitcnt lgkmcnt(4)
	v_mfma_f32_32x32x16_bf16 v[16:31], v[178:181], v[36:39], v[16:31]
	v_exp_f32_e32 v52, v52
	v_exp_f32_e32 v53, v53
	v_exp_f32_e32 v54, v54
	v_exp_f32_e32 v55, v55
	v_and_b32_e32 v52, v147, v52
	v_and_b32_e32 v53, v148, v53
	v_and_b32_e32 v54, v149, v54
	v_and_b32_e32 v55, v150, v55
	v_add_f32_e32 v161, v161, v52
	v_add_f32_e32 v163, v163, v53
	v_add_f32_e32 v164, v164, v54
	v_add_f32_e32 v165, v165, v55
	v_cvt_pk_bf16_f32 v50, v52, v53
	v_cvt_pk_bf16_f32 v51, v54, v55
	s_waitcnt lgkmcnt(3)
	s_nop 0
	v_mfma_f32_32x32x16_bf16 v[0:15], v[182:185], v[48:51], v[0:15]
	v_exp_f32_e32 v56, v56
	v_exp_f32_e32 v57, v57
	v_exp_f32_e32 v58, v58
	v_exp_f32_e32 v59, v59
	v_and_b32_e32 v56, v151, v56
	v_and_b32_e32 v57, v152, v57
	v_and_b32_e32 v58, v153, v58
	v_and_b32_e32 v59, v154, v59
	v_add_f32_e32 v161, v161, v56
	v_add_f32_e32 v163, v163, v57
	v_add_f32_e32 v164, v164, v58
	v_add_f32_e32 v165, v165, v59
	v_cvt_pk_bf16_f32 v52, v56, v57
	v_cvt_pk_bf16_f32 v53, v58, v59
	s_waitcnt lgkmcnt(2)
	v_mfma_f32_32x32x16_bf16 v[16:31], v[186:189], v[48:51], v[16:31]
	v_exp_f32_e32 v60, v60
	v_exp_f32_e32 v61, v61
	v_exp_f32_e32 v62, v62
	v_exp_f32_e32 v63, v63
	v_and_b32_e32 v60, v155, v60
	v_and_b32_e32 v61, v156, v61
	v_and_b32_e32 v62, v157, v62
	v_and_b32_e32 v63, v158, v63
	v_add_f32_e32 v161, v161, v60
	v_add_f32_e32 v163, v163, v61
	v_add_f32_e32 v164, v164, v62
	v_add_f32_e32 v165, v165, v63
	v_cvt_pk_bf16_f32 v54, v60, v61
	v_cvt_pk_bf16_f32 v55, v62, v63
	s_waitcnt lgkmcnt(1)
	s_nop 0
	v_mfma_f32_32x32x16_bf16 v[0:15], v[226:229], v[52:55], v[0:15]
	s_waitcnt lgkmcnt(0)
	v_mfma_f32_32x32x16_bf16 v[16:31], v[230:233], v[52:55], v[16:31]
	v_add_f32_e32 v161, v161, v163
	v_add_f32_e32 v164, v164, v165
	v_add_f32_e32 v161, v161, v164
	v_add_f32_e32 v131, v131, v161
.LBB0_1044:
	s_cmp_ge_u32 s35, s27
	s_cbranch_scc1 .LBB0_1046
	s_cmp_ge_u32 s33, s6
	s_cbranch_scc1 .Lvm0_dsa_a
	s_waitcnt vmcnt(2)
	s_branch .Lvm1_dsa_a

.Lvm1_dsa_a:
	ds_write_b128 v137, v[74:77] offset:9216
	ds_write_b128 v137, v[78:81] offset:27648
.LBB0_1046:
	s_cmp_ge_u32 s5, s6
	s_waitcnt lgkmcnt(0)
	s_barrier
	s_cbranch_scc1 .LBB0_1048
	v_lshl_add_u64 v[32:33], v[132:133], 0, v[64:65]
	v_add_co_u32_e32 v32, vcc, 0x10c06000, v32
	v_lshl_add_u64 v[34:35], v[134:135], 0, v[64:65]
	s_nop 0
	v_addc_co_u32_e32 v33, vcc, 0, v33, vcc
	global_load_dwordx4 v[74:77], v[32:33], off
	v_add_co_u32_e32 v32, vcc, 0x11a80000, v34
	s_nop 1
	v_addc_co_u32_e32 v33, vcc, 0, v35, vcc
	global_load_dwordx4 v[78:81], v[32:33], off offset:384
.LBB0_1048:
	s_add_i32 s35, s5, -2
	s_add_i32 s34, s34, -2
	s_cmp_gt_i32 s34, -1
	s_cselect_b64 s[36:37], -1, 0
	s_add_i32 s34, s28, 64
	s_cmp_gt_i32 s34, s7
	s_cselect_b64 s[38:39], -1, 0
	s_and_b64 s[36:37], s[36:37], s[38:39]
	s_and_b64 vcc, exec, s[36:37]
	s_cbranch_vccnz .LBB0_1050
	v_add_u32_e32 v159, v141, v136
	v_add_u32_e32 v160, v142, v140
	ds_read_b128 v[166:169], v159 offset:9216
	ds_read_b128 v[170:173], v159 offset:13824
	ds_read_b128 v[174:177], v159 offset:9248
	ds_read_b128 v[178:181], v159 offset:13856
	ds_read_b128 v[182:185], v159 offset:9280
	ds_read_b128 v[186:189], v159 offset:13888
	ds_read_b128 v[226:229], v159 offset:9312
	ds_read_b128 v[230:233], v159 offset:13920
	v_bfe_i32 v234, v122, s35, 1
	v_bfe_i32 v235, v123, s35, 1
	v_bfe_i32 v236, v124, s35, 1
	v_bfe_i32 v237, v125, s35, 1
	s_waitcnt lgkmcnt(7)
	v_mfma_f32_32x32x16_bf16 v[32:47], v[166:169], v[90:93], 0
	ds_read_b128 v[166:169], v160 offset:27648
	v_bfe_i32 v238, v98, s35, 1
	v_bfe_i32 v239, v99, s35, 1
	v_bfe_i32 v240, v100, s35, 1
	s_waitcnt lgkmcnt(7)
	v_mfma_f32_32x32x16_bf16 v[48:63], v[170:173], v[90:93], 0
	ds_read_b128 v[170:173], v160 offset:32256
	v_bfe_i32 v241, v101, s35, 1
	v_bfe_i32 v242, v102, s35, 1
	v_bfe_i32 v243, v103, s35, 1
	s_waitcnt lgkmcnt(7)
	v_mfma_f32_32x32x16_bf16 v[32:47], v[174:177], v[82:85], v[32:47]
	ds_read_b128 v[174:177], v160 offset:27664
	v_bfe_i32 v244, v104, s35, 1
	v_bfe_i32 v245, v105, s35, 1
	v_bfe_i32 v246, v118, s35, 1
	s_waitcnt lgkmcnt(7)
	v_mfma_f32_32x32x16_bf16 v[48:63], v[178:181], v[82:85], v[48:63]
	ds_read_b128 v[178:181], v160 offset:32272
	v_bfe_i32 v247, v119, s35, 1
	v_bfe_i32 v248, v120, s35, 1
	v_bfe_i32 v249, v121, s35, 1
	s_waitcnt lgkmcnt(7)
	v_mfma_f32_32x32x16_bf16 v[32:47], v[182:185], v[86:89], v[32:47]
	ds_read_b128 v[182:185], v160 offset:27712
	v_bfe_i32 v143, v114, s35, 1
	v_bfe_i32 v144, v115, s35, 1
	v_bfe_i32 v145, v116, s35, 1
	s_waitcnt lgkmcnt(7)
	v_mfma_f32_32x32x16_bf16 v[48:63], v[186:189], v[86:89], v[48:63]
	ds_read_b128 v[186:189], v160 offset:32320
	v_bfe_i32 v146, v117, s35, 1
	v_bfe_i32 v147, v106, s35, 1
	v_bfe_i32 v148, v107, s35, 1
	s_waitcnt lgkmcnt(7)
	v_mfma_f32_32x32x16_bf16 v[32:47], v[226:229], v[94:97], v[32:47]
	ds_read_b128 v[226:229], v160 offset:27728
	v_bfe_i32 v149, v108, s35, 1
	v_bfe_i32 v150, v109, s35, 1
	v_bfe_i32 v151, v110, s35, 1
	s_waitcnt lgkmcnt(7)
	v_mfma_f32_32x32x16_bf16 v[48:63], v[230:233], v[94:97], v[48:63]
	ds_read_b128 v[230:233], v160 offset:32336
	v_bfe_i32 v152, v111, s35, 1
	v_bfe_i32 v153, v112, s35, 1
	v_bfe_i32 v154, v113, s35, 1
	v_bfe_i32 v155, v126, s35, 1
	v_bfe_i32 v156, v127, s35, 1
	v_bfe_i32 v157, v128, s35, 1
	v_bfe_i32 v158, v129, s35, 1
	v_exp_f32_e32 v32, v32
	v_exp_f32_e32 v33, v33
	v_exp_f32_e32 v34, v34
	v_exp_f32_e32 v35, v35
	v_and_b32_e32 v32, v234, v32
	v_and_b32_e32 v33, v235, v33
	v_and_b32_e32 v34, v236, v34
	v_and_b32_e32 v35, v237, v35
	v_add_f32_e32 v161, 0, v32
	v_add_f32_e32 v163, 0, v33
	v_add_f32_e32 v164, 0, v34
	v_add_f32_e32 v165, 0, v35
	v_cvt_pk_bf16_f32 v32, v32, v33
	v_cvt_pk_bf16_f32 v33, v34, v35
	v_exp_f32_e32 v36, v36
	v_exp_f32_e32 v37, v37
	v_exp_f32_e32 v38, v38
	v_exp_f32_e32 v39, v39
	v_and_b32_e32 v36, v238, v36
	v_and_b32_e32 v37, v239, v37
	v_and_b32_e32 v38, v240, v38
	v_and_b32_e32 v39, v241, v39
	v_add_f32_e32 v161, v161, v36
	v_add_f32_e32 v163, v163, v37
	v_add_f32_e32 v164, v164, v38
	v_add_f32_e32 v165, v165, v39
	v_cvt_pk_bf16_f32 v34, v36, v37
	v_cvt_pk_bf16_f32 v35, v38, v39
	s_waitcnt lgkmcnt(7)
	s_nop 0
	v_mfma_f32_32x32x16_bf16 v[0:15], v[166:169], v[32:35], v[0:15]
	v_exp_f32_e32 v40, v40
	v_exp_f32_e32 v41, v41
	v_exp_f32_e32 v42, v42
	v_exp_f32_e32 v43, v43
	v_and_b32_e32 v40, v242, v40
	v_and_b32_e32 v41, v243, v41
	v_and_b32_e32 v42, v244, v42
	v_and_b32_e32 v43, v245, v43
	v_add_f32_e32 v161, v161, v40
	v_add_f32_e32 v163, v163, v41
	v_add_f32_e32 v164, v164, v42
	v_add_f32_e32 v165, v165, v43
	v_cvt_pk_bf16_f32 v36, v40, v41
	v_cvt_pk_bf16_f32 v37, v42, v43
	s_waitcnt lgkmcnt(6)
	v_mfma_f32_32x32x16_bf16 v[16:31], v[170:173], v[32:35], v[16:31]
	v_exp_f32_e32 v44, v44
	v_exp_f32_e32 v45, v45
	v_exp_f32_e32 v46, v46
	v_exp_f32_e32 v47, v47
	v_and_b32_e32 v44, v246, v44
	v_and_b32_e32 v45, v247, v45
	v_and_b32_e32 v46, v248, v46
	v_and_b32_e32 v47, v249, v47
	v_add_f32_e32 v161, v161, v44
	v_add_f32_e32 v163, v163, v45
	v_add_f32_e32 v164, v164, v46
	v_add_f32_e32 v165, v165, v47
	v_cvt_pk_bf16_f32 v38, v44, v45
	v_cvt_pk_bf16_f32 v39, v46, v47
	s_waitcnt lgkmcnt(5)
	s_nop 0
	v_mfma_f32_32x32x16_bf16 v[0:15], v[174:177], v[36:39], v[0:15]
	v_exp_f32_e32 v48, v48
	v_exp_f32_e32 v49, v49
	v_exp_f32_e32 v50, v50
	v_exp_f32_e32 v51, v51
	v_and_b32_e32 v48, v143, v48
	v_and_b32_e32 v49, v144, v49
	v_and_b32_e32 v50, v145, v50
	v_and_b32_e32 v51, v146, v51
	v_add_f32_e32 v161, v161, v48
	v_add_f32_e32 v163, v163, v49
	v_add_f32_e32 v164, v164, v50
	v_add_f32_e32 v165, v165, v51
	v_cvt_pk_bf16_f32 v48, v48, v49
	v_cvt_pk_bf16_f32 v49, v50, v51
	s_waitcnt lgkmcnt(4)
	v_mfma_f32_32x32x16_bf16 v[16:31], v[178:181], v[36:39], v[16:31]
	v_exp_f32_e32 v52, v52
	v_exp_f32_e32 v53, v53
	v_exp_f32_e32 v54, v54
	v_exp_f32_e32 v55, v55
	v_and_b32_e32 v52, v147, v52
	v_and_b32_e32 v53, v148, v53
	v_and_b32_e32 v54, v149, v54
	v_and_b32_e32 v55, v150, v55
	v_add_f32_e32 v161, v161, v52
	v_add_f32_e32 v163, v163, v53
	v_add_f32_e32 v164, v164, v54
	v_add_f32_e32 v165, v165, v55
	v_cvt_pk_bf16_f32 v50, v52, v53
	v_cvt_pk_bf16_f32 v51, v54, v55
	s_waitcnt lgkmcnt(3)
	s_nop 0
	v_mfma_f32_32x32x16_bf16 v[0:15], v[182:185], v[48:51], v[0:15]
	v_exp_f32_e32 v56, v56
	v_exp_f32_e32 v57, v57
	v_exp_f32_e32 v58, v58
	v_exp_f32_e32 v59, v59
	v_and_b32_e32 v56, v151, v56
	v_and_b32_e32 v57, v152, v57
	v_and_b32_e32 v58, v153, v58
	v_and_b32_e32 v59, v154, v59
	v_add_f32_e32 v161, v161, v56
	v_add_f32_e32 v163, v163, v57
	v_add_f32_e32 v164, v164, v58
	v_add_f32_e32 v165, v165, v59
	v_cvt_pk_bf16_f32 v52, v56, v57
	v_cvt_pk_bf16_f32 v53, v58, v59
	s_waitcnt lgkmcnt(2)
	v_mfma_f32_32x32x16_bf16 v[16:31], v[186:189], v[48:51], v[16:31]
	v_exp_f32_e32 v60, v60
	v_exp_f32_e32 v61, v61
	v_exp_f32_e32 v62, v62
	v_exp_f32_e32 v63, v63
	v_and_b32_e32 v60, v155, v60
	v_and_b32_e32 v61, v156, v61
	v_and_b32_e32 v62, v157, v62
	v_and_b32_e32 v63, v158, v63
	v_add_f32_e32 v161, v161, v60
	v_add_f32_e32 v163, v163, v61
	v_add_f32_e32 v164, v164, v62
	v_add_f32_e32 v165, v165, v63
	v_cvt_pk_bf16_f32 v54, v60, v61
	v_cvt_pk_bf16_f32 v55, v62, v63
	s_waitcnt lgkmcnt(1)
	s_nop 0
	v_mfma_f32_32x32x16_bf16 v[0:15], v[226:229], v[52:55], v[0:15]
	s_waitcnt lgkmcnt(0)
	v_mfma_f32_32x32x16_bf16 v[16:31], v[230:233], v[52:55], v[16:31]
	v_add_f32_e32 v161, v161, v163
	v_add_f32_e32 v164, v164, v165
	v_add_f32_e32 v161, v161, v164
	v_add_f32_e32 v131, v131, v161
.LBB0_1050:
	s_cmp_ge_u32 s35, s27
	s_cbranch_scc1 .LBB0_1039
	s_cmp_ge_u32 s5, s6
	s_cbranch_scc1 .Lvm0_dsa_b
	s_waitcnt vmcnt(2)
	s_branch .Lvm1_dsa_b

.Lvm1_dsa_b:
	ds_write_b128 v137, v[66:69]
	ds_write_b128 v137, v[70:73] offset:18432
	s_branch .LBB0_1039
.LBB0_1052:
	s_mul_i32 s1, s1, 6
	s_sub_i32 s5, s0, s1
	s_mov_b64 s[0:1], s[40:41]
	v_lshlrev_b64 v[32:33], 11, v[138:139]
	s_lshl_b32 s42, s5, 7
	v_lshl_add_u64 v[32:33], s[0:1], 0, v[32:33]
	v_lshl_add_u64 v[34:35], v[32:33], 0, s[42:43]
	ds_bpermute_b32 v32, v193, v131
	s_mov_b32 s1, s43
	v_writelane_b32 v254, s0, 43
	v_lshlrev_b32_e32 v64, 1, v130
	v_readlane_b32 s33, v255, 5
	s_waitcnt lgkmcnt(0)
	v_add_f32_e32 v32, v131, v32
	v_writelane_b32 v254, s1, 44
	v_div_scale_f32 v33, s[0:1], v32, v32, 1.0
	v_rcp_f32_e32 v36, v33
	s_mov_b64 s[0:1], 0x6000500
	v_fma_f32 v37, -v33, v36, 1.0
	v_fmac_f32_e32 v36, v37, v36
	v_div_scale_f32 v37, vcc, 1.0, v32, 1.0
	v_mul_f32_e32 v38, v37, v36
	v_fma_f32 v39, -v33, v38, v37
	v_fmac_f32_e32 v38, v39, v36
	v_fma_f32 v33, -v33, v38, v37
	v_div_fmas_f32 v33, v33, v36, v38
	v_div_fixup_f32 v32, v33, v32, 1.0
	v_lshl_add_u64 v[36:37], v[34:35], 0, v[64:65]
	v_lshl_add_u64 v[34:35], v[36:37], 0, s[0:1]
	v_pk_mul_f32 v[0:1], v[0:1], v[32:33] op_sel_hi:[1,0]
	v_pk_mul_f32 v[2:3], v[2:3], v[32:33] op_sel_hi:[1,0]
	s_mov_b32 s0, 0x6000000
	v_cvt_pk_bf16_f32 v0, v0, v1
	v_cvt_pk_bf16_f32 v1, v2, v3
	v_add_co_u32_e32 v2, vcc, s0, v36
	s_mov_b64 s[0:1], 0
	s_nop 0
	v_addc_co_u32_e32 v3, vcc, 0, v37, vcc
	global_store_dwordx2 v[2:3], v[0:1], off offset:1280
	v_pk_mul_f32 v[0:1], v[4:5], v[32:33] op_sel_hi:[1,0]
	v_pk_mul_f32 v[2:3], v[6:7], v[32:33] op_sel_hi:[1,0]
	v_cvt_pk_bf16_f32 v0, v0, v1
	v_cvt_pk_bf16_f32 v1, v2, v3
	global_store_dwordx2 v[34:35], v[0:1], off offset:16
	v_pk_mul_f32 v[0:1], v[8:9], v[32:33] op_sel_hi:[1,0]
	v_pk_mul_f32 v[2:3], v[10:11], v[32:33] op_sel_hi:[1,0]
	v_cvt_pk_bf16_f32 v0, v0, v1
	v_cvt_pk_bf16_f32 v1, v2, v3
	global_store_dwordx2 v[34:35], v[0:1], off offset:32
	v_pk_mul_f32 v[0:1], v[12:13], v[32:33] op_sel_hi:[1,0]
	v_pk_mul_f32 v[36:37], v[14:15], v[32:33] op_sel_hi:[1,0]
	v_cvt_pk_bf16_f32 v0, v0, v1
.LBB0_1053:
	s_and_b64 vcc, exec, s[0:1]
	s_cbranch_vccz .LBB0_1036
	s_and_b32 s27, s4, 0xff
	s_mul_i32 s0, s27, 0xab
	s_lshr_b32 s67, s0, 10
	s_mul_i32 s5, s67, 6
	s_sub_i32 s0, s4, s5
	s_and_b32 s66, s0, 0xff
	s_mov_b32 s0, -1
	s_add_i32 s42, s5, s66
	v_mbcnt_lo_u32_b32 v0, s0, 0
	v_mbcnt_hi_u32_b32 v0, s0, v0
	v_readlane_b32 s0, v252, 5
	s_lshl_b32 s4, s42, 18
	s_mul_i32 s28, s67, 5
	v_add_u32_e32 v17, s0, v0
	v_mov_b32_e32 v9, v65
	v_readfirstlane_b32 s0, v17
	s_ashr_i32 s35, s0, 6
	s_mov_b64 s[0:1], s[40:41]
	s_add_u32 s6, s0, s4
	s_addc_u32 s7, s1, 0
	s_mov_b64 s[0:1], s[40:41]
	v_ashrrev_i32_e32 v10, 3, v17
	s_add_u32 s36, s0, s4
	v_ashrrev_i32_e32 v11, 31, v10
	s_addc_u32 s37, s1, 0
	v_lshlrev_b64 v[4:5], 7, v[10:11]
	v_and_b32_e32 v2, 7, v17
	s_add_i32 s29, s42, s28
	v_lshl_add_u64 v[0:1], s[36:37], 0, v[4:5]
	v_lshlrev_b32_e32 v64, 4, v2
	s_mov_b64 s[4:5], s[40:41]
	s_lshl_b32 s28, s29, 17
	s_lshl_b32 s29, s29, 18
	v_lshl_add_u64 v[0:1], v[0:1], 0, v[64:65]
	v_ashrrev_i32_e32 v12, 4, v17
	s_mov_b32 s36, 0xe400000
	s_add_u32 s38, s4, s29
	v_ashrrev_i32_e32 v13, 31, v12
	v_add_co_u32_e32 v14, vcc, s36, v0
	s_addc_u32 s39, s5, 0
	v_lshlrev_b64 v[6:7], 12, v[12:13]
	v_and_b32_e32 v8, 15, v17
	v_addc_co_u32_e32 v15, vcc, 0, v1, vcc
	s_mov_b32 s36, 0xe402000
	v_lshl_add_u64 v[2:3], s[38:39], 0, v[6:7]
	v_lshlrev_b32_e32 v8, 4, v8
	v_add_co_u32_e32 v0, vcc, s36, v0
	s_lshl_b32 s29, s26, 8
	s_lshl_b32 s34, s35, 5
	v_lshl_add_u64 v[2:3], v[2:3], 0, v[8:9]
	v_addc_co_u32_e32 v1, vcc, 0, v1, vcc
	s_mov_b32 s36, 0x11800000
	v_and_b32_e32 v16, 31, v17
	s_add_i32 s33, s34, s29
	s_waitcnt vmcnt(0)
	global_load_dwordx4 v[98:101], v[14:15], off
	global_load_dwordx4 v[102:105], v[0:1], off
	v_add_co_u32_e32 v0, vcc, s36, v2
	v_or_b32_e32 v130, s33, v16
	s_nop 0
	v_addc_co_u32_e32 v1, vcc, 0, v3, vcc
	s_mov_b32 s36, 0x11820000
	v_add_co_u32_e32 v2, vcc, s36, v2
	v_ashrrev_i32_e32 v131, 31, v130
	v_bfe_u32 v18, v17, 5, 1
	v_addc_co_u32_e32 v3, vcc, 0, v3, vcc
	global_load_dwordx4 v[106:109], v[0:1], off
	global_load_dwordx4 v[126:129], v[2:3], off
	v_lshlrev_b64 v[0:1], 7, v[130:131]
	v_lshl_add_u64 v[0:1], s[6:7], 0, v[0:1]
	v_lshlrev_b32_e32 v132, 4, v18
	v_mov_b32_e32 v133, v65
	v_lshl_add_u64 v[0:1], v[0:1], 0, v[132:133]
	s_mov_b64 s[6:7], 0xd800000
	v_lshl_add_u64 v[2:3], v[0:1], 0, s[6:7]
	s_mov_b32 s6, 0xd800000
	v_add_co_u32_e32 v0, vcc, s6, v0
	s_mov_b64 s[6:7], s[40:41]
	s_nop 0
	v_addc_co_u32_e32 v1, vcc, 0, v1, vcc
	global_load_dwordx4 v[110:113], v[2:3], off offset:32
	global_load_dwordx4 v[114:117], v[2:3], off offset:64
	global_load_dwordx4 v[118:121], v[0:1], off
	global_load_dwordx4 v[122:125], v[2:3], off offset:96
	s_lshl_b32 s36, s42, 13
	s_add_u32 s6, s6, s36
	v_lshlrev_b32_e32 v14, 2, v17
	s_addc_u32 s7, s7, 0
	v_ashrrev_i32_e32 v15, 31, v14
	v_lshl_add_u64 v[0:1], v[14:15], 2, s[6:7]
	v_add_co_u32_e32 v0, vcc, 0x12f00000, v0
	v_and_b32_e32 v11, 63, v17
	s_nop 0
	v_addc_co_u32_e32 v1, vcc, 0, v1, vcc
	global_load_dwordx4 v[0:3], v[0:1], off
	s_mov_b32 s6, 1
	s_waitcnt vmcnt(0) lgkmcnt(0)
	v_add_f32_e32 v1, v0, v1
	v_add_f32_e32 v2, v2, v1
	v_add_f32_e32 v3, v3, v2
	v_mov_b32_e32 v9, v3

.LBB0_1074:
	s_add_i32 s74, s0, 1
	s_cmp_lt_u32 s74, s69
	s_cselect_b64 s[62:63], -1, 0
	s_cmp_ge_u32 s74, s69
	s_cbranch_scc1 .LBB0_1076
	v_add_co_u32_e32 v0, vcc, 0x2000, v134
	s_waitcnt vmcnt(0)
	global_load_dwordx4 v[98:101], v[134:135], off
	v_addc_co_u32_e32 v1, vcc, 0, v135, vcc
	global_load_dwordx4 v[102:105], v[0:1], off
	v_add_co_u32_e32 v0, vcc, 0x20000, v136
	s_nop 1
	v_addc_co_u32_e32 v1, vcc, 0, v137, vcc
	global_load_dwordx4 v[106:109], v[136:137], off
	global_load_dwordx4 v[126:129], v[0:1], off

.LBB0_1086:
	s_and_b64 vcc, exec, s[0:1]
	s_cbranch_vccz .LBB0_1082
	v_add3_u32 v154, s29, v228, v132
	v_add_u32_e32 v155, s73, v230
	v_add3_u32 v156, s28, v226, v227
	v_add_u32_e32 v155, 0x11c00, v155
	ds_read_b128 v[0:3], v155 offset:0
	ds_read_b128 v[4:7], v155 offset:32
	ds_read_b128 v[8:11], v155 offset:64
	ds_read_b128 v[12:15], v155 offset:96
	ds_read_b128 v[16:19], v155 offset:128
	ds_read_b128 v[20:23], v155 offset:160
	ds_read_b128 v[24:27], v155 offset:192
	ds_read_b128 v[28:31], v155 offset:224
	ds_read_b128 v[82:85], v154
	ds_read_b128 v[86:89], v154 offset:4608
	ds_read_b128 v[90:93], v154 offset:32
	ds_read_b128 v[94:97], v154 offset:4640
	ds_read_b128 v[180:183], v154 offset:64
	ds_read_b128 v[184:187], v154 offset:4672
	ds_read_b128 v[188:191], v154 offset:96
	s_waitcnt lgkmcnt(14)
	v_sub_f32_e32 v0, v66, v0
	v_sub_f32_e32 v1, v66, v1
	v_sub_f32_e32 v2, v66, v2
	v_sub_f32_e32 v3, v66, v3
	s_waitcnt lgkmcnt(13)
	v_sub_f32_e32 v4, v66, v4
	v_sub_f32_e32 v5, v66, v5
	v_sub_f32_e32 v6, v66, v6
	v_sub_f32_e32 v7, v66, v7
	s_waitcnt lgkmcnt(12)
	v_sub_f32_e32 v8, v66, v8
	v_sub_f32_e32 v9, v66, v9
	v_sub_f32_e32 v10, v66, v10
	v_sub_f32_e32 v11, v66, v11
	s_waitcnt lgkmcnt(11)
	v_sub_f32_e32 v12, v66, v12
	v_sub_f32_e32 v13, v66, v13
	v_sub_f32_e32 v14, v66, v14
	v_sub_f32_e32 v15, v66, v15
	ds_read_b128 v[232:235], v154 offset:4704
	ds_read_b128 v[138:141], v155 offset:256
	ds_read_b128 v[142:145], v155 offset:288
	ds_read_b128 v[146:149], v155 offset:320
	s_waitcnt lgkmcnt(14)
	ds_read_b128 v[150:153], v155 offset:352
	s_waitcnt lgkmcnt(11)
	v_mfma_f32_32x32x16_bf16 v[0:15], v[82:85], v[118:121], v[0:15]
	v_sub_f32_e32 v16, v66, v16
	v_sub_f32_e32 v17, v66, v17
	v_sub_f32_e32 v18, v66, v18
	v_sub_f32_e32 v19, v66, v19
	v_sub_f32_e32 v20, v66, v20
	v_sub_f32_e32 v21, v66, v21
	v_sub_f32_e32 v22, v66, v22
	v_sub_f32_e32 v23, v66, v23
	v_sub_f32_e32 v24, v66, v24
	v_sub_f32_e32 v25, v66, v25
	v_sub_f32_e32 v26, v66, v26
	v_sub_f32_e32 v27, v66, v27
	v_sub_f32_e32 v28, v66, v28
	v_sub_f32_e32 v29, v66, v29
	v_sub_f32_e32 v30, v66, v30
	v_sub_f32_e32 v31, v66, v31
	ds_read_b128 v[164:167], v155 offset:384
	ds_read_b128 v[168:171], v155 offset:416
	ds_read_b128 v[172:175], v155 offset:448
	ds_read_b128 v[176:179], v155 offset:480
	s_waitcnt lgkmcnt(14)
	v_mfma_f32_32x32x16_bf16 v[16:31], v[86:89], v[118:121], v[16:31]
	ds_read_b128 v[82:85], v154 offset:9216
	s_waitcnt lgkmcnt(14)
	ds_read_b128 v[86:89], v154 offset:13824
	s_waitcnt lgkmcnt(9)
	v_sub_f32_e32 v138, v66, v138
	v_sub_f32_e32 v139, v66, v139
	v_sub_f32_e32 v140, v66, v140
	v_sub_f32_e32 v141, v66, v141
	s_waitcnt lgkmcnt(8)
	v_sub_f32_e32 v142, v66, v142
	v_sub_f32_e32 v143, v66, v143
	v_mfma_f32_32x32x16_bf16 v[0:15], v[90:93], v[110:113], v[0:15]
	ds_read_b128 v[90:93], v154 offset:9248
	v_sub_f32_e32 v144, v66, v144
	v_sub_f32_e32 v145, v66, v145
	s_waitcnt lgkmcnt(8)
	v_sub_f32_e32 v146, v66, v146
	v_sub_f32_e32 v147, v66, v147
	v_sub_f32_e32 v148, v66, v148
	v_mfma_f32_32x32x16_bf16 v[16:31], v[94:97], v[110:113], v[16:31]
	ds_read_b128 v[94:97], v154 offset:13856
	v_sub_f32_e32 v149, v66, v149
	s_waitcnt lgkmcnt(8)
	v_sub_f32_e32 v150, v66, v150
	v_sub_f32_e32 v151, v66, v151
	v_sub_f32_e32 v152, v66, v152
	v_sub_f32_e32 v153, v66, v153
	v_mfma_f32_32x32x16_bf16 v[0:15], v[180:183], v[114:117], v[0:15]
	ds_read_b128 v[180:183], v154 offset:9280
	s_waitcnt lgkmcnt(8)
	v_sub_f32_e32 v164, v66, v164
	v_sub_f32_e32 v165, v66, v165
	v_sub_f32_e32 v166, v66, v166
	v_sub_f32_e32 v167, v66, v167
	s_waitcnt lgkmcnt(7)
	v_sub_f32_e32 v168, v66, v168
	v_sub_f32_e32 v169, v66, v169
	v_mfma_f32_32x32x16_bf16 v[16:31], v[184:187], v[114:117], v[16:31]
	ds_read_b128 v[184:187], v154 offset:13888
	v_sub_f32_e32 v170, v66, v170
	v_sub_f32_e32 v171, v66, v171
	s_waitcnt lgkmcnt(7)
	v_sub_f32_e32 v172, v66, v172
	v_sub_f32_e32 v173, v66, v173
	v_sub_f32_e32 v174, v66, v174
	v_mfma_f32_32x32x16_bf16 v[0:15], v[188:191], v[122:125], v[0:15]
	ds_read_b128 v[188:191], v154 offset:9312
	v_sub_f32_e32 v175, v66, v175
	s_waitcnt lgkmcnt(7)
	v_sub_f32_e32 v176, v66, v176
	v_sub_f32_e32 v177, v66, v177
	v_sub_f32_e32 v178, v66, v178
	v_sub_f32_e32 v179, v66, v179
	v_mfma_f32_32x32x16_bf16 v[16:31], v[232:235], v[122:125], v[16:31]
	ds_read_b128 v[232:235], v154 offset:13920
	s_waitcnt lgkmcnt(7)
	v_mfma_f32_32x32x16_bf16 v[138:153], v[82:85], v[118:121], v[138:153]
	ds_read_b128 v[82:85], v156
	v_exp_f32_e32 v0, v0
	v_exp_f32_e32 v1, v1
	v_exp_f32_e32 v2, v2
	v_exp_f32_e32 v3, v3
	v_mov_b32_e32 v236, v0
	v_mov_b32_e32 v237, v1
	v_mov_b32_e32 v238, v2
	v_mov_b32_e32 v239, v3
	v_cvt_pk_bf16_f32 v0, v0, v1
	v_cvt_pk_bf16_f32 v1, v2, v3
	s_waitcnt lgkmcnt(7)
	v_mfma_f32_32x32x16_bf16 v[164:179], v[86:89], v[118:121], v[164:179]
	ds_read_b128 v[86:89], v156 offset:8704
	v_exp_f32_e32 v4, v4
	v_exp_f32_e32 v5, v5
	v_exp_f32_e32 v6, v6
	v_exp_f32_e32 v7, v7
	v_add_f32_e32 v236, v236, v4
	v_add_f32_e32 v237, v237, v5
	v_add_f32_e32 v238, v238, v6
	v_add_f32_e32 v239, v239, v7
	v_cvt_pk_bf16_f32 v2, v4, v5
	v_cvt_pk_bf16_f32 v3, v6, v7
	s_waitcnt lgkmcnt(7)
	v_mfma_f32_32x32x16_bf16 v[138:153], v[90:93], v[110:113], v[138:153]
	ds_read_b128 v[90:93], v156 offset:16
	v_exp_f32_e32 v8, v8
	v_exp_f32_e32 v9, v9
	v_exp_f32_e32 v10, v10
	v_exp_f32_e32 v11, v11
	v_add_f32_e32 v236, v236, v8
	v_add_f32_e32 v237, v237, v9
	v_add_f32_e32 v238, v238, v10
	v_add_f32_e32 v239, v239, v11
	v_cvt_pk_bf16_f32 v4, v8, v9
	v_cvt_pk_bf16_f32 v5, v10, v11
	s_waitcnt lgkmcnt(7)
	v_mfma_f32_32x32x16_bf16 v[164:179], v[94:97], v[110:113], v[164:179]
	ds_read_b128 v[94:97], v156 offset:8720
	v_exp_f32_e32 v12, v12
	v_exp_f32_e32 v13, v13
	v_exp_f32_e32 v14, v14
	v_exp_f32_e32 v15, v15
	v_add_f32_e32 v236, v236, v12
	v_add_f32_e32 v237, v237, v13
	v_add_f32_e32 v238, v238, v14
	v_add_f32_e32 v239, v239, v15
	v_cvt_pk_bf16_f32 v6, v12, v13
	v_cvt_pk_bf16_f32 v7, v14, v15
	s_waitcnt lgkmcnt(7)
	v_mfma_f32_32x32x16_bf16 v[138:153], v[180:183], v[114:117], v[138:153]
	ds_read_b128 v[180:183], v156 offset:64
	v_exp_f32_e32 v16, v16
	v_exp_f32_e32 v17, v17
	v_exp_f32_e32 v18, v18
	v_exp_f32_e32 v19, v19
	v_add_f32_e32 v236, v236, v16
	v_add_f32_e32 v237, v237, v17
	v_add_f32_e32 v238, v238, v18
	v_add_f32_e32 v239, v239, v19
	v_cvt_pk_bf16_f32 v16, v16, v17
	v_cvt_pk_bf16_f32 v17, v18, v19
	s_waitcnt lgkmcnt(7)
	v_mfma_f32_32x32x16_bf16 v[164:179], v[184:187], v[114:117], v[164:179]
	ds_read_b128 v[184:187], v156 offset:8768
	v_exp_f32_e32 v20, v20
	v_exp_f32_e32 v21, v21
	v_exp_f32_e32 v22, v22
	v_exp_f32_e32 v23, v23
	v_add_f32_e32 v236, v236, v20
	v_add_f32_e32 v237, v237, v21
	v_add_f32_e32 v238, v238, v22
	v_add_f32_e32 v239, v239, v23
	v_cvt_pk_bf16_f32 v18, v20, v21
	v_cvt_pk_bf16_f32 v19, v22, v23
	s_waitcnt lgkmcnt(7)
	v_mfma_f32_32x32x16_bf16 v[138:153], v[188:191], v[122:125], v[138:153]
	ds_read_b128 v[188:191], v156 offset:80
	v_exp_f32_e32 v24, v24
	v_exp_f32_e32 v25, v25
	v_exp_f32_e32 v26, v26
	v_exp_f32_e32 v27, v27
	v_add_f32_e32 v236, v236, v24
	v_add_f32_e32 v237, v237, v25
	v_add_f32_e32 v238, v238, v26
	v_add_f32_e32 v239, v239, v27
	v_cvt_pk_bf16_f32 v20, v24, v25
	v_cvt_pk_bf16_f32 v21, v26, v27
	s_waitcnt lgkmcnt(7)
	v_mfma_f32_32x32x16_bf16 v[164:179], v[232:235], v[122:125], v[164:179]
	ds_read_b128 v[232:235], v156 offset:8784
	v_exp_f32_e32 v28, v28
	v_exp_f32_e32 v29, v29
	v_exp_f32_e32 v30, v30
	v_exp_f32_e32 v31, v31
	v_add_f32_e32 v236, v236, v28
	v_add_f32_e32 v237, v237, v29
	v_add_f32_e32 v238, v238, v30
	v_add_f32_e32 v239, v239, v31
	v_cvt_pk_bf16_f32 v22, v28, v29
	v_cvt_pk_bf16_f32 v23, v30, v31
	s_waitcnt lgkmcnt(7)
	v_mfma_f32_32x32x16_bf16 v[32:47], v[82:85], v[0:3], v[32:47]
	ds_read_b128 v[82:85], v156 offset:128
	v_exp_f32_e32 v138, v138
	v_exp_f32_e32 v139, v139
	v_exp_f32_e32 v140, v140
	v_exp_f32_e32 v141, v141
	v_cvt_pk_bf16_f32 v8, v138, v139
	v_cvt_pk_bf16_f32 v9, v140, v141
	s_waitcnt lgkmcnt(7)
	v_mfma_f32_32x32x16_bf16 v[48:63], v[86:89], v[0:3], v[48:63]
	ds_read_b128 v[86:89], v156 offset:8832
	v_exp_f32_e32 v142, v142
	v_exp_f32_e32 v143, v143
	v_exp_f32_e32 v144, v144
	v_exp_f32_e32 v145, v145
	v_cvt_pk_bf16_f32 v10, v142, v143
	v_cvt_pk_bf16_f32 v11, v144, v145
	s_waitcnt lgkmcnt(7)
	v_mfma_f32_32x32x16_bf16 v[32:47], v[90:93], v[4:7], v[32:47]
	ds_read_b128 v[90:93], v156 offset:144
	v_exp_f32_e32 v146, v146
	v_exp_f32_e32 v147, v147
	v_exp_f32_e32 v148, v148
	v_exp_f32_e32 v149, v149
	v_cvt_pk_bf16_f32 v12, v146, v147
	v_cvt_pk_bf16_f32 v13, v148, v149
	s_waitcnt lgkmcnt(7)
	v_mfma_f32_32x32x16_bf16 v[48:63], v[94:97], v[4:7], v[48:63]
	ds_read_b128 v[94:97], v156 offset:8848
	v_exp_f32_e32 v150, v150
	v_exp_f32_e32 v151, v151
	v_exp_f32_e32 v152, v152
	v_exp_f32_e32 v153, v153
	v_cvt_pk_bf16_f32 v14, v150, v151
	v_cvt_pk_bf16_f32 v15, v152, v153
	s_waitcnt lgkmcnt(7)
	v_mfma_f32_32x32x16_bf16 v[32:47], v[180:183], v[16:19], v[32:47]
	ds_read_b128 v[180:183], v156 offset:192
	v_exp_f32_e32 v164, v164
	v_exp_f32_e32 v165, v165
	v_exp_f32_e32 v166, v166
	v_exp_f32_e32 v167, v167
	v_cvt_pk_bf16_f32 v24, v164, v165
	v_cvt_pk_bf16_f32 v25, v166, v167
	s_waitcnt lgkmcnt(7)
	v_mfma_f32_32x32x16_bf16 v[48:63], v[184:187], v[16:19], v[48:63]
	ds_read_b128 v[184:187], v156 offset:8896
	v_exp_f32_e32 v168, v168
	v_exp_f32_e32 v169, v169
	v_exp_f32_e32 v170, v170
	v_exp_f32_e32 v171, v171
	v_cvt_pk_bf16_f32 v26, v168, v169
	v_cvt_pk_bf16_f32 v27, v170, v171
	s_waitcnt lgkmcnt(7)
	v_mfma_f32_32x32x16_bf16 v[32:47], v[188:191], v[20:23], v[32:47]
	ds_read_b128 v[188:191], v156 offset:208
	v_exp_f32_e32 v172, v172
	v_exp_f32_e32 v173, v173
	v_exp_f32_e32 v174, v174
	v_exp_f32_e32 v175, v175
	v_cvt_pk_bf16_f32 v28, v172, v173
	v_cvt_pk_bf16_f32 v29, v174, v175
	s_waitcnt lgkmcnt(7)
	v_mfma_f32_32x32x16_bf16 v[48:63], v[232:235], v[20:23], v[48:63]
	ds_read_b128 v[232:235], v156 offset:8912
	v_exp_f32_e32 v176, v176
	v_exp_f32_e32 v177, v177
	v_exp_f32_e32 v178, v178
	v_exp_f32_e32 v179, v179
	v_cvt_pk_bf16_f32 v30, v176, v177
	v_cvt_pk_bf16_f32 v31, v178, v179
	s_waitcnt lgkmcnt(7)
	v_mfma_f32_32x32x16_bf16 v[32:47], v[82:85], v[8:11], v[32:47]
	v_add_f32_e32 v236, v236, v138
	v_add_f32_e32 v237, v237, v139
	v_add_f32_e32 v238, v238, v140
	v_add_f32_e32 v239, v239, v141
	s_waitcnt lgkmcnt(6)
	v_mfma_f32_32x32x16_bf16 v[48:63], v[86:89], v[8:11], v[48:63]
	v_add_f32_e32 v236, v236, v142
	v_add_f32_e32 v237, v237, v143
	v_add_f32_e32 v238, v238, v144
	v_add_f32_e32 v239, v239, v145
	s_waitcnt lgkmcnt(5)
	v_mfma_f32_32x32x16_bf16 v[32:47], v[90:93], v[12:15], v[32:47]
	v_add_f32_e32 v236, v236, v146
	v_add_f32_e32 v237, v237, v147
	v_add_f32_e32 v238, v238, v148
	v_add_f32_e32 v239, v239, v149
	s_waitcnt lgkmcnt(4)
	v_mfma_f32_32x32x16_bf16 v[48:63], v[94:97], v[12:15], v[48:63]
	v_add_f32_e32 v236, v236, v150
	v_add_f32_e32 v237, v237, v151
	v_add_f32_e32 v238, v238, v152
	v_add_f32_e32 v239, v239, v153
	s_waitcnt lgkmcnt(3)
	v_mfma_f32_32x32x16_bf16 v[32:47], v[180:183], v[24:27], v[32:47]
	v_add_f32_e32 v236, v236, v164
	v_add_f32_e32 v237, v237, v165
	v_add_f32_e32 v238, v238, v166
	v_add_f32_e32 v239, v239, v167
	s_waitcnt lgkmcnt(2)
	v_mfma_f32_32x32x16_bf16 v[48:63], v[184:187], v[24:27], v[48:63]
	v_add_f32_e32 v236, v236, v168
	v_add_f32_e32 v237, v237, v169
	v_add_f32_e32 v238, v238, v170
	v_add_f32_e32 v239, v239, v171
	s_waitcnt lgkmcnt(1)
	v_mfma_f32_32x32x16_bf16 v[32:47], v[188:191], v[28:31], v[32:47]
	v_add_f32_e32 v236, v236, v172
	v_add_f32_e32 v237, v237, v173
	v_add_f32_e32 v238, v238, v174
	v_add_f32_e32 v239, v239, v175
	s_waitcnt lgkmcnt(0)
	v_mfma_f32_32x32x16_bf16 v[48:63], v[232:235], v[28:31], v[48:63]
	v_add_f32_e32 v236, v236, v176
	v_add_f32_e32 v237, v237, v177
	v_add_f32_e32 v238, v238, v178
	v_add_f32_e32 v239, v239, v179
	v_add_f32_e32 v236, v236, v237
	v_add_f32_e32 v238, v238, v239
	v_add_f32_e32 v236, v236, v238
	v_add_f32_e32 v231, v231, v236
	s_and_b64 s[0:1], s[64:65], exec
	s_cselect_b32 s0, 0x4800, 0
	v_add_u32_e32 v154, s0, v133
	s_cselect_b32 s0, 0xd400, s75
	v_add_u32_e32 v155, s0, v163
	s_waitcnt vmcnt(0)
	ds_write_b128 v154, v[98:101]
	ds_write_b128 v154, v[102:105] offset:9216
	ds_write_b128 v155, v[106:109]
	ds_write_b128 v155, v[126:129] offset:8704
	s_addk_i32 s73, 0x200
	s_addk_i32 s71, 0x80
	s_add_i32 s72, s72, 2
	v_add_u32_e32 v229, 0xffffff80, v229
	v_lshl_add_u64 v[134:135], v[134:135], 0, s[82:83]
	v_lshl_add_u64 v[136:137], v[136:137], 0, s[80:81]
	s_mov_b32 s0, s74
	s_waitcnt lgkmcnt(0)
	s_barrier
	s_branch .LBB0_1074

.LBB0_1164:
	v_lshl_add_u32 v138, s35, 8, v140
	v_lshl_or_b32 v136, s34, 8, v142
	v_ashrrev_i32_e32 v139, 31, v138
	v_ashrrev_i32_e32 v137, 31, v136
	v_lshlrev_b64 v[144:145], 10, v[138:139]
	v_lshl_add_u64 v[148:149], v[144:145], 0, v[136:137]
	v_readlane_b32 s52, v255, 6
	v_lshlrev_b64 v[150:151], 2, v[148:149]
	v_readlane_b32 s53, v255, 7
	v_lshl_add_u64 v[154:155], v[148:149], 1, s[6:7]
	s_nop 0
	v_lshl_add_u64 v[152:153], s[52:53], 0, v[150:151]
	global_load_dwordx4 v[144:147], v[152:153], off
	v_readlane_b32 s52, v254, 45
	v_readlane_b32 s58, v254, 51
	v_readlane_b32 s59, v254, 52
	v_readlane_b32 s53, v254, 46
	s_lshl_b32 s52, s34, 2
	v_lshl_add_u64 v[156:157], s[58:59], 0, v[150:151]
	v_readlane_b32 s54, v254, 47
	v_readlane_b32 s55, v254, 48
	s_ashr_i32 s53, s52, 31
	v_readlane_b32 s56, v254, 49
	v_readlane_b32 s57, v254, 50
	s_waitcnt vmcnt(0) lgkmcnt(0)
	v_pk_add_f32 v[128:129], v[128:129], v[146:147]
	v_pk_add_f32 v[126:127], v[126:127], v[144:145]
	v_cvt_pk_bf16_f32 v145, v128, v129
	v_cvt_pk_bf16_f32 v144, v126, v127
	global_store_dwordx4 v[156:157], v[126:129], off
	global_store_dwordx2 v[154:155], v[144:145], off
	global_load_dwordx4 v[144:147], v[152:153], off offset:64
	s_waitcnt vmcnt(0) lgkmcnt(0)
	v_pk_add_f32 v[124:125], v[124:125], v[146:147]
	v_pk_add_f32 v[122:123], v[122:123], v[144:145]
	v_cvt_pk_bf16_f32 v145, v124, v125
	v_cvt_pk_bf16_f32 v144, v122, v123
	global_store_dwordx4 v[156:157], v[122:125], off offset:64
	global_store_dwordx2 v[154:155], v[144:145], off offset:32
	global_load_dwordx4 v[144:147], v[152:153], off offset:512
	s_waitcnt vmcnt(0) lgkmcnt(0)
	v_pk_add_f32 v[146:147], v[120:121], v[146:147]
	v_pk_add_f32 v[144:145], v[118:119], v[144:145]
	v_cvt_pk_bf16_f32 v119, v146, v147
	v_cvt_pk_bf16_f32 v118, v144, v145
	global_store_dwordx4 v[156:157], v[144:147], off offset:512
	global_store_dwordx2 v[154:155], v[118:119], off offset:256
	global_load_dwordx4 v[148:151], v[152:153], off offset:576
	v_mul_f32_e32 v120, v127, v127
	v_mul_f32_e32 v121, v129, v129
	v_fmac_f32_e32 v120, v126, v126
	v_fmac_f32_e32 v121, v128, v128
	v_add_f32_e32 v120, v120, v121
	v_mul_f32_e32 v121, v123, v123
	v_mul_f32_e32 v123, v125, v125
	v_fmac_f32_e32 v121, v122, v122
	v_fmac_f32_e32 v123, v124, v124
	v_add_f32_e32 v121, v121, v123
	v_add_f32_e32 v120, v120, v121
	v_mul_f32_e32 v121, v145, v145
	v_mul_f32_e32 v122, v147, v147
	v_fmac_f32_e32 v121, v144, v144
	v_fmac_f32_e32 v122, v146, v146
	v_add_f32_e32 v121, v121, v122
	v_and_b32_e32 v119, 64, v197
	v_add_f32_e32 v124, v120, v121
	v_xor_b32_e32 v118, 16, v197
	v_add_u32_e32 v119, 64, v119
	v_cmp_lt_i32_e32 vcc, v118, v119
	s_waitcnt vmcnt(0) lgkmcnt(0)
	v_pk_add_f32 v[122:123], v[116:117], v[150:151]
	v_pk_add_f32 v[120:121], v[114:115], v[148:149]
	v_mul_f32_e32 v115, v123, v123
	v_mul_f32_e32 v114, v121, v121
	v_fmac_f32_e32 v114, v120, v120
	v_fmac_f32_e32 v115, v122, v122
	v_cndmask_b32_e32 v118, v197, v118, vcc
	v_add_f32_e32 v114, v114, v115
	v_lshlrev_b32_e32 v118, 2, v118
	v_add_f32_e32 v114, v124, v114
	ds_bpermute_b32 v115, v118, v114
	v_xor_b32_e32 v116, 32, v197
	v_cmp_lt_i32_e32 vcc, v116, v119
	global_store_dwordx4 v[156:157], v[120:123], off offset:576
	s_waitcnt lgkmcnt(0)
	v_add_f32_e32 v114, v114, v115
	v_cndmask_b32_e32 v116, v197, v116, vcc
	v_lshlrev_b32_e32 v116, 2, v116
	ds_bpermute_b32 v115, v116, v114
	v_cvt_pk_bf16_f32 v120, v120, v121
	v_cvt_pk_bf16_f32 v121, v122, v123
	global_store_dwordx2 v[154:155], v[120:121], off offset:288
	s_and_saveexec_b64 s[54:55], s[0:1]
	s_cbranch_execz .LBB0_1166
	v_readlane_b32 s34, v254, 43
	v_lshlrev_b64 v[120:121], 6, v[138:139]
	v_readlane_b32 s35, v254, 44
	v_lshl_add_u64 v[120:121], s[42:43], 0, v[120:121]
	s_mov_b32 s31, s35
	v_lshl_add_u64 v[120:121], s[52:53], 2, v[120:121]
	s_lshl_b32 s34, s64, 2
	v_writelane_b32 v254, s30, 43
	v_lshl_add_u64 v[120:121], v[120:121], 0, s[34:35]
	s_waitcnt lgkmcnt(0)
	v_add_f32_e32 v114, v114, v115
	v_writelane_b32 v254, s31, 44
	global_store_dword v[120:121], v114, off
.LBB0_1166:
	s_or_b64 exec, exec, s[54:55]
	v_or_b32_e32 v114, 16, v138
	s_waitcnt lgkmcnt(0)
	v_ashrrev_i32_e32 v115, 31, v114
	v_lshlrev_b64 v[120:121], 10, v[114:115]
	v_lshl_add_u64 v[124:125], v[120:121], 0, v[136:137]
	v_readlane_b32 s34, v255, 6
	v_lshlrev_b64 v[126:127], 2, v[124:125]
	v_readlane_b32 s35, v255, 7
	v_readlane_b32 s68, v254, 45
	v_readlane_b32 s74, v254, 51
	v_lshl_add_u64 v[128:129], s[34:35], 0, v[126:127]
	global_load_dwordx4 v[120:123], v[128:129], off
	v_readlane_b32 s75, v254, 52
	v_lshl_add_u64 v[124:125], v[124:125], 1, s[6:7]
	v_readlane_b32 s69, v254, 46
	v_lshl_add_u64 v[126:127], s[74:75], 0, v[126:127]
	v_readlane_b32 s70, v254, 47
	v_readlane_b32 s71, v254, 48
	v_readlane_b32 s72, v254, 49
	v_readlane_b32 s73, v254, 50
	s_waitcnt vmcnt(0) lgkmcnt(0)
	v_pk_add_f32 v[112:113], v[112:113], v[122:123]
	v_pk_add_f32 v[110:111], v[110:111], v[120:121]
	v_cvt_pk_bf16_f32 v121, v112, v113
	v_cvt_pk_bf16_f32 v120, v110, v111
	global_store_dwordx4 v[126:127], v[110:113], off
	global_store_dwordx2 v[124:125], v[120:121], off
	global_load_dwordx4 v[120:123], v[128:129], off offset:64
	v_mul_f32_e32 v111, v111, v111
	v_mul_f32_e32 v113, v113, v113
	v_fmac_f32_e32 v111, v110, v110
	v_fmac_f32_e32 v113, v112, v112
	v_add_f32_e32 v110, v111, v113
	s_waitcnt vmcnt(0) lgkmcnt(0)
	v_pk_add_f32 v[108:109], v[108:109], v[122:123]
	v_pk_add_f32 v[106:107], v[106:107], v[120:121]
	v_cvt_pk_bf16_f32 v121, v108, v109
	v_cvt_pk_bf16_f32 v120, v106, v107
	global_store_dwordx4 v[126:127], v[106:109], off offset:64
	global_store_dwordx2 v[124:125], v[120:121], off offset:32
	global_load_dwordx4 v[120:123], v[128:129], off offset:512
	v_mul_f32_e32 v107, v107, v107
	v_mul_f32_e32 v109, v109, v109
	v_fmac_f32_e32 v107, v106, v106
	v_fmac_f32_e32 v109, v108, v108
	v_add_f32_e32 v106, v107, v109
	v_add_f32_e32 v106, v110, v106
	s_waitcnt vmcnt(0) lgkmcnt(0)
	v_pk_add_f32 v[104:105], v[104:105], v[122:123]
	v_pk_add_f32 v[102:103], v[102:103], v[120:121]
	v_cvt_pk_bf16_f32 v121, v104, v105
	v_cvt_pk_bf16_f32 v120, v102, v103
	global_store_dwordx4 v[126:127], v[102:105], off offset:512
	global_store_dwordx2 v[124:125], v[120:121], off offset:256
	global_load_dwordx4 v[120:123], v[128:129], off offset:576
	v_mul_f32_e32 v103, v103, v103
	v_mul_f32_e32 v105, v105, v105
	v_fmac_f32_e32 v103, v102, v102
	v_fmac_f32_e32 v105, v104, v104
	v_add_f32_e32 v102, v103, v105
	v_add_f32_e32 v104, v106, v102
	s_waitcnt vmcnt(0) lgkmcnt(0)
	v_pk_add_f32 v[102:103], v[100:101], v[122:123]
	v_pk_add_f32 v[100:101], v[98:99], v[120:121]
	v_mul_f32_e32 v99, v103, v103
	v_mul_f32_e32 v98, v101, v101
	v_fmac_f32_e32 v98, v100, v100
	v_fmac_f32_e32 v99, v102, v102
	v_add_f32_e32 v98, v98, v99
	v_add_f32_e32 v98, v104, v98
	ds_bpermute_b32 v99, v118, v98
	global_store_dwordx4 v[126:127], v[100:103], off offset:576
	s_waitcnt lgkmcnt(0)
	v_add_f32_e32 v98, v98, v99
	ds_bpermute_b32 v99, v116, v98
	v_cvt_pk_bf16_f32 v100, v100, v101
	v_cvt_pk_bf16_f32 v101, v102, v103
	global_store_dwordx2 v[124:125], v[100:101], off offset:288
	s_and_saveexec_b64 s[54:55], s[0:1]
	s_cbranch_execz .LBB0_1168
	v_readlane_b32 s34, v254, 43
	v_lshlrev_b64 v[100:101], 6, v[114:115]
	v_readlane_b32 s35, v254, 44
	v_lshl_add_u64 v[100:101], s[42:43], 0, v[100:101]
	s_mov_b32 s31, s35
	v_lshl_add_u64 v[100:101], s[52:53], 2, v[100:101]
	s_lshl_b32 s34, s64, 2
	v_writelane_b32 v254, s30, 43
	v_lshl_add_u64 v[100:101], v[100:101], 0, s[34:35]
	s_waitcnt lgkmcnt(0)
	v_add_f32_e32 v98, v98, v99
	v_writelane_b32 v254, s31, 44
	global_store_dword v[100:101], v98, off
.LBB0_1168:
	s_or_b64 exec, exec, s[54:55]
	v_or_b32_e32 v98, 32, v138
	s_waitcnt lgkmcnt(0)
	v_ashrrev_i32_e32 v99, 31, v98
	v_lshlrev_b64 v[100:101], 10, v[98:99]
	v_lshl_add_u64 v[104:105], v[100:101], 0, v[136:137]
	v_readlane_b32 s34, v255, 6
	v_lshlrev_b64 v[106:107], 2, v[104:105]
	v_readlane_b32 s35, v255, 7
	v_readlane_b32 s68, v254, 45
	v_readlane_b32 s74, v254, 51
	v_lshl_add_u64 v[108:109], s[34:35], 0, v[106:107]
	global_load_dwordx4 v[100:103], v[108:109], off
	v_readlane_b32 s75, v254, 52
	v_lshl_add_u64 v[104:105], v[104:105], 1, s[6:7]
	v_readlane_b32 s69, v254, 46
	v_lshl_add_u64 v[106:107], s[74:75], 0, v[106:107]
	v_readlane_b32 s70, v254, 47
	v_readlane_b32 s71, v254, 48
	v_readlane_b32 s72, v254, 49
	v_readlane_b32 s73, v254, 50
	s_waitcnt vmcnt(0) lgkmcnt(0)
	v_pk_add_f32 v[96:97], v[96:97], v[102:103]
	v_pk_add_f32 v[94:95], v[94:95], v[100:101]
	v_cvt_pk_bf16_f32 v101, v96, v97
	v_cvt_pk_bf16_f32 v100, v94, v95
	global_store_dwordx4 v[106:107], v[94:97], off
	global_store_dwordx2 v[104:105], v[100:101], off
	global_load_dwordx4 v[100:103], v[108:109], off offset:64
	v_mul_f32_e32 v95, v95, v95
	v_mul_f32_e32 v97, v97, v97
	v_fmac_f32_e32 v95, v94, v94
	v_fmac_f32_e32 v97, v96, v96
	v_add_f32_e32 v94, v95, v97
	s_waitcnt vmcnt(0) lgkmcnt(0)
	v_pk_add_f32 v[92:93], v[92:93], v[102:103]
	v_pk_add_f32 v[90:91], v[90:91], v[100:101]
	v_cvt_pk_bf16_f32 v101, v92, v93
	v_cvt_pk_bf16_f32 v100, v90, v91
	global_store_dwordx4 v[106:107], v[90:93], off offset:64
	global_store_dwordx2 v[104:105], v[100:101], off offset:32
	global_load_dwordx4 v[100:103], v[108:109], off offset:512
	v_mul_f32_e32 v91, v91, v91
	v_mul_f32_e32 v93, v93, v93
	v_fmac_f32_e32 v91, v90, v90
	v_fmac_f32_e32 v93, v92, v92
	v_add_f32_e32 v90, v91, v93
	v_add_f32_e32 v90, v94, v90
	s_waitcnt vmcnt(0) lgkmcnt(0)
	v_pk_add_f32 v[88:89], v[88:89], v[102:103]
	v_pk_add_f32 v[86:87], v[86:87], v[100:101]
	v_cvt_pk_bf16_f32 v101, v88, v89
	v_cvt_pk_bf16_f32 v100, v86, v87
	global_store_dwordx4 v[106:107], v[86:89], off offset:512
	global_store_dwordx2 v[104:105], v[100:101], off offset:256
	global_load_dwordx4 v[100:103], v[108:109], off offset:576
	v_mul_f32_e32 v87, v87, v87
	v_mul_f32_e32 v89, v89, v89
	v_fmac_f32_e32 v87, v86, v86
	v_fmac_f32_e32 v89, v88, v88
	v_add_f32_e32 v86, v87, v89
	v_add_f32_e32 v88, v90, v86
	s_waitcnt vmcnt(0) lgkmcnt(0)
	v_pk_add_f32 v[86:87], v[84:85], v[102:103]
	v_pk_add_f32 v[84:85], v[82:83], v[100:101]
	v_mul_f32_e32 v83, v87, v87
	v_mul_f32_e32 v82, v85, v85
	v_fmac_f32_e32 v82, v84, v84
	v_fmac_f32_e32 v83, v86, v86
	v_add_f32_e32 v82, v82, v83
	v_add_f32_e32 v82, v88, v82
	ds_bpermute_b32 v83, v118, v82
	global_store_dwordx4 v[106:107], v[84:87], off offset:576
	s_waitcnt lgkmcnt(0)
	v_add_f32_e32 v82, v82, v83
	ds_bpermute_b32 v83, v116, v82
	v_cvt_pk_bf16_f32 v84, v84, v85
	v_cvt_pk_bf16_f32 v85, v86, v87
	global_store_dwordx2 v[104:105], v[84:85], off offset:288
	s_mov_b64 s[54:55], exec
	v_readlane_b32 s92, v252, 6
	s_and_b64 s[34:35], s[54:55], s[0:1]
	v_readlane_b32 s93, v252, 7
	v_mov_b32_e32 v200, v202
	s_mov_b64 exec, s[34:35]
	s_cbranch_execz .LBB0_1170
	v_readlane_b32 s34, v254, 43
	v_lshlrev_b64 v[84:85], 6, v[98:99]
	v_readlane_b32 s35, v254, 44
	v_lshl_add_u64 v[84:85], s[42:43], 0, v[84:85]
	s_mov_b32 s31, s35
	v_lshl_add_u64 v[84:85], s[52:53], 2, v[84:85]
	s_lshl_b32 s34, s64, 2
	v_writelane_b32 v254, s30, 43
	v_lshl_add_u64 v[84:85], v[84:85], 0, s[34:35]
	s_waitcnt lgkmcnt(0)
	v_add_f32_e32 v82, v82, v83
	v_writelane_b32 v254, s31, 44
	global_store_dword v[84:85], v82, off
.LBB0_1170:
	s_or_b64 exec, exec, s[54:55]
	v_or_b32_e32 v82, 48, v138
	s_waitcnt lgkmcnt(0)
	v_ashrrev_i32_e32 v83, 31, v82
	v_lshlrev_b64 v[84:85], 10, v[82:83]
	v_lshl_add_u64 v[88:89], v[84:85], 0, v[136:137]
	v_readlane_b32 s34, v255, 6
	v_lshlrev_b64 v[90:91], 2, v[88:89]
	v_readlane_b32 s35, v255, 7
	v_readlane_b32 s84, v254, 45
	v_readlane_b32 s90, v254, 51
	v_lshl_add_u64 v[92:93], s[34:35], 0, v[90:91]
	global_load_dwordx4 v[84:87], v[92:93], off
	v_readlane_b32 s91, v254, 52
	v_lshl_add_u64 v[88:89], v[88:89], 1, s[6:7]
	v_readlane_b32 s85, v254, 46
	v_lshl_add_u64 v[90:91], s[90:91], 0, v[90:91]
	v_readlane_b32 s86, v254, 47
	v_readlane_b32 s87, v254, 48
	v_readlane_b32 s88, v254, 49
	v_readlane_b32 s89, v254, 50
	s_waitcnt vmcnt(0) lgkmcnt(0)
	v_pk_add_f32 v[80:81], v[80:81], v[86:87]
	v_pk_add_f32 v[78:79], v[78:79], v[84:85]
	v_cvt_pk_bf16_f32 v85, v80, v81
	v_cvt_pk_bf16_f32 v84, v78, v79
	global_store_dwordx4 v[90:91], v[78:81], off
	global_store_dwordx2 v[88:89], v[84:85], off
	global_load_dwordx4 v[84:87], v[92:93], off offset:64
	v_mul_f32_e32 v79, v79, v79
	v_mul_f32_e32 v81, v81, v81
	v_fmac_f32_e32 v79, v78, v78
	v_fmac_f32_e32 v81, v80, v80
	v_add_f32_e32 v78, v79, v81
	s_waitcnt vmcnt(0) lgkmcnt(0)
	v_pk_add_f32 v[76:77], v[76:77], v[86:87]
	v_pk_add_f32 v[74:75], v[74:75], v[84:85]
	v_cvt_pk_bf16_f32 v85, v76, v77
	v_cvt_pk_bf16_f32 v84, v74, v75
	global_store_dwordx4 v[90:91], v[74:77], off offset:64
	global_store_dwordx2 v[88:89], v[84:85], off offset:32
	global_load_dwordx4 v[84:87], v[92:93], off offset:512
	v_mul_f32_e32 v75, v75, v75
	v_mul_f32_e32 v77, v77, v77
	v_fmac_f32_e32 v75, v74, v74
	v_fmac_f32_e32 v77, v76, v76
	v_add_f32_e32 v74, v75, v77
	v_add_f32_e32 v74, v78, v74
	s_waitcnt vmcnt(0) lgkmcnt(0)
	v_pk_add_f32 v[72:73], v[72:73], v[86:87]
	v_pk_add_f32 v[70:71], v[70:71], v[84:85]
	v_cvt_pk_bf16_f32 v85, v72, v73
	v_cvt_pk_bf16_f32 v84, v70, v71
	global_store_dwordx4 v[90:91], v[70:73], off offset:512
	global_store_dwordx2 v[88:89], v[84:85], off offset:256
	global_load_dwordx4 v[84:87], v[92:93], off offset:576
	v_mul_f32_e32 v71, v71, v71
	v_mul_f32_e32 v73, v73, v73
	v_fmac_f32_e32 v71, v70, v70
	v_fmac_f32_e32 v73, v72, v72
	v_add_f32_e32 v70, v71, v73
	v_add_f32_e32 v72, v74, v70
	s_waitcnt vmcnt(0) lgkmcnt(0)
	v_pk_add_f32 v[70:71], v[68:69], v[86:87]
	v_pk_add_f32 v[68:69], v[66:67], v[84:85]
	v_mul_f32_e32 v67, v71, v71
	v_mul_f32_e32 v66, v69, v69
	v_fmac_f32_e32 v66, v68, v68
	v_fmac_f32_e32 v67, v70, v70
	v_add_f32_e32 v66, v66, v67
	v_add_f32_e32 v66, v72, v66
	ds_bpermute_b32 v67, v118, v66
	global_store_dwordx4 v[90:91], v[68:71], off offset:576
	s_waitcnt lgkmcnt(0)
	v_add_f32_e32 v66, v66, v67
	ds_bpermute_b32 v67, v116, v66
	v_cvt_pk_bf16_f32 v68, v68, v69
	v_cvt_pk_bf16_f32 v69, v70, v71
	global_store_dwordx2 v[88:89], v[68:69], off offset:288
	s_and_saveexec_b64 s[54:55], s[0:1]
	s_cbranch_execz .LBB0_1172
	v_readlane_b32 s34, v254, 43
	v_lshlrev_b64 v[68:69], 6, v[82:83]
	v_readlane_b32 s35, v254, 44
	v_lshl_add_u64 v[68:69], s[42:43], 0, v[68:69]
	s_mov_b32 s31, s35
	v_lshl_add_u64 v[68:69], s[52:53], 2, v[68:69]
	s_lshl_b32 s34, s64, 2
	v_writelane_b32 v254, s30, 43
	v_lshl_add_u64 v[68:69], v[68:69], 0, s[34:35]
	s_waitcnt lgkmcnt(0)
	v_add_f32_e32 v66, v66, v67
	v_writelane_b32 v254, s31, 44
	global_store_dword v[68:69], v66, off
.LBB0_1172:
	s_or_b64 exec, exec, s[54:55]
	v_add_u32_e32 v66, 0x80, v138
	s_waitcnt lgkmcnt(0)
	v_ashrrev_i32_e32 v67, 31, v66
	v_lshlrev_b64 v[68:69], 10, v[66:67]
	v_lshl_add_u64 v[72:73], v[68:69], 0, v[136:137]
	v_readlane_b32 s34, v255, 6
	v_lshlrev_b64 v[74:75], 2, v[72:73]
	v_readlane_b32 s35, v255, 7
	v_readlane_b32 s84, v254, 45
	v_readlane_b32 s90, v254, 51
	v_lshl_add_u64 v[76:77], s[34:35], 0, v[74:75]
	global_load_dwordx4 v[68:71], v[76:77], off
	v_readlane_b32 s91, v254, 52
	v_lshl_add_u64 v[72:73], v[72:73], 1, s[6:7]
	v_readlane_b32 s85, v254, 46
	v_lshl_add_u64 v[74:75], s[90:91], 0, v[74:75]
	v_readlane_b32 s86, v254, 47
	v_readlane_b32 s87, v254, 48
	v_readlane_b32 s88, v254, 49
	v_readlane_b32 s89, v254, 50
	s_waitcnt vmcnt(0) lgkmcnt(0)
	v_pk_add_f32 v[62:63], v[62:63], v[70:71]
	v_pk_add_f32 v[60:61], v[60:61], v[68:69]
	v_cvt_pk_bf16_f32 v69, v62, v63
	v_cvt_pk_bf16_f32 v68, v60, v61
	global_store_dwordx4 v[74:75], v[60:63], off
	global_store_dwordx2 v[72:73], v[68:69], off
	global_load_dwordx4 v[68:71], v[76:77], off offset:64
	v_mul_f32_e32 v61, v61, v61
	v_mul_f32_e32 v63, v63, v63
	v_fmac_f32_e32 v61, v60, v60
	v_fmac_f32_e32 v63, v62, v62
	v_add_f32_e32 v60, v61, v63
	s_waitcnt vmcnt(0) lgkmcnt(0)
	v_pk_add_f32 v[58:59], v[58:59], v[70:71]
	v_pk_add_f32 v[56:57], v[56:57], v[68:69]
	v_cvt_pk_bf16_f32 v69, v58, v59
	v_cvt_pk_bf16_f32 v68, v56, v57
	global_store_dwordx4 v[74:75], v[56:59], off offset:64
	global_store_dwordx2 v[72:73], v[68:69], off offset:32
	global_load_dwordx4 v[68:71], v[76:77], off offset:512
	v_mul_f32_e32 v57, v57, v57
	v_mul_f32_e32 v59, v59, v59
	v_fmac_f32_e32 v57, v56, v56
	v_fmac_f32_e32 v59, v58, v58
	v_add_f32_e32 v56, v57, v59
	v_add_f32_e32 v56, v60, v56
	s_waitcnt vmcnt(0) lgkmcnt(0)
	v_pk_add_f32 v[54:55], v[54:55], v[70:71]
	v_pk_add_f32 v[52:53], v[52:53], v[68:69]
	v_cvt_pk_bf16_f32 v69, v54, v55
	v_cvt_pk_bf16_f32 v68, v52, v53
	global_store_dwordx4 v[74:75], v[52:55], off offset:512
	global_store_dwordx2 v[72:73], v[68:69], off offset:256
	global_load_dwordx4 v[68:71], v[76:77], off offset:576
	v_mul_f32_e32 v53, v53, v53
	v_mul_f32_e32 v55, v55, v55
	v_fmac_f32_e32 v53, v52, v52
	v_fmac_f32_e32 v55, v54, v54
	v_add_f32_e32 v52, v53, v55
	v_add_f32_e32 v54, v56, v52
	s_waitcnt vmcnt(0) lgkmcnt(0)
	v_pk_add_f32 v[52:53], v[50:51], v[70:71]
	v_pk_add_f32 v[50:51], v[48:49], v[68:69]
	v_mul_f32_e32 v49, v53, v53
	v_mul_f32_e32 v48, v51, v51
	v_fmac_f32_e32 v48, v50, v50
	v_fmac_f32_e32 v49, v52, v52
	v_add_f32_e32 v48, v48, v49
	v_add_f32_e32 v48, v54, v48
	ds_bpermute_b32 v49, v118, v48
	global_store_dwordx4 v[74:75], v[50:53], off offset:576
	s_waitcnt lgkmcnt(0)
	v_add_f32_e32 v48, v48, v49
	ds_bpermute_b32 v49, v116, v48
	v_cvt_pk_bf16_f32 v50, v50, v51
	v_cvt_pk_bf16_f32 v51, v52, v53
	global_store_dwordx2 v[72:73], v[50:51], off offset:288
	s_and_saveexec_b64 s[54:55], s[0:1]
	s_cbranch_execz .LBB0_1174
	v_readlane_b32 s34, v254, 43
	v_lshlrev_b64 v[50:51], 6, v[66:67]
	v_readlane_b32 s35, v254, 44
	v_lshl_add_u64 v[50:51], s[42:43], 0, v[50:51]
	s_mov_b32 s31, s35
	v_lshl_add_u64 v[50:51], s[52:53], 2, v[50:51]
	s_lshl_b32 s34, s64, 2
	v_writelane_b32 v254, s30, 43
	v_lshl_add_u64 v[50:51], v[50:51], 0, s[34:35]
	s_waitcnt lgkmcnt(0)
	v_add_f32_e32 v48, v48, v49
	v_writelane_b32 v254, s31, 44
	global_store_dword v[50:51], v48, off
.LBB0_1174:
	s_or_b64 exec, exec, s[54:55]
	v_add_u32_e32 v48, 0x90, v138
	s_waitcnt lgkmcnt(0)
	v_ashrrev_i32_e32 v49, 31, v48
	v_lshlrev_b64 v[50:51], 10, v[48:49]
	v_lshl_add_u64 v[54:55], v[50:51], 0, v[136:137]
	v_readlane_b32 s34, v255, 6
	v_lshlrev_b64 v[56:57], 2, v[54:55]
	v_readlane_b32 s35, v255, 7
	v_readlane_b32 s84, v254, 45
	v_readlane_b32 s90, v254, 51
	v_lshl_add_u64 v[58:59], s[34:35], 0, v[56:57]
	global_load_dwordx4 v[50:53], v[58:59], off
	v_readlane_b32 s91, v254, 52
	v_lshl_add_u64 v[54:55], v[54:55], 1, s[6:7]
	v_readlane_b32 s85, v254, 46
	v_lshl_add_u64 v[56:57], s[90:91], 0, v[56:57]
	v_readlane_b32 s86, v254, 47
	v_readlane_b32 s87, v254, 48
	v_readlane_b32 s88, v254, 49
	v_readlane_b32 s89, v254, 50
	s_waitcnt vmcnt(0) lgkmcnt(0)
	v_pk_add_f32 v[46:47], v[46:47], v[52:53]
	v_pk_add_f32 v[44:45], v[44:45], v[50:51]
	v_cvt_pk_bf16_f32 v51, v46, v47
	v_cvt_pk_bf16_f32 v50, v44, v45
	global_store_dwordx4 v[56:57], v[44:47], off
	global_store_dwordx2 v[54:55], v[50:51], off
	global_load_dwordx4 v[50:53], v[58:59], off offset:64
	v_mul_f32_e32 v45, v45, v45
	v_mul_f32_e32 v47, v47, v47
	v_fmac_f32_e32 v45, v44, v44
	v_fmac_f32_e32 v47, v46, v46
	v_add_f32_e32 v44, v45, v47
	s_waitcnt vmcnt(0) lgkmcnt(0)
	v_pk_add_f32 v[42:43], v[42:43], v[52:53]
	v_pk_add_f32 v[40:41], v[40:41], v[50:51]
	v_cvt_pk_bf16_f32 v51, v42, v43
	v_cvt_pk_bf16_f32 v50, v40, v41
	global_store_dwordx4 v[56:57], v[40:43], off offset:64
	global_store_dwordx2 v[54:55], v[50:51], off offset:32
	global_load_dwordx4 v[50:53], v[58:59], off offset:512
	v_mul_f32_e32 v41, v41, v41
	v_mul_f32_e32 v43, v43, v43
	v_fmac_f32_e32 v41, v40, v40
	v_fmac_f32_e32 v43, v42, v42
	v_add_f32_e32 v40, v41, v43
	v_add_f32_e32 v40, v44, v40
	s_waitcnt vmcnt(0) lgkmcnt(0)
	v_pk_add_f32 v[38:39], v[38:39], v[52:53]
	v_pk_add_f32 v[36:37], v[36:37], v[50:51]
	v_cvt_pk_bf16_f32 v51, v38, v39
	v_cvt_pk_bf16_f32 v50, v36, v37
	global_store_dwordx4 v[56:57], v[36:39], off offset:512
	global_store_dwordx2 v[54:55], v[50:51], off offset:256
	global_load_dwordx4 v[50:53], v[58:59], off offset:576
	v_mul_f32_e32 v37, v37, v37
	v_mul_f32_e32 v39, v39, v39
	v_fmac_f32_e32 v37, v36, v36
	v_fmac_f32_e32 v39, v38, v38
	v_add_f32_e32 v36, v37, v39
	v_add_f32_e32 v38, v40, v36
	s_waitcnt vmcnt(0) lgkmcnt(0)
	v_pk_add_f32 v[36:37], v[34:35], v[52:53]
	v_pk_add_f32 v[34:35], v[32:33], v[50:51]
	v_mul_f32_e32 v33, v37, v37
	v_mul_f32_e32 v32, v35, v35
	v_fmac_f32_e32 v32, v34, v34
	v_fmac_f32_e32 v33, v36, v36
	v_add_f32_e32 v32, v32, v33
	v_add_f32_e32 v32, v38, v32
	ds_bpermute_b32 v33, v118, v32
	global_store_dwordx4 v[56:57], v[34:37], off offset:576
	s_waitcnt lgkmcnt(0)
	v_add_f32_e32 v32, v32, v33
	ds_bpermute_b32 v33, v116, v32
	v_cvt_pk_bf16_f32 v34, v34, v35
	v_cvt_pk_bf16_f32 v35, v36, v37
	global_store_dwordx2 v[54:55], v[34:35], off offset:288
	s_and_saveexec_b64 s[54:55], s[0:1]
	s_cbranch_execz .LBB0_1176
	v_readlane_b32 s34, v254, 43
	v_lshlrev_b64 v[34:35], 6, v[48:49]
	v_readlane_b32 s35, v254, 44
	v_lshl_add_u64 v[34:35], s[42:43], 0, v[34:35]
	s_mov_b32 s31, s35
	v_lshl_add_u64 v[34:35], s[52:53], 2, v[34:35]
	s_lshl_b32 s34, s64, 2
	v_writelane_b32 v254, s30, 43
	v_lshl_add_u64 v[34:35], v[34:35], 0, s[34:35]
	s_waitcnt lgkmcnt(0)
	v_add_f32_e32 v32, v32, v33
	v_writelane_b32 v254, s31, 44
	global_store_dword v[34:35], v32, off
.LBB0_1176:
	s_or_b64 exec, exec, s[54:55]
	v_add_u32_e32 v32, 0xa0, v138
	s_waitcnt lgkmcnt(0)
	v_ashrrev_i32_e32 v33, 31, v32
	v_lshlrev_b64 v[34:35], 10, v[32:33]
	v_lshl_add_u64 v[38:39], v[34:35], 0, v[136:137]
	v_readlane_b32 s34, v255, 6
	v_lshlrev_b64 v[40:41], 2, v[38:39]
	v_readlane_b32 s35, v255, 7
	v_readlane_b32 s84, v254, 45
	v_readlane_b32 s90, v254, 51
	v_lshl_add_u64 v[42:43], s[34:35], 0, v[40:41]
	global_load_dwordx4 v[34:37], v[42:43], off
	v_readlane_b32 s91, v254, 52
	v_lshl_add_u64 v[38:39], v[38:39], 1, s[6:7]
	v_readlane_b32 s85, v254, 46
	v_lshl_add_u64 v[40:41], s[90:91], 0, v[40:41]
	v_readlane_b32 s86, v254, 47
	v_readlane_b32 s87, v254, 48
	v_readlane_b32 s88, v254, 49
	v_readlane_b32 s89, v254, 50
	s_waitcnt vmcnt(0) lgkmcnt(0)
	v_pk_add_f32 v[30:31], v[30:31], v[36:37]
	v_pk_add_f32 v[28:29], v[28:29], v[34:35]
	v_cvt_pk_bf16_f32 v35, v30, v31
	v_cvt_pk_bf16_f32 v34, v28, v29
	global_store_dwordx4 v[40:41], v[28:31], off
	global_store_dwordx2 v[38:39], v[34:35], off
	global_load_dwordx4 v[34:37], v[42:43], off offset:64
	v_mul_f32_e32 v29, v29, v29
	v_mul_f32_e32 v31, v31, v31
	v_fmac_f32_e32 v29, v28, v28
	v_fmac_f32_e32 v31, v30, v30
	v_add_f32_e32 v28, v29, v31
	s_waitcnt vmcnt(0) lgkmcnt(0)
	v_pk_add_f32 v[26:27], v[26:27], v[36:37]
	v_pk_add_f32 v[24:25], v[24:25], v[34:35]
	v_cvt_pk_bf16_f32 v35, v26, v27
	v_cvt_pk_bf16_f32 v34, v24, v25
	global_store_dwordx4 v[40:41], v[24:27], off offset:64
	global_store_dwordx2 v[38:39], v[34:35], off offset:32
	global_load_dwordx4 v[34:37], v[42:43], off offset:512
	v_mul_f32_e32 v25, v25, v25
	v_mul_f32_e32 v27, v27, v27
	v_fmac_f32_e32 v25, v24, v24
	v_fmac_f32_e32 v27, v26, v26
	v_add_f32_e32 v24, v25, v27
	v_add_f32_e32 v24, v28, v24
	s_waitcnt vmcnt(0) lgkmcnt(0)
	v_pk_add_f32 v[22:23], v[22:23], v[36:37]
	v_pk_add_f32 v[20:21], v[20:21], v[34:35]
	v_cvt_pk_bf16_f32 v35, v22, v23
	v_cvt_pk_bf16_f32 v34, v20, v21
	global_store_dwordx4 v[40:41], v[20:23], off offset:512
	global_store_dwordx2 v[38:39], v[34:35], off offset:256
	global_load_dwordx4 v[34:37], v[42:43], off offset:576
	v_mul_f32_e32 v21, v21, v21
	v_mul_f32_e32 v23, v23, v23
	v_fmac_f32_e32 v21, v20, v20
	v_fmac_f32_e32 v23, v22, v22
	v_add_f32_e32 v20, v21, v23
	v_add_f32_e32 v22, v24, v20
	s_waitcnt vmcnt(0) lgkmcnt(0)
	v_pk_add_f32 v[20:21], v[18:19], v[36:37]
	v_pk_add_f32 v[18:19], v[16:17], v[34:35]
	v_mul_f32_e32 v17, v21, v21
	v_mul_f32_e32 v16, v19, v19
	v_fmac_f32_e32 v16, v18, v18
	v_fmac_f32_e32 v17, v20, v20
	v_add_f32_e32 v16, v16, v17
	v_add_f32_e32 v16, v22, v16
	ds_bpermute_b32 v17, v118, v16
	global_store_dwordx4 v[40:41], v[18:21], off offset:576
	s_waitcnt lgkmcnt(0)
	v_add_f32_e32 v16, v16, v17
	ds_bpermute_b32 v17, v116, v16
	v_cvt_pk_bf16_f32 v18, v18, v19
	v_cvt_pk_bf16_f32 v19, v20, v21
	global_store_dwordx2 v[38:39], v[18:19], off offset:288
	s_and_saveexec_b64 s[54:55], s[0:1]
	s_cbranch_execz .LBB0_1178
	v_readlane_b32 s34, v254, 43
	v_lshlrev_b64 v[18:19], 6, v[32:33]
	v_readlane_b32 s35, v254, 44
	v_lshl_add_u64 v[18:19], s[42:43], 0, v[18:19]
	s_mov_b32 s31, s35
	v_lshl_add_u64 v[18:19], s[52:53], 2, v[18:19]
	s_lshl_b32 s34, s64, 2
	v_writelane_b32 v254, s30, 43
	v_lshl_add_u64 v[18:19], v[18:19], 0, s[34:35]
	s_waitcnt lgkmcnt(0)
	v_add_f32_e32 v16, v16, v17
	v_writelane_b32 v254, s31, 44
	global_store_dword v[18:19], v16, off
.LBB0_1178:
	s_or_b64 exec, exec, s[54:55]
	v_add_u32_e32 v16, 0xb0, v138
	s_waitcnt lgkmcnt(0)
	v_ashrrev_i32_e32 v17, 31, v16
	v_lshlrev_b64 v[18:19], 10, v[16:17]
	v_lshl_add_u64 v[22:23], v[18:19], 0, v[136:137]
	v_readlane_b32 s34, v255, 6
	v_lshlrev_b64 v[24:25], 2, v[22:23]
	v_readlane_b32 s35, v255, 7
	v_readlane_b32 s84, v254, 45
	v_readlane_b32 s90, v254, 51
	v_lshl_add_u64 v[26:27], s[34:35], 0, v[24:25]
	global_load_dwordx4 v[18:21], v[26:27], off
	v_readlane_b32 s91, v254, 52
	v_lshl_add_u64 v[22:23], v[22:23], 1, s[6:7]
	v_readlane_b32 s85, v254, 46
	v_lshl_add_u64 v[24:25], s[90:91], 0, v[24:25]
	v_readlane_b32 s86, v254, 47
	v_readlane_b32 s87, v254, 48
	v_readlane_b32 s88, v254, 49
	v_readlane_b32 s89, v254, 50
	s_waitcnt vmcnt(0) lgkmcnt(0)
	v_pk_add_f32 v[14:15], v[14:15], v[20:21]
	v_pk_add_f32 v[12:13], v[12:13], v[18:19]
	v_cvt_pk_bf16_f32 v19, v14, v15
	v_cvt_pk_bf16_f32 v18, v12, v13
	global_store_dwordx4 v[24:25], v[12:15], off
	global_store_dwordx2 v[22:23], v[18:19], off
	global_load_dwordx4 v[18:21], v[26:27], off offset:64
	v_mul_f32_e32 v13, v13, v13
	v_mul_f32_e32 v15, v15, v15
	v_fmac_f32_e32 v13, v12, v12
	v_fmac_f32_e32 v15, v14, v14
	v_add_f32_e32 v12, v13, v15
	s_waitcnt vmcnt(0) lgkmcnt(0)
	v_pk_add_f32 v[10:11], v[10:11], v[20:21]
	v_pk_add_f32 v[8:9], v[8:9], v[18:19]
	v_cvt_pk_bf16_f32 v19, v10, v11
	v_cvt_pk_bf16_f32 v18, v8, v9
	global_store_dwordx4 v[24:25], v[8:11], off offset:64
	global_store_dwordx2 v[22:23], v[18:19], off offset:32
	global_load_dwordx4 v[18:21], v[26:27], off offset:512
	v_mul_f32_e32 v9, v9, v9
	v_mul_f32_e32 v11, v11, v11
	v_fmac_f32_e32 v9, v8, v8
	v_fmac_f32_e32 v11, v10, v10
	v_add_f32_e32 v8, v9, v11
	v_add_f32_e32 v8, v12, v8
	s_waitcnt vmcnt(0) lgkmcnt(0)
	v_pk_add_f32 v[6:7], v[6:7], v[20:21]
	v_pk_add_f32 v[4:5], v[4:5], v[18:19]
	v_cvt_pk_bf16_f32 v19, v6, v7
	v_cvt_pk_bf16_f32 v18, v4, v5
	global_store_dwordx4 v[24:25], v[4:7], off offset:512
	global_store_dwordx2 v[22:23], v[18:19], off offset:256
	global_load_dwordx4 v[18:21], v[26:27], off offset:576
	v_mul_f32_e32 v5, v5, v5
	v_mul_f32_e32 v7, v7, v7
	v_fmac_f32_e32 v5, v4, v4
	v_fmac_f32_e32 v7, v6, v6
	v_add_f32_e32 v4, v5, v7
	v_add_f32_e32 v6, v8, v4
	s_waitcnt vmcnt(0) lgkmcnt(0)
	v_pk_add_f32 v[4:5], v[2:3], v[20:21]
	v_pk_add_f32 v[2:3], v[0:1], v[18:19]
	v_mul_f32_e32 v1, v5, v5
	v_mul_f32_e32 v0, v3, v3
	v_fmac_f32_e32 v0, v2, v2
	v_fmac_f32_e32 v1, v4, v4
	v_add_f32_e32 v0, v0, v1
	v_add_f32_e32 v0, v6, v0
	ds_bpermute_b32 v1, v118, v0
	global_store_dwordx4 v[24:25], v[2:5], off offset:576
	s_waitcnt lgkmcnt(0)
	v_add_f32_e32 v0, v0, v1
	ds_bpermute_b32 v1, v116, v0
	v_cvt_pk_bf16_f32 v2, v2, v3
	v_cvt_pk_bf16_f32 v3, v4, v5
	global_store_dwordx2 v[22:23], v[2:3], off offset:288
	s_and_saveexec_b64 s[54:55], s[0:1]
	s_cbranch_execz .LBB0_1180
	v_readlane_b32 s34, v254, 43
	v_lshlrev_b64 v[2:3], 6, v[16:17]
	v_readlane_b32 s35, v254, 44
	v_lshl_add_u64 v[2:3], s[42:43], 0, v[2:3]
	s_mov_b32 s31, s35
	v_lshl_add_u64 v[2:3], s[52:53], 2, v[2:3]
	s_lshl_b32 s34, s64, 2
	v_writelane_b32 v254, s30, 43
	v_lshl_add_u64 v[2:3], v[2:3], 0, s[34:35]
	s_waitcnt lgkmcnt(0)
	v_add_f32_e32 v0, v0, v1
	v_writelane_b32 v254, s31, 44
	global_store_dword v[2:3], v0, off

.LBB0_1255:
	v_lshl_add_u32 v140, s27, 8, v144
	v_ashrrev_i32_e32 v141, 31, v140
	v_lshlrev_b64 v[148:149], 6, v[140:141]
	v_lshl_add_u64 v[160:161], s[30:31], 0, v[148:149]
	global_load_dwordx4 v[148:151], v[160:161], off
	global_load_dwordx4 v[152:155], v[160:161], off offset:16
	global_load_dwordx4 v[156:159], v[160:161], off offset:32
	global_load_dwordx4 v[164:167], v[160:161], off offset:48
	s_mov_b32 s27, 0xf800000
	v_lshl_or_b32 v142, s26, 7, v146
	v_ashrrev_i32_e32 v143, 31, v142
	s_movk_i32 s26, 0x1600
	v_mov_b32_e32 v200, v202
	s_waitcnt vmcnt(0) lgkmcnt(0)
	v_mov_b32_e32 v160, v148
	v_mov_b32_e32 v161, v156
	v_mov_b32_e32 v156, v149
	v_pk_add_f32 v[148:149], v[160:161], v[156:157]
	v_mov_b32_e32 v156, v150
	v_mov_b32_e32 v157, v158
	v_mov_b32_e32 v158, v151
	v_pk_add_f32 v[150:151], v[156:157], v[158:159]
	s_nop 0
	v_pk_add_f32 v[148:149], v[148:149], v[150:151]
	v_mov_b32_e32 v150, v152
	v_mov_b32_e32 v151, v164
	v_mov_b32_e32 v164, v153
	v_mov_b32_e32 v152, v154
	v_mov_b32_e32 v153, v166
	v_mov_b32_e32 v166, v155
	v_pk_add_f32 v[150:151], v[150:151], v[164:165]
	v_pk_add_f32 v[152:153], v[152:153], v[166:167]
	s_nop 0
	v_pk_add_f32 v[150:151], v[150:151], v[152:153]
	s_nop 0
	v_pk_add_f32 v[148:149], v[148:149], v[150:151]
	s_nop 0
	v_add_f32_e32 v141, v148, v149
	v_fmamk_f32 v141, v141, 0x3a800000, v194
	v_cmp_gt_f32_e32 vcc, s27, v141
	v_mul_f32_e32 v148, 0x4f800000, v141
	s_nop 0
	v_cndmask_b32_e32 v141, v141, v148, vcc
	v_sqrt_f32_e32 v148, v141
	s_nop 0
	v_add_u32_e32 v149, -1, v148
	v_fma_f32 v150, -v149, v148, v141
	v_cmp_ge_f32_e64 s[0:1], 0, v150
	v_add_u32_e32 v150, 1, v148
	s_nop 0
	v_cndmask_b32_e64 v149, v148, v149, s[0:1]
	v_fma_f32 v148, -v150, v148, v141
	v_cmp_lt_f32_e64 s[0:1], 0, v148
	s_nop 1
	v_cndmask_b32_e64 v148, v149, v150, s[0:1]
	v_mul_f32_e32 v149, 0x37800000, v148
	v_cndmask_b32_e32 v148, v148, v149, vcc
	v_cmp_class_f32_e32 vcc, v141, v195
	s_nop 1
	v_cndmask_b32_e32 v141, v148, v141, vcc
	v_div_scale_f32 v148, s[0:1], v141, v141, 1.0
	v_rcp_f32_e32 v149, v148
	s_nop 0
	v_fma_f32 v150, -v148, v149, 1.0
	v_fmac_f32_e32 v149, v150, v149
	v_div_scale_f32 v150, vcc, 1.0, v141, 1.0
	v_mul_f32_e32 v151, v150, v149
	v_fma_f32 v152, -v148, v151, v150
	v_fmac_f32_e32 v151, v152, v149
	v_fma_f32 v148, -v148, v151, v150
	v_div_fmas_f32 v148, v148, v149, v151
	v_div_fixup_f32 v148, v148, v141, 1.0
	v_pk_mul_f32 v[126:127], v[126:127], v[148:149] op_sel_hi:[1,0]
	v_pk_mul_f32 v[118:119], v[118:119], v[148:149] op_sel_hi:[1,0]
	v_mul_f32_e32 v141, 0xbfb8aa3b, v126
	v_exp_f32_e32 v141, v141
	v_pk_mul_f32 v[120:121], v[120:121], v[148:149] op_sel_hi:[1,0]
	v_pk_mul_f32 v[122:123], v[122:123], v[148:149] op_sel_hi:[1,0]
	v_pk_mul_f32 v[114:115], v[114:115], v[148:149] op_sel_hi:[1,0]
	v_add_f32_e32 v141, 1.0, v141
	v_rcp_f32_e32 v150, v141
	v_mul_f32_e32 v141, 0xbfb8aa3b, v127
	v_exp_f32_e32 v141, v141
	v_pk_mul_f32 v[116:117], v[116:117], v[148:149] op_sel_hi:[1,0]
	v_add_f32_e32 v141, 1.0, v141
	v_rcp_f32_e32 v151, v141
	s_nop 0
	v_pk_mul_f32 v[126:127], v[126:127], v[150:151]
	s_nop 0
	v_pk_mul_f32 v[118:119], v[118:119], v[126:127]
	v_pk_mul_f32 v[126:127], v[128:129], v[148:149] op_sel_hi:[1,0]
	s_nop 0
	v_mul_f32_e32 v128, 0xbfb8aa3b, v126
	v_mul_f32_e32 v129, 0xbfb8aa3b, v127
	v_exp_f32_e32 v128, v128
	v_exp_f32_e32 v129, v129
	v_add_f32_e32 v128, 1.0, v128
	v_add_f32_e32 v129, 1.0, v129
	v_rcp_f32_e32 v128, v128
	v_rcp_f32_e32 v129, v129
	s_nop 0
	v_pk_mul_f32 v[126:127], v[126:127], v[128:129]
	s_nop 0
	v_pk_mul_f32 v[120:121], v[120:121], v[126:127]
	v_mul_f32_e32 v126, 0xbfb8aa3b, v122
	v_mul_f32_e32 v127, 0xbfb8aa3b, v123
	v_exp_f32_e32 v126, v126
	v_exp_f32_e32 v127, v127
	v_add_f32_e32 v126, 1.0, v126
	v_add_f32_e32 v127, 1.0, v127
	v_rcp_f32_e32 v126, v126
	v_rcp_f32_e32 v127, v127
	s_nop 0
	v_pk_mul_f32 v[122:123], v[122:123], v[126:127]
	s_nop 0
	v_pk_mul_f32 v[122:123], v[114:115], v[122:123]
	v_pk_mul_f32 v[114:115], v[124:125], v[148:149] op_sel_hi:[1,0]
	s_nop 0
	v_mul_f32_e32 v124, 0xbfb8aa3b, v114
	v_mul_f32_e32 v125, 0xbfb8aa3b, v115
	v_exp_f32_e32 v124, v124
	v_exp_f32_e32 v125, v125
	v_add_f32_e32 v124, 1.0, v124
	v_add_f32_e32 v125, 1.0, v125
	v_rcp_f32_e32 v124, v124
	v_rcp_f32_e32 v125, v125
	s_nop 0
	v_pk_mul_f32 v[114:115], v[114:115], v[124:125]
	s_nop 0
	v_pk_mul_f32 v[124:125], v[116:117], v[114:115]
	v_cvt_pk_bf16_f32 v114, v118, v119
	v_mov_b64_e32 v[118:119], s[6:7]
	v_cvt_pk_bf16_f32 v115, v120, v121
	v_cvt_pk_bf16_f32 v116, v122, v123
	v_mad_i64_i32 v[122:123], s[0:1], v140, s26, v[118:119]
	v_lshlrev_b64 v[120:121], 1, v[142:143]
	v_cvt_pk_bf16_f32 v117, v124, v125
	v_lshl_add_u64 v[122:123], v[122:123], 0, v[120:121]
	global_store_dwordx4 v[122:123], v[114:117], off
	s_nop 1
	v_or_b32_e32 v114, 16, v140
	v_ashrrev_i32_e32 v115, 31, v114
	v_lshlrev_b64 v[116:117], 6, v[114:115]
	v_lshl_add_u64 v[116:117], s[30:31], 0, v[116:117]
	global_load_dwordx4 v[122:125], v[116:117], off
	global_load_dwordx4 v[126:129], v[116:117], off offset:16
	global_load_dwordx4 v[148:151], v[116:117], off offset:32
	global_load_dwordx4 v[152:155], v[116:117], off offset:48
	s_waitcnt vmcnt(0) lgkmcnt(0)
	v_mov_b32_e32 v116, v122
	v_mov_b32_e32 v122, v124
	v_mov_b32_e32 v117, v148
	v_mov_b32_e32 v148, v123
	v_mov_b32_e32 v123, v150
	v_mov_b32_e32 v150, v125
	v_pk_add_f32 v[116:117], v[116:117], v[148:149]
	v_pk_add_f32 v[122:123], v[122:123], v[150:151]
	v_mov_b32_e32 v124, v128
	v_pk_add_f32 v[116:117], v[116:117], v[122:123]
	v_mov_b32_e32 v122, v126
	v_mov_b32_e32 v123, v152
	v_mov_b32_e32 v152, v127
	v_mov_b32_e32 v125, v154
	v_mov_b32_e32 v154, v129
	v_pk_add_f32 v[122:123], v[122:123], v[152:153]
	v_pk_add_f32 v[124:125], v[124:125], v[154:155]
	s_nop 0
	v_pk_add_f32 v[122:123], v[122:123], v[124:125]
	s_nop 0
	v_pk_add_f32 v[116:117], v[116:117], v[122:123]
	s_nop 0
	v_add_f32_e32 v115, v116, v117
	v_fmamk_f32 v115, v115, 0x3a800000, v194
	v_cmp_gt_f32_e32 vcc, s27, v115
	v_mul_f32_e32 v116, 0x4f800000, v115
	s_nop 0
	v_cndmask_b32_e32 v115, v115, v116, vcc
	v_sqrt_f32_e32 v116, v115
	s_nop 0
	v_add_u32_e32 v117, -1, v116
	v_fma_f32 v122, -v117, v116, v115
	v_cmp_ge_f32_e64 s[0:1], 0, v122
	v_add_u32_e32 v122, 1, v116
	s_nop 0
	v_cndmask_b32_e64 v117, v116, v117, s[0:1]
	v_fma_f32 v116, -v122, v116, v115
	v_cmp_lt_f32_e64 s[0:1], 0, v116
	s_nop 1
	v_cndmask_b32_e64 v116, v117, v122, s[0:1]
	v_mul_f32_e32 v117, 0x37800000, v116
	v_cndmask_b32_e32 v116, v116, v117, vcc
	v_cmp_class_f32_e32 vcc, v115, v195
	s_nop 1
	v_cndmask_b32_e32 v115, v116, v115, vcc
	v_div_scale_f32 v116, s[0:1], v115, v115, 1.0
	v_rcp_f32_e32 v117, v116
	s_nop 0
	v_fma_f32 v122, -v116, v117, 1.0
	v_fmac_f32_e32 v117, v122, v117
	v_div_scale_f32 v122, vcc, 1.0, v115, 1.0
	v_mul_f32_e32 v123, v122, v117
	v_fma_f32 v124, -v116, v123, v122
	v_fmac_f32_e32 v123, v124, v117
	v_fma_f32 v116, -v116, v123, v122
	v_div_fmas_f32 v116, v116, v117, v123
	v_div_fixup_f32 v116, v116, v115, 1.0
	v_pk_mul_f32 v[110:111], v[110:111], v[116:117] op_sel_hi:[1,0]
	v_pk_mul_f32 v[102:103], v[102:103], v[116:117] op_sel_hi:[1,0]
	v_mul_f32_e32 v115, 0xbfb8aa3b, v110
	v_exp_f32_e32 v115, v115
	v_pk_mul_f32 v[104:105], v[104:105], v[116:117] op_sel_hi:[1,0]
	v_pk_mul_f32 v[106:107], v[106:107], v[116:117] op_sel_hi:[1,0]
	v_pk_mul_f32 v[98:99], v[98:99], v[116:117] op_sel_hi:[1,0]
	v_add_f32_e32 v115, 1.0, v115
	v_rcp_f32_e32 v122, v115
	v_mul_f32_e32 v115, 0xbfb8aa3b, v111
	v_exp_f32_e32 v115, v115
	v_pk_mul_f32 v[100:101], v[100:101], v[116:117] op_sel_hi:[1,0]
	v_add_f32_e32 v115, 1.0, v115
	v_rcp_f32_e32 v123, v115
	s_nop 0
	v_pk_mul_f32 v[110:111], v[110:111], v[122:123]
	s_nop 0
	v_pk_mul_f32 v[102:103], v[102:103], v[110:111]
	v_pk_mul_f32 v[110:111], v[112:113], v[116:117] op_sel_hi:[1,0]
	s_nop 0
	v_mul_f32_e32 v112, 0xbfb8aa3b, v110
	v_mul_f32_e32 v113, 0xbfb8aa3b, v111
	v_exp_f32_e32 v112, v112
	v_exp_f32_e32 v113, v113
	v_add_f32_e32 v112, 1.0, v112
	v_add_f32_e32 v113, 1.0, v113
	v_rcp_f32_e32 v112, v112
	v_rcp_f32_e32 v113, v113
	s_nop 0
	v_pk_mul_f32 v[110:111], v[110:111], v[112:113]
	s_nop 0
	v_pk_mul_f32 v[104:105], v[104:105], v[110:111]
	v_mul_f32_e32 v110, 0xbfb8aa3b, v106
	v_mul_f32_e32 v111, 0xbfb8aa3b, v107
	v_exp_f32_e32 v110, v110
	v_exp_f32_e32 v111, v111
	v_add_f32_e32 v110, 1.0, v110
	v_add_f32_e32 v111, 1.0, v111
	v_rcp_f32_e32 v110, v110
	v_rcp_f32_e32 v111, v111
	s_nop 0
	v_pk_mul_f32 v[106:107], v[106:107], v[110:111]
	s_nop 0
	v_pk_mul_f32 v[106:107], v[98:99], v[106:107]
	v_pk_mul_f32 v[98:99], v[108:109], v[116:117] op_sel_hi:[1,0]
	s_nop 0
	v_mul_f32_e32 v108, 0xbfb8aa3b, v98
	v_mul_f32_e32 v109, 0xbfb8aa3b, v99
	v_exp_f32_e32 v108, v108
	v_exp_f32_e32 v109, v109
	v_add_f32_e32 v108, 1.0, v108
	v_add_f32_e32 v109, 1.0, v109
	v_rcp_f32_e32 v108, v108
	v_rcp_f32_e32 v109, v109
	s_nop 0
	v_pk_mul_f32 v[98:99], v[98:99], v[108:109]
	s_nop 0
	v_pk_mul_f32 v[108:109], v[100:101], v[98:99]
	v_cvt_pk_bf16_f32 v98, v102, v103
	v_mad_i64_i32 v[102:103], s[0:1], v114, s26, v[118:119]
	v_cvt_pk_bf16_f32 v99, v104, v105
	v_cvt_pk_bf16_f32 v100, v106, v107
	v_cvt_pk_bf16_f32 v101, v108, v109
	v_lshl_add_u64 v[102:103], v[102:103], 0, v[120:121]
	global_store_dwordx4 v[102:103], v[98:101], off
	s_nop 1
	v_or_b32_e32 v98, 32, v140
	v_ashrrev_i32_e32 v99, 31, v98
	v_lshlrev_b64 v[100:101], 6, v[98:99]
	v_lshl_add_u64 v[100:101], s[30:31], 0, v[100:101]
	global_load_dwordx4 v[102:105], v[100:101], off
	global_load_dwordx4 v[106:109], v[100:101], off offset:16
	global_load_dwordx4 v[110:113], v[100:101], off offset:32
	global_load_dwordx4 v[114:117], v[100:101], off offset:48
	s_waitcnt vmcnt(0) lgkmcnt(0)
	v_mov_b32_e32 v100, v102
	v_mov_b32_e32 v102, v104
	v_mov_b32_e32 v101, v110
	v_mov_b32_e32 v110, v103
	v_mov_b32_e32 v103, v112
	v_mov_b32_e32 v112, v105
	v_pk_add_f32 v[100:101], v[100:101], v[110:111]
	v_pk_add_f32 v[102:103], v[102:103], v[112:113]
	v_mov_b32_e32 v104, v108
	v_pk_add_f32 v[100:101], v[100:101], v[102:103]
	v_mov_b32_e32 v102, v106
	v_mov_b32_e32 v103, v114
	v_mov_b32_e32 v114, v107
	v_mov_b32_e32 v105, v116
	v_mov_b32_e32 v116, v109
	v_pk_add_f32 v[102:103], v[102:103], v[114:115]
	v_pk_add_f32 v[104:105], v[104:105], v[116:117]
	s_nop 0
	v_pk_add_f32 v[102:103], v[102:103], v[104:105]
	s_nop 0
	v_pk_add_f32 v[100:101], v[100:101], v[102:103]
	s_nop 0
	v_add_f32_e32 v99, v100, v101
	v_fmamk_f32 v99, v99, 0x3a800000, v194
	v_cmp_gt_f32_e32 vcc, s27, v99
	v_mul_f32_e32 v100, 0x4f800000, v99
	s_nop 0
	v_cndmask_b32_e32 v99, v99, v100, vcc
	v_sqrt_f32_e32 v100, v99
	s_nop 0
	v_add_u32_e32 v101, -1, v100
	v_fma_f32 v102, -v101, v100, v99
	v_cmp_ge_f32_e64 s[0:1], 0, v102
	v_add_u32_e32 v102, 1, v100
	s_nop 0
	v_cndmask_b32_e64 v101, v100, v101, s[0:1]
	v_fma_f32 v100, -v102, v100, v99
	v_cmp_lt_f32_e64 s[0:1], 0, v100
	s_nop 1
	v_cndmask_b32_e64 v100, v101, v102, s[0:1]
	v_mul_f32_e32 v101, 0x37800000, v100
	v_cndmask_b32_e32 v100, v100, v101, vcc
	v_cmp_class_f32_e32 vcc, v99, v195
	s_nop 1
	v_cndmask_b32_e32 v99, v100, v99, vcc
	v_div_scale_f32 v100, s[0:1], v99, v99, 1.0
	v_rcp_f32_e32 v101, v100
	s_nop 0
	v_fma_f32 v102, -v100, v101, 1.0
	v_fmac_f32_e32 v101, v102, v101
	v_div_scale_f32 v102, vcc, 1.0, v99, 1.0
	v_mul_f32_e32 v103, v102, v101
	v_fma_f32 v104, -v100, v103, v102
	v_fmac_f32_e32 v103, v104, v101
	v_fma_f32 v100, -v100, v103, v102
	v_div_fmas_f32 v100, v100, v101, v103
	v_div_fixup_f32 v100, v100, v99, 1.0
	v_pk_mul_f32 v[94:95], v[94:95], v[100:101] op_sel_hi:[1,0]
	v_pk_mul_f32 v[86:87], v[86:87], v[100:101] op_sel_hi:[1,0]
	v_mul_f32_e32 v99, 0xbfb8aa3b, v94
	v_exp_f32_e32 v99, v99
	v_pk_mul_f32 v[88:89], v[88:89], v[100:101] op_sel_hi:[1,0]
	v_pk_mul_f32 v[90:91], v[90:91], v[100:101] op_sel_hi:[1,0]
	v_pk_mul_f32 v[82:83], v[82:83], v[100:101] op_sel_hi:[1,0]
	v_add_f32_e32 v99, 1.0, v99
	v_rcp_f32_e32 v102, v99
	v_mul_f32_e32 v99, 0xbfb8aa3b, v95
	v_exp_f32_e32 v99, v99
	v_pk_mul_f32 v[84:85], v[84:85], v[100:101] op_sel_hi:[1,0]
	v_add_f32_e32 v99, 1.0, v99
	v_rcp_f32_e32 v103, v99
	s_nop 0
	v_pk_mul_f32 v[94:95], v[94:95], v[102:103]
	s_nop 0
	v_pk_mul_f32 v[86:87], v[86:87], v[94:95]
	v_pk_mul_f32 v[94:95], v[96:97], v[100:101] op_sel_hi:[1,0]
	s_nop 0
	v_mul_f32_e32 v96, 0xbfb8aa3b, v94
	v_mul_f32_e32 v97, 0xbfb8aa3b, v95
	v_exp_f32_e32 v96, v96
	v_exp_f32_e32 v97, v97
	v_add_f32_e32 v96, 1.0, v96
	v_add_f32_e32 v97, 1.0, v97
	v_rcp_f32_e32 v96, v96
	v_rcp_f32_e32 v97, v97
	s_nop 0
	v_pk_mul_f32 v[94:95], v[94:95], v[96:97]
	s_nop 0
	v_pk_mul_f32 v[88:89], v[88:89], v[94:95]
	v_mul_f32_e32 v94, 0xbfb8aa3b, v90
	v_mul_f32_e32 v95, 0xbfb8aa3b, v91
	v_exp_f32_e32 v94, v94
	v_exp_f32_e32 v95, v95
	v_add_f32_e32 v94, 1.0, v94
	v_add_f32_e32 v95, 1.0, v95
	v_rcp_f32_e32 v94, v94
	v_rcp_f32_e32 v95, v95
	s_nop 0
	v_pk_mul_f32 v[90:91], v[90:91], v[94:95]
	s_nop 0
	v_pk_mul_f32 v[90:91], v[82:83], v[90:91]
	v_pk_mul_f32 v[82:83], v[92:93], v[100:101] op_sel_hi:[1,0]
	s_nop 0
	v_mul_f32_e32 v92, 0xbfb8aa3b, v82
	v_mul_f32_e32 v93, 0xbfb8aa3b, v83
	v_exp_f32_e32 v92, v92
	v_exp_f32_e32 v93, v93
	v_add_f32_e32 v92, 1.0, v92
	v_add_f32_e32 v93, 1.0, v93
	v_rcp_f32_e32 v92, v92
	v_rcp_f32_e32 v93, v93
	s_nop 0
	v_pk_mul_f32 v[82:83], v[82:83], v[92:93]
	s_nop 0
	v_pk_mul_f32 v[92:93], v[84:85], v[82:83]
	v_cvt_pk_bf16_f32 v82, v86, v87
	v_mad_i64_i32 v[86:87], s[0:1], v98, s26, v[118:119]
	v_cvt_pk_bf16_f32 v83, v88, v89
	v_cvt_pk_bf16_f32 v84, v90, v91
	v_cvt_pk_bf16_f32 v85, v92, v93
	v_lshl_add_u64 v[86:87], v[86:87], 0, v[120:121]
	global_store_dwordx4 v[86:87], v[82:85], off
	s_nop 1
	v_or_b32_e32 v82, 48, v140
	v_ashrrev_i32_e32 v83, 31, v82
	v_lshlrev_b64 v[84:85], 6, v[82:83]
	v_lshl_add_u64 v[84:85], s[30:31], 0, v[84:85]
	global_load_dwordx4 v[86:89], v[84:85], off
	global_load_dwordx4 v[90:93], v[84:85], off offset:16
	global_load_dwordx4 v[94:97], v[84:85], off offset:32
	global_load_dwordx4 v[98:101], v[84:85], off offset:48
	s_waitcnt vmcnt(0) lgkmcnt(0)
	v_mov_b32_e32 v84, v86
	v_mov_b32_e32 v86, v88
	v_mov_b32_e32 v85, v94
	v_mov_b32_e32 v94, v87
	v_mov_b32_e32 v87, v96
	v_mov_b32_e32 v96, v89
	v_pk_add_f32 v[84:85], v[84:85], v[94:95]
	v_pk_add_f32 v[86:87], v[86:87], v[96:97]
	v_mov_b32_e32 v88, v92
	v_pk_add_f32 v[84:85], v[84:85], v[86:87]
	v_mov_b32_e32 v86, v90
	v_mov_b32_e32 v87, v98
	v_mov_b32_e32 v98, v91
	v_mov_b32_e32 v89, v100
	v_mov_b32_e32 v100, v93
	v_pk_add_f32 v[86:87], v[86:87], v[98:99]
	v_pk_add_f32 v[88:89], v[88:89], v[100:101]
	s_nop 0
	v_pk_add_f32 v[86:87], v[86:87], v[88:89]
	s_nop 0
	v_pk_add_f32 v[84:85], v[84:85], v[86:87]
	s_nop 0
	v_add_f32_e32 v83, v84, v85
	v_fmamk_f32 v83, v83, 0x3a800000, v194
	v_cmp_gt_f32_e32 vcc, s27, v83
	v_mul_f32_e32 v84, 0x4f800000, v83
	s_nop 0
	v_cndmask_b32_e32 v83, v83, v84, vcc
	v_sqrt_f32_e32 v84, v83
	s_nop 0
	v_add_u32_e32 v85, -1, v84
	v_fma_f32 v86, -v85, v84, v83
	v_cmp_ge_f32_e64 s[0:1], 0, v86
	v_add_u32_e32 v86, 1, v84
	s_nop 0
	v_cndmask_b32_e64 v85, v84, v85, s[0:1]
	v_fma_f32 v84, -v86, v84, v83
	v_cmp_lt_f32_e64 s[0:1], 0, v84
	s_nop 1
	v_cndmask_b32_e64 v84, v85, v86, s[0:1]
	v_mul_f32_e32 v85, 0x37800000, v84
	v_cndmask_b32_e32 v84, v84, v85, vcc
	v_cmp_class_f32_e32 vcc, v83, v195
	s_nop 1
	v_cndmask_b32_e32 v83, v84, v83, vcc
	v_div_scale_f32 v84, s[0:1], v83, v83, 1.0
	v_rcp_f32_e32 v85, v84
	s_nop 0
	v_fma_f32 v86, -v84, v85, 1.0
	v_fmac_f32_e32 v85, v86, v85
	v_div_scale_f32 v86, vcc, 1.0, v83, 1.0
	v_mul_f32_e32 v87, v86, v85
	v_fma_f32 v88, -v84, v87, v86
	v_fmac_f32_e32 v87, v88, v85
	v_fma_f32 v84, -v84, v87, v86
	v_div_fmas_f32 v84, v84, v85, v87
	v_div_fixup_f32 v84, v84, v83, 1.0
	v_pk_mul_f32 v[78:79], v[78:79], v[84:85] op_sel_hi:[1,0]
	v_pk_mul_f32 v[70:71], v[70:71], v[84:85] op_sel_hi:[1,0]
	v_mul_f32_e32 v83, 0xbfb8aa3b, v78
	v_exp_f32_e32 v83, v83
	v_pk_mul_f32 v[72:73], v[72:73], v[84:85] op_sel_hi:[1,0]
	v_pk_mul_f32 v[74:75], v[74:75], v[84:85] op_sel_hi:[1,0]
	v_pk_mul_f32 v[66:67], v[66:67], v[84:85] op_sel_hi:[1,0]
	v_add_f32_e32 v83, 1.0, v83
	v_rcp_f32_e32 v86, v83
	v_mul_f32_e32 v83, 0xbfb8aa3b, v79
	v_exp_f32_e32 v83, v83
	v_pk_mul_f32 v[68:69], v[68:69], v[84:85] op_sel_hi:[1,0]
	v_add_f32_e32 v83, 1.0, v83
	v_rcp_f32_e32 v87, v83
	s_nop 0
	v_pk_mul_f32 v[78:79], v[78:79], v[86:87]
	s_nop 0
	v_pk_mul_f32 v[70:71], v[70:71], v[78:79]
	v_pk_mul_f32 v[78:79], v[80:81], v[84:85] op_sel_hi:[1,0]
	s_nop 0
	v_mul_f32_e32 v80, 0xbfb8aa3b, v78
	v_mul_f32_e32 v81, 0xbfb8aa3b, v79
	v_exp_f32_e32 v80, v80
	v_exp_f32_e32 v81, v81
	v_add_f32_e32 v80, 1.0, v80
	v_add_f32_e32 v81, 1.0, v81
	v_rcp_f32_e32 v80, v80
	v_rcp_f32_e32 v81, v81
	s_nop 0
	v_pk_mul_f32 v[78:79], v[78:79], v[80:81]
	s_nop 0
	v_pk_mul_f32 v[72:73], v[72:73], v[78:79]
	v_mul_f32_e32 v78, 0xbfb8aa3b, v74
	v_mul_f32_e32 v79, 0xbfb8aa3b, v75
	v_exp_f32_e32 v78, v78
	v_exp_f32_e32 v79, v79
	v_add_f32_e32 v78, 1.0, v78
	v_add_f32_e32 v79, 1.0, v79
	v_rcp_f32_e32 v78, v78
	v_rcp_f32_e32 v79, v79
	s_nop 0
	v_pk_mul_f32 v[74:75], v[74:75], v[78:79]
	s_nop 0
	v_pk_mul_f32 v[74:75], v[66:67], v[74:75]
	v_pk_mul_f32 v[66:67], v[76:77], v[84:85] op_sel_hi:[1,0]
	s_nop 0
	v_mul_f32_e32 v76, 0xbfb8aa3b, v66
	v_mul_f32_e32 v77, 0xbfb8aa3b, v67
	v_exp_f32_e32 v76, v76
	v_exp_f32_e32 v77, v77
	v_add_f32_e32 v76, 1.0, v76
	v_add_f32_e32 v77, 1.0, v77
	v_rcp_f32_e32 v76, v76
	v_rcp_f32_e32 v77, v77
	s_nop 0
	v_pk_mul_f32 v[66:67], v[66:67], v[76:77]
	s_nop 0
	v_pk_mul_f32 v[76:77], v[68:69], v[66:67]
	v_cvt_pk_bf16_f32 v66, v70, v71
	v_mad_i64_i32 v[70:71], s[0:1], v82, s26, v[118:119]
	v_cvt_pk_bf16_f32 v67, v72, v73
	v_cvt_pk_bf16_f32 v68, v74, v75
	v_cvt_pk_bf16_f32 v69, v76, v77
	v_lshl_add_u64 v[70:71], v[70:71], 0, v[120:121]
	global_store_dwordx4 v[70:71], v[66:69], off
	s_nop 1
	v_add_u32_e32 v66, 0x80, v140
	v_ashrrev_i32_e32 v67, 31, v66
	v_lshlrev_b64 v[68:69], 6, v[66:67]
	v_lshl_add_u64 v[68:69], s[30:31], 0, v[68:69]
	global_load_dwordx4 v[70:73], v[68:69], off
	global_load_dwordx4 v[74:77], v[68:69], off offset:16
	global_load_dwordx4 v[78:81], v[68:69], off offset:32
	global_load_dwordx4 v[82:85], v[68:69], off offset:48
	s_waitcnt vmcnt(0) lgkmcnt(0)
	v_mov_b32_e32 v68, v70
	v_mov_b32_e32 v70, v72
	v_mov_b32_e32 v69, v78
	v_mov_b32_e32 v78, v71
	v_mov_b32_e32 v71, v80
	v_mov_b32_e32 v80, v73
	v_pk_add_f32 v[68:69], v[68:69], v[78:79]
	v_pk_add_f32 v[70:71], v[70:71], v[80:81]
	v_mov_b32_e32 v72, v76
	v_pk_add_f32 v[68:69], v[68:69], v[70:71]
	v_mov_b32_e32 v70, v74
	v_mov_b32_e32 v71, v82
	v_mov_b32_e32 v82, v75
	v_mov_b32_e32 v73, v84
	v_mov_b32_e32 v84, v77
	v_pk_add_f32 v[70:71], v[70:71], v[82:83]
	v_pk_add_f32 v[72:73], v[72:73], v[84:85]
	s_nop 0
	v_pk_add_f32 v[70:71], v[70:71], v[72:73]
	s_nop 0
	v_pk_add_f32 v[68:69], v[68:69], v[70:71]
	s_nop 0
	v_add_f32_e32 v67, v68, v69
	v_fmamk_f32 v67, v67, 0x3a800000, v194
	v_cmp_gt_f32_e32 vcc, s27, v67
	v_mul_f32_e32 v68, 0x4f800000, v67
	s_nop 0
	v_cndmask_b32_e32 v67, v67, v68, vcc
	v_sqrt_f32_e32 v68, v67
	s_nop 0
	v_add_u32_e32 v69, -1, v68
	v_fma_f32 v70, -v69, v68, v67
	v_cmp_ge_f32_e64 s[0:1], 0, v70
	v_add_u32_e32 v70, 1, v68
	s_nop 0
	v_cndmask_b32_e64 v69, v68, v69, s[0:1]
	v_fma_f32 v68, -v70, v68, v67
	v_cmp_lt_f32_e64 s[0:1], 0, v68
	s_nop 1
	v_cndmask_b32_e64 v68, v69, v70, s[0:1]
	v_mul_f32_e32 v69, 0x37800000, v68
	v_cndmask_b32_e32 v68, v68, v69, vcc
	v_cmp_class_f32_e32 vcc, v67, v195
	s_nop 1
	v_cndmask_b32_e32 v67, v68, v67, vcc
	v_div_scale_f32 v68, s[0:1], v67, v67, 1.0
	v_rcp_f32_e32 v69, v68
	s_nop 0
	v_fma_f32 v70, -v68, v69, 1.0
	v_fmac_f32_e32 v69, v70, v69
	v_div_scale_f32 v70, vcc, 1.0, v67, 1.0
	v_mul_f32_e32 v71, v70, v69
	v_fma_f32 v72, -v68, v71, v70
	v_fmac_f32_e32 v71, v72, v69
	v_fma_f32 v68, -v68, v71, v70
	v_div_fmas_f32 v68, v68, v69, v71
	v_div_fixup_f32 v68, v68, v67, 1.0
	v_pk_mul_f32 v[60:61], v[60:61], v[68:69] op_sel_hi:[1,0]
	v_pk_mul_f32 v[52:53], v[52:53], v[68:69] op_sel_hi:[1,0]
	v_mul_f32_e32 v67, 0xbfb8aa3b, v60
	v_exp_f32_e32 v67, v67
	v_pk_mul_f32 v[54:55], v[54:55], v[68:69] op_sel_hi:[1,0]
	v_pk_mul_f32 v[56:57], v[56:57], v[68:69] op_sel_hi:[1,0]
	v_pk_mul_f32 v[48:49], v[48:49], v[68:69] op_sel_hi:[1,0]
	v_add_f32_e32 v67, 1.0, v67
	v_rcp_f32_e32 v70, v67
	v_mul_f32_e32 v67, 0xbfb8aa3b, v61
	v_exp_f32_e32 v67, v67
	v_pk_mul_f32 v[50:51], v[50:51], v[68:69] op_sel_hi:[1,0]
	v_add_f32_e32 v67, 1.0, v67
	v_rcp_f32_e32 v71, v67
	s_nop 0
	v_pk_mul_f32 v[60:61], v[60:61], v[70:71]
	s_nop 0
	v_pk_mul_f32 v[52:53], v[52:53], v[60:61]
	v_pk_mul_f32 v[60:61], v[62:63], v[68:69] op_sel_hi:[1,0]
	s_nop 0
	v_mul_f32_e32 v62, 0xbfb8aa3b, v60
	v_mul_f32_e32 v63, 0xbfb8aa3b, v61
	v_exp_f32_e32 v62, v62
	v_exp_f32_e32 v63, v63
	v_add_f32_e32 v62, 1.0, v62
	v_add_f32_e32 v63, 1.0, v63
	v_rcp_f32_e32 v62, v62
	v_rcp_f32_e32 v63, v63
	s_nop 0
	v_pk_mul_f32 v[60:61], v[60:61], v[62:63]
	s_nop 0
	v_pk_mul_f32 v[54:55], v[54:55], v[60:61]
	v_mul_f32_e32 v60, 0xbfb8aa3b, v56
	v_mul_f32_e32 v61, 0xbfb8aa3b, v57
	v_exp_f32_e32 v60, v60
	v_exp_f32_e32 v61, v61
	v_add_f32_e32 v60, 1.0, v60
	v_add_f32_e32 v61, 1.0, v61
	v_rcp_f32_e32 v60, v60
	v_rcp_f32_e32 v61, v61
	s_nop 0
	v_pk_mul_f32 v[56:57], v[56:57], v[60:61]
	s_nop 0
	v_pk_mul_f32 v[56:57], v[48:49], v[56:57]
	v_pk_mul_f32 v[48:49], v[58:59], v[68:69] op_sel_hi:[1,0]
	s_nop 0
	v_mul_f32_e32 v58, 0xbfb8aa3b, v48
	v_mul_f32_e32 v59, 0xbfb8aa3b, v49
	v_exp_f32_e32 v58, v58
	v_exp_f32_e32 v59, v59
	v_add_f32_e32 v58, 1.0, v58
	v_add_f32_e32 v59, 1.0, v59
	v_rcp_f32_e32 v58, v58
	v_rcp_f32_e32 v59, v59
	s_nop 0
	v_pk_mul_f32 v[48:49], v[48:49], v[58:59]
	s_nop 0
	v_pk_mul_f32 v[58:59], v[50:51], v[48:49]
	v_cvt_pk_bf16_f32 v48, v52, v53
	v_mad_i64_i32 v[52:53], s[0:1], v66, s26, v[118:119]
	v_cvt_pk_bf16_f32 v49, v54, v55
	v_cvt_pk_bf16_f32 v50, v56, v57
	v_cvt_pk_bf16_f32 v51, v58, v59
	v_lshl_add_u64 v[52:53], v[52:53], 0, v[120:121]
	global_store_dwordx4 v[52:53], v[48:51], off
	s_nop 1
	v_add_u32_e32 v48, 0x90, v140
	v_ashrrev_i32_e32 v49, 31, v48
	v_lshlrev_b64 v[50:51], 6, v[48:49]
	v_lshl_add_u64 v[50:51], s[30:31], 0, v[50:51]
	global_load_dwordx4 v[52:55], v[50:51], off
	global_load_dwordx4 v[56:59], v[50:51], off offset:16
	global_load_dwordx4 v[60:63], v[50:51], off offset:32
	global_load_dwordx4 v[66:69], v[50:51], off offset:48
	s_waitcnt vmcnt(0) lgkmcnt(0)
	v_mov_b32_e32 v50, v52
	v_mov_b32_e32 v52, v54
	v_mov_b32_e32 v51, v60
	v_mov_b32_e32 v60, v53
	v_mov_b32_e32 v53, v62
	v_mov_b32_e32 v62, v55
	v_pk_add_f32 v[50:51], v[50:51], v[60:61]
	v_pk_add_f32 v[52:53], v[52:53], v[62:63]
	v_mov_b32_e32 v54, v58
	v_pk_add_f32 v[50:51], v[50:51], v[52:53]
	v_mov_b32_e32 v52, v56
	v_mov_b32_e32 v53, v66
	v_mov_b32_e32 v66, v57
	v_mov_b32_e32 v55, v68
	v_mov_b32_e32 v68, v59
	v_pk_add_f32 v[52:53], v[52:53], v[66:67]
	v_pk_add_f32 v[54:55], v[54:55], v[68:69]
	s_nop 0
	v_pk_add_f32 v[52:53], v[52:53], v[54:55]
	s_nop 0
	v_pk_add_f32 v[50:51], v[50:51], v[52:53]
	s_nop 0
	v_add_f32_e32 v49, v50, v51
	v_fmamk_f32 v49, v49, 0x3a800000, v194
	v_cmp_gt_f32_e32 vcc, s27, v49
	v_mul_f32_e32 v50, 0x4f800000, v49
	s_nop 0
	v_cndmask_b32_e32 v49, v49, v50, vcc
	v_sqrt_f32_e32 v50, v49
	s_nop 0
	v_add_u32_e32 v51, -1, v50
	v_fma_f32 v52, -v51, v50, v49
	v_cmp_ge_f32_e64 s[0:1], 0, v52
	v_add_u32_e32 v52, 1, v50
	s_nop 0
	v_cndmask_b32_e64 v51, v50, v51, s[0:1]
	v_fma_f32 v50, -v52, v50, v49
	v_cmp_lt_f32_e64 s[0:1], 0, v50
	s_nop 1
	v_cndmask_b32_e64 v50, v51, v52, s[0:1]
	v_mul_f32_e32 v51, 0x37800000, v50
	v_cndmask_b32_e32 v50, v50, v51, vcc
	v_cmp_class_f32_e32 vcc, v49, v195
	s_nop 1
	v_cndmask_b32_e32 v49, v50, v49, vcc
	v_div_scale_f32 v50, s[0:1], v49, v49, 1.0
	v_rcp_f32_e32 v51, v50
	s_nop 0
	v_fma_f32 v52, -v50, v51, 1.0
	v_fmac_f32_e32 v51, v52, v51
	v_div_scale_f32 v52, vcc, 1.0, v49, 1.0
	v_mul_f32_e32 v53, v52, v51
	v_fma_f32 v54, -v50, v53, v52
	v_fmac_f32_e32 v53, v54, v51
	v_fma_f32 v50, -v50, v53, v52
	v_div_fmas_f32 v50, v50, v51, v53
	v_div_fixup_f32 v50, v50, v49, 1.0
	v_pk_mul_f32 v[44:45], v[44:45], v[50:51] op_sel_hi:[1,0]
	v_pk_mul_f32 v[36:37], v[36:37], v[50:51] op_sel_hi:[1,0]
	v_mul_f32_e32 v49, 0xbfb8aa3b, v44
	v_exp_f32_e32 v49, v49
	v_pk_mul_f32 v[38:39], v[38:39], v[50:51] op_sel_hi:[1,0]
	v_pk_mul_f32 v[40:41], v[40:41], v[50:51] op_sel_hi:[1,0]
	v_pk_mul_f32 v[32:33], v[32:33], v[50:51] op_sel_hi:[1,0]
	v_add_f32_e32 v49, 1.0, v49
	v_rcp_f32_e32 v52, v49
	v_mul_f32_e32 v49, 0xbfb8aa3b, v45
	v_exp_f32_e32 v49, v49
	v_pk_mul_f32 v[34:35], v[34:35], v[50:51] op_sel_hi:[1,0]
	v_add_f32_e32 v49, 1.0, v49
	v_rcp_f32_e32 v53, v49
	s_nop 0
	v_pk_mul_f32 v[44:45], v[44:45], v[52:53]
	s_nop 0
	v_pk_mul_f32 v[36:37], v[36:37], v[44:45]
	v_pk_mul_f32 v[44:45], v[46:47], v[50:51] op_sel_hi:[1,0]
	s_nop 0
	v_mul_f32_e32 v46, 0xbfb8aa3b, v44
	v_mul_f32_e32 v47, 0xbfb8aa3b, v45
	v_exp_f32_e32 v46, v46
	v_exp_f32_e32 v47, v47
	v_add_f32_e32 v46, 1.0, v46
	v_add_f32_e32 v47, 1.0, v47
	v_rcp_f32_e32 v46, v46
	v_rcp_f32_e32 v47, v47
	s_nop 0
	v_pk_mul_f32 v[44:45], v[44:45], v[46:47]
	s_nop 0
	v_pk_mul_f32 v[38:39], v[38:39], v[44:45]
	v_mul_f32_e32 v44, 0xbfb8aa3b, v40
	v_mul_f32_e32 v45, 0xbfb8aa3b, v41
	v_exp_f32_e32 v44, v44
	v_exp_f32_e32 v45, v45
	v_add_f32_e32 v44, 1.0, v44
	v_add_f32_e32 v45, 1.0, v45
	v_rcp_f32_e32 v44, v44
	v_rcp_f32_e32 v45, v45
	s_nop 0
	v_pk_mul_f32 v[40:41], v[40:41], v[44:45]
	s_nop 0
	v_pk_mul_f32 v[40:41], v[32:33], v[40:41]
	v_pk_mul_f32 v[32:33], v[42:43], v[50:51] op_sel_hi:[1,0]
	s_nop 0
	v_mul_f32_e32 v42, 0xbfb8aa3b, v32
	v_mul_f32_e32 v43, 0xbfb8aa3b, v33
	v_exp_f32_e32 v42, v42
	v_exp_f32_e32 v43, v43
	v_add_f32_e32 v42, 1.0, v42
	v_add_f32_e32 v43, 1.0, v43
	v_rcp_f32_e32 v42, v42
	v_rcp_f32_e32 v43, v43
	s_nop 0
	v_pk_mul_f32 v[32:33], v[32:33], v[42:43]
	s_nop 0
	v_pk_mul_f32 v[42:43], v[34:35], v[32:33]
	v_cvt_pk_bf16_f32 v32, v36, v37
	v_mad_i64_i32 v[36:37], s[0:1], v48, s26, v[118:119]
	v_cvt_pk_bf16_f32 v33, v38, v39
	v_cvt_pk_bf16_f32 v34, v40, v41
	v_cvt_pk_bf16_f32 v35, v42, v43
	v_lshl_add_u64 v[36:37], v[36:37], 0, v[120:121]
	global_store_dwordx4 v[36:37], v[32:35], off
	s_nop 1
	v_add_u32_e32 v32, 0xa0, v140
	v_ashrrev_i32_e32 v33, 31, v32
	v_lshlrev_b64 v[34:35], 6, v[32:33]
	v_lshl_add_u64 v[34:35], s[30:31], 0, v[34:35]
	global_load_dwordx4 v[36:39], v[34:35], off
	global_load_dwordx4 v[40:43], v[34:35], off offset:16
	global_load_dwordx4 v[44:47], v[34:35], off offset:32
	global_load_dwordx4 v[48:51], v[34:35], off offset:48
	s_waitcnt vmcnt(0) lgkmcnt(0)
	v_mov_b32_e32 v34, v36
	v_mov_b32_e32 v36, v38
	v_mov_b32_e32 v35, v44
	v_mov_b32_e32 v44, v37
	v_mov_b32_e32 v37, v46
	v_mov_b32_e32 v46, v39
	v_pk_add_f32 v[34:35], v[34:35], v[44:45]
	v_pk_add_f32 v[36:37], v[36:37], v[46:47]
	v_mov_b32_e32 v38, v42
	v_pk_add_f32 v[34:35], v[34:35], v[36:37]
	v_mov_b32_e32 v36, v40
	v_mov_b32_e32 v37, v48
	v_mov_b32_e32 v48, v41
	v_mov_b32_e32 v39, v50
	v_mov_b32_e32 v50, v43
	v_pk_add_f32 v[36:37], v[36:37], v[48:49]
	v_pk_add_f32 v[38:39], v[38:39], v[50:51]
	s_nop 0
	v_pk_add_f32 v[36:37], v[36:37], v[38:39]
	s_nop 0
	v_pk_add_f32 v[34:35], v[34:35], v[36:37]
	s_nop 0
	v_add_f32_e32 v33, v34, v35
	v_fmamk_f32 v33, v33, 0x3a800000, v194
	v_cmp_gt_f32_e32 vcc, s27, v33
	v_mul_f32_e32 v34, 0x4f800000, v33
	s_nop 0
	v_cndmask_b32_e32 v33, v33, v34, vcc
	v_sqrt_f32_e32 v34, v33
	s_nop 0
	v_add_u32_e32 v35, -1, v34
	v_fma_f32 v36, -v35, v34, v33
	v_cmp_ge_f32_e64 s[0:1], 0, v36
	v_add_u32_e32 v36, 1, v34
	s_nop 0
	v_cndmask_b32_e64 v35, v34, v35, s[0:1]
	v_fma_f32 v34, -v36, v34, v33
	v_cmp_lt_f32_e64 s[0:1], 0, v34
	s_nop 1
	v_cndmask_b32_e64 v34, v35, v36, s[0:1]
	v_mul_f32_e32 v35, 0x37800000, v34
	v_cndmask_b32_e32 v34, v34, v35, vcc
	v_cmp_class_f32_e32 vcc, v33, v195
	s_nop 1
	v_cndmask_b32_e32 v33, v34, v33, vcc
	v_div_scale_f32 v34, s[0:1], v33, v33, 1.0
	v_rcp_f32_e32 v35, v34
	s_nop 0
	v_fma_f32 v36, -v34, v35, 1.0
	v_fmac_f32_e32 v35, v36, v35
	v_div_scale_f32 v36, vcc, 1.0, v33, 1.0
	v_mul_f32_e32 v37, v36, v35
	v_fma_f32 v38, -v34, v37, v36
	v_fmac_f32_e32 v37, v38, v35
	v_fma_f32 v34, -v34, v37, v36
	v_div_fmas_f32 v34, v34, v35, v37
	v_div_fixup_f32 v34, v34, v33, 1.0
	v_pk_mul_f32 v[28:29], v[28:29], v[34:35] op_sel_hi:[1,0]
	v_pk_mul_f32 v[20:21], v[20:21], v[34:35] op_sel_hi:[1,0]
	v_mul_f32_e32 v33, 0xbfb8aa3b, v28
	v_exp_f32_e32 v33, v33
	v_pk_mul_f32 v[22:23], v[22:23], v[34:35] op_sel_hi:[1,0]
	v_pk_mul_f32 v[24:25], v[24:25], v[34:35] op_sel_hi:[1,0]
	v_pk_mul_f32 v[16:17], v[16:17], v[34:35] op_sel_hi:[1,0]
	v_add_f32_e32 v33, 1.0, v33
	v_rcp_f32_e32 v36, v33
	v_mul_f32_e32 v33, 0xbfb8aa3b, v29
	v_exp_f32_e32 v33, v33
	v_pk_mul_f32 v[18:19], v[18:19], v[34:35] op_sel_hi:[1,0]
	v_add_f32_e32 v33, 1.0, v33
	v_rcp_f32_e32 v37, v33
	s_nop 0
	v_pk_mul_f32 v[28:29], v[28:29], v[36:37]
	s_nop 0
	v_pk_mul_f32 v[20:21], v[20:21], v[28:29]
	v_pk_mul_f32 v[28:29], v[30:31], v[34:35] op_sel_hi:[1,0]
	s_nop 0
	v_mul_f32_e32 v30, 0xbfb8aa3b, v28
	v_mul_f32_e32 v31, 0xbfb8aa3b, v29
	v_exp_f32_e32 v30, v30
	v_exp_f32_e32 v31, v31
	v_add_f32_e32 v30, 1.0, v30
	v_add_f32_e32 v31, 1.0, v31
	v_rcp_f32_e32 v30, v30
	v_rcp_f32_e32 v31, v31
	s_nop 0
	v_pk_mul_f32 v[28:29], v[28:29], v[30:31]
	s_nop 0
	v_pk_mul_f32 v[22:23], v[22:23], v[28:29]
	v_mul_f32_e32 v28, 0xbfb8aa3b, v24
	v_mul_f32_e32 v29, 0xbfb8aa3b, v25
	v_exp_f32_e32 v28, v28
	v_exp_f32_e32 v29, v29
	v_add_f32_e32 v28, 1.0, v28
	v_add_f32_e32 v29, 1.0, v29
	v_rcp_f32_e32 v28, v28
	v_rcp_f32_e32 v29, v29
	s_nop 0
	v_pk_mul_f32 v[24:25], v[24:25], v[28:29]
	s_nop 0
	v_pk_mul_f32 v[24:25], v[16:17], v[24:25]
	v_pk_mul_f32 v[16:17], v[26:27], v[34:35] op_sel_hi:[1,0]
	s_nop 0
	v_mul_f32_e32 v26, 0xbfb8aa3b, v16
	v_mul_f32_e32 v27, 0xbfb8aa3b, v17
	v_exp_f32_e32 v26, v26
	v_exp_f32_e32 v27, v27
	v_add_f32_e32 v26, 1.0, v26
	v_add_f32_e32 v27, 1.0, v27
	v_rcp_f32_e32 v26, v26
	v_rcp_f32_e32 v27, v27
	s_nop 0
	v_pk_mul_f32 v[16:17], v[16:17], v[26:27]
	s_nop 0
	v_pk_mul_f32 v[26:27], v[18:19], v[16:17]
	v_cvt_pk_bf16_f32 v16, v20, v21
	v_mad_i64_i32 v[20:21], s[0:1], v32, s26, v[118:119]
	v_cvt_pk_bf16_f32 v17, v22, v23
	v_cvt_pk_bf16_f32 v18, v24, v25
	v_cvt_pk_bf16_f32 v19, v26, v27
	v_lshl_add_u64 v[20:21], v[20:21], 0, v[120:121]
	global_store_dwordx4 v[20:21], v[16:19], off
	s_nop 1
	v_add_u32_e32 v16, 0xb0, v140
	v_ashrrev_i32_e32 v17, 31, v16
	v_lshlrev_b64 v[18:19], 6, v[16:17]
	v_lshl_add_u64 v[18:19], s[30:31], 0, v[18:19]
	global_load_dwordx4 v[20:23], v[18:19], off
	global_load_dwordx4 v[24:27], v[18:19], off offset:16
	global_load_dwordx4 v[28:31], v[18:19], off offset:32
	global_load_dwordx4 v[32:35], v[18:19], off offset:48
	s_waitcnt vmcnt(0) lgkmcnt(0)
	v_mov_b32_e32 v18, v20
	v_mov_b32_e32 v20, v22
	v_mov_b32_e32 v19, v28
	v_mov_b32_e32 v28, v21
	v_mov_b32_e32 v21, v30
	v_mov_b32_e32 v30, v23
	v_pk_add_f32 v[18:19], v[18:19], v[28:29]
	v_pk_add_f32 v[20:21], v[20:21], v[30:31]
	v_mov_b32_e32 v22, v26
	v_pk_add_f32 v[18:19], v[18:19], v[20:21]
	v_mov_b32_e32 v20, v24
	v_mov_b32_e32 v21, v32
	v_mov_b32_e32 v32, v25
	v_mov_b32_e32 v23, v34
	v_mov_b32_e32 v34, v27
	v_pk_add_f32 v[20:21], v[20:21], v[32:33]
	v_pk_add_f32 v[22:23], v[22:23], v[34:35]
	s_nop 0
	v_pk_add_f32 v[20:21], v[20:21], v[22:23]
	s_nop 0
	v_pk_add_f32 v[18:19], v[18:19], v[20:21]
	s_nop 0
	v_add_f32_e32 v17, v18, v19
	v_fmamk_f32 v17, v17, 0x3a800000, v194
	v_cmp_gt_f32_e32 vcc, s27, v17
	v_mul_f32_e32 v18, 0x4f800000, v17
	s_nop 0
	v_cndmask_b32_e32 v17, v17, v18, vcc
	v_sqrt_f32_e32 v18, v17
	s_nop 0
	v_add_u32_e32 v19, -1, v18
	v_fma_f32 v20, -v19, v18, v17
	v_cmp_ge_f32_e64 s[0:1], 0, v20
	v_add_u32_e32 v20, 1, v18
	s_nop 0
	v_cndmask_b32_e64 v19, v18, v19, s[0:1]
	v_fma_f32 v18, -v20, v18, v17
	v_cmp_lt_f32_e64 s[0:1], 0, v18
	s_nop 1
	v_cndmask_b32_e64 v18, v19, v20, s[0:1]
	v_mul_f32_e32 v19, 0x37800000, v18
	v_cndmask_b32_e32 v18, v18, v19, vcc
	v_cmp_class_f32_e32 vcc, v17, v195
	s_nop 1
	v_cndmask_b32_e32 v17, v18, v17, vcc
	v_div_scale_f32 v18, s[0:1], v17, v17, 1.0
	v_rcp_f32_e32 v19, v18
	s_nop 0
	v_fma_f32 v20, -v18, v19, 1.0
	v_fmac_f32_e32 v19, v20, v19
	v_div_scale_f32 v20, vcc, 1.0, v17, 1.0
	v_mul_f32_e32 v21, v20, v19
	v_fma_f32 v22, -v18, v21, v20
	v_fmac_f32_e32 v21, v22, v19
	v_fma_f32 v18, -v18, v21, v20
	v_div_fmas_f32 v18, v18, v19, v21
	v_div_fixup_f32 v18, v18, v17, 1.0
	v_pk_mul_f32 v[12:13], v[12:13], v[18:19] op_sel_hi:[1,0]
	v_pk_mul_f32 v[4:5], v[4:5], v[18:19] op_sel_hi:[1,0]
	v_mul_f32_e32 v17, 0xbfb8aa3b, v12
	v_exp_f32_e32 v17, v17
	v_pk_mul_f32 v[6:7], v[6:7], v[18:19] op_sel_hi:[1,0]
	v_pk_mul_f32 v[8:9], v[8:9], v[18:19] op_sel_hi:[1,0]
	v_pk_mul_f32 v[0:1], v[0:1], v[18:19] op_sel_hi:[1,0]
	v_add_f32_e32 v17, 1.0, v17
	v_rcp_f32_e32 v20, v17
	v_mul_f32_e32 v17, 0xbfb8aa3b, v13
	v_exp_f32_e32 v17, v17
	v_pk_mul_f32 v[2:3], v[2:3], v[18:19] op_sel_hi:[1,0]
	s_andn2_b64 vcc, exec, s[38:39]
	v_add_f32_e32 v17, 1.0, v17
	v_rcp_f32_e32 v21, v17
	s_nop 0
	v_pk_mul_f32 v[12:13], v[12:13], v[20:21]
	s_nop 0
	v_pk_mul_f32 v[4:5], v[4:5], v[12:13]
	v_pk_mul_f32 v[12:13], v[14:15], v[18:19] op_sel_hi:[1,0]
	s_nop 0
	v_mul_f32_e32 v14, 0xbfb8aa3b, v12
	v_mul_f32_e32 v15, 0xbfb8aa3b, v13
	v_exp_f32_e32 v14, v14
	v_exp_f32_e32 v15, v15
	v_add_f32_e32 v14, 1.0, v14
	v_add_f32_e32 v15, 1.0, v15
	v_rcp_f32_e32 v14, v14
	v_rcp_f32_e32 v15, v15
	s_nop 0
	v_pk_mul_f32 v[12:13], v[12:13], v[14:15]
	s_nop 0
	v_pk_mul_f32 v[6:7], v[6:7], v[12:13]
	v_mul_f32_e32 v12, 0xbfb8aa3b, v8
	v_mul_f32_e32 v13, 0xbfb8aa3b, v9
	v_exp_f32_e32 v12, v12
	v_exp_f32_e32 v13, v13
	v_add_f32_e32 v12, 1.0, v12
	v_add_f32_e32 v13, 1.0, v13
	v_rcp_f32_e32 v12, v12
	v_rcp_f32_e32 v13, v13
	s_nop 0
	v_pk_mul_f32 v[8:9], v[8:9], v[12:13]
	s_nop 0
	v_pk_mul_f32 v[8:9], v[0:1], v[8:9]
	v_pk_mul_f32 v[0:1], v[10:11], v[18:19] op_sel_hi:[1,0]
	s_nop 0
	v_mul_f32_e32 v10, 0xbfb8aa3b, v0
	v_mul_f32_e32 v11, 0xbfb8aa3b, v1
	v_exp_f32_e32 v10, v10
	v_exp_f32_e32 v11, v11
	v_add_f32_e32 v10, 1.0, v10
	v_add_f32_e32 v11, 1.0, v11
	v_rcp_f32_e32 v10, v10
	v_rcp_f32_e32 v11, v11
	s_nop 0
	v_pk_mul_f32 v[0:1], v[0:1], v[10:11]
	s_nop 0
	v_pk_mul_f32 v[10:11], v[2:3], v[0:1]
	v_cvt_pk_bf16_f32 v0, v4, v5
	v_mad_i64_i32 v[4:5], s[0:1], v16, s26, v[118:119]
	v_cvt_pk_bf16_f32 v1, v6, v7
	v_cvt_pk_bf16_f32 v2, v8, v9
	v_cvt_pk_bf16_f32 v3, v10, v11
	v_lshl_add_u64 v[4:5], v[4:5], 0, v[120:121]
	s_mov_b64 s[0:1], -1
	global_store_dwordx4 v[4:5], v[0:3], off
	s_cbranch_vccnz .LBB0_1248
	s_andn2_b64 vcc, exec, s[4:5]
	s_cbranch_vccnz .LBB0_1247
	s_barrier
	s_branch .LBB0_1247

.LBB0_1263:
	v_add_u32_e32 v8, 0x1450, v31
	ds_write2_b32 v8, v10, v11 offset1:1
	v_pk_mul_f32 v[8:9], v[18:19], v[14:15] op_sel_hi:[1,0]
	v_add_u32_e32 v10, 0x1658, v31
	ds_write2_b32 v10, v8, v9 offset1:1
	s_waitcnt lgkmcnt(0)
	ds_read_b32 v8, v80
	ds_read_b32 v9, v80 offset:260
	s_add_u32 s0, s42, s57
	v_add3_u32 v14, v99, v107, v110
	s_addc_u32 s1, s43, s56
	v_lshl_add_u64 v[6:7], v[6:7], 1, s[0:1]
	s_waitcnt lgkmcnt(0)
	v_cvt_pk_bf16_f32 v8, v8, v9
	ds_read_b32 v9, v80 offset:520
	ds_read_b32 v10, v80 offset:780
	v_lshlrev_b32_e32 v64, 1, v4
	v_lshl_add_u64 v[6:7], v[6:7], 0, v[64:65]
	s_waitcnt lgkmcnt(0)
	v_cvt_pk_bf16_f32 v9, v9, v10
	ds_read_b32 v10, v80 offset:1040
	ds_read_b32 v11, v80 offset:1300
	s_waitcnt lgkmcnt(0)
	v_cvt_pk_bf16_f32 v10, v10, v11
	ds_read_b32 v11, v80 offset:1560
	ds_read_b32 v12, v80 offset:1820
	s_waitcnt lgkmcnt(0)
	v_cvt_pk_bf16_f32 v11, v11, v12
	v_add_u32_e32 v12, 0xffff0000, v14
	v_ashrrev_i32_e32 v13, 31, v12
	v_lshlrev_b64 v[12:13], 11, v[12:13]
	v_lshl_add_u64 v[12:13], v[6:7], 0, v[12:13]
	global_store_dwordx4 v[12:13], v[8:11], off
	ds_read_b32 v8, v80 offset:32
	ds_read_b32 v9, v80 offset:292
	s_waitcnt lgkmcnt(0)
	v_cvt_pk_bf16_f32 v8, v8, v9
	ds_read_b32 v9, v80 offset:552
	ds_read_b32 v10, v80 offset:812
	s_waitcnt lgkmcnt(0)
	v_cvt_pk_bf16_f32 v9, v9, v10
	ds_read_b32 v10, v80 offset:1072
	ds_read_b32 v11, v80 offset:1332
	s_waitcnt lgkmcnt(0)
	v_cvt_pk_bf16_f32 v10, v10, v11
	ds_read_b32 v11, v80 offset:1592
	ds_read_b32 v12, v80 offset:1852
	s_waitcnt lgkmcnt(0)
	v_cvt_pk_bf16_f32 v11, v11, v12
	v_add_u32_e32 v12, 0xffff0008, v14
	v_ashrrev_i32_e32 v13, 31, v12
	v_lshlrev_b64 v[12:13], 11, v[12:13]
	v_lshl_add_u64 v[12:13], v[6:7], 0, v[12:13]
	global_store_dwordx4 v[12:13], v[8:11], off
	ds_read_b32 v8, v80 offset:64
	ds_read_b32 v9, v80 offset:324
	s_waitcnt lgkmcnt(0)
	v_cvt_pk_bf16_f32 v8, v8, v9
	ds_read_b32 v9, v80 offset:584
	ds_read_b32 v10, v80 offset:844
	s_waitcnt lgkmcnt(0)
	v_cvt_pk_bf16_f32 v9, v9, v10
	ds_read_b32 v10, v80 offset:1104
	ds_read_b32 v11, v80 offset:1364
	s_waitcnt lgkmcnt(0)
	v_cvt_pk_bf16_f32 v10, v10, v11
	ds_read_b32 v11, v80 offset:1624
	ds_read_b32 v12, v80 offset:1884
	s_waitcnt lgkmcnt(0)
	v_cvt_pk_bf16_f32 v11, v11, v12
	v_add_u32_e32 v12, 0xffff0010, v14
	v_ashrrev_i32_e32 v13, 31, v12
	v_lshlrev_b64 v[12:13], 11, v[12:13]
	v_lshl_add_u64 v[12:13], v[6:7], 0, v[12:13]
	global_store_dwordx4 v[12:13], v[8:11], off
	ds_read_b32 v8, v80 offset:96
	ds_read_b32 v9, v80 offset:356
	s_waitcnt lgkmcnt(0)
	v_cvt_pk_bf16_f32 v8, v8, v9
	ds_read_b32 v9, v80 offset:616
	ds_read_b32 v10, v80 offset:876
	s_waitcnt lgkmcnt(0)
	v_cvt_pk_bf16_f32 v9, v9, v10
	ds_read_b32 v10, v80 offset:1136
	ds_read_b32 v11, v80 offset:1396
	s_waitcnt lgkmcnt(0)
	v_cvt_pk_bf16_f32 v10, v10, v11
	ds_read_b32 v11, v80 offset:1656
	ds_read_b32 v12, v80 offset:1916
	s_waitcnt lgkmcnt(0)
	v_cvt_pk_bf16_f32 v11, v11, v12
	v_add_u32_e32 v12, 0xffff0018, v14
	v_ashrrev_i32_e32 v13, 31, v12
	v_lshlrev_b64 v[12:13], 11, v[12:13]
	v_lshl_add_u64 v[12:13], v[6:7], 0, v[12:13]
	global_store_dwordx4 v[12:13], v[8:11], off
	ds_read_b32 v8, v80 offset:128
	ds_read_b32 v9, v80 offset:388
	s_waitcnt lgkmcnt(0)
	v_cvt_pk_bf16_f32 v8, v8, v9
	ds_read_b32 v9, v80 offset:648
	ds_read_b32 v10, v80 offset:908
	s_waitcnt lgkmcnt(0)
	v_cvt_pk_bf16_f32 v9, v9, v10
	ds_read_b32 v10, v80 offset:1168
	ds_read_b32 v11, v80 offset:1428
	s_waitcnt lgkmcnt(0)
	v_cvt_pk_bf16_f32 v10, v10, v11
	ds_read_b32 v11, v80 offset:1688
	ds_read_b32 v12, v80 offset:1948
	s_waitcnt lgkmcnt(0)
	v_cvt_pk_bf16_f32 v11, v11, v12
	v_add_u32_e32 v12, 0xffff0020, v14
	v_ashrrev_i32_e32 v13, 31, v12
	v_lshlrev_b64 v[12:13], 11, v[12:13]
	v_lshl_add_u64 v[12:13], v[6:7], 0, v[12:13]
	global_store_dwordx4 v[12:13], v[8:11], off
	ds_read_b32 v8, v80 offset:160
	ds_read_b32 v9, v80 offset:420
	s_waitcnt lgkmcnt(0)
	v_cvt_pk_bf16_f32 v8, v8, v9
	ds_read_b32 v9, v80 offset:680
	ds_read_b32 v10, v80 offset:940
	s_waitcnt lgkmcnt(0)
	v_cvt_pk_bf16_f32 v9, v9, v10
	ds_read_b32 v10, v80 offset:1200
	ds_read_b32 v11, v80 offset:1460
	s_waitcnt lgkmcnt(0)
	v_cvt_pk_bf16_f32 v10, v10, v11
	ds_read_b32 v11, v80 offset:1720
	ds_read_b32 v12, v80 offset:1980
	s_waitcnt lgkmcnt(0)
	v_cvt_pk_bf16_f32 v11, v11, v12
	v_add_u32_e32 v12, 0xffff0028, v14
	v_ashrrev_i32_e32 v13, 31, v12
	v_lshlrev_b64 v[12:13], 11, v[12:13]
	v_lshl_add_u64 v[12:13], v[6:7], 0, v[12:13]
	global_store_dwordx4 v[12:13], v[8:11], off
	ds_read_b32 v8, v80 offset:192
	ds_read_b32 v9, v80 offset:452
	s_waitcnt lgkmcnt(0)
	v_cvt_pk_bf16_f32 v8, v8, v9
	ds_read_b32 v9, v80 offset:712
	ds_read_b32 v10, v80 offset:972
	s_waitcnt lgkmcnt(0)
	v_cvt_pk_bf16_f32 v9, v9, v10
	ds_read_b32 v10, v80 offset:1232
	ds_read_b32 v11, v80 offset:1492
	s_waitcnt lgkmcnt(0)
	v_cvt_pk_bf16_f32 v10, v10, v11
	ds_read_b32 v11, v80 offset:1752
	ds_read_b32 v12, v80 offset:2012
	s_waitcnt lgkmcnt(0)
	v_cvt_pk_bf16_f32 v11, v11, v12
	v_add_u32_e32 v12, 0xffff0030, v14
	v_ashrrev_i32_e32 v13, 31, v12
	v_lshlrev_b64 v[12:13], 11, v[12:13]
	v_lshl_add_u64 v[12:13], v[6:7], 0, v[12:13]
	global_store_dwordx4 v[12:13], v[8:11], off
	ds_read_b32 v8, v80 offset:224
	ds_read_b32 v9, v80 offset:484
	s_waitcnt lgkmcnt(0)
	v_cvt_pk_bf16_f32 v8, v8, v9
	ds_read_b32 v9, v80 offset:744
	ds_read_b32 v10, v80 offset:1004
	s_waitcnt lgkmcnt(0)
	v_cvt_pk_bf16_f32 v9, v9, v10
	ds_read_b32 v10, v80 offset:1264
	ds_read_b32 v11, v80 offset:1524
	s_waitcnt lgkmcnt(0)
	v_cvt_pk_bf16_f32 v10, v10, v11
	ds_read_b32 v11, v80 offset:1784
	ds_read_b32 v12, v80 offset:2044
	s_waitcnt lgkmcnt(0)
	v_cvt_pk_bf16_f32 v11, v11, v12
	v_add_u32_e32 v12, 0xffff0038, v14
	v_ashrrev_i32_e32 v13, 31, v12
	v_lshlrev_b64 v[12:13], 11, v[12:13]
	v_lshl_add_u64 v[6:7], v[6:7], 0, v[12:13]
	global_store_dwordx4 v[6:7], v[8:11], off
	s_waitcnt lgkmcnt(0)

.LBB0_1265:
	v_add_u32_e32 v109, 0x940, v101
	s_movk_i32 s0, 0x2bf
	v_cmp_lt_i32_e32 vcc, s0, v109
	s_and_saveexec_b64 s[0:1], vcc
	s_xor_b64 s[38:39], exec, s[0:1]
	s_cbranch_execz .LBB0_1490
	s_movk_i32 s0, 0x3bf
	v_cmp_lt_u32_e32 vcc, s0, v109
	s_and_saveexec_b64 s[0:1], vcc
	s_xor_b64 s[42:43], exec, s[0:1]
	s_cbranch_execz .LBB0_1423
	s_movk_i32 s0, 0x93f
	v_cmp_lt_u32_e32 vcc, s0, v109
	s_and_saveexec_b64 s[0:1], vcc
	s_xor_b64 s[44:45], exec, s[0:1]
	s_cbranch_execz .LBB0_1333
	v_readlane_b32 s64, v254, 45
	v_lshrrev_b32_e32 v6, 4, v101
	v_readlane_b32 s68, v254, 49
	v_readlane_b32 s69, v254, 50
	v_lshlrev_b32_e32 v76, 10, v6
	s_mov_b64 s[0:1], s[68:69]
	v_sub_u32_e32 v7, v103, v76
	v_add_u32_e32 v74, s62, v102
	s_add_u32 s26, s0, s55
	v_lshlrev_b32_e32 v75, 6, v6
	v_add_u32_e32 v6, v74, v7
	s_movk_i32 s0, 0x400
	v_cmp_gt_i32_e32 vcc, s0, v6
	s_addc_u32 s27, s1, s54
	s_mov_b64 s[46:47], s[40:41]
	v_cndmask_b32_e32 v64, -1, v6, vcc
	v_cmp_lt_i32_e64 s[0:1], -1, v64
	v_or_b32_e32 v77, v75, v2
	v_lshl_add_u64 v[10:11], v[64:65], 2, s[26:27]
	v_mov_b32_e32 v8, 0
	v_mov_b32_e32 v6, 0
	v_mov_b32_e32 v7, 0
	v_readlane_b32 s65, v254, 46
	v_readlane_b32 s66, v254, 47
	v_readlane_b32 s67, v254, 48
	v_readlane_b32 s70, v254, 51
	v_readlane_b32 s71, v254, 52
	s_and_saveexec_b64 s[48:49], s[0:1]
	s_cbranch_execz .LBB0_1270
	v_lshlrev_b32_e32 v64, 10, v77
	v_lshl_add_u64 v[6:7], v[64:65], 2, v[10:11]
	global_load_dwordx2 v[6:7], v[6:7], off
.LBB0_1270:
	s_or_b64 exec, exec, s[48:49]
	v_mov_b32_e32 v9, 0
	s_and_saveexec_b64 s[48:49], s[0:1]
	s_cbranch_execz .LBB0_1272
	v_lshlrev_b32_e32 v64, 10, v77
	v_lshl_add_u64 v[8:9], v[64:65], 2, v[10:11]
	v_add_co_u32_e32 v8, vcc, 0x2000, v8
	s_nop 1
	v_addc_co_u32_e32 v9, vcc, 0, v9, vcc
	global_load_dwordx2 v[8:9], v[8:9], off
.LBB0_1272:
	s_or_b64 exec, exec, s[48:49]
	v_mov_b32_e32 v12, 0
	v_mov_b32_e32 v14, 0
	v_mov_b32_e32 v15, 0
	s_and_saveexec_b64 s[48:49], s[0:1]
	s_cbranch_execz .LBB0_1274
	v_lshlrev_b32_e32 v64, 10, v77
	v_lshl_add_u64 v[14:15], v[64:65], 2, v[10:11]
	v_add_co_u32_e32 v14, vcc, 0x4000, v14
	s_nop 1
	v_addc_co_u32_e32 v15, vcc, 0, v15, vcc
	global_load_dwordx2 v[14:15], v[14:15], off
.LBB0_1274:
	s_or_b64 exec, exec, s[48:49]
	v_mov_b32_e32 v13, 0
	s_and_saveexec_b64 s[48:49], s[0:1]
	s_cbranch_execz .LBB0_1276
	v_lshlrev_b32_e32 v64, 10, v77
	v_lshl_add_u64 v[12:13], v[64:65], 2, v[10:11]
	v_add_co_u32_e32 v12, vcc, 0x6000, v12
	s_nop 1
	v_addc_co_u32_e32 v13, vcc, 0, v13, vcc
	global_load_dwordx2 v[12:13], v[12:13], off
.LBB0_1276:
	s_or_b64 exec, exec, s[48:49]
	v_mov_b32_e32 v16, 0
	v_mov_b32_e32 v18, 0
	v_mov_b32_e32 v19, 0
	s_and_saveexec_b64 s[48:49], s[0:1]
	s_cbranch_execz .LBB0_1278
	v_lshlrev_b32_e32 v64, 10, v77
	v_lshl_add_u64 v[18:19], v[64:65], 2, v[10:11]
	v_add_co_u32_e32 v18, vcc, 0x8000, v18
	s_nop 1
	v_addc_co_u32_e32 v19, vcc, 0, v19, vcc
	global_load_dwordx2 v[18:19], v[18:19], off
.LBB0_1278:
	s_or_b64 exec, exec, s[48:49]
	v_mov_b32_e32 v17, 0
	s_and_saveexec_b64 s[48:49], s[0:1]
	s_cbranch_execz .LBB0_1280
	v_lshlrev_b32_e32 v64, 10, v77
	v_lshl_add_u64 v[16:17], v[64:65], 2, v[10:11]
	v_add_co_u32_e32 v16, vcc, 0xa000, v16
	s_nop 1
	v_addc_co_u32_e32 v17, vcc, 0, v17, vcc
	global_load_dwordx2 v[16:17], v[16:17], off
.LBB0_1280:
	s_or_b64 exec, exec, s[48:49]
	v_mov_b32_e32 v20, 0
	v_mov_b32_e32 v22, 0
	v_mov_b32_e32 v23, 0
	s_and_saveexec_b64 s[48:49], s[0:1]
	s_cbranch_execz .LBB0_1282
	v_lshlrev_b32_e32 v64, 10, v77
	v_lshl_add_u64 v[22:23], v[64:65], 2, v[10:11]
	v_add_co_u32_e32 v22, vcc, 0xc000, v22
	s_nop 1
	v_addc_co_u32_e32 v23, vcc, 0, v23, vcc
	global_load_dwordx2 v[22:23], v[22:23], off
.LBB0_1282:
	s_or_b64 exec, exec, s[48:49]
	v_mov_b32_e32 v21, 0
	s_and_saveexec_b64 s[48:49], s[0:1]
	s_cbranch_execz .LBB0_1284
	v_lshlrev_b32_e32 v64, 10, v77
	v_lshl_add_u64 v[20:21], v[64:65], 2, v[10:11]
	v_add_co_u32_e32 v20, vcc, 0xe000, v20
	s_nop 1
	v_addc_co_u32_e32 v21, vcc, 0, v21, vcc
	global_load_dwordx2 v[20:21], v[20:21], off
.LBB0_1284:
	s_or_b64 exec, exec, s[48:49]
	v_mov_b32_e32 v24, 0
	v_mov_b32_e32 v26, 0
	v_mov_b32_e32 v27, 0
	s_and_saveexec_b64 s[48:49], s[0:1]
	s_cbranch_execz .LBB0_1286
	v_lshlrev_b32_e32 v64, 10, v77
	v_lshl_add_u64 v[26:27], v[64:65], 2, v[10:11]
	v_add_co_u32_e32 v26, vcc, 0x10000, v26
	s_nop 1
	v_addc_co_u32_e32 v27, vcc, 0, v27, vcc
	global_load_dwordx2 v[26:27], v[26:27], off
.LBB0_1286:
	s_or_b64 exec, exec, s[48:49]
	v_mov_b32_e32 v25, 0
	s_and_saveexec_b64 s[48:49], s[0:1]
	s_cbranch_execz .LBB0_1288
	v_lshlrev_b32_e32 v64, 10, v77
	v_lshl_add_u64 v[24:25], v[64:65], 2, v[10:11]
	v_add_co_u32_e32 v24, vcc, 0x12000, v24
	s_nop 1
	v_addc_co_u32_e32 v25, vcc, 0, v25, vcc
	global_load_dwordx2 v[24:25], v[24:25], off
.LBB0_1288:
	s_or_b64 exec, exec, s[48:49]
	v_mov_b32_e32 v28, 0
	v_mov_b32_e32 v30, 0
	v_mov_b32_e32 v31, 0
	s_and_saveexec_b64 s[48:49], s[0:1]
	s_cbranch_execz .LBB0_1290
	v_lshlrev_b32_e32 v64, 10, v77
	v_lshl_add_u64 v[30:31], v[64:65], 2, v[10:11]
	v_add_co_u32_e32 v30, vcc, 0x14000, v30
	s_nop 1
	v_addc_co_u32_e32 v31, vcc, 0, v31, vcc
	global_load_dwordx2 v[30:31], v[30:31], off
.LBB0_1290:
	s_or_b64 exec, exec, s[48:49]
	v_mov_b32_e32 v29, 0
	s_and_saveexec_b64 s[48:49], s[0:1]
	s_cbranch_execz .LBB0_1292
	v_lshlrev_b32_e32 v64, 10, v77
	v_lshl_add_u64 v[28:29], v[64:65], 2, v[10:11]
	v_add_co_u32_e32 v28, vcc, 0x16000, v28
	s_nop 1
	v_addc_co_u32_e32 v29, vcc, 0, v29, vcc
	global_load_dwordx2 v[28:29], v[28:29], off
.LBB0_1292:
	s_or_b64 exec, exec, s[48:49]
	v_mov_b32_e32 v32, 0
	v_mov_b32_e32 v34, 0
	v_mov_b32_e32 v35, 0
	s_and_saveexec_b64 s[48:49], s[0:1]
	s_cbranch_execz .LBB0_1294
	v_lshlrev_b32_e32 v64, 10, v77
	v_lshl_add_u64 v[34:35], v[64:65], 2, v[10:11]
	v_add_co_u32_e32 v34, vcc, 0x18000, v34
	s_nop 1
	v_addc_co_u32_e32 v35, vcc, 0, v35, vcc
	global_load_dwordx2 v[34:35], v[34:35], off
.LBB0_1294:
	s_or_b64 exec, exec, s[48:49]
	v_mov_b32_e32 v33, 0
	s_and_saveexec_b64 s[48:49], s[0:1]
	s_cbranch_execz .LBB0_1296
	v_lshlrev_b32_e32 v64, 10, v77
	v_lshl_add_u64 v[32:33], v[64:65], 2, v[10:11]
	v_add_co_u32_e32 v32, vcc, 0x1a000, v32
	s_nop 1
	v_addc_co_u32_e32 v33, vcc, 0, v33, vcc
	global_load_dwordx2 v[32:33], v[32:33], off
.LBB0_1296:
	s_or_b64 exec, exec, s[48:49]
	v_mov_b32_e32 v36, 0
	v_mov_b32_e32 v38, 0
	v_mov_b32_e32 v39, 0
	s_and_saveexec_b64 s[48:49], s[0:1]
	s_cbranch_execz .LBB0_1298
	v_lshlrev_b32_e32 v64, 10, v77
	v_lshl_add_u64 v[38:39], v[64:65], 2, v[10:11]
	v_add_co_u32_e32 v38, vcc, 0x1c000, v38
	s_nop 1
	v_addc_co_u32_e32 v39, vcc, 0, v39, vcc
	global_load_dwordx2 v[38:39], v[38:39], off
.LBB0_1298:
	s_or_b64 exec, exec, s[48:49]
	v_mov_b32_e32 v37, 0
	s_and_saveexec_b64 s[48:49], s[0:1]
	s_cbranch_execz .LBB0_1300
	v_lshlrev_b32_e32 v64, 10, v77
	v_lshl_add_u64 v[36:37], v[64:65], 2, v[10:11]
	v_add_co_u32_e32 v36, vcc, 0x1e000, v36
	s_nop 1
	v_addc_co_u32_e32 v37, vcc, 0, v37, vcc
	global_load_dwordx2 v[36:37], v[36:37], off
.LBB0_1300:
	s_or_b64 exec, exec, s[48:49]
	v_mov_b32_e32 v40, 0
	v_mov_b32_e32 v42, 0
	v_mov_b32_e32 v43, 0
	s_and_saveexec_b64 s[48:49], s[0:1]
	s_cbranch_execz .LBB0_1302
	v_lshlrev_b32_e32 v64, 10, v77
	v_lshl_add_u64 v[42:43], v[64:65], 2, v[10:11]
	v_add_co_u32_e32 v42, vcc, 0x20000, v42
	s_nop 1
	v_addc_co_u32_e32 v43, vcc, 0, v43, vcc
	global_load_dwordx2 v[42:43], v[42:43], off
.LBB0_1302:
	s_or_b64 exec, exec, s[48:49]
	v_mov_b32_e32 v41, 0
	s_and_saveexec_b64 s[48:49], s[0:1]
	s_cbranch_execz .LBB0_1304
	v_lshlrev_b32_e32 v64, 10, v77
	v_lshl_add_u64 v[40:41], v[64:65], 2, v[10:11]
	v_add_co_u32_e32 v40, vcc, 0x22000, v40
	s_nop 1
	v_addc_co_u32_e32 v41, vcc, 0, v41, vcc
	global_load_dwordx2 v[40:41], v[40:41], off
.LBB0_1304:
	s_or_b64 exec, exec, s[48:49]
	v_mov_b32_e32 v44, 0
	v_mov_b32_e32 v46, 0
	v_mov_b32_e32 v47, 0
	s_and_saveexec_b64 s[48:49], s[0:1]
	s_cbranch_execz .LBB0_1306
	v_lshlrev_b32_e32 v64, 10, v77
	v_lshl_add_u64 v[46:47], v[64:65], 2, v[10:11]
	v_add_co_u32_e32 v46, vcc, 0x24000, v46
	s_nop 1
	v_addc_co_u32_e32 v47, vcc, 0, v47, vcc
	global_load_dwordx2 v[46:47], v[46:47], off
.LBB0_1306:
	s_or_b64 exec, exec, s[48:49]
	v_mov_b32_e32 v45, 0
	s_and_saveexec_b64 s[48:49], s[0:1]
	s_cbranch_execz .LBB0_1308
	v_lshlrev_b32_e32 v64, 10, v77
	v_lshl_add_u64 v[44:45], v[64:65], 2, v[10:11]
	v_add_co_u32_e32 v44, vcc, 0x26000, v44
	s_nop 1
	v_addc_co_u32_e32 v45, vcc, 0, v45, vcc
	global_load_dwordx2 v[44:45], v[44:45], off
.LBB0_1308:
	s_or_b64 exec, exec, s[48:49]
	v_mov_b32_e32 v48, 0
	v_mov_b32_e32 v50, 0
	v_mov_b32_e32 v51, 0
	s_and_saveexec_b64 s[48:49], s[0:1]
	s_cbranch_execz .LBB0_1310
	v_lshlrev_b32_e32 v64, 10, v77
	v_lshl_add_u64 v[50:51], v[64:65], 2, v[10:11]
	v_add_co_u32_e32 v50, vcc, 0x28000, v50
	s_nop 1
	v_addc_co_u32_e32 v51, vcc, 0, v51, vcc
	global_load_dwordx2 v[50:51], v[50:51], off
.LBB0_1310:
	s_or_b64 exec, exec, s[48:49]
	v_mov_b32_e32 v49, 0
	s_and_saveexec_b64 s[48:49], s[0:1]
	s_cbranch_execz .LBB0_1312
	v_lshlrev_b32_e32 v64, 10, v77
	v_lshl_add_u64 v[48:49], v[64:65], 2, v[10:11]
	v_add_co_u32_e32 v48, vcc, 0x2a000, v48
	s_nop 1
	v_addc_co_u32_e32 v49, vcc, 0, v49, vcc
	global_load_dwordx2 v[48:49], v[48:49], off
.LBB0_1312:
	s_or_b64 exec, exec, s[48:49]
	v_mov_b32_e32 v52, 0
	v_mov_b32_e32 v54, 0
	v_mov_b32_e32 v55, 0
	s_and_saveexec_b64 s[48:49], s[0:1]
	s_cbranch_execz .LBB0_1314
	v_lshlrev_b32_e32 v64, 10, v77
	v_lshl_add_u64 v[54:55], v[64:65], 2, v[10:11]
	v_add_co_u32_e32 v54, vcc, 0x2c000, v54
	s_nop 1
	v_addc_co_u32_e32 v55, vcc, 0, v55, vcc
	global_load_dwordx2 v[54:55], v[54:55], off
.LBB0_1314:
	s_or_b64 exec, exec, s[48:49]
	v_mov_b32_e32 v53, 0
	s_and_saveexec_b64 s[48:49], s[0:1]
	s_cbranch_execz .LBB0_1316
	v_lshlrev_b32_e32 v64, 10, v77
	v_lshl_add_u64 v[52:53], v[64:65], 2, v[10:11]
	v_add_co_u32_e32 v52, vcc, 0x2e000, v52
	s_nop 1
	v_addc_co_u32_e32 v53, vcc, 0, v53, vcc
	global_load_dwordx2 v[52:53], v[52:53], off
.LBB0_1316:
	s_or_b64 exec, exec, s[48:49]
	v_mov_b32_e32 v56, 0
	v_mov_b32_e32 v58, 0
	v_mov_b32_e32 v59, 0
	s_and_saveexec_b64 s[48:49], s[0:1]
	s_cbranch_execz .LBB0_1318
	v_lshlrev_b32_e32 v64, 10, v77
	v_lshl_add_u64 v[58:59], v[64:65], 2, v[10:11]
	v_add_co_u32_e32 v58, vcc, 0x30000, v58
	s_nop 1
	v_addc_co_u32_e32 v59, vcc, 0, v59, vcc
	global_load_dwordx2 v[58:59], v[58:59], off
.LBB0_1318:
	s_or_b64 exec, exec, s[48:49]
	v_mov_b32_e32 v57, 0
	s_and_saveexec_b64 s[48:49], s[0:1]
	s_cbranch_execz .LBB0_1320
	v_lshlrev_b32_e32 v64, 10, v77
	v_lshl_add_u64 v[56:57], v[64:65], 2, v[10:11]
	v_add_co_u32_e32 v56, vcc, 0x32000, v56
	s_nop 1
	v_addc_co_u32_e32 v57, vcc, 0, v57, vcc
	global_load_dwordx2 v[56:57], v[56:57], off
.LBB0_1320:
	s_or_b64 exec, exec, s[48:49]
	v_mov_b32_e32 v60, 0
	v_mov_b32_e32 v62, 0
	v_mov_b32_e32 v63, 0
	s_and_saveexec_b64 s[48:49], s[0:1]
	s_cbranch_execz .LBB0_1322
	v_lshlrev_b32_e32 v64, 10, v77
	v_lshl_add_u64 v[62:63], v[64:65], 2, v[10:11]
	v_add_co_u32_e32 v62, vcc, 0x34000, v62
	s_nop 1
	v_addc_co_u32_e32 v63, vcc, 0, v63, vcc
	global_load_dwordx2 v[62:63], v[62:63], off
.LBB0_1322:
	s_or_b64 exec, exec, s[48:49]
	v_mov_b32_e32 v61, 0
	s_and_saveexec_b64 s[48:49], s[0:1]
	s_cbranch_execz .LBB0_1324
	v_lshlrev_b32_e32 v64, 10, v77
	v_lshl_add_u64 v[60:61], v[64:65], 2, v[10:11]
	v_add_co_u32_e32 v60, vcc, 0x36000, v60
	s_nop 1
	v_addc_co_u32_e32 v61, vcc, 0, v61, vcc
	global_load_dwordx2 v[60:61], v[60:61], off
.LBB0_1324:
	s_or_b64 exec, exec, s[48:49]
	v_mov_b32_e32 v66, 0
	v_mov_b32_e32 v68, 0
	v_mov_b32_e32 v69, 0
	s_and_saveexec_b64 s[48:49], s[0:1]
	s_cbranch_execz .LBB0_1326
	v_lshlrev_b32_e32 v64, 10, v77
	v_lshl_add_u64 v[68:69], v[64:65], 2, v[10:11]
	v_add_co_u32_e32 v68, vcc, 0x38000, v68
	s_nop 1
	v_addc_co_u32_e32 v69, vcc, 0, v69, vcc
	global_load_dwordx2 v[68:69], v[68:69], off
.LBB0_1326:
	s_or_b64 exec, exec, s[48:49]
	v_mov_b32_e32 v67, 0
	s_and_saveexec_b64 s[48:49], s[0:1]
	s_cbranch_execz .LBB0_1328
	v_lshlrev_b32_e32 v64, 10, v77
	v_lshl_add_u64 v[66:67], v[64:65], 2, v[10:11]
	v_add_co_u32_e32 v66, vcc, 0x3a000, v66
	s_nop 1
	v_addc_co_u32_e32 v67, vcc, 0, v67, vcc
	global_load_dwordx2 v[66:67], v[66:67], off
.LBB0_1328:
	s_or_b64 exec, exec, s[48:49]
	v_mov_b32_e32 v70, 0
	v_mov_b32_e32 v72, 0
	v_mov_b32_e32 v73, 0
	s_and_saveexec_b64 s[48:49], s[0:1]
	s_cbranch_execz .LBB0_1330
	v_lshlrev_b32_e32 v64, 10, v77
	v_lshl_add_u64 v[72:73], v[64:65], 2, v[10:11]
	v_add_co_u32_e32 v72, vcc, 0x3c000, v72
	s_nop 1
	v_addc_co_u32_e32 v73, vcc, 0, v73, vcc
	global_load_dwordx2 v[72:73], v[72:73], off
.LBB0_1330:
	s_or_b64 exec, exec, s[48:49]
	v_mov_b32_e32 v71, 0
	s_and_saveexec_b64 s[48:49], s[0:1]
	s_cbranch_execz .LBB0_1332
	v_lshlrev_b32_e32 v64, 10, v77
	v_lshl_add_u64 v[10:11], v[64:65], 2, v[10:11]
	v_add_co_u32_e32 v10, vcc, 0x3e000, v10
	s_nop 1
	v_addc_co_u32_e32 v11, vcc, 0, v11, vcc
	global_load_dwordx2 v[70:71], v[10:11], off
.LBB0_1332:
	s_or_b64 exec, exec, s[48:49]
	v_add_u32_e32 v10, v5, v78
	s_waitcnt vmcnt(0) lgkmcnt(0)
	ds_write2_b32 v10, v6, v7 offset1:1
	ds_write2_b32 v10, v8, v9 offset0:130 offset1:131
	v_add_u32_e32 v6, 0x410, v10
	ds_write2_b32 v6, v14, v15 offset1:1
	v_add_u32_e32 v6, 0x618, v10
	ds_write2_b32 v6, v12, v13 offset1:1
	v_add_u32_e32 v6, 0x820, v10
	ds_write2_b32 v6, v18, v19 offset1:1
	v_add_u32_e32 v6, 0xa28, v10
	ds_write2_b32 v6, v16, v17 offset1:1
	v_add_u32_e32 v6, 0xc30, v10
	ds_write2_b32 v6, v22, v23 offset1:1
	v_add_u32_e32 v6, 0xe38, v10
	ds_write2_b32 v6, v20, v21 offset1:1
	v_add_u32_e32 v6, 0x1040, v10
	ds_write2_b32 v6, v26, v27 offset1:1
	v_add_u32_e32 v6, 0x1248, v10
	ds_write2_b32 v6, v24, v25 offset1:1
	v_add_u32_e32 v6, 0x1450, v10
	ds_write2_b32 v6, v30, v31 offset1:1
	v_add_u32_e32 v6, 0x1658, v10
	ds_write2_b32 v6, v28, v29 offset1:1
	v_add_u32_e32 v6, 0x1860, v10
	ds_write2_b32 v6, v34, v35 offset1:1
	v_add_u32_e32 v6, 0x1a68, v10
	ds_write2_b32 v6, v32, v33 offset1:1
	v_add_u32_e32 v6, 0x1c70, v10
	ds_write2_b32 v6, v38, v39 offset1:1
	v_add_u32_e32 v6, 0x1e78, v10
	ds_write2_b32 v6, v36, v37 offset1:1
	v_add_u32_e32 v6, 0x2080, v10
	ds_write2_b32 v6, v42, v43 offset1:1
	v_add_u32_e32 v6, 0x2288, v10
	ds_write2_b32 v6, v40, v41 offset1:1
	v_add_u32_e32 v6, 0x2490, v10
	ds_write2_b32 v6, v46, v47 offset1:1
	v_add_u32_e32 v6, 0x2698, v10
	ds_write2_b32 v6, v44, v45 offset1:1
	v_add_u32_e32 v6, 0x28a0, v10
	ds_write2_b32 v6, v50, v51 offset1:1
	v_add_u32_e32 v6, 0x2aa8, v10
	ds_write2_b32 v6, v48, v49 offset1:1
	v_add_u32_e32 v6, 0x2cb0, v10
	ds_write2_b32 v6, v54, v55 offset1:1
	v_add_u32_e32 v6, 0x2eb8, v10
	ds_write2_b32 v6, v52, v53 offset1:1
	v_add_u32_e32 v6, 0x30c0, v10
	ds_write2_b32 v6, v58, v59 offset1:1
	v_add_u32_e32 v6, 0x32c8, v10
	ds_write2_b32 v6, v56, v57 offset1:1
	v_add_u32_e32 v6, 0x34d0, v10
	ds_write2_b32 v6, v62, v63 offset1:1
	v_add_u32_e32 v6, 0x36d8, v10
	ds_write2_b32 v6, v60, v61 offset1:1
	v_add_u32_e32 v6, 0x38e0, v10
	ds_write2_b32 v6, v68, v69 offset1:1
	v_add_u32_e32 v6, 0x3ae8, v10
	ds_write2_b32 v6, v66, v67 offset1:1
	v_add_u32_e32 v6, 0x3cf0, v10
	ds_write2_b32 v6, v72, v73 offset1:1
	v_add_u32_e32 v6, 0x3ef8, v10
	ds_write2_b32 v6, v70, v71 offset1:1
	s_add_u32 s0, s46, s57
	s_waitcnt lgkmcnt(0)
	s_addc_u32 s1, s47, s56
	v_lshlrev_b32_e32 v64, 1, v75
	ds_read_b32 v8, v80
	ds_read_b32 v9, v80 offset:260
	ds_read_b32 v12, v80 offset:520
	ds_read_b32 v13, v80 offset:780
	ds_read_b32 v14, v80 offset:1040
	ds_read_b32 v15, v80 offset:1300
	ds_read_b32 v16, v80 offset:1560
	ds_read_b32 v17, v80 offset:1820
	v_lshl_add_u64 v[6:7], s[0:1], 0, v[64:65]
	v_lshlrev_b32_e32 v64, 1, v4
	v_sub_u32_e32 v76, v100, v76
	v_lshl_add_u64 v[6:7], v[6:7], 0, v[64:65]
	s_mov_b64 s[0:1], 0x4a00000
	v_lshl_add_u64 v[10:11], v[6:7], 0, s[0:1]
	s_waitcnt lgkmcnt(6)
	v_cvt_pk_bf16_f32 v6, v8, v9
	s_waitcnt lgkmcnt(2)
	v_cvt_pk_bf16_f32 v8, v14, v15
	v_add_u32_e32 v14, v74, v76
	v_cvt_pk_bf16_f32 v7, v12, v13
	v_subrev_u32_e32 v12, 56, v14
	s_movk_i32 s26, 0x1600
	s_waitcnt lgkmcnt(0)
	v_cvt_pk_bf16_f32 v9, v16, v17
	v_mad_i64_i32 v[12:13], s[0:1], v12, s26, v[10:11]
	global_store_dwordx4 v[12:13], v[6:9], off
	ds_read_b32 v6, v80 offset:32
	ds_read_b32 v7, v80 offset:292
	ds_read_b32 v8, v80 offset:552
	ds_read_b32 v9, v80 offset:812
	ds_read_b32 v12, v80 offset:1072
	ds_read_b32 v13, v80 offset:1332
	ds_read_b32 v15, v80 offset:1592
	ds_read_b32 v16, v80 offset:1852
	s_waitcnt lgkmcnt(0)
	v_cvt_pk_bf16_f32 v6, v6, v7
	v_cvt_pk_bf16_f32 v7, v8, v9
	v_cvt_pk_bf16_f32 v8, v12, v13
	v_subrev_u32_e32 v12, 48, v14
	v_cvt_pk_bf16_f32 v9, v15, v16
	v_mad_i64_i32 v[12:13], s[0:1], v12, s26, v[10:11]
	global_store_dwordx4 v[12:13], v[6:9], off
	ds_read_b32 v6, v80 offset:64
	ds_read_b32 v7, v80 offset:324
	ds_read_b32 v8, v80 offset:584
	ds_read_b32 v9, v80 offset:844
	ds_read_b32 v12, v80 offset:1104
	ds_read_b32 v13, v80 offset:1364
	ds_read_b32 v15, v80 offset:1624
	ds_read_b32 v16, v80 offset:1884
	s_waitcnt lgkmcnt(0)
	v_cvt_pk_bf16_f32 v6, v6, v7
	v_cvt_pk_bf16_f32 v7, v8, v9
	v_cvt_pk_bf16_f32 v8, v12, v13
	v_subrev_u32_e32 v12, 40, v14
	v_cvt_pk_bf16_f32 v9, v15, v16
	v_mad_i64_i32 v[12:13], s[0:1], v12, s26, v[10:11]
	global_store_dwordx4 v[12:13], v[6:9], off
	ds_read_b32 v6, v80 offset:96
	ds_read_b32 v7, v80 offset:356
	ds_read_b32 v8, v80 offset:616
	ds_read_b32 v9, v80 offset:876
	ds_read_b32 v12, v80 offset:1136
	ds_read_b32 v13, v80 offset:1396
	ds_read_b32 v15, v80 offset:1656
	ds_read_b32 v16, v80 offset:1916
	s_waitcnt lgkmcnt(0)
	v_cvt_pk_bf16_f32 v6, v6, v7
	v_cvt_pk_bf16_f32 v7, v8, v9
	v_cvt_pk_bf16_f32 v8, v12, v13
	v_subrev_u32_e32 v12, 32, v14
	v_cvt_pk_bf16_f32 v9, v15, v16
	v_mad_i64_i32 v[12:13], s[0:1], v12, s26, v[10:11]
	global_store_dwordx4 v[12:13], v[6:9], off
	ds_read_b32 v6, v80 offset:128
	ds_read_b32 v7, v80 offset:388
	ds_read_b32 v8, v80 offset:648
	ds_read_b32 v9, v80 offset:908
	ds_read_b32 v12, v80 offset:1168
	ds_read_b32 v13, v80 offset:1428
	ds_read_b32 v15, v80 offset:1688
	ds_read_b32 v16, v80 offset:1948
	s_waitcnt lgkmcnt(0)
	v_cvt_pk_bf16_f32 v6, v6, v7
	v_cvt_pk_bf16_f32 v7, v8, v9
	v_cvt_pk_bf16_f32 v8, v12, v13
	v_subrev_u32_e32 v12, 24, v14
	v_cvt_pk_bf16_f32 v9, v15, v16
	v_mad_i64_i32 v[12:13], s[0:1], v12, s26, v[10:11]
	global_store_dwordx4 v[12:13], v[6:9], off
	ds_read_b32 v6, v80 offset:160
	ds_read_b32 v7, v80 offset:420
	ds_read_b32 v8, v80 offset:680
	ds_read_b32 v9, v80 offset:940
	ds_read_b32 v12, v80 offset:1200
	ds_read_b32 v13, v80 offset:1460
	ds_read_b32 v15, v80 offset:1720
	ds_read_b32 v16, v80 offset:1980
	s_waitcnt lgkmcnt(0)
	v_cvt_pk_bf16_f32 v6, v6, v7
	v_cvt_pk_bf16_f32 v7, v8, v9
	v_cvt_pk_bf16_f32 v8, v12, v13
	v_add_u32_e32 v12, -16, v14
	v_cvt_pk_bf16_f32 v9, v15, v16
	v_mad_i64_i32 v[12:13], s[0:1], v12, s26, v[10:11]
	global_store_dwordx4 v[12:13], v[6:9], off
	ds_read_b32 v6, v80 offset:192
	ds_read_b32 v7, v80 offset:452
	ds_read_b32 v8, v80 offset:712
	ds_read_b32 v9, v80 offset:972
	ds_read_b32 v12, v80 offset:1232
	ds_read_b32 v13, v80 offset:1492
	ds_read_b32 v15, v80 offset:1752
	ds_read_b32 v16, v80 offset:2012
	s_waitcnt lgkmcnt(0)
	v_cvt_pk_bf16_f32 v6, v6, v7
	v_cvt_pk_bf16_f32 v7, v8, v9
	v_cvt_pk_bf16_f32 v8, v12, v13
	v_add_u32_e32 v12, -8, v14
	v_cvt_pk_bf16_f32 v9, v15, v16
	v_mad_i64_i32 v[12:13], s[0:1], v12, s26, v[10:11]
	global_store_dwordx4 v[12:13], v[6:9], off
	ds_read_b32 v6, v80 offset:224
	ds_read_b32 v7, v80 offset:484
	ds_read_b32 v8, v80 offset:744
	ds_read_b32 v9, v80 offset:1004
	ds_read_b32 v12, v80 offset:1264
	ds_read_b32 v13, v80 offset:1524
	ds_read_b32 v15, v80 offset:1784
	ds_read_b32 v16, v80 offset:2044
	s_waitcnt lgkmcnt(0)
	v_cvt_pk_bf16_f32 v6, v6, v7
	v_cvt_pk_bf16_f32 v7, v8, v9
	v_cvt_pk_bf16_f32 v8, v12, v13
	v_mad_i64_i32 v[10:11], s[0:1], v14, s26, v[10:11]
	v_cvt_pk_bf16_f32 v9, v15, v16
	global_store_dwordx4 v[10:11], v[6:9], off
	s_waitcnt lgkmcnt(0)
.LBB0_1333:
	s_andn2_saveexec_b64 s[44:45], s[44:45]
	s_cbranch_execz .LBB0_1596
	v_readlane_b32 s64, v254, 45
	v_readlane_b32 s66, v254, 47
	v_readlane_b32 s67, v254, 48
	v_add_u32_e32 v6, 0x580, v101
	s_mov_b64 s[0:1], s[66:67]
	v_mul_u32_u24_e32 v7, 0xba2f, v6
	s_add_u32 s26, s0, s59
	v_lshrrev_b32_e32 v7, 22, v7
	s_movk_i32 s0, 0xffa8
	v_mad_i32_i24 v8, v7, s0, v6
	v_lshlrev_b32_e32 v110, 6, v8
	v_lshlrev_b32_e32 v6, 6, v7
	v_and_b32_e32 v7, 0xc0, v110
	v_lshlrev_b32_e32 v8, 5, v8
	v_or_b32_e32 v9, v7, v1
	v_and_b32_e32 v8, 0xffffff80, v8
	s_movk_i32 s0, 0xa80
	v_or_b32_e32 v10, v9, v8
	v_add3_u32 v8, v8, v9, s0
	s_movk_i32 s0, 0x80
	v_cmp_gt_u32_e32 vcc, s0, v7
	v_readlane_b32 s65, v254, 46
	s_addc_u32 s27, s1, s58
	v_cndmask_b32_e32 v64, v8, v10, vcc
	v_mov_b32_e32 v24, 0
	s_mov_b64 s[48:49], s[64:65]
	s_mov_b64 s[46:47], s[40:41]
	v_cmp_lt_i32_e64 s[0:1], -1, v64
	v_or_b32_e32 v7, v6, v2
	v_lshl_add_u64 v[74:75], v[64:65], 2, s[26:27]
	v_mov_b32_e32 v22, 0
	v_mov_b32_e32 v23, v24
	v_readlane_b32 s68, v254, 49
	v_readlane_b32 s69, v254, 50
	v_readlane_b32 s70, v254, 51
	v_readlane_b32 s71, v254, 52
	s_and_saveexec_b64 s[50:51], s[0:1]
	s_cbranch_execz .LBB0_1336
	v_mul_u32_u24_e32 v8, 0x1600, v7
	v_lshlrev_b32_e32 v64, 2, v8
	v_lshl_add_u64 v[8:9], v[74:75], 0, v[64:65]
	global_load_dwordx2 v[22:23], v[8:9], off
.LBB0_1336:
	s_or_b64 exec, exec, s[50:51]
	v_mov_b32_e32 v25, 0
	s_and_saveexec_b64 s[50:51], s[0:1]
	s_cbranch_execz .LBB0_1338
	v_mul_u32_u24_e32 v8, 0x1600, v7
	v_lshlrev_b32_e32 v64, 2, v8
	v_lshl_add_u64 v[8:9], v[74:75], 0, v[64:65]
	v_add_co_u32_e32 v8, vcc, 0xb000, v8
	s_nop 1
	v_addc_co_u32_e32 v9, vcc, 0, v9, vcc
	global_load_dwordx2 v[24:25], v[8:9], off
.LBB0_1338:
	s_or_b64 exec, exec, s[50:51]
	v_mov_b32_e32 v64, v65
	v_mov_b64_e32 v[42:43], v[64:65]
	s_and_saveexec_b64 s[50:51], s[0:1]
	s_cbranch_execz .LBB0_1340
	v_mul_u32_u24_e32 v8, 0x1600, v7
	v_lshlrev_b32_e32 v64, 2, v8
	v_lshl_add_u64 v[8:9], v[74:75], 0, v[64:65]
	v_add_co_u32_e32 v8, vcc, 0x16000, v8
	s_nop 1
	v_addc_co_u32_e32 v9, vcc, 0, v9, vcc
	global_load_dwordx2 v[42:43], v[8:9], off
.LBB0_1340:
	s_or_b64 exec, exec, s[50:51]
	v_mov_b32_e32 v8, 0
	v_mov_b32_e32 v56, 0
	v_mov_b32_e32 v57, 0
	s_and_saveexec_b64 s[50:51], s[0:1]
	s_cbranch_execz .LBB0_1342
	v_mul_u32_u24_e32 v9, 0x1600, v7
	v_lshlrev_b32_e32 v64, 2, v9
	v_lshl_add_u64 v[10:11], v[74:75], 0, v[64:65]
	v_add_co_u32_e32 v10, vcc, 0x21000, v10
	s_nop 1
	v_addc_co_u32_e32 v11, vcc, 0, v11, vcc
	global_load_dwordx2 v[56:57], v[10:11], off
.LBB0_1342:
	s_or_b64 exec, exec, s[50:51]
	v_mov_b32_e32 v9, 0
	s_and_saveexec_b64 s[50:51], s[0:1]
	s_cbranch_execz .LBB0_1344
	v_mul_u32_u24_e32 v8, 0x1600, v7
	v_lshlrev_b32_e32 v64, 2, v8
	v_lshl_add_u64 v[8:9], v[74:75], 0, v[64:65]
	v_add_co_u32_e32 v8, vcc, 0x2c000, v8
	s_nop 1
	v_addc_co_u32_e32 v9, vcc, 0, v9, vcc
	global_load_dwordx2 v[8:9], v[8:9], off
.LBB0_1344:
	s_or_b64 exec, exec, s[50:51]
	v_mov_b32_e32 v26, 0
	v_mov_b32_e32 v27, v26
	s_and_saveexec_b64 s[50:51], s[0:1]
	s_cbranch_execz .LBB0_1346
	v_mul_u32_u24_e32 v10, 0x1600, v7
	v_lshlrev_b32_e32 v64, 2, v10
	v_lshl_add_u64 v[10:11], v[74:75], 0, v[64:65]
	v_add_co_u32_e32 v10, vcc, 0x37000, v10
	s_nop 1
	v_addc_co_u32_e32 v11, vcc, 0, v11, vcc
	global_load_dwordx2 v[26:27], v[10:11], off
.LBB0_1346:
	s_or_b64 exec, exec, s[50:51]
	v_mov_b32_e32 v64, v65
	v_mov_b64_e32 v[40:41], v[64:65]
	s_and_saveexec_b64 s[50:51], s[0:1]
	s_cbranch_execz .LBB0_1348
	v_mul_u32_u24_e32 v10, 0x1600, v7
	v_lshlrev_b32_e32 v64, 2, v10
	v_lshl_add_u64 v[10:11], v[74:75], 0, v[64:65]
	v_add_co_u32_e32 v10, vcc, 0x42000, v10
	s_nop 1
	v_addc_co_u32_e32 v11, vcc, 0, v11, vcc
	global_load_dwordx2 v[40:41], v[10:11], off
.LBB0_1348:
	s_or_b64 exec, exec, s[50:51]
	v_mov_b32_e32 v10, 0
	v_mov_b32_e32 v52, 0
	v_mov_b32_e32 v53, 0
	s_and_saveexec_b64 s[50:51], s[0:1]
	s_cbranch_execz .LBB0_1350
	v_mul_u32_u24_e32 v11, 0x1600, v7
	v_lshlrev_b32_e32 v64, 2, v11
	v_lshl_add_u64 v[12:13], v[74:75], 0, v[64:65]
	v_add_co_u32_e32 v12, vcc, 0x4d000, v12
	s_nop 1
	v_addc_co_u32_e32 v13, vcc, 0, v13, vcc
	global_load_dwordx2 v[52:53], v[12:13], off
.LBB0_1350:
	s_or_b64 exec, exec, s[50:51]
	v_mov_b32_e32 v11, 0
	s_and_saveexec_b64 s[50:51], s[0:1]
	s_cbranch_execz .LBB0_1352
	v_mul_u32_u24_e32 v10, 0x1600, v7
	v_lshlrev_b32_e32 v64, 2, v10
	v_lshl_add_u64 v[10:11], v[74:75], 0, v[64:65]
	v_add_co_u32_e32 v10, vcc, 0x58000, v10
	s_nop 1
	v_addc_co_u32_e32 v11, vcc, 0, v11, vcc
	global_load_dwordx2 v[10:11], v[10:11], off
.LBB0_1352:
	s_or_b64 exec, exec, s[50:51]
	v_mov_b32_e32 v28, 0
	v_mov_b32_e32 v29, v28
	s_and_saveexec_b64 s[50:51], s[0:1]
	s_cbranch_execz .LBB0_1354
	v_mul_u32_u24_e32 v12, 0x1600, v7
	v_lshlrev_b32_e32 v64, 2, v12
	v_lshl_add_u64 v[12:13], v[74:75], 0, v[64:65]
	v_add_co_u32_e32 v12, vcc, 0x63000, v12
	s_nop 1
	v_addc_co_u32_e32 v13, vcc, 0, v13, vcc
	global_load_dwordx2 v[28:29], v[12:13], off
.LBB0_1354:
	s_or_b64 exec, exec, s[50:51]
	v_mov_b32_e32 v64, v65
	v_mov_b64_e32 v[44:45], v[64:65]
	s_and_saveexec_b64 s[50:51], s[0:1]
	s_cbranch_execz .LBB0_1356
	v_mul_u32_u24_e32 v12, 0x1600, v7
	v_lshlrev_b32_e32 v64, 2, v12
	v_lshl_add_u64 v[12:13], v[74:75], 0, v[64:65]
	v_add_co_u32_e32 v12, vcc, 0x6e000, v12
	s_nop 1
	v_addc_co_u32_e32 v13, vcc, 0, v13, vcc
	global_load_dwordx2 v[44:45], v[12:13], off
.LBB0_1356:
	s_or_b64 exec, exec, s[50:51]
	v_mov_b32_e32 v12, 0
	v_mov_b32_e32 v54, 0
	v_mov_b32_e32 v55, 0
	s_and_saveexec_b64 s[50:51], s[0:1]
	s_cbranch_execz .LBB0_1358
	v_mul_u32_u24_e32 v13, 0x1600, v7
	v_lshlrev_b32_e32 v64, 2, v13
	v_lshl_add_u64 v[14:15], v[74:75], 0, v[64:65]
	v_add_co_u32_e32 v14, vcc, 0x79000, v14
	s_nop 1
	v_addc_co_u32_e32 v15, vcc, 0, v15, vcc
	global_load_dwordx2 v[54:55], v[14:15], off
.LBB0_1358:
	s_or_b64 exec, exec, s[50:51]
	v_mov_b32_e32 v13, 0
	s_and_saveexec_b64 s[50:51], s[0:1]
	s_cbranch_execz .LBB0_1360
	v_mul_u32_u24_e32 v12, 0x1600, v7
	v_lshlrev_b32_e32 v64, 2, v12
	v_lshl_add_u64 v[12:13], v[74:75], 0, v[64:65]
	v_add_co_u32_e32 v12, vcc, 0x84000, v12
	s_nop 1
	v_addc_co_u32_e32 v13, vcc, 0, v13, vcc
	global_load_dwordx2 v[12:13], v[12:13], off
.LBB0_1360:
	s_or_b64 exec, exec, s[50:51]
	v_mov_b32_e32 v30, 0
	v_mov_b32_e32 v31, v30
	s_and_saveexec_b64 s[50:51], s[0:1]
	s_cbranch_execz .LBB0_1362
	v_mul_u32_u24_e32 v14, 0x1600, v7
	v_lshlrev_b32_e32 v64, 2, v14
	v_lshl_add_u64 v[14:15], v[74:75], 0, v[64:65]
	v_add_co_u32_e32 v14, vcc, 0x8f000, v14
	s_nop 1
	v_addc_co_u32_e32 v15, vcc, 0, v15, vcc
	global_load_dwordx2 v[30:31], v[14:15], off
.LBB0_1362:
	s_or_b64 exec, exec, s[50:51]
	v_mov_b32_e32 v64, v65
	v_mov_b64_e32 v[46:47], v[64:65]
	s_and_saveexec_b64 s[50:51], s[0:1]
	s_cbranch_execz .LBB0_1364
	v_mul_u32_u24_e32 v14, 0x1600, v7
	v_lshlrev_b32_e32 v64, 2, v14
	v_lshl_add_u64 v[14:15], v[74:75], 0, v[64:65]
	v_add_co_u32_e32 v14, vcc, 0x9a000, v14
	s_nop 1
	v_addc_co_u32_e32 v15, vcc, 0, v15, vcc
	global_load_dwordx2 v[46:47], v[14:15], off
.LBB0_1364:
	s_or_b64 exec, exec, s[50:51]
	v_mov_b32_e32 v14, 0
	v_mov_b32_e32 v60, 0
	v_mov_b32_e32 v61, 0
	s_and_saveexec_b64 s[50:51], s[0:1]
	s_cbranch_execz .LBB0_1366
	v_mul_u32_u24_e32 v15, 0x1600, v7
	v_lshlrev_b32_e32 v64, 2, v15
	v_lshl_add_u64 v[16:17], v[74:75], 0, v[64:65]
	v_add_co_u32_e32 v16, vcc, 0xa5000, v16
	s_nop 1
	v_addc_co_u32_e32 v17, vcc, 0, v17, vcc
	global_load_dwordx2 v[60:61], v[16:17], off
.LBB0_1366:
	s_or_b64 exec, exec, s[50:51]
	v_mov_b32_e32 v15, 0
	s_and_saveexec_b64 s[50:51], s[0:1]
	s_cbranch_execz .LBB0_1368
	v_mul_u32_u24_e32 v14, 0x1600, v7
	v_lshlrev_b32_e32 v64, 2, v14
	v_lshl_add_u64 v[14:15], v[74:75], 0, v[64:65]
	v_add_co_u32_e32 v14, vcc, 0xb0000, v14
	s_nop 1
	v_addc_co_u32_e32 v15, vcc, 0, v15, vcc
	global_load_dwordx2 v[14:15], v[14:15], off
.LBB0_1368:
	s_or_b64 exec, exec, s[50:51]
	v_mov_b32_e32 v32, 0
	v_mov_b32_e32 v33, v32
	s_and_saveexec_b64 s[50:51], s[0:1]
	s_cbranch_execz .LBB0_1370
	v_mul_u32_u24_e32 v16, 0x1600, v7
	v_lshlrev_b32_e32 v64, 2, v16
	v_lshl_add_u64 v[16:17], v[74:75], 0, v[64:65]
	v_add_co_u32_e32 v16, vcc, 0xbb000, v16
	s_nop 1
	v_addc_co_u32_e32 v17, vcc, 0, v17, vcc
	global_load_dwordx2 v[32:33], v[16:17], off
.LBB0_1370:
	s_or_b64 exec, exec, s[50:51]
	v_mov_b32_e32 v64, v65
	v_mov_b64_e32 v[48:49], v[64:65]
	s_and_saveexec_b64 s[50:51], s[0:1]
	s_cbranch_execz .LBB0_1372
	v_mul_u32_u24_e32 v16, 0x1600, v7
	v_lshlrev_b32_e32 v64, 2, v16
	v_lshl_add_u64 v[16:17], v[74:75], 0, v[64:65]
	v_add_co_u32_e32 v16, vcc, 0xc6000, v16
	s_nop 1
	v_addc_co_u32_e32 v17, vcc, 0, v17, vcc
	global_load_dwordx2 v[48:49], v[16:17], off
.LBB0_1372:
	s_or_b64 exec, exec, s[50:51]
	v_mov_b32_e32 v16, 0
	v_mov_b32_e32 v66, 0
	v_mov_b32_e32 v67, 0
	s_and_saveexec_b64 s[50:51], s[0:1]
	s_cbranch_execz .LBB0_1374
	v_mul_u32_u24_e32 v17, 0x1600, v7
	v_lshlrev_b32_e32 v64, 2, v17
	v_lshl_add_u64 v[18:19], v[74:75], 0, v[64:65]
	v_add_co_u32_e32 v18, vcc, 0xd1000, v18
	s_nop 1
	v_addc_co_u32_e32 v19, vcc, 0, v19, vcc
	global_load_dwordx2 v[66:67], v[18:19], off
.LBB0_1374:
	s_or_b64 exec, exec, s[50:51]
	v_mov_b32_e32 v17, 0
	s_and_saveexec_b64 s[50:51], s[0:1]
	s_cbranch_execz .LBB0_1376
	v_mul_u32_u24_e32 v16, 0x1600, v7
	v_lshlrev_b32_e32 v64, 2, v16
	v_lshl_add_u64 v[16:17], v[74:75], 0, v[64:65]
	v_add_co_u32_e32 v16, vcc, 0xdc000, v16
	s_nop 1
	v_addc_co_u32_e32 v17, vcc, 0, v17, vcc
	global_load_dwordx2 v[16:17], v[16:17], off
.LBB0_1376:
	s_or_b64 exec, exec, s[50:51]
	v_mov_b32_e32 v34, 0
	v_mov_b32_e32 v35, v34
	s_and_saveexec_b64 s[50:51], s[0:1]
	s_cbranch_execz .LBB0_1378
	v_mul_u32_u24_e32 v18, 0x1600, v7
	v_lshlrev_b32_e32 v64, 2, v18
	v_lshl_add_u64 v[18:19], v[74:75], 0, v[64:65]
	v_add_co_u32_e32 v18, vcc, 0xe7000, v18
	s_nop 1
	v_addc_co_u32_e32 v19, vcc, 0, v19, vcc
	global_load_dwordx2 v[34:35], v[18:19], off
.LBB0_1378:
	s_or_b64 exec, exec, s[50:51]
	v_mov_b32_e32 v64, v65
	v_mov_b64_e32 v[50:51], v[64:65]
	s_and_saveexec_b64 s[50:51], s[0:1]
	s_cbranch_execz .LBB0_1380
	v_mul_u32_u24_e32 v18, 0x1600, v7
	v_lshlrev_b32_e32 v64, 2, v18
	v_lshl_add_u64 v[18:19], v[74:75], 0, v[64:65]
	v_add_co_u32_e32 v18, vcc, 0xf2000, v18
	s_nop 1
	v_addc_co_u32_e32 v19, vcc, 0, v19, vcc
	global_load_dwordx2 v[50:51], v[18:19], off
.LBB0_1380:
	s_or_b64 exec, exec, s[50:51]
	v_mov_b32_e32 v18, 0
	v_mov_b32_e32 v62, 0
	v_mov_b32_e32 v63, 0
	s_and_saveexec_b64 s[50:51], s[0:1]
	s_cbranch_execz .LBB0_1382
	v_mul_u32_u24_e32 v19, 0x1600, v7
	v_lshlrev_b32_e32 v64, 2, v19
	v_lshl_add_u64 v[20:21], v[74:75], 0, v[64:65]
	v_add_co_u32_e32 v20, vcc, 0xfd000, v20
	s_nop 1
	v_addc_co_u32_e32 v21, vcc, 0, v21, vcc
	global_load_dwordx2 v[62:63], v[20:21], off
.LBB0_1382:
	s_or_b64 exec, exec, s[50:51]
	v_mov_b32_e32 v19, 0
	s_and_saveexec_b64 s[50:51], s[0:1]
	s_cbranch_execz .LBB0_1384
	v_mul_u32_u24_e32 v18, 0x1600, v7
	v_lshlrev_b32_e32 v64, 2, v18
	v_lshl_add_u64 v[18:19], v[74:75], 0, v[64:65]
	v_add_co_u32_e32 v18, vcc, 0x108000, v18
	s_nop 1
	v_addc_co_u32_e32 v19, vcc, 0, v19, vcc
	global_load_dwordx2 v[18:19], v[18:19], off
.LBB0_1384:
	s_or_b64 exec, exec, s[50:51]
	v_mov_b32_e32 v36, 0
	v_mov_b32_e32 v37, v36
	s_and_saveexec_b64 s[50:51], s[0:1]
	s_cbranch_execz .LBB0_1386
	v_mul_u32_u24_e32 v20, 0x1600, v7
	v_lshlrev_b32_e32 v64, 2, v20
	v_lshl_add_u64 v[20:21], v[74:75], 0, v[64:65]
	v_add_co_u32_e32 v20, vcc, 0x113000, v20
	s_nop 1
	v_addc_co_u32_e32 v21, vcc, 0, v21, vcc
	global_load_dwordx2 v[36:37], v[20:21], off
.LBB0_1386:
	s_or_b64 exec, exec, s[50:51]
	v_mov_b32_e32 v64, v65
	v_mov_b64_e32 v[58:59], v[64:65]
	s_and_saveexec_b64 s[50:51], s[0:1]
	s_cbranch_execz .LBB0_1388
	v_mul_u32_u24_e32 v20, 0x1600, v7
	v_lshlrev_b32_e32 v64, 2, v20
	v_lshl_add_u64 v[20:21], v[74:75], 0, v[64:65]
	v_add_co_u32_e32 v20, vcc, 0x11e000, v20
	s_nop 1
	v_addc_co_u32_e32 v21, vcc, 0, v21, vcc
	global_load_dwordx2 v[58:59], v[20:21], off
.LBB0_1388:
	s_or_b64 exec, exec, s[50:51]
	v_mov_b32_e32 v20, 0
	v_mov_b32_e32 v70, 0
	v_mov_b32_e32 v71, 0
	s_and_saveexec_b64 s[50:51], s[0:1]
	s_cbranch_execz .LBB0_1390
	v_mul_u32_u24_e32 v21, 0x1600, v7
	v_lshlrev_b32_e32 v64, 2, v21
	v_lshl_add_u64 v[38:39], v[74:75], 0, v[64:65]
	v_add_co_u32_e32 v38, vcc, 0x129000, v38
	s_nop 1
	v_addc_co_u32_e32 v39, vcc, 0, v39, vcc
	global_load_dwordx2 v[70:71], v[38:39], off
.LBB0_1390:
	s_or_b64 exec, exec, s[50:51]
	v_mov_b32_e32 v21, 0
	s_and_saveexec_b64 s[50:51], s[0:1]
	s_cbranch_execz .LBB0_1392
	v_mul_u32_u24_e32 v20, 0x1600, v7
	v_lshlrev_b32_e32 v64, 2, v20
	v_lshl_add_u64 v[20:21], v[74:75], 0, v[64:65]
	v_add_co_u32_e32 v20, vcc, 0x134000, v20
	s_nop 1
	v_addc_co_u32_e32 v21, vcc, 0, v21, vcc
	global_load_dwordx2 v[20:21], v[20:21], off
.LBB0_1392:
	s_or_b64 exec, exec, s[50:51]
	v_mov_b32_e32 v38, 0
	v_mov_b32_e32 v39, v38
	s_and_saveexec_b64 s[50:51], s[0:1]
	s_cbranch_execz .LBB0_1394
	v_mul_u32_u24_e32 v38, 0x1600, v7
	v_lshlrev_b32_e32 v64, 2, v38
	v_lshl_add_u64 v[38:39], v[74:75], 0, v[64:65]
	v_add_co_u32_e32 v38, vcc, 0x13f000, v38
	s_nop 1
	v_addc_co_u32_e32 v39, vcc, 0, v39, vcc
	global_load_dwordx2 v[38:39], v[38:39], off
.LBB0_1394:
	s_or_b64 exec, exec, s[50:51]
	v_mov_b32_e32 v64, v65
	v_mov_b64_e32 v[68:69], v[64:65]
	s_and_saveexec_b64 s[50:51], s[0:1]
	s_cbranch_execz .LBB0_1396
	v_mul_u32_u24_e32 v64, 0x1600, v7
	v_lshlrev_b32_e32 v64, 2, v64
	v_lshl_add_u64 v[68:69], v[74:75], 0, v[64:65]
	v_add_co_u32_e32 v68, vcc, 0x14a000, v68
	s_nop 1
	v_addc_co_u32_e32 v69, vcc, 0, v69, vcc
	global_load_dwordx2 v[68:69], v[68:69], off
.LBB0_1396:
	s_or_b64 exec, exec, s[50:51]
	v_mov_b32_e32 v72, 0
	v_mov_b32_e32 v73, 0
	s_and_saveexec_b64 s[50:51], s[0:1]
	s_cbranch_execz .LBB0_1398
	v_mul_u32_u24_e32 v64, 0x1600, v7
	v_lshlrev_b32_e32 v64, 2, v64
	v_lshl_add_u64 v[72:73], v[74:75], 0, v[64:65]
	v_add_co_u32_e32 v72, vcc, 0x155000, v72
	s_nop 1
	v_addc_co_u32_e32 v73, vcc, 0, v73, vcc
	global_load_dwordx2 v[72:73], v[72:73], off
.LBB0_1398:
	s_or_b64 exec, exec, s[50:51]
	v_readlane_b32 s0, v254, 43
	v_readlane_b32 s1, v254, 44
	s_lshl_b64 s[0:1], s[0:1], 2
	s_add_u32 s50, s48, s0
	s_addc_u32 s51, s49, s1
	s_cmp_lg_u64 s[48:49], 0
	s_cselect_b64 s[52:53], -1, 0
	s_cmp_eq_u64 s[48:49], 0
	v_add_lshl_u32 v74, v6, v2, 2
	s_cbranch_scc1 .LBB0_1597
	v_lshlrev_b32_e32 v64, 2, v7
	v_lshl_add_u64 v[76:77], s[50:51], 0, v[64:65]
	global_load_dword v64, v[76:77], off
	v_mov_b32_e32 v75, v65
	v_lshl_add_u64 v[112:113], s[50:51], 0, v[74:75]
	v_add_u32_e32 v7, v5, v78
	s_waitcnt vmcnt(0) lgkmcnt(0)
	v_pk_mul_f32 v[76:77], v[22:23], v[64:65] op_sel_hi:[1,0]
	global_load_dword v64, v[112:113], off offset:8
	ds_write2_b32 v7, v76, v77 offset1:1
	v_add_u32_e32 v7, v5, v88
	s_waitcnt vmcnt(0) lgkmcnt(0)
	v_pk_mul_f32 v[76:77], v[24:25], v[64:65] op_sel_hi:[1,0]
	global_load_dword v64, v[112:113], off offset:16
	ds_write2_b32 v7, v76, v77 offset1:1
	s_waitcnt vmcnt(0) lgkmcnt(0)
	v_pk_mul_f32 v[76:77], v[42:43], v[64:65] op_sel_hi:[1,0]
	global_load_dword v64, v[112:113], off offset:24
	s_cbranch_execnz .LBB0_1401

.LBB0_1401:
	s_waitcnt vmcnt(0) lgkmcnt(0)
	v_cndmask_b32_e64 v24, 0, 1, s[52:53]
	v_add_u32_e32 v7, v5, v89
	v_pk_mul_f32 v[22:23], v[56:57], v[64:65] op_sel_hi:[1,0]
	v_cmp_ne_u32_e64 s[0:1], 1, v24
	s_andn2_b64 vcc, exec, s[52:53]
	ds_write2_b32 v7, v76, v77 offset1:1
	ds_write2_b32 v7, v22, v23 offset0:130 offset1:131
	s_cbranch_vccnz .LBB0_1598
	v_mov_b32_e32 v75, v65
	v_lshl_add_u64 v[24:25], s[50:51], 0, v[74:75]
	global_load_dword v22, v[24:25], off offset:32
	global_load_dword v42, v[24:25], off offset:40
	v_add_u32_e32 v7, v5, v90
	s_waitcnt vmcnt(0) lgkmcnt(0)
	v_pk_mul_f32 v[22:23], v[8:9], v[22:23] op_sel_hi:[1,0]
	ds_write2_b32 v7, v22, v23 offset1:1
	v_pk_mul_f32 v[22:23], v[26:27], v[42:43] op_sel_hi:[1,0]
	ds_write2_b32 v7, v22, v23 offset0:130 offset1:131
	global_load_dword v22, v[24:25], off offset:48
	s_waitcnt vmcnt(0) lgkmcnt(0)
	v_pk_mul_f32 v[22:23], v[40:41], v[22:23] op_sel_hi:[1,0]
	global_load_dword v24, v[24:25], off offset:56
	s_cbranch_execnz .LBB0_1404

.LBB0_1404:
	v_add_u32_e32 v7, v5, v91
	s_waitcnt vmcnt(0) lgkmcnt(0)
	v_pk_mul_f32 v[8:9], v[52:53], v[24:25] op_sel_hi:[1,0]
	s_and_b64 vcc, exec, s[0:1]
	ds_write2_b32 v7, v22, v23 offset1:1
	ds_write2_b32 v7, v8, v9 offset0:130 offset1:131
	s_cbranch_vccnz .LBB0_1599
	v_mov_b32_e32 v75, v65
	v_lshl_add_u64 v[22:23], s[50:51], 0, v[74:75]
	global_load_dword v8, v[22:23], off offset:64
	global_load_dword v24, v[22:23], off offset:72
	v_add_u32_e32 v7, v5, v92
	s_waitcnt vmcnt(0) lgkmcnt(0)
	v_pk_mul_f32 v[8:9], v[10:11], v[8:9] op_sel_hi:[1,0]
	ds_write2_b32 v7, v8, v9 offset1:1
	v_pk_mul_f32 v[8:9], v[28:29], v[24:25] op_sel_hi:[1,0]
	ds_write2_b32 v7, v8, v9 offset0:130 offset1:131
	global_load_dword v8, v[22:23], off offset:80
	s_waitcnt vmcnt(0) lgkmcnt(0)
	v_pk_mul_f32 v[8:9], v[44:45], v[8:9] op_sel_hi:[1,0]
	global_load_dword v22, v[22:23], off offset:88
	s_cbranch_execnz .LBB0_1407

.LBB0_1407:
	v_add_u32_e32 v7, v5, v93
	ds_write2_b32 v7, v8, v9 offset1:1
	s_waitcnt vmcnt(0) lgkmcnt(0)
	v_pk_mul_f32 v[8:9], v[54:55], v[22:23] op_sel_hi:[1,0]
	s_and_b64 vcc, exec, s[0:1]
	ds_write2_b32 v7, v8, v9 offset0:130 offset1:131
	s_cbranch_vccnz .LBB0_1600
	v_mov_b32_e32 v75, v65
	v_lshl_add_u64 v[10:11], s[50:51], 0, v[74:75]
	global_load_dword v8, v[10:11], off offset:96
	global_load_dword v22, v[10:11], off offset:104
	v_add_u32_e32 v7, v5, v94
	s_waitcnt vmcnt(0) lgkmcnt(0)
	v_pk_mul_f32 v[8:9], v[12:13], v[8:9] op_sel_hi:[1,0]
	ds_write2_b32 v7, v8, v9 offset1:1
	v_pk_mul_f32 v[8:9], v[30:31], v[22:23] op_sel_hi:[1,0]
	ds_write2_b32 v7, v8, v9 offset0:130 offset1:131
	global_load_dword v8, v[10:11], off offset:112
	s_waitcnt vmcnt(0) lgkmcnt(0)
	v_pk_mul_f32 v[8:9], v[46:47], v[8:9] op_sel_hi:[1,0]
	global_load_dword v10, v[10:11], off offset:120
	s_cbranch_execnz .LBB0_1410

.LBB0_1410:
	v_add_u32_e32 v7, v5, v95
	ds_write2_b32 v7, v8, v9 offset1:1
	s_waitcnt vmcnt(0) lgkmcnt(0)
	v_pk_mul_f32 v[8:9], v[60:61], v[10:11] op_sel_hi:[1,0]
	s_and_b64 vcc, exec, s[0:1]
	ds_write2_b32 v7, v8, v9 offset0:130 offset1:131
	s_cbranch_vccnz .LBB0_1601
	v_mov_b32_e32 v75, v65
	v_lshl_add_u64 v[10:11], s[50:51], 0, v[74:75]
	global_load_dword v8, v[10:11], off offset:128
	global_load_dword v12, v[10:11], off offset:136
	v_add_u32_e32 v7, v5, v96
	s_waitcnt vmcnt(0) lgkmcnt(0)
	v_pk_mul_f32 v[8:9], v[14:15], v[8:9] op_sel_hi:[1,0]
	ds_write2_b32 v7, v8, v9 offset1:1
	v_pk_mul_f32 v[8:9], v[32:33], v[12:13] op_sel_hi:[1,0]
	ds_write2_b32 v7, v8, v9 offset0:130 offset1:131
	global_load_dword v8, v[10:11], off offset:144
	s_waitcnt vmcnt(0) lgkmcnt(0)
	v_pk_mul_f32 v[8:9], v[48:49], v[8:9] op_sel_hi:[1,0]
	global_load_dword v10, v[10:11], off offset:152
	s_cbranch_execnz .LBB0_1413

.LBB0_1413:
	v_add_u32_e32 v7, v5, v97
	ds_write2_b32 v7, v8, v9 offset1:1
	s_waitcnt vmcnt(0) lgkmcnt(0)
	v_pk_mul_f32 v[8:9], v[66:67], v[10:11] op_sel_hi:[1,0]
	s_and_b64 vcc, exec, s[0:1]
	ds_write2_b32 v7, v8, v9 offset0:130 offset1:131
	s_cbranch_vccnz .LBB0_1602
	v_mov_b32_e32 v75, v65
	v_lshl_add_u64 v[10:11], s[50:51], 0, v[74:75]
	global_load_dword v8, v[10:11], off offset:160
	global_load_dword v12, v[10:11], off offset:168
	v_add_u32_e32 v7, v5, v98
	s_waitcnt vmcnt(0) lgkmcnt(0)
	v_pk_mul_f32 v[8:9], v[16:17], v[8:9] op_sel_hi:[1,0]
	ds_write2_b32 v7, v8, v9 offset1:1
	v_pk_mul_f32 v[8:9], v[34:35], v[12:13] op_sel_hi:[1,0]
	ds_write2_b32 v7, v8, v9 offset0:130 offset1:131
	global_load_dword v8, v[10:11], off offset:176
	s_waitcnt vmcnt(0) lgkmcnt(0)
	v_pk_mul_f32 v[8:9], v[50:51], v[8:9] op_sel_hi:[1,0]
	global_load_dword v10, v[10:11], off offset:184
	s_cbranch_execnz .LBB0_1416

.LBB0_1416:
	v_add_u32_e32 v7, v5, v98
	v_add_u32_e32 v11, 0x410, v7
	ds_write2_b32 v11, v8, v9 offset1:1
	s_waitcnt vmcnt(0) lgkmcnt(0)
	v_pk_mul_f32 v[8:9], v[62:63], v[10:11] op_sel_hi:[1,0]
	v_add_u32_e32 v10, 0x618, v7
	s_and_b64 vcc, exec, s[0:1]
	v_add_u32_e32 v11, 0x820, v7
	v_add_u32_e32 v12, 0xa28, v7
	ds_write2_b32 v10, v8, v9 offset1:1
	s_cbranch_vccnz .LBB0_1603
	v_mov_b32_e32 v75, v65
	v_lshl_add_u64 v[14:15], s[50:51], 0, v[74:75]
	global_load_dword v8, v[14:15], off offset:192
	global_load_dword v10, v[14:15], off offset:200
	s_waitcnt vmcnt(0) lgkmcnt(0)
	v_pk_mul_f32 v[8:9], v[18:19], v[8:9] op_sel_hi:[1,0]
	ds_write2_b32 v11, v8, v9 offset1:1
	v_pk_mul_f32 v[8:9], v[36:37], v[10:11] op_sel_hi:[1,0]
	ds_write2_b32 v12, v8, v9 offset1:1
	global_load_dword v8, v[14:15], off offset:208
	global_load_dword v10, v[14:15], off offset:216
	s_waitcnt vmcnt(0) lgkmcnt(0)
	v_pk_mul_f32 v[8:9], v[58:59], v[8:9] op_sel_hi:[1,0]
	s_cbranch_execnz .LBB0_1419

.LBB0_1419:
	v_add_u32_e32 v11, 0xc30, v7
	ds_write2_b32 v11, v8, v9 offset1:1
	v_pk_mul_f32 v[8:9], v[70:71], v[10:11] op_sel_hi:[1,0]
	v_add_u32_e32 v10, 0xe38, v7
	s_and_b64 vcc, exec, s[0:1]
	v_add_u32_e32 v11, 0x1040, v7
	v_add_u32_e32 v12, 0x1248, v7
	ds_write2_b32 v10, v8, v9 offset1:1
	s_cbranch_vccnz .LBB0_1604
	v_mov_b32_e32 v75, v65
	v_lshl_add_u64 v[14:15], s[50:51], 0, v[74:75]
	global_load_dword v8, v[14:15], off offset:224
	global_load_dword v10, v[14:15], off offset:232
	s_waitcnt vmcnt(0) lgkmcnt(0)
	v_pk_mul_f32 v[8:9], v[20:21], v[8:9] op_sel_hi:[1,0]
	ds_write2_b32 v11, v8, v9 offset1:1
	v_pk_mul_f32 v[8:9], v[38:39], v[10:11] op_sel_hi:[1,0]
	ds_write2_b32 v12, v8, v9 offset1:1
	global_load_dword v8, v[14:15], off offset:240
	global_load_dword v10, v[14:15], off offset:248
	s_waitcnt vmcnt(0) lgkmcnt(0)
	v_pk_mul_f32 v[8:9], v[68:69], v[8:9] op_sel_hi:[1,0]
	s_cbranch_execnz .LBB0_1422

.LBB0_1422:
	v_add_u32_e32 v11, 0x1450, v7
	ds_write2_b32 v11, v8, v9 offset1:1
	v_pk_mul_f32 v[8:9], v[72:73], v[10:11] op_sel_hi:[1,0]
	v_add_u32_e32 v7, 0x1658, v7
	ds_write2_b32 v7, v8, v9 offset1:1
	s_waitcnt lgkmcnt(0)
	ds_read_b32 v8, v80
	ds_read_b32 v9, v80 offset:260
	s_add_u32 s0, s46, s55
	s_addc_u32 s1, s47, s54
	v_lshlrev_b32_e32 v64, 1, v6
	v_lshl_add_u64 v[6:7], s[0:1], 0, v[64:65]
	s_waitcnt lgkmcnt(0)
	v_cvt_pk_bf16_f32 v8, v8, v9
	ds_read_b32 v9, v80 offset:520
	ds_read_b32 v10, v80 offset:780
	v_lshlrev_b32_e32 v64, 1, v4
	v_lshl_add_u64 v[6:7], v[6:7], 0, v[64:65]
	s_mov_b64 s[0:1], 0x1e00000
	v_lshl_add_u64 v[6:7], v[6:7], 0, s[0:1]
	s_waitcnt lgkmcnt(0)
	v_cvt_pk_bf16_f32 v9, v9, v10
	ds_read_b32 v10, v80 offset:1040
	ds_read_b32 v11, v80 offset:1300
	s_waitcnt lgkmcnt(0)
	v_cvt_pk_bf16_f32 v10, v10, v11
	ds_read_b32 v11, v80 offset:1560
	ds_read_b32 v12, v80 offset:1820
	s_waitcnt lgkmcnt(0)
	v_cvt_pk_bf16_f32 v11, v11, v12
	v_or_b32_e32 v12, v110, v79
	v_ashrrev_i32_e32 v13, 31, v12
	v_lshlrev_b64 v[12:13], 11, v[12:13]
	v_lshl_add_u64 v[12:13], v[6:7], 0, v[12:13]
	global_store_dwordx4 v[12:13], v[8:11], off
	ds_read_b32 v8, v80 offset:32
	ds_read_b32 v9, v80 offset:292
	s_waitcnt lgkmcnt(0)
	v_cvt_pk_bf16_f32 v8, v8, v9
	ds_read_b32 v9, v80 offset:552
	ds_read_b32 v10, v80 offset:812
	s_waitcnt lgkmcnt(0)
	v_cvt_pk_bf16_f32 v9, v9, v10
	ds_read_b32 v10, v80 offset:1072
	ds_read_b32 v11, v80 offset:1332
	s_waitcnt lgkmcnt(0)
	v_cvt_pk_bf16_f32 v10, v10, v11
	ds_read_b32 v11, v80 offset:1592
	ds_read_b32 v12, v80 offset:1852
	s_waitcnt lgkmcnt(0)
	v_cvt_pk_bf16_f32 v11, v11, v12
	v_or_b32_e32 v12, v110, v81
	v_ashrrev_i32_e32 v13, 31, v12
	v_lshlrev_b64 v[12:13], 11, v[12:13]
	v_lshl_add_u64 v[12:13], v[6:7], 0, v[12:13]
	global_store_dwordx4 v[12:13], v[8:11], off
	ds_read_b32 v8, v80 offset:64
	ds_read_b32 v9, v80 offset:324
	s_waitcnt lgkmcnt(0)
	v_cvt_pk_bf16_f32 v8, v8, v9
	ds_read_b32 v9, v80 offset:584
	ds_read_b32 v10, v80 offset:844
	s_waitcnt lgkmcnt(0)
	v_cvt_pk_bf16_f32 v9, v9, v10
	ds_read_b32 v10, v80 offset:1104
	ds_read_b32 v11, v80 offset:1364
	s_waitcnt lgkmcnt(0)
	v_cvt_pk_bf16_f32 v10, v10, v11
	ds_read_b32 v11, v80 offset:1624
	ds_read_b32 v12, v80 offset:1884
	s_waitcnt lgkmcnt(0)
	v_cvt_pk_bf16_f32 v11, v11, v12
	v_or_b32_e32 v12, v110, v82
	v_ashrrev_i32_e32 v13, 31, v12
	v_lshlrev_b64 v[12:13], 11, v[12:13]
	v_lshl_add_u64 v[12:13], v[6:7], 0, v[12:13]
	global_store_dwordx4 v[12:13], v[8:11], off
	ds_read_b32 v8, v80 offset:96
	ds_read_b32 v9, v80 offset:356
	s_waitcnt lgkmcnt(0)
	v_cvt_pk_bf16_f32 v8, v8, v9
	ds_read_b32 v9, v80 offset:616
	ds_read_b32 v10, v80 offset:876
	s_waitcnt lgkmcnt(0)
	v_cvt_pk_bf16_f32 v9, v9, v10
	ds_read_b32 v10, v80 offset:1136
	ds_read_b32 v11, v80 offset:1396
	s_waitcnt lgkmcnt(0)
	v_cvt_pk_bf16_f32 v10, v10, v11
	ds_read_b32 v11, v80 offset:1656
	ds_read_b32 v12, v80 offset:1916
	s_waitcnt lgkmcnt(0)
	v_cvt_pk_bf16_f32 v11, v11, v12
	v_or_b32_e32 v12, v110, v83
	v_ashrrev_i32_e32 v13, 31, v12
	v_lshlrev_b64 v[12:13], 11, v[12:13]
	v_lshl_add_u64 v[12:13], v[6:7], 0, v[12:13]
	global_store_dwordx4 v[12:13], v[8:11], off
	ds_read_b32 v8, v80 offset:128
	ds_read_b32 v9, v80 offset:388
	s_waitcnt lgkmcnt(0)
	v_cvt_pk_bf16_f32 v8, v8, v9
	ds_read_b32 v9, v80 offset:648
	ds_read_b32 v10, v80 offset:908
	s_waitcnt lgkmcnt(0)
	v_cvt_pk_bf16_f32 v9, v9, v10
	ds_read_b32 v10, v80 offset:1168
	ds_read_b32 v11, v80 offset:1428
	s_waitcnt lgkmcnt(0)
	v_cvt_pk_bf16_f32 v10, v10, v11
	ds_read_b32 v11, v80 offset:1688
	ds_read_b32 v12, v80 offset:1948
	s_waitcnt lgkmcnt(0)
	v_cvt_pk_bf16_f32 v11, v11, v12
	v_or_b32_e32 v12, v110, v84
	v_ashrrev_i32_e32 v13, 31, v12
	v_lshlrev_b64 v[12:13], 11, v[12:13]
	v_lshl_add_u64 v[12:13], v[6:7], 0, v[12:13]
	global_store_dwordx4 v[12:13], v[8:11], off
	ds_read_b32 v8, v80 offset:160
	ds_read_b32 v9, v80 offset:420
	s_waitcnt lgkmcnt(0)
	v_cvt_pk_bf16_f32 v8, v8, v9
	ds_read_b32 v9, v80 offset:680
	ds_read_b32 v10, v80 offset:940
	s_waitcnt lgkmcnt(0)
	v_cvt_pk_bf16_f32 v9, v9, v10
	ds_read_b32 v10, v80 offset:1200
	ds_read_b32 v11, v80 offset:1460
	s_waitcnt lgkmcnt(0)
	v_cvt_pk_bf16_f32 v10, v10, v11
	ds_read_b32 v11, v80 offset:1720
	ds_read_b32 v12, v80 offset:1980
	s_waitcnt lgkmcnt(0)
	v_cvt_pk_bf16_f32 v11, v11, v12
	v_or_b32_e32 v12, v110, v85
	v_ashrrev_i32_e32 v13, 31, v12
	v_lshlrev_b64 v[12:13], 11, v[12:13]
	v_lshl_add_u64 v[12:13], v[6:7], 0, v[12:13]
	global_store_dwordx4 v[12:13], v[8:11], off
	ds_read_b32 v8, v80 offset:192
	ds_read_b32 v9, v80 offset:452
	s_waitcnt lgkmcnt(0)
	v_cvt_pk_bf16_f32 v8, v8, v9
	ds_read_b32 v9, v80 offset:712
	ds_read_b32 v10, v80 offset:972
	s_waitcnt lgkmcnt(0)
	v_cvt_pk_bf16_f32 v9, v9, v10
	ds_read_b32 v10, v80 offset:1232
	ds_read_b32 v11, v80 offset:1492
	s_waitcnt lgkmcnt(0)
	v_cvt_pk_bf16_f32 v10, v10, v11
	ds_read_b32 v11, v80 offset:1752
	ds_read_b32 v12, v80 offset:2012
	s_waitcnt lgkmcnt(0)
	v_cvt_pk_bf16_f32 v11, v11, v12
	v_or_b32_e32 v12, v110, v86
	v_ashrrev_i32_e32 v13, 31, v12
	v_lshlrev_b64 v[12:13], 11, v[12:13]
	v_lshl_add_u64 v[12:13], v[6:7], 0, v[12:13]
	global_store_dwordx4 v[12:13], v[8:11], off
	ds_read_b32 v8, v80 offset:224
	ds_read_b32 v9, v80 offset:484
	s_waitcnt lgkmcnt(0)
	v_cvt_pk_bf16_f32 v8, v8, v9
	ds_read_b32 v9, v80 offset:744
	ds_read_b32 v10, v80 offset:1004
	s_waitcnt lgkmcnt(0)
	v_cvt_pk_bf16_f32 v9, v9, v10
	ds_read_b32 v10, v80 offset:1264
	ds_read_b32 v11, v80 offset:1524
	s_waitcnt lgkmcnt(0)
	v_cvt_pk_bf16_f32 v10, v10, v11
	ds_read_b32 v11, v80 offset:1784
	ds_read_b32 v12, v80 offset:2044
	s_waitcnt lgkmcnt(0)
	v_cvt_pk_bf16_f32 v11, v11, v12
	v_or_b32_e32 v12, v110, v87
	v_ashrrev_i32_e32 v13, 31, v12
	v_lshlrev_b64 v[12:13], 11, v[12:13]
	v_lshl_add_u64 v[6:7], v[6:7], 0, v[12:13]
	global_store_dwordx4 v[6:7], v[8:11], off
	s_waitcnt lgkmcnt(0)
	s_or_b64 exec, exec, s[44:45]

.LBB0_1424:
	v_lshlrev_b32_e32 v6, 6, v105
	v_and_b32_e32 v7, 0xfffffc00, v6
	s_mov_b64 s[0:1], s[22:23]
	v_sub_u32_e32 v8, v106, v7
	s_lshl_b64 s[26:27], s[6:7], 2
	v_mov_b32_e32 v6, 0x1a00
	v_add_u32_e32 v76, s62, v102
	s_add_u32 s26, s0, s26
	v_lshl_add_u32 v6, v101, 2, v6
	v_add_u32_e32 v8, v76, v8
	s_movk_i32 s0, 0x400
	v_and_b32_e32 v6, 0xffffffc0, v6
	v_cmp_gt_i32_e32 vcc, s0, v8
	s_addc_u32 s27, s1, s27
	s_mov_b64 s[44:45], s[40:41]
	v_cndmask_b32_e32 v64, -1, v8, vcc
	v_or_b32_e32 v8, v6, v2
	v_cmp_lt_i32_e64 s[0:1], -1, v64
	v_lshl_add_u64 v[12:13], v[64:65], 2, s[26:27]
	v_mov_b32_e32 v10, 0
	v_lshlrev_b32_e32 v64, 10, v8
	v_mov_b32_e32 v8, 0
	v_mov_b32_e32 v9, 0
	s_and_saveexec_b64 s[46:47], s[0:1]
	s_cbranch_execz .LBB0_1426
	v_lshl_add_u64 v[8:9], v[64:65], 2, v[12:13]
	global_load_dwordx2 v[8:9], v[8:9], off
.LBB0_1426:
	s_or_b64 exec, exec, s[46:47]
	v_mov_b32_e32 v11, 0
	s_and_saveexec_b64 s[46:47], s[0:1]
	s_cbranch_execz .LBB0_1428
	v_lshl_add_u64 v[10:11], v[64:65], 2, v[12:13]
	v_add_co_u32_e32 v10, vcc, 0x2000, v10
	s_nop 1
	v_addc_co_u32_e32 v11, vcc, 0, v11, vcc
	global_load_dwordx2 v[10:11], v[10:11], off
.LBB0_1428:
	s_or_b64 exec, exec, s[46:47]
	v_mov_b32_e32 v14, 0
	v_mov_b32_e32 v16, 0
	v_mov_b32_e32 v17, 0
	s_and_saveexec_b64 s[46:47], s[0:1]
	s_cbranch_execz .LBB0_1430
	v_lshl_add_u64 v[16:17], v[64:65], 2, v[12:13]
	v_add_co_u32_e32 v16, vcc, 0x4000, v16
	s_nop 1
	v_addc_co_u32_e32 v17, vcc, 0, v17, vcc
	global_load_dwordx2 v[16:17], v[16:17], off
.LBB0_1430:
	s_or_b64 exec, exec, s[46:47]
	v_mov_b32_e32 v15, 0
	s_and_saveexec_b64 s[46:47], s[0:1]
	s_cbranch_execz .LBB0_1432
	v_lshl_add_u64 v[14:15], v[64:65], 2, v[12:13]
	v_add_co_u32_e32 v14, vcc, 0x6000, v14
	s_nop 1
	v_addc_co_u32_e32 v15, vcc, 0, v15, vcc
	global_load_dwordx2 v[14:15], v[14:15], off
.LBB0_1432:
	s_or_b64 exec, exec, s[46:47]
	v_mov_b32_e32 v18, 0
	v_mov_b32_e32 v20, 0
	v_mov_b32_e32 v21, 0
	s_and_saveexec_b64 s[46:47], s[0:1]
	s_cbranch_execz .LBB0_1434
	v_lshl_add_u64 v[20:21], v[64:65], 2, v[12:13]
	v_add_co_u32_e32 v20, vcc, 0x8000, v20
	s_nop 1
	v_addc_co_u32_e32 v21, vcc, 0, v21, vcc
	global_load_dwordx2 v[20:21], v[20:21], off
.LBB0_1434:
	s_or_b64 exec, exec, s[46:47]
	v_mov_b32_e32 v19, 0
	s_and_saveexec_b64 s[46:47], s[0:1]
	s_cbranch_execz .LBB0_1436
	v_lshl_add_u64 v[18:19], v[64:65], 2, v[12:13]
	v_add_co_u32_e32 v18, vcc, 0xa000, v18
	s_nop 1
	v_addc_co_u32_e32 v19, vcc, 0, v19, vcc
	global_load_dwordx2 v[18:19], v[18:19], off
.LBB0_1436:
	s_or_b64 exec, exec, s[46:47]
	v_mov_b32_e32 v22, 0
	v_mov_b32_e32 v24, 0
	v_mov_b32_e32 v25, 0
	s_and_saveexec_b64 s[46:47], s[0:1]
	s_cbranch_execz .LBB0_1438
	v_lshl_add_u64 v[24:25], v[64:65], 2, v[12:13]
	v_add_co_u32_e32 v24, vcc, 0xc000, v24
	s_nop 1
	v_addc_co_u32_e32 v25, vcc, 0, v25, vcc
	global_load_dwordx2 v[24:25], v[24:25], off
.LBB0_1438:
	s_or_b64 exec, exec, s[46:47]
	v_mov_b32_e32 v23, 0
	s_and_saveexec_b64 s[46:47], s[0:1]
	s_cbranch_execz .LBB0_1440
	v_lshl_add_u64 v[22:23], v[64:65], 2, v[12:13]
	v_add_co_u32_e32 v22, vcc, 0xe000, v22
	s_nop 1
	v_addc_co_u32_e32 v23, vcc, 0, v23, vcc
	global_load_dwordx2 v[22:23], v[22:23], off
.LBB0_1440:
	s_or_b64 exec, exec, s[46:47]
	v_mov_b32_e32 v26, 0
	v_mov_b32_e32 v28, 0
	v_mov_b32_e32 v29, 0
	s_and_saveexec_b64 s[46:47], s[0:1]
	s_cbranch_execz .LBB0_1442
	v_lshl_add_u64 v[28:29], v[64:65], 2, v[12:13]
	v_add_co_u32_e32 v28, vcc, 0x10000, v28
	s_nop 1
	v_addc_co_u32_e32 v29, vcc, 0, v29, vcc
	global_load_dwordx2 v[28:29], v[28:29], off
.LBB0_1442:
	s_or_b64 exec, exec, s[46:47]
	v_mov_b32_e32 v27, 0
	s_and_saveexec_b64 s[46:47], s[0:1]
	s_cbranch_execz .LBB0_1444
	v_lshl_add_u64 v[26:27], v[64:65], 2, v[12:13]
	v_add_co_u32_e32 v26, vcc, 0x12000, v26
	s_nop 1
	v_addc_co_u32_e32 v27, vcc, 0, v27, vcc
	global_load_dwordx2 v[26:27], v[26:27], off
.LBB0_1444:
	s_or_b64 exec, exec, s[46:47]
	v_mov_b32_e32 v30, 0
	v_mov_b32_e32 v32, 0
	v_mov_b32_e32 v33, 0
	s_and_saveexec_b64 s[46:47], s[0:1]
	s_cbranch_execz .LBB0_1446
	v_lshl_add_u64 v[32:33], v[64:65], 2, v[12:13]
	v_add_co_u32_e32 v32, vcc, 0x14000, v32
	s_nop 1
	v_addc_co_u32_e32 v33, vcc, 0, v33, vcc
	global_load_dwordx2 v[32:33], v[32:33], off
.LBB0_1446:
	s_or_b64 exec, exec, s[46:47]
	v_mov_b32_e32 v31, 0
	s_and_saveexec_b64 s[46:47], s[0:1]
	s_cbranch_execz .LBB0_1448
	v_lshl_add_u64 v[30:31], v[64:65], 2, v[12:13]
	v_add_co_u32_e32 v30, vcc, 0x16000, v30
	s_nop 1
	v_addc_co_u32_e32 v31, vcc, 0, v31, vcc
	global_load_dwordx2 v[30:31], v[30:31], off
.LBB0_1448:
	s_or_b64 exec, exec, s[46:47]
	v_mov_b32_e32 v34, 0
	v_mov_b32_e32 v36, 0
	v_mov_b32_e32 v37, 0
	s_and_saveexec_b64 s[46:47], s[0:1]
	s_cbranch_execz .LBB0_1450
	v_lshl_add_u64 v[36:37], v[64:65], 2, v[12:13]
	v_add_co_u32_e32 v36, vcc, 0x18000, v36
	s_nop 1
	v_addc_co_u32_e32 v37, vcc, 0, v37, vcc
	global_load_dwordx2 v[36:37], v[36:37], off
.LBB0_1450:
	s_or_b64 exec, exec, s[46:47]
	v_mov_b32_e32 v35, 0
	s_and_saveexec_b64 s[46:47], s[0:1]
	s_cbranch_execz .LBB0_1452
	v_lshl_add_u64 v[34:35], v[64:65], 2, v[12:13]
	v_add_co_u32_e32 v34, vcc, 0x1a000, v34
	s_nop 1
	v_addc_co_u32_e32 v35, vcc, 0, v35, vcc
	global_load_dwordx2 v[34:35], v[34:35], off
.LBB0_1452:
	s_or_b64 exec, exec, s[46:47]
	v_mov_b32_e32 v38, 0
	v_mov_b32_e32 v40, 0
	v_mov_b32_e32 v41, 0
	s_and_saveexec_b64 s[46:47], s[0:1]
	s_cbranch_execz .LBB0_1454
	v_lshl_add_u64 v[40:41], v[64:65], 2, v[12:13]
	v_add_co_u32_e32 v40, vcc, 0x1c000, v40
	s_nop 1
	v_addc_co_u32_e32 v41, vcc, 0, v41, vcc
	global_load_dwordx2 v[40:41], v[40:41], off
.LBB0_1454:
	s_or_b64 exec, exec, s[46:47]
	v_mov_b32_e32 v39, 0
	s_and_saveexec_b64 s[46:47], s[0:1]
	s_cbranch_execz .LBB0_1456
	v_lshl_add_u64 v[38:39], v[64:65], 2, v[12:13]
	v_add_co_u32_e32 v38, vcc, 0x1e000, v38
	s_nop 1
	v_addc_co_u32_e32 v39, vcc, 0, v39, vcc
	global_load_dwordx2 v[38:39], v[38:39], off
.LBB0_1456:
	s_or_b64 exec, exec, s[46:47]
	v_mov_b32_e32 v42, 0
	v_mov_b32_e32 v44, 0
	v_mov_b32_e32 v45, 0
	s_and_saveexec_b64 s[46:47], s[0:1]
	s_cbranch_execz .LBB0_1458
	v_lshl_add_u64 v[44:45], v[64:65], 2, v[12:13]
	v_add_co_u32_e32 v44, vcc, 0x20000, v44
	s_nop 1
	v_addc_co_u32_e32 v45, vcc, 0, v45, vcc
	global_load_dwordx2 v[44:45], v[44:45], off
.LBB0_1458:
	s_or_b64 exec, exec, s[46:47]
	v_mov_b32_e32 v43, 0
	s_and_saveexec_b64 s[46:47], s[0:1]
	s_cbranch_execz .LBB0_1460
	v_lshl_add_u64 v[42:43], v[64:65], 2, v[12:13]
	v_add_co_u32_e32 v42, vcc, 0x22000, v42
	s_nop 1
	v_addc_co_u32_e32 v43, vcc, 0, v43, vcc
	global_load_dwordx2 v[42:43], v[42:43], off
.LBB0_1460:
	s_or_b64 exec, exec, s[46:47]
	v_mov_b32_e32 v46, 0
	v_mov_b32_e32 v48, 0
	v_mov_b32_e32 v49, 0
	s_and_saveexec_b64 s[46:47], s[0:1]
	s_cbranch_execz .LBB0_1462
	v_lshl_add_u64 v[48:49], v[64:65], 2, v[12:13]
	v_add_co_u32_e32 v48, vcc, 0x24000, v48
	s_nop 1
	v_addc_co_u32_e32 v49, vcc, 0, v49, vcc
	global_load_dwordx2 v[48:49], v[48:49], off
.LBB0_1462:
	s_or_b64 exec, exec, s[46:47]
	v_mov_b32_e32 v47, 0
	s_and_saveexec_b64 s[46:47], s[0:1]
	s_cbranch_execz .LBB0_1464
	v_lshl_add_u64 v[46:47], v[64:65], 2, v[12:13]
	v_add_co_u32_e32 v46, vcc, 0x26000, v46
	s_nop 1
	v_addc_co_u32_e32 v47, vcc, 0, v47, vcc
	global_load_dwordx2 v[46:47], v[46:47], off
.LBB0_1464:
	s_or_b64 exec, exec, s[46:47]
	v_mov_b32_e32 v50, 0
	v_mov_b32_e32 v52, 0
	v_mov_b32_e32 v53, 0
	s_and_saveexec_b64 s[46:47], s[0:1]
	s_cbranch_execz .LBB0_1466
	v_lshl_add_u64 v[52:53], v[64:65], 2, v[12:13]
	v_add_co_u32_e32 v52, vcc, 0x28000, v52
	s_nop 1
	v_addc_co_u32_e32 v53, vcc, 0, v53, vcc
	global_load_dwordx2 v[52:53], v[52:53], off
.LBB0_1466:
	s_or_b64 exec, exec, s[46:47]
	v_mov_b32_e32 v51, 0
	s_and_saveexec_b64 s[46:47], s[0:1]
	s_cbranch_execz .LBB0_1468
	v_lshl_add_u64 v[50:51], v[64:65], 2, v[12:13]
	v_add_co_u32_e32 v50, vcc, 0x2a000, v50
	s_nop 1
	v_addc_co_u32_e32 v51, vcc, 0, v51, vcc
	global_load_dwordx2 v[50:51], v[50:51], off
.LBB0_1468:
	s_or_b64 exec, exec, s[46:47]
	v_mov_b32_e32 v54, 0
	v_mov_b32_e32 v56, 0
	v_mov_b32_e32 v57, 0
	s_and_saveexec_b64 s[46:47], s[0:1]
	s_cbranch_execz .LBB0_1470
	v_lshl_add_u64 v[56:57], v[64:65], 2, v[12:13]
	v_add_co_u32_e32 v56, vcc, 0x2c000, v56
	s_nop 1
	v_addc_co_u32_e32 v57, vcc, 0, v57, vcc
	global_load_dwordx2 v[56:57], v[56:57], off
.LBB0_1470:
	s_or_b64 exec, exec, s[46:47]
	v_mov_b32_e32 v55, 0
	s_and_saveexec_b64 s[46:47], s[0:1]
	s_cbranch_execz .LBB0_1472
	v_lshl_add_u64 v[54:55], v[64:65], 2, v[12:13]
	v_add_co_u32_e32 v54, vcc, 0x2e000, v54
	s_nop 1
	v_addc_co_u32_e32 v55, vcc, 0, v55, vcc
	global_load_dwordx2 v[54:55], v[54:55], off
.LBB0_1472:
	s_or_b64 exec, exec, s[46:47]
	v_mov_b32_e32 v58, 0
	v_mov_b32_e32 v60, 0
	v_mov_b32_e32 v61, 0
	s_and_saveexec_b64 s[46:47], s[0:1]
	s_cbranch_execz .LBB0_1474
	v_lshl_add_u64 v[60:61], v[64:65], 2, v[12:13]
	v_add_co_u32_e32 v60, vcc, 0x30000, v60
	s_nop 1
	v_addc_co_u32_e32 v61, vcc, 0, v61, vcc
	global_load_dwordx2 v[60:61], v[60:61], off
.LBB0_1474:
	s_or_b64 exec, exec, s[46:47]
	v_mov_b32_e32 v59, 0
	s_and_saveexec_b64 s[46:47], s[0:1]
	s_cbranch_execz .LBB0_1476
	v_lshl_add_u64 v[58:59], v[64:65], 2, v[12:13]
	v_add_co_u32_e32 v58, vcc, 0x32000, v58
	s_nop 1
	v_addc_co_u32_e32 v59, vcc, 0, v59, vcc
	global_load_dwordx2 v[58:59], v[58:59], off
.LBB0_1476:
	s_or_b64 exec, exec, s[46:47]
	v_mov_b32_e32 v62, 0
	v_mov_b32_e32 v66, 0
	v_mov_b32_e32 v67, 0
	s_and_saveexec_b64 s[46:47], s[0:1]
	s_cbranch_execz .LBB0_1478
	v_lshl_add_u64 v[66:67], v[64:65], 2, v[12:13]
	v_add_co_u32_e32 v66, vcc, 0x34000, v66
	s_nop 1
	v_addc_co_u32_e32 v67, vcc, 0, v67, vcc
	global_load_dwordx2 v[66:67], v[66:67], off
.LBB0_1478:
	s_or_b64 exec, exec, s[46:47]
	v_mov_b32_e32 v63, 0
	s_and_saveexec_b64 s[46:47], s[0:1]
	s_cbranch_execz .LBB0_1480
	v_lshl_add_u64 v[62:63], v[64:65], 2, v[12:13]
	v_add_co_u32_e32 v62, vcc, 0x36000, v62
	s_nop 1
	v_addc_co_u32_e32 v63, vcc, 0, v63, vcc
	global_load_dwordx2 v[62:63], v[62:63], off
.LBB0_1480:
	s_or_b64 exec, exec, s[46:47]
	v_mov_b32_e32 v68, 0
	v_mov_b32_e32 v70, 0
	v_mov_b32_e32 v71, 0
	s_and_saveexec_b64 s[46:47], s[0:1]
	s_cbranch_execz .LBB0_1482
	v_lshl_add_u64 v[70:71], v[64:65], 2, v[12:13]
	v_add_co_u32_e32 v70, vcc, 0x38000, v70
	s_nop 1
	v_addc_co_u32_e32 v71, vcc, 0, v71, vcc
	global_load_dwordx2 v[70:71], v[70:71], off
.LBB0_1482:
	s_or_b64 exec, exec, s[46:47]
	v_mov_b32_e32 v69, 0
	s_and_saveexec_b64 s[46:47], s[0:1]
	s_cbranch_execz .LBB0_1484
	v_lshl_add_u64 v[68:69], v[64:65], 2, v[12:13]
	v_add_co_u32_e32 v68, vcc, 0x3a000, v68
	s_nop 1
	v_addc_co_u32_e32 v69, vcc, 0, v69, vcc
	global_load_dwordx2 v[68:69], v[68:69], off
.LBB0_1484:
	s_or_b64 exec, exec, s[46:47]
	v_mov_b32_e32 v72, 0
	v_mov_b32_e32 v74, 0
	v_mov_b32_e32 v75, 0
	s_and_saveexec_b64 s[46:47], s[0:1]
	s_cbranch_execz .LBB0_1486
	v_lshl_add_u64 v[74:75], v[64:65], 2, v[12:13]
	v_add_co_u32_e32 v74, vcc, 0x3c000, v74
	s_nop 1
	v_addc_co_u32_e32 v75, vcc, 0, v75, vcc
	global_load_dwordx2 v[74:75], v[74:75], off
.LBB0_1486:
	s_or_b64 exec, exec, s[46:47]
	v_mov_b32_e32 v73, 0
	s_and_saveexec_b64 s[46:47], s[0:1]
	s_cbranch_execz .LBB0_1488
	v_lshl_add_u64 v[12:13], v[64:65], 2, v[12:13]
	v_add_co_u32_e32 v12, vcc, 0x3e000, v12
	s_nop 1
	v_addc_co_u32_e32 v13, vcc, 0, v13, vcc
	global_load_dwordx2 v[72:73], v[12:13], off
.LBB0_1488:
	s_or_b64 exec, exec, s[46:47]
	v_sub_u32_e32 v12, v104, v7
	v_add_u32_e32 v7, v5, v78
	s_waitcnt vmcnt(0) lgkmcnt(0)
	ds_write2_b32 v7, v8, v9 offset1:1
	ds_write2_b32 v7, v10, v11 offset0:130 offset1:131
	v_add_u32_e32 v8, 0x410, v7
	ds_write2_b32 v8, v16, v17 offset1:1
	v_add_u32_e32 v8, 0x618, v7
	ds_write2_b32 v8, v14, v15 offset1:1
	v_add_u32_e32 v8, 0x820, v7
	ds_write2_b32 v8, v20, v21 offset1:1
	v_add_u32_e32 v8, 0xa28, v7
	ds_write2_b32 v8, v18, v19 offset1:1
	v_add_u32_e32 v8, 0xc30, v7
	ds_write2_b32 v8, v24, v25 offset1:1
	v_add_u32_e32 v8, 0xe38, v7
	ds_write2_b32 v8, v22, v23 offset1:1
	v_add_u32_e32 v8, 0x1040, v7
	ds_write2_b32 v8, v28, v29 offset1:1
	v_add_u32_e32 v8, 0x1248, v7
	ds_write2_b32 v8, v26, v27 offset1:1
	v_add_u32_e32 v8, 0x1450, v7
	ds_write2_b32 v8, v32, v33 offset1:1
	v_add_u32_e32 v8, 0x1658, v7
	ds_write2_b32 v8, v30, v31 offset1:1
	v_add_u32_e32 v8, 0x1860, v7
	ds_write2_b32 v8, v36, v37 offset1:1
	v_add_u32_e32 v8, 0x1a68, v7
	ds_write2_b32 v8, v34, v35 offset1:1
	v_add_u32_e32 v8, 0x1c70, v7
	ds_write2_b32 v8, v40, v41 offset1:1
	v_add_u32_e32 v8, 0x1e78, v7
	ds_write2_b32 v8, v38, v39 offset1:1
	v_add_u32_e32 v8, 0x2080, v7
	ds_write2_b32 v8, v44, v45 offset1:1
	v_add_u32_e32 v8, 0x2288, v7
	ds_write2_b32 v8, v42, v43 offset1:1
	v_add_u32_e32 v8, 0x2490, v7
	ds_write2_b32 v8, v48, v49 offset1:1
	v_add_u32_e32 v8, 0x2698, v7
	ds_write2_b32 v8, v46, v47 offset1:1
	v_add_u32_e32 v8, 0x28a0, v7
	ds_write2_b32 v8, v52, v53 offset1:1
	v_add_u32_e32 v8, 0x2aa8, v7
	ds_write2_b32 v8, v50, v51 offset1:1
	v_add_u32_e32 v8, 0x2cb0, v7
	ds_write2_b32 v8, v56, v57 offset1:1
	v_add_u32_e32 v8, 0x2eb8, v7
	ds_write2_b32 v8, v54, v55 offset1:1
	v_add_u32_e32 v8, 0x30c0, v7
	ds_write2_b32 v8, v60, v61 offset1:1
	v_add_u32_e32 v8, 0x32c8, v7
	ds_write2_b32 v8, v58, v59 offset1:1
	v_add_u32_e32 v8, 0x34d0, v7
	ds_write2_b32 v8, v66, v67 offset1:1
	v_add_u32_e32 v8, 0x36d8, v7
	ds_write2_b32 v8, v62, v63 offset1:1
	v_add_u32_e32 v8, 0x38e0, v7
	ds_write2_b32 v8, v70, v71 offset1:1
	v_add_u32_e32 v8, 0x3ae8, v7
	s_lshl_b64 s[0:1], s[6:7], 1
	ds_write2_b32 v8, v68, v69 offset1:1
	v_add_u32_e32 v8, 0x3cf0, v7
	v_add_u32_e32 v7, 0x3ef8, v7
	s_add_u32 s0, s44, s0
	ds_write2_b32 v8, v74, v75 offset1:1
	ds_write2_b32 v7, v72, v73 offset1:1
	s_addc_u32 s1, s45, s1
	s_waitcnt lgkmcnt(0)
	v_mov_b32_e32 v7, v65
	v_lshl_add_u64 v[6:7], v[6:7], 1, s[0:1]
	v_lshlrev_b32_e32 v64, 1, v4
	ds_read_b32 v8, v80
	ds_read_b32 v9, v80 offset:260
	ds_read_b32 v13, v80 offset:520
	ds_read_b32 v14, v80 offset:780
	ds_read_b32 v15, v80 offset:1040
	ds_read_b32 v16, v80 offset:1300
	ds_read_b32 v17, v80 offset:1560
	ds_read_b32 v18, v80 offset:1820
	v_lshl_add_u64 v[6:7], v[6:7], 0, v[64:65]
	s_mov_b64 s[0:1], 0x1600000
	v_add_u32_e32 v12, v76, v12
	v_lshl_add_u64 v[10:11], v[6:7], 0, s[0:1]
	s_waitcnt lgkmcnt(4)
	v_cvt_pk_bf16_f32 v7, v13, v14
	v_subrev_u32_e32 v14, 56, v12
	v_cvt_pk_bf16_f32 v6, v8, v9
	s_waitcnt lgkmcnt(2)
	v_cvt_pk_bf16_f32 v8, v15, v16
	v_ashrrev_i32_e32 v15, 31, v14
	v_lshlrev_b64 v[14:15], 11, v[14:15]
	s_waitcnt lgkmcnt(0)
	v_cvt_pk_bf16_f32 v9, v17, v18
	v_lshl_add_u64 v[14:15], v[10:11], 0, v[14:15]
	global_store_dwordx4 v[14:15], v[6:9], off
	ds_read_b32 v6, v80 offset:32
	ds_read_b32 v7, v80 offset:292
	ds_read_b32 v8, v80 offset:552
	ds_read_b32 v9, v80 offset:812
	ds_read_b32 v13, v80 offset:1072
	ds_read_b32 v14, v80 offset:1332
	ds_read_b32 v15, v80 offset:1592
	ds_read_b32 v16, v80 offset:1852
	s_waitcnt lgkmcnt(0)
	v_cvt_pk_bf16_f32 v6, v6, v7
	v_cvt_pk_bf16_f32 v7, v8, v9
	v_cvt_pk_bf16_f32 v8, v13, v14
	v_subrev_u32_e32 v14, 48, v12
	v_cvt_pk_bf16_f32 v9, v15, v16
	v_ashrrev_i32_e32 v15, 31, v14
	v_lshlrev_b64 v[14:15], 11, v[14:15]
	v_lshl_add_u64 v[14:15], v[10:11], 0, v[14:15]
	global_store_dwordx4 v[14:15], v[6:9], off
	ds_read_b32 v6, v80 offset:64
	ds_read_b32 v7, v80 offset:324
	ds_read_b32 v8, v80 offset:584
	ds_read_b32 v9, v80 offset:844
	ds_read_b32 v13, v80 offset:1104
	ds_read_b32 v14, v80 offset:1364
	ds_read_b32 v15, v80 offset:1624
	ds_read_b32 v16, v80 offset:1884
	s_waitcnt lgkmcnt(0)
	v_cvt_pk_bf16_f32 v6, v6, v7
	v_cvt_pk_bf16_f32 v7, v8, v9
	v_cvt_pk_bf16_f32 v8, v13, v14
	v_subrev_u32_e32 v14, 40, v12
	v_cvt_pk_bf16_f32 v9, v15, v16
	v_ashrrev_i32_e32 v15, 31, v14
	v_lshlrev_b64 v[14:15], 11, v[14:15]
	v_lshl_add_u64 v[14:15], v[10:11], 0, v[14:15]
	global_store_dwordx4 v[14:15], v[6:9], off
	ds_read_b32 v6, v80 offset:96
	ds_read_b32 v7, v80 offset:356
	ds_read_b32 v8, v80 offset:616
	ds_read_b32 v9, v80 offset:876
	ds_read_b32 v13, v80 offset:1136
	ds_read_b32 v14, v80 offset:1396
	ds_read_b32 v15, v80 offset:1656
	ds_read_b32 v16, v80 offset:1916
	s_waitcnt lgkmcnt(0)
	v_cvt_pk_bf16_f32 v6, v6, v7
	v_cvt_pk_bf16_f32 v7, v8, v9
	v_cvt_pk_bf16_f32 v8, v13, v14
	v_subrev_u32_e32 v14, 32, v12
	v_cvt_pk_bf16_f32 v9, v15, v16
	v_ashrrev_i32_e32 v15, 31, v14
	v_lshlrev_b64 v[14:15], 11, v[14:15]
	v_lshl_add_u64 v[14:15], v[10:11], 0, v[14:15]
	global_store_dwordx4 v[14:15], v[6:9], off
	ds_read_b32 v6, v80 offset:128
	ds_read_b32 v7, v80 offset:388
	ds_read_b32 v8, v80 offset:648
	ds_read_b32 v9, v80 offset:908
	ds_read_b32 v13, v80 offset:1168
	ds_read_b32 v14, v80 offset:1428
	ds_read_b32 v15, v80 offset:1688
	ds_read_b32 v16, v80 offset:1948
	s_waitcnt lgkmcnt(0)
	v_cvt_pk_bf16_f32 v6, v6, v7
	v_cvt_pk_bf16_f32 v7, v8, v9
	v_cvt_pk_bf16_f32 v8, v13, v14
	v_subrev_u32_e32 v14, 24, v12
	v_cvt_pk_bf16_f32 v9, v15, v16
	v_ashrrev_i32_e32 v15, 31, v14
	v_lshlrev_b64 v[14:15], 11, v[14:15]
	v_lshl_add_u64 v[14:15], v[10:11], 0, v[14:15]
	global_store_dwordx4 v[14:15], v[6:9], off
	ds_read_b32 v6, v80 offset:160
	ds_read_b32 v7, v80 offset:420
	ds_read_b32 v8, v80 offset:680
	ds_read_b32 v9, v80 offset:940
	ds_read_b32 v13, v80 offset:1200
	ds_read_b32 v14, v80 offset:1460
	ds_read_b32 v15, v80 offset:1720
	ds_read_b32 v16, v80 offset:1980
	s_waitcnt lgkmcnt(0)
	v_cvt_pk_bf16_f32 v6, v6, v7
	v_cvt_pk_bf16_f32 v7, v8, v9
	v_cvt_pk_bf16_f32 v8, v13, v14
	v_add_u32_e32 v14, -16, v12
	v_cvt_pk_bf16_f32 v9, v15, v16
	v_ashrrev_i32_e32 v15, 31, v14
	v_lshlrev_b64 v[14:15], 11, v[14:15]
	v_lshl_add_u64 v[14:15], v[10:11], 0, v[14:15]
	global_store_dwordx4 v[14:15], v[6:9], off
	ds_read_b32 v6, v80 offset:192
	ds_read_b32 v7, v80 offset:452
	ds_read_b32 v8, v80 offset:712
	ds_read_b32 v9, v80 offset:972
	ds_read_b32 v13, v80 offset:1232
	ds_read_b32 v14, v80 offset:1492
	ds_read_b32 v15, v80 offset:1752
	ds_read_b32 v16, v80 offset:2012
	s_waitcnt lgkmcnt(0)
	v_cvt_pk_bf16_f32 v6, v6, v7
	v_cvt_pk_bf16_f32 v7, v8, v9
	v_cvt_pk_bf16_f32 v8, v13, v14
	v_add_u32_e32 v14, -8, v12
	v_cvt_pk_bf16_f32 v9, v15, v16
	v_ashrrev_i32_e32 v15, 31, v14
	v_lshlrev_b64 v[14:15], 11, v[14:15]
	v_lshl_add_u64 v[14:15], v[10:11], 0, v[14:15]
	global_store_dwordx4 v[14:15], v[6:9], off
	ds_read_b32 v6, v80 offset:224
	ds_read_b32 v7, v80 offset:484
	ds_read_b32 v8, v80 offset:744
	ds_read_b32 v9, v80 offset:1004
	ds_read_b32 v13, v80 offset:1264
	ds_read_b32 v14, v80 offset:1524
	ds_read_b32 v15, v80 offset:1784
	ds_read_b32 v16, v80 offset:2044
	s_waitcnt lgkmcnt(0)
	v_cvt_pk_bf16_f32 v6, v6, v7
	v_cvt_pk_bf16_f32 v7, v8, v9
	v_cvt_pk_bf16_f32 v8, v13, v14
	v_ashrrev_i32_e32 v13, 31, v12
	v_lshlrev_b64 v[12:13], 11, v[12:13]
	v_cvt_pk_bf16_f32 v9, v15, v16
	v_lshl_add_u64 v[10:11], v[10:11], 0, v[12:13]
	global_store_dwordx4 v[10:11], v[6:9], off
	s_waitcnt lgkmcnt(0)

.LBB0_1501:
	s_or_b64 exec, exec, s[46:47]
	s_add_u32 s26, s44, s61
	s_addc_u32 s27, s45, s60
	v_lshlrev_b32_e32 v6, 6, v6
	v_cmp_lt_i32_e32 vcc, -1, v64
	v_or_b32_e32 v74, v6, v2
	v_lshl_add_u64 v[76:77], v[64:65], 2, s[26:27]
	v_mov_b32_e32 v60, 0
	v_mov_b32_e32 v62, 0
	v_mov_b32_e32 v63, 0
	s_and_saveexec_b64 s[44:45], vcc
	s_cbranch_execz .LBB0_1503
	s_movk_i32 s26, 0x2b28
	v_mad_i64_i32 v[8:9], s[26:27], v74, s26, v[76:77]
	global_load_dwordx2 v[62:63], v[8:9], off
.LBB0_1503:
	s_or_b64 exec, exec, s[44:45]
	v_mov_b32_e32 v61, 0
	s_and_saveexec_b64 s[44:45], vcc
	s_cbranch_execz .LBB0_1505
	v_or_b32_e32 v7, 2, v74
	s_movk_i32 s26, 0x2b28
	v_mad_i64_i32 v[8:9], s[26:27], v7, s26, v[76:77]
	global_load_dwordx2 v[60:61], v[8:9], off
.LBB0_1505:
	s_or_b64 exec, exec, s[44:45]
	v_mov_b32_e32 v64, v65
	v_mov_b64_e32 v[70:71], v[64:65]
	s_and_saveexec_b64 s[44:45], vcc
	s_cbranch_execz .LBB0_1507
	v_or_b32_e32 v7, 4, v74
	s_movk_i32 s26, 0x2b28
	v_mad_i64_i32 v[8:9], s[26:27], v7, s26, v[76:77]
	global_load_dwordx2 v[70:71], v[8:9], off
.LBB0_1507:
	s_or_b64 exec, exec, s[44:45]
	v_mov_b32_e32 v46, 0
	v_mov_b32_e32 v72, 0
	v_mov_b32_e32 v73, 0
	s_and_saveexec_b64 s[44:45], vcc
	s_cbranch_execz .LBB0_1509
	v_or_b32_e32 v7, 6, v74
	s_movk_i32 s26, 0x2b28
	v_mad_i64_i32 v[8:9], s[26:27], v7, s26, v[76:77]
	global_load_dwordx2 v[72:73], v[8:9], off
.LBB0_1509:
	s_or_b64 exec, exec, s[44:45]
	v_mov_b32_e32 v47, 0
	s_and_saveexec_b64 s[44:45], vcc
	s_cbranch_execz .LBB0_1511
	v_or_b32_e32 v7, 8, v74
	s_movk_i32 s26, 0x2b28
	v_mad_i64_i32 v[8:9], s[26:27], v7, s26, v[76:77]
	global_load_dwordx2 v[46:47], v[8:9], off
.LBB0_1511:
	s_or_b64 exec, exec, s[44:45]
	v_mov_b32_e32 v56, 0
	v_mov_b32_e32 v57, v56
	s_and_saveexec_b64 s[44:45], vcc
	s_cbranch_execz .LBB0_1513
	v_or_b32_e32 v7, 10, v74
	s_movk_i32 s26, 0x2b28
	v_mad_i64_i32 v[8:9], s[26:27], v7, s26, v[76:77]
	global_load_dwordx2 v[56:57], v[8:9], off
.LBB0_1513:
	s_or_b64 exec, exec, s[44:45]
	v_mov_b32_e32 v64, v65
	v_mov_b64_e32 v[66:67], v[64:65]
	s_and_saveexec_b64 s[44:45], vcc
	s_cbranch_execz .LBB0_1515
	v_or_b32_e32 v7, 12, v74
	s_movk_i32 s26, 0x2b28
	v_mad_i64_i32 v[8:9], s[26:27], v7, s26, v[76:77]
	global_load_dwordx2 v[66:67], v[8:9], off
.LBB0_1515:
	s_or_b64 exec, exec, s[44:45]
	v_mov_b32_e32 v38, 0
	v_mov_b32_e32 v68, 0
	v_mov_b32_e32 v69, 0
	s_and_saveexec_b64 s[44:45], vcc
	s_cbranch_execz .LBB0_1517
	v_or_b32_e32 v7, 14, v74
	s_movk_i32 s26, 0x2b28
	v_mad_i64_i32 v[8:9], s[26:27], v7, s26, v[76:77]
	global_load_dwordx2 v[68:69], v[8:9], off
.LBB0_1517:
	s_or_b64 exec, exec, s[44:45]
	v_mov_b32_e32 v39, 0
	s_and_saveexec_b64 s[44:45], vcc
	s_cbranch_execz .LBB0_1519
	v_or_b32_e32 v7, 16, v74
	s_movk_i32 s26, 0x2b28
	v_mad_i64_i32 v[8:9], s[26:27], v7, s26, v[76:77]
	global_load_dwordx2 v[38:39], v[8:9], off
.LBB0_1519:
	s_or_b64 exec, exec, s[44:45]
	v_mov_b32_e32 v50, 0
	v_mov_b32_e32 v51, v50
	s_and_saveexec_b64 s[44:45], vcc
	s_cbranch_execz .LBB0_1521
	v_or_b32_e32 v7, 18, v74
	s_movk_i32 s26, 0x2b28
	v_mad_i64_i32 v[8:9], s[26:27], v7, s26, v[76:77]
	global_load_dwordx2 v[50:51], v[8:9], off
.LBB0_1521:
	s_or_b64 exec, exec, s[44:45]
	v_mov_b32_e32 v64, v65
	v_mov_b64_e32 v[54:55], v[64:65]
	s_and_saveexec_b64 s[44:45], vcc
	s_cbranch_execz .LBB0_1523
	v_or_b32_e32 v7, 20, v74
	s_movk_i32 s26, 0x2b28
	v_mad_i64_i32 v[8:9], s[26:27], v7, s26, v[76:77]
	global_load_dwordx2 v[54:55], v[8:9], off
.LBB0_1523:
	s_or_b64 exec, exec, s[44:45]
	v_mov_b32_e32 v30, 0
	v_mov_b32_e32 v58, 0
	v_mov_b32_e32 v59, 0
	s_and_saveexec_b64 s[44:45], vcc
	s_cbranch_execz .LBB0_1525
	v_or_b32_e32 v7, 22, v74
	s_movk_i32 s26, 0x2b28
	v_mad_i64_i32 v[8:9], s[26:27], v7, s26, v[76:77]
	global_load_dwordx2 v[58:59], v[8:9], off
.LBB0_1525:
	s_or_b64 exec, exec, s[44:45]
	v_mov_b32_e32 v31, 0
	s_and_saveexec_b64 s[44:45], vcc
	s_cbranch_execz .LBB0_1527
	v_or_b32_e32 v7, 24, v74
	s_movk_i32 s26, 0x2b28
	v_mad_i64_i32 v[8:9], s[26:27], v7, s26, v[76:77]
	global_load_dwordx2 v[30:31], v[8:9], off
.LBB0_1527:
	s_or_b64 exec, exec, s[44:45]
	v_mov_b32_e32 v42, 0
	v_mov_b32_e32 v43, v42
	s_and_saveexec_b64 s[44:45], vcc
	s_cbranch_execz .LBB0_1529
	v_or_b32_e32 v7, 26, v74
	s_movk_i32 s26, 0x2b28
	v_mad_i64_i32 v[8:9], s[26:27], v7, s26, v[76:77]
	global_load_dwordx2 v[42:43], v[8:9], off
.LBB0_1529:
	s_or_b64 exec, exec, s[44:45]
	v_mov_b32_e32 v64, v65
	v_mov_b64_e32 v[48:49], v[64:65]
	s_and_saveexec_b64 s[44:45], vcc
	s_cbranch_execz .LBB0_1531
	v_or_b32_e32 v7, 28, v74
	s_movk_i32 s26, 0x2b28
	v_mad_i64_i32 v[8:9], s[26:27], v7, s26, v[76:77]
	global_load_dwordx2 v[48:49], v[8:9], off
.LBB0_1531:
	s_or_b64 exec, exec, s[44:45]
	v_mov_b32_e32 v22, 0
	v_mov_b32_e32 v52, 0
	v_mov_b32_e32 v53, 0
	s_and_saveexec_b64 s[44:45], vcc
	s_cbranch_execz .LBB0_1533
	v_or_b32_e32 v7, 30, v74
	s_movk_i32 s26, 0x2b28
	v_mad_i64_i32 v[8:9], s[26:27], v7, s26, v[76:77]
	global_load_dwordx2 v[52:53], v[8:9], off
.LBB0_1533:
	s_or_b64 exec, exec, s[44:45]
	v_mov_b32_e32 v23, 0
	s_and_saveexec_b64 s[44:45], vcc
	s_cbranch_execz .LBB0_1535
	v_or_b32_e32 v7, 32, v74
	s_movk_i32 s26, 0x2b28
	v_mad_i64_i32 v[8:9], s[26:27], v7, s26, v[76:77]
	global_load_dwordx2 v[22:23], v[8:9], off
.LBB0_1535:
	s_or_b64 exec, exec, s[44:45]
	v_mov_b32_e32 v34, 0
	v_mov_b32_e32 v35, v34
	s_and_saveexec_b64 s[44:45], vcc
	s_cbranch_execz .LBB0_1537
	v_or_b32_e32 v7, 34, v74
	s_movk_i32 s26, 0x2b28
	v_mad_i64_i32 v[8:9], s[26:27], v7, s26, v[76:77]
	global_load_dwordx2 v[34:35], v[8:9], off
.LBB0_1537:
	s_or_b64 exec, exec, s[44:45]
	v_mov_b32_e32 v64, v65
	v_mov_b64_e32 v[40:41], v[64:65]
	s_and_saveexec_b64 s[44:45], vcc
	s_cbranch_execz .LBB0_1539
	v_or_b32_e32 v7, 36, v74
	s_movk_i32 s26, 0x2b28
	v_mad_i64_i32 v[8:9], s[26:27], v7, s26, v[76:77]
	global_load_dwordx2 v[40:41], v[8:9], off
.LBB0_1539:
	s_or_b64 exec, exec, s[44:45]
	v_mov_b32_e32 v14, 0
	v_mov_b32_e32 v44, 0
	v_mov_b32_e32 v45, 0
	s_and_saveexec_b64 s[44:45], vcc
	s_cbranch_execz .LBB0_1541
	v_or_b32_e32 v7, 38, v74
	s_movk_i32 s26, 0x2b28
	v_mad_i64_i32 v[8:9], s[26:27], v7, s26, v[76:77]
	global_load_dwordx2 v[44:45], v[8:9], off
.LBB0_1541:
	s_or_b64 exec, exec, s[44:45]
	v_mov_b32_e32 v15, 0
	s_and_saveexec_b64 s[44:45], vcc
	s_cbranch_execz .LBB0_1543
	v_or_b32_e32 v7, 40, v74
	s_movk_i32 s26, 0x2b28
	v_mad_i64_i32 v[8:9], s[26:27], v7, s26, v[76:77]
	global_load_dwordx2 v[14:15], v[8:9], off
.LBB0_1543:
	s_or_b64 exec, exec, s[44:45]
	v_mov_b32_e32 v28, 0
	v_mov_b32_e32 v29, v28
	s_and_saveexec_b64 s[44:45], vcc
	s_cbranch_execz .LBB0_1545
	v_or_b32_e32 v7, 42, v74
	s_movk_i32 s26, 0x2b28
	v_mad_i64_i32 v[8:9], s[26:27], v7, s26, v[76:77]
	global_load_dwordx2 v[28:29], v[8:9], off
.LBB0_1545:
	s_or_b64 exec, exec, s[44:45]
	v_mov_b32_e32 v64, v65
	v_mov_b64_e32 v[32:33], v[64:65]
	s_and_saveexec_b64 s[44:45], vcc
	s_cbranch_execz .LBB0_1547
	v_or_b32_e32 v7, 44, v74
	s_movk_i32 s26, 0x2b28
	v_mad_i64_i32 v[8:9], s[26:27], v7, s26, v[76:77]
	global_load_dwordx2 v[32:33], v[8:9], off
.LBB0_1547:
	s_or_b64 exec, exec, s[44:45]
	v_mov_b32_e32 v10, 0
	v_mov_b32_e32 v36, 0
	v_mov_b32_e32 v37, 0
	s_and_saveexec_b64 s[44:45], vcc
	s_cbranch_execz .LBB0_1549
	v_or_b32_e32 v7, 46, v74
	s_movk_i32 s26, 0x2b28
	v_mad_i64_i32 v[8:9], s[26:27], v7, s26, v[76:77]
	global_load_dwordx2 v[36:37], v[8:9], off
.LBB0_1549:
	s_or_b64 exec, exec, s[44:45]
	v_mov_b32_e32 v11, 0
	s_and_saveexec_b64 s[44:45], vcc
	s_cbranch_execz .LBB0_1551
	v_or_b32_e32 v7, 48, v74
	s_movk_i32 s26, 0x2b28
	v_mad_i64_i32 v[8:9], s[26:27], v7, s26, v[76:77]
	global_load_dwordx2 v[10:11], v[8:9], off
.LBB0_1551:
	s_or_b64 exec, exec, s[44:45]
	v_mov_b32_e32 v20, 0
	v_mov_b32_e32 v21, v20
	s_and_saveexec_b64 s[44:45], vcc
	s_cbranch_execz .LBB0_1553
	v_or_b32_e32 v7, 50, v74
	s_movk_i32 s26, 0x2b28
	v_mad_i64_i32 v[8:9], s[26:27], v7, s26, v[76:77]
	global_load_dwordx2 v[20:21], v[8:9], off
.LBB0_1553:
	s_or_b64 exec, exec, s[44:45]
	v_mov_b32_e32 v64, v65
	v_mov_b64_e32 v[24:25], v[64:65]
	s_and_saveexec_b64 s[44:45], vcc
	s_cbranch_execz .LBB0_1555
	v_or_b32_e32 v7, 52, v74
	s_movk_i32 s26, 0x2b28
	v_mad_i64_i32 v[8:9], s[26:27], v7, s26, v[76:77]
	global_load_dwordx2 v[24:25], v[8:9], off
.LBB0_1555:
	s_or_b64 exec, exec, s[44:45]
	v_mov_b32_e32 v8, 0
	v_mov_b32_e32 v26, 0
	v_mov_b32_e32 v27, 0
	s_and_saveexec_b64 s[44:45], vcc
	s_cbranch_execz .LBB0_1557
	v_or_b32_e32 v7, 54, v74
	s_movk_i32 s26, 0x2b28
	v_mad_i64_i32 v[12:13], s[26:27], v7, s26, v[76:77]
	global_load_dwordx2 v[26:27], v[12:13], off
.LBB0_1557:
	s_or_b64 exec, exec, s[44:45]
	v_mov_b32_e32 v9, 0
	s_and_saveexec_b64 s[44:45], vcc
	s_cbranch_execz .LBB0_1559
	v_or_b32_e32 v7, 56, v74
	s_movk_i32 s26, 0x2b28
	v_mad_i64_i32 v[8:9], s[26:27], v7, s26, v[76:77]
	global_load_dwordx2 v[8:9], v[8:9], off
.LBB0_1559:
	s_or_b64 exec, exec, s[44:45]
	v_mov_b32_e32 v12, 0
	v_mov_b32_e32 v13, v12
	s_and_saveexec_b64 s[44:45], vcc
	s_cbranch_execz .LBB0_1561
	v_or_b32_e32 v7, 58, v74
	s_movk_i32 s26, 0x2b28
	v_mad_i64_i32 v[12:13], s[26:27], v7, s26, v[76:77]
	global_load_dwordx2 v[12:13], v[12:13], off
.LBB0_1561:
	s_or_b64 exec, exec, s[44:45]
	v_mov_b32_e32 v64, v65
	v_mov_b64_e32 v[16:17], v[64:65]
	s_and_saveexec_b64 s[44:45], vcc
	s_cbranch_execz .LBB0_1563
	v_or_b32_e32 v7, 60, v74
	s_movk_i32 s26, 0x2b28
	v_mad_i64_i32 v[16:17], s[26:27], v7, s26, v[76:77]
	global_load_dwordx2 v[16:17], v[16:17], off
.LBB0_1563:
	s_or_b64 exec, exec, s[44:45]
	v_mov_b32_e32 v18, 0
	v_mov_b32_e32 v19, 0
	s_and_saveexec_b64 s[44:45], vcc
	s_cbranch_execz .LBB0_1565
	v_or_b32_e32 v7, 62, v74
	s_movk_i32 s26, 0x2b28
	v_mad_i64_i32 v[18:19], s[26:27], v7, s26, v[76:77]
	global_load_dwordx2 v[18:19], v[18:19], off
.LBB0_1565:
	s_or_b64 exec, exec, s[44:45]
	v_readlane_b32 s26, v254, 43
	v_readlane_b32 s27, v254, 44
	s_lshl_b64 s[26:27], s[26:27], 2
	s_add_u32 s44, s0, s26
	s_addc_u32 s45, s1, s27
	s_cmp_lg_u64 s[0:1], 0
	s_cselect_b64 s[46:47], -1, 0
	s_cmp_eq_u64 s[0:1], 0
	v_ashrrev_i32_e32 v7, 31, v6
	v_add_u32_e32 v76, v5, v78
	v_add_u32_e32 v77, v5, v88
	s_cbranch_scc1 .LBB0_1588
	v_ashrrev_i32_e32 v75, 31, v74
	v_lshl_add_u64 v[74:75], v[74:75], 2, s[44:45]
	global_load_dword v64, v[74:75], off
	v_lshl_add_u64 v[112:113], v[6:7], 0, v[2:3]
	v_lshl_add_u64 v[112:113], v[112:113], 2, s[44:45]
	s_waitcnt vmcnt(0) lgkmcnt(0)
	v_pk_mul_f32 v[74:75], v[62:63], v[64:65] op_sel_hi:[1,0]
	global_load_dword v64, v[112:113], off offset:8
	ds_write2_b32 v76, v74, v75 offset1:1
	s_waitcnt vmcnt(0) lgkmcnt(0)
	v_pk_mul_f32 v[74:75], v[60:61], v[64:65] op_sel_hi:[1,0]
	global_load_dword v64, v[112:113], off offset:16
	ds_write2_b32 v77, v74, v75 offset1:1
	s_waitcnt vmcnt(0) lgkmcnt(0)
	v_pk_mul_f32 v[74:75], v[70:71], v[64:65] op_sel_hi:[1,0]
	global_load_dword v64, v[112:113], off offset:24
	s_cbranch_execnz .LBB0_1568

.LBB0_1568:
	s_waitcnt vmcnt(0) lgkmcnt(0)
	v_add_u32_e32 v62, v5, v89
	v_pk_mul_f32 v[60:61], v[72:73], v[64:65] op_sel_hi:[1,0]
	ds_write2_b32 v62, v60, v61 offset0:130 offset1:131
	v_cndmask_b32_e64 v60, 0, 1, s[46:47]
	v_cmp_ne_u32_e64 s[0:1], 1, v60
	s_andn2_b64 vcc, exec, s[46:47]
	v_add_u32_e32 v63, v5, v90
	ds_write2_b32 v62, v74, v75 offset1:1
	s_cbranch_vccnz .LBB0_1589
	v_lshl_add_u64 v[60:61], v[6:7], 0, v[2:3]
	v_lshl_add_u64 v[70:71], v[60:61], 2, s[44:45]
	global_load_dword v60, v[70:71], off offset:32
	global_load_dword v62, v[70:71], off offset:40
	s_waitcnt vmcnt(0) lgkmcnt(0)
	v_pk_mul_f32 v[60:61], v[46:47], v[60:61] op_sel_hi:[1,0]
	ds_write2_b32 v63, v60, v61 offset1:1
	v_pk_mul_f32 v[60:61], v[56:57], v[62:63] op_sel_hi:[1,0]
	ds_write2_b32 v63, v60, v61 offset0:130 offset1:131
	global_load_dword v60, v[70:71], off offset:48
	global_load_dword v62, v[70:71], off offset:56
	s_waitcnt vmcnt(0) lgkmcnt(0)
	v_pk_mul_f32 v[60:61], v[66:67], v[60:61] op_sel_hi:[1,0]
	s_cbranch_execnz .LBB0_1571

.LBB0_1571:
	v_add_u32_e32 v56, v5, v91
	v_pk_mul_f32 v[46:47], v[68:69], v[62:63] op_sel_hi:[1,0]
	s_and_b64 vcc, exec, s[0:1]
	v_add_u32_e32 v57, v5, v92
	ds_write2_b32 v56, v60, v61 offset1:1
	ds_write2_b32 v56, v46, v47 offset0:130 offset1:131
	s_cbranch_vccnz .LBB0_1590
	v_lshl_add_u64 v[46:47], v[6:7], 0, v[2:3]
	v_lshl_add_u64 v[60:61], v[46:47], 2, s[44:45]
	global_load_dword v46, v[60:61], off offset:64
	global_load_dword v56, v[60:61], off offset:72
	s_waitcnt vmcnt(0) lgkmcnt(0)
	v_pk_mul_f32 v[46:47], v[38:39], v[46:47] op_sel_hi:[1,0]
	ds_write2_b32 v57, v46, v47 offset1:1
	v_pk_mul_f32 v[46:47], v[50:51], v[56:57] op_sel_hi:[1,0]
	ds_write2_b32 v57, v46, v47 offset0:130 offset1:131
	global_load_dword v46, v[60:61], off offset:80
	global_load_dword v56, v[60:61], off offset:88
	s_waitcnt vmcnt(0) lgkmcnt(0)
	v_pk_mul_f32 v[46:47], v[54:55], v[46:47] op_sel_hi:[1,0]
	s_cbranch_execnz .LBB0_1574

.LBB0_1574:
	v_add_u32_e32 v50, v5, v93
	ds_write2_b32 v50, v46, v47 offset1:1
	v_pk_mul_f32 v[38:39], v[58:59], v[56:57] op_sel_hi:[1,0]
	s_and_b64 vcc, exec, s[0:1]
	v_add_u32_e32 v47, v5, v94
	ds_write2_b32 v50, v38, v39 offset0:130 offset1:131
	s_cbranch_vccnz .LBB0_1591
	v_lshl_add_u64 v[38:39], v[6:7], 0, v[2:3]
	v_lshl_add_u64 v[50:51], v[38:39], 2, s[44:45]
	global_load_dword v38, v[50:51], off offset:96
	global_load_dword v46, v[50:51], off offset:104
	s_waitcnt vmcnt(0) lgkmcnt(0)
	v_pk_mul_f32 v[38:39], v[30:31], v[38:39] op_sel_hi:[1,0]
	ds_write2_b32 v47, v38, v39 offset1:1
	v_pk_mul_f32 v[38:39], v[42:43], v[46:47] op_sel_hi:[1,0]
	ds_write2_b32 v47, v38, v39 offset0:130 offset1:131
	global_load_dword v38, v[50:51], off offset:112
	global_load_dword v46, v[50:51], off offset:120
	s_waitcnt vmcnt(0) lgkmcnt(0)
	v_pk_mul_f32 v[38:39], v[48:49], v[38:39] op_sel_hi:[1,0]
	s_cbranch_execnz .LBB0_1577

.LBB0_1577:
	v_add_u32_e32 v42, v5, v95
	ds_write2_b32 v42, v38, v39 offset1:1
	v_pk_mul_f32 v[30:31], v[52:53], v[46:47] op_sel_hi:[1,0]
	s_and_b64 vcc, exec, s[0:1]
	v_add_u32_e32 v39, v5, v96
	ds_write2_b32 v42, v30, v31 offset0:130 offset1:131
	s_cbranch_vccnz .LBB0_1592
	v_lshl_add_u64 v[30:31], v[6:7], 0, v[2:3]
	v_lshl_add_u64 v[42:43], v[30:31], 2, s[44:45]
	global_load_dword v30, v[42:43], off offset:128
	global_load_dword v38, v[42:43], off offset:136
	s_waitcnt vmcnt(0) lgkmcnt(0)
	v_pk_mul_f32 v[30:31], v[22:23], v[30:31] op_sel_hi:[1,0]
	ds_write2_b32 v39, v30, v31 offset1:1
	v_pk_mul_f32 v[30:31], v[34:35], v[38:39] op_sel_hi:[1,0]
	ds_write2_b32 v39, v30, v31 offset0:130 offset1:131
	global_load_dword v30, v[42:43], off offset:144
	global_load_dword v38, v[42:43], off offset:152
	s_waitcnt vmcnt(0) lgkmcnt(0)
	v_pk_mul_f32 v[30:31], v[40:41], v[30:31] op_sel_hi:[1,0]
	s_cbranch_execnz .LBB0_1580

.LBB0_1580:
	v_add_u32_e32 v34, v5, v97
	ds_write2_b32 v34, v30, v31 offset1:1
	v_pk_mul_f32 v[22:23], v[44:45], v[38:39] op_sel_hi:[1,0]
	s_and_b64 vcc, exec, s[0:1]
	v_add_u32_e32 v31, v5, v98
	ds_write2_b32 v34, v22, v23 offset0:130 offset1:131
	s_cbranch_vccnz .LBB0_1593
	v_lshl_add_u64 v[22:23], v[6:7], 0, v[2:3]
	v_lshl_add_u64 v[34:35], v[22:23], 2, s[44:45]
	global_load_dword v22, v[34:35], off offset:160
	global_load_dword v30, v[34:35], off offset:168
	s_waitcnt vmcnt(0) lgkmcnt(0)
	v_pk_mul_f32 v[22:23], v[14:15], v[22:23] op_sel_hi:[1,0]
	ds_write2_b32 v31, v22, v23 offset1:1
	v_pk_mul_f32 v[22:23], v[28:29], v[30:31] op_sel_hi:[1,0]
	ds_write2_b32 v31, v22, v23 offset0:130 offset1:131
	global_load_dword v22, v[34:35], off offset:176
	global_load_dword v30, v[34:35], off offset:184
	s_waitcnt vmcnt(0) lgkmcnt(0)
	v_pk_mul_f32 v[22:23], v[32:33], v[22:23] op_sel_hi:[1,0]
	s_cbranch_execnz .LBB0_1583

.LBB0_1583:
	v_add_u32_e32 v14, 0x410, v31
	ds_write2_b32 v14, v22, v23 offset1:1
	v_pk_mul_f32 v[14:15], v[36:37], v[30:31] op_sel_hi:[1,0]
	v_add_u32_e32 v22, 0x618, v31
	s_and_b64 vcc, exec, s[0:1]
	v_add_u32_e32 v23, 0x820, v31
	v_add_u32_e32 v28, 0xa28, v31
	ds_write2_b32 v22, v14, v15 offset1:1
	s_cbranch_vccnz .LBB0_1594
	v_lshl_add_u64 v[14:15], v[6:7], 0, v[2:3]
	v_lshl_add_u64 v[32:33], v[14:15], 2, s[44:45]
	global_load_dword v14, v[32:33], off offset:192
	global_load_dword v22, v[32:33], off offset:200
	s_waitcnt vmcnt(0) lgkmcnt(0)
	v_pk_mul_f32 v[14:15], v[10:11], v[14:15] op_sel_hi:[1,0]
	ds_write2_b32 v23, v14, v15 offset1:1
	v_pk_mul_f32 v[14:15], v[20:21], v[22:23] op_sel_hi:[1,0]
	ds_write2_b32 v28, v14, v15 offset1:1
	global_load_dword v14, v[32:33], off offset:208
	global_load_dword v22, v[32:33], off offset:216
	s_waitcnt vmcnt(0) lgkmcnt(0)
	v_pk_mul_f32 v[14:15], v[24:25], v[14:15] op_sel_hi:[1,0]
	s_cbranch_execnz .LBB0_1586

.LBB0_1586:
	v_add_u32_e32 v10, 0xc30, v31
	ds_write2_b32 v10, v14, v15 offset1:1
	v_pk_mul_f32 v[10:11], v[26:27], v[22:23] op_sel_hi:[1,0]
	v_add_u32_e32 v14, 0xe38, v31
	s_and_b64 vcc, exec, s[0:1]
	v_add_u32_e32 v15, 0x1040, v31
	v_add_u32_e32 v20, 0x1248, v31
	ds_write2_b32 v14, v10, v11 offset1:1
	s_cbranch_vccnz .LBB0_1595
	v_lshl_add_u64 v[10:11], v[6:7], 0, v[2:3]
	v_lshl_add_u64 v[22:23], v[10:11], 2, s[44:45]
	global_load_dword v10, v[22:23], off offset:224
	global_load_dword v14, v[22:23], off offset:232
	s_waitcnt vmcnt(0) lgkmcnt(0)
	v_pk_mul_f32 v[10:11], v[8:9], v[10:11] op_sel_hi:[1,0]
	ds_write2_b32 v15, v10, v11 offset1:1
	v_pk_mul_f32 v[10:11], v[12:13], v[14:15] op_sel_hi:[1,0]
	ds_write2_b32 v20, v10, v11 offset1:1
	global_load_dword v10, v[22:23], off offset:240
	global_load_dword v14, v[22:23], off offset:248
	s_waitcnt vmcnt(0) lgkmcnt(0)
	v_pk_mul_f32 v[10:11], v[16:17], v[10:11] op_sel_hi:[1,0]
	s_cbranch_execnz .LBB0_1263
	s_branch .LBB0_1262

.LBB0_1685:
	v_lshl_add_u32 v138, s27, 8, v144
	v_lshl_or_b32 v136, s26, 8, v146
	v_ashrrev_i32_e32 v139, 31, v138
	v_ashrrev_i32_e32 v137, 31, v136
	v_lshlrev_b64 v[140:141], 10, v[138:139]
	v_readlane_b32 s84, v254, 45
	v_lshl_add_u64 v[142:143], v[140:141], 0, v[136:137]
	v_readlane_b32 s90, v254, 51
	v_readlane_b32 s91, v254, 52
	s_lshl_b32 s50, s26, 2
	v_cndmask_b32_e64 v152, 0, 1, s[44:45]
	v_lshl_add_u64 v[140:141], v[142:143], 2, s[90:91]
	global_load_dwordx4 v[148:151], v[140:141], off
	s_ashr_i32 s51, s50, 31
	v_cmp_ne_u32_e64 s[38:39], 1, v152
	s_andn2_b64 vcc, exec, s[44:45]
	v_readlane_b32 s33, v255, 5
	v_readlane_b32 s85, v254, 46
	v_readlane_b32 s86, v254, 47
	v_readlane_b32 s87, v254, 48
	v_readlane_b32 s88, v254, 49
	v_readlane_b32 s89, v254, 50
	s_waitcnt vmcnt(0)
	v_pk_add_f32 v[128:129], v[128:129], v[150:151]
	v_pk_add_f32 v[126:127], v[126:127], v[148:149]
	global_store_dwordx4 v[140:141], v[126:129], off
	s_cbranch_vccnz .LBB0_1728
	v_cvt_pk_bf16_f32 v148, v126, v127
	v_mul_f32_e32 v127, v127, v127
	v_cvt_pk_bf16_f32 v149, v128, v129
	v_lshl_add_u64 v[142:143], v[142:143], 1, s[4:5]
	v_fmac_f32_e32 v127, v126, v126
	v_mul_f32_e32 v126, v129, v129
	global_store_dwordx2 v[142:143], v[148:149], off
	v_fmac_f32_e32 v126, v128, v128
	v_add_f32_e32 v150, v127, v126
	global_load_dwordx4 v[126:129], v[140:141], off offset:64
	s_waitcnt vmcnt(0)
	v_pk_add_f32 v[128:129], v[124:125], v[128:129]
	v_pk_add_f32 v[126:127], v[122:123], v[126:127]
	global_store_dwordx4 v[140:141], v[126:129], off offset:64
	v_cvt_pk_bf16_f32 v148, v126, v127
	v_cvt_pk_bf16_f32 v149, v128, v129
	v_mul_f32_e32 v127, v127, v127
	v_fmac_f32_e32 v127, v126, v126
	v_mul_f32_e32 v126, v129, v129
	v_fmac_f32_e32 v126, v128, v128
	global_store_dwordx2 v[142:143], v[148:149], off offset:32
	v_add_f32_e32 v126, v127, v126
	v_add_f32_e32 v150, v150, v126
	global_load_dwordx4 v[126:129], v[140:141], off offset:512
	s_waitcnt vmcnt(0)
	v_pk_add_f32 v[128:129], v[120:121], v[128:129]
	v_pk_add_f32 v[126:127], v[118:119], v[126:127]
	global_store_dwordx4 v[140:141], v[126:129], off offset:512
	v_cvt_pk_bf16_f32 v148, v126, v127
	v_cvt_pk_bf16_f32 v149, v128, v129
	v_mul_f32_e32 v127, v127, v127
	v_fmac_f32_e32 v127, v126, v126
	v_mul_f32_e32 v126, v129, v129
	v_fmac_f32_e32 v126, v128, v128
	global_store_dwordx2 v[142:143], v[148:149], off offset:256
	v_add_f32_e32 v126, v127, v126
	v_add_f32_e32 v150, v150, v126
	global_load_dwordx4 v[126:129], v[140:141], off offset:576
	s_waitcnt vmcnt(0)
	v_pk_add_f32 v[128:129], v[116:117], v[128:129]
	v_pk_add_f32 v[126:127], v[114:115], v[126:127]
	global_store_dwordx4 v[140:141], v[126:129], off offset:576
	v_cvt_pk_bf16_f32 v148, v126, v127
	v_cvt_pk_bf16_f32 v149, v128, v129
	v_mul_f32_e32 v127, v127, v127
	v_fmac_f32_e32 v127, v126, v126
	v_mul_f32_e32 v126, v129, v129
	v_fmac_f32_e32 v126, v128, v128
	v_and_b32_e32 v128, 64, v197
	v_add_f32_e32 v126, v127, v126
	v_xor_b32_e32 v127, 16, v197
	v_add_u32_e32 v128, 64, v128
	v_cmp_lt_i32_e32 vcc, v127, v128
	v_add_f32_e32 v126, v150, v126
	global_store_dwordx2 v[142:143], v[148:149], off offset:288
	v_cndmask_b32_e32 v127, v197, v127, vcc
	v_lshlrev_b32_e32 v127, 2, v127
	ds_bpermute_b32 v127, v127, v126
	s_waitcnt lgkmcnt(0)
	v_add_f32_e32 v126, v126, v127
	v_xor_b32_e32 v127, 32, v197
	v_cmp_lt_i32_e32 vcc, v127, v128
	s_nop 1
	v_cndmask_b32_e32 v127, v197, v127, vcc
	v_lshlrev_b32_e32 v127, 2, v127
	ds_bpermute_b32 v127, v127, v126
	s_and_saveexec_b64 s[52:53], s[0:1]
	s_cbranch_execz .LBB0_1688
	v_lshlrev_b64 v[128:129], 6, v[138:139]
	v_readlane_b32 s26, v254, 43
	v_lshl_add_u64 v[128:129], s[30:31], 0, v[128:129]
	v_readlane_b32 s27, v254, 44
	v_lshl_add_u64 v[128:129], s[50:51], 2, v[128:129]
	s_mov_b32 s29, s27
	s_lshl_b32 s28, s65, 2
	v_writelane_b32 v254, s26, 43
	v_lshl_add_u64 v[128:129], v[128:129], 0, s[28:29]
	s_waitcnt lgkmcnt(0)
	v_add_f32_e32 v126, v126, v127
	v_writelane_b32 v254, s27, 44
	global_store_dword v[128:129], v126, off

.LBB0_1690:
	s_nop 1
	v_or_b32_e32 v116, 16, v138
	v_ashrrev_i32_e32 v117, 31, v116
	v_lshlrev_b64 v[114:115], 10, v[116:117]
	v_readlane_b32 s84, v254, 45
	v_lshl_add_u64 v[118:119], v[114:115], 0, v[136:137]
	v_readlane_b32 s90, v254, 51
	v_readlane_b32 s91, v254, 52
	s_and_b64 vcc, exec, s[38:39]
	v_readlane_b32 s85, v254, 46
	v_lshl_add_u64 v[114:115], v[118:119], 2, s[90:91]
	global_load_dwordx4 v[120:123], v[114:115], off
	v_readlane_b32 s86, v254, 47
	v_readlane_b32 s87, v254, 48
	v_readlane_b32 s88, v254, 49
	v_readlane_b32 s89, v254, 50
	s_waitcnt vmcnt(0)
	v_pk_add_f32 v[112:113], v[112:113], v[122:123]
	v_pk_add_f32 v[110:111], v[110:111], v[120:121]
	global_store_dwordx4 v[114:115], v[110:113], off
	s_cbranch_vccnz .LBB0_1729
	v_cvt_pk_bf16_f32 v120, v110, v111
	v_mul_f32_e32 v111, v111, v111
	v_cvt_pk_bf16_f32 v121, v112, v113
	v_lshl_add_u64 v[118:119], v[118:119], 1, s[4:5]
	v_fmac_f32_e32 v111, v110, v110
	v_mul_f32_e32 v110, v113, v113
	global_store_dwordx2 v[118:119], v[120:121], off
	v_fmac_f32_e32 v110, v112, v112
	v_add_f32_e32 v122, v111, v110
	global_load_dwordx4 v[110:113], v[114:115], off offset:64
	s_waitcnt vmcnt(0)
	v_pk_add_f32 v[112:113], v[108:109], v[112:113]
	v_pk_add_f32 v[110:111], v[106:107], v[110:111]
	global_store_dwordx4 v[114:115], v[110:113], off offset:64
	v_cvt_pk_bf16_f32 v120, v110, v111
	v_cvt_pk_bf16_f32 v121, v112, v113
	v_mul_f32_e32 v111, v111, v111
	v_fmac_f32_e32 v111, v110, v110
	v_mul_f32_e32 v110, v113, v113
	v_fmac_f32_e32 v110, v112, v112
	global_store_dwordx2 v[118:119], v[120:121], off offset:32
	v_add_f32_e32 v110, v111, v110
	v_add_f32_e32 v122, v122, v110
	global_load_dwordx4 v[110:113], v[114:115], off offset:512
	s_waitcnt vmcnt(0)
	v_pk_add_f32 v[112:113], v[104:105], v[112:113]
	v_pk_add_f32 v[110:111], v[102:103], v[110:111]
	global_store_dwordx4 v[114:115], v[110:113], off offset:512
	v_cvt_pk_bf16_f32 v120, v110, v111
	v_cvt_pk_bf16_f32 v121, v112, v113
	v_mul_f32_e32 v111, v111, v111
	v_fmac_f32_e32 v111, v110, v110
	v_mul_f32_e32 v110, v113, v113
	v_fmac_f32_e32 v110, v112, v112
	global_store_dwordx2 v[118:119], v[120:121], off offset:256
	v_add_f32_e32 v110, v111, v110
	v_add_f32_e32 v122, v122, v110
	global_load_dwordx4 v[110:113], v[114:115], off offset:576
	s_waitcnt vmcnt(0)
	v_pk_add_f32 v[112:113], v[100:101], v[112:113]
	v_pk_add_f32 v[110:111], v[98:99], v[110:111]
	global_store_dwordx4 v[114:115], v[110:113], off offset:576
	v_cvt_pk_bf16_f32 v120, v110, v111
	v_cvt_pk_bf16_f32 v121, v112, v113
	v_mul_f32_e32 v111, v111, v111
	v_fmac_f32_e32 v111, v110, v110
	v_mul_f32_e32 v110, v113, v113
	v_fmac_f32_e32 v110, v112, v112
	v_and_b32_e32 v112, 64, v197
	v_add_f32_e32 v110, v111, v110
	v_xor_b32_e32 v111, 16, v197
	v_add_u32_e32 v112, 64, v112
	v_cmp_lt_i32_e32 vcc, v111, v112
	v_add_f32_e32 v110, v122, v110
	global_store_dwordx2 v[118:119], v[120:121], off offset:288
	v_cndmask_b32_e32 v111, v197, v111, vcc
	v_lshlrev_b32_e32 v111, 2, v111
	ds_bpermute_b32 v111, v111, v110
	s_waitcnt lgkmcnt(0)
	v_add_f32_e32 v110, v110, v111
	v_xor_b32_e32 v111, 32, v197
	v_cmp_lt_i32_e32 vcc, v111, v112
	s_nop 1
	v_cndmask_b32_e32 v111, v197, v111, vcc
	v_lshlrev_b32_e32 v111, 2, v111
	ds_bpermute_b32 v111, v111, v110
	s_and_saveexec_b64 s[52:53], s[0:1]
	s_cbranch_execz .LBB0_1693
	v_lshlrev_b64 v[112:113], 6, v[116:117]
	v_readlane_b32 s26, v254, 43
	v_lshl_add_u64 v[112:113], s[30:31], 0, v[112:113]
	v_readlane_b32 s27, v254, 44
	v_lshl_add_u64 v[112:113], s[50:51], 2, v[112:113]
	s_mov_b32 s29, s27
	s_lshl_b32 s28, s65, 2
	v_writelane_b32 v254, s26, 43
	v_lshl_add_u64 v[112:113], v[112:113], 0, s[28:29]
	s_waitcnt lgkmcnt(0)
	v_add_f32_e32 v110, v110, v111
	v_writelane_b32 v254, s27, 44
	global_store_dword v[112:113], v110, off

.LBB0_1695:
	s_nop 1
	v_or_b32_e32 v100, 32, v138
	v_ashrrev_i32_e32 v101, 31, v100
	v_lshlrev_b64 v[98:99], 10, v[100:101]
	v_readlane_b32 s84, v254, 45
	v_lshl_add_u64 v[102:103], v[98:99], 0, v[136:137]
	v_readlane_b32 s90, v254, 51
	v_readlane_b32 s91, v254, 52
	s_and_b64 vcc, exec, s[38:39]
	v_readlane_b32 s85, v254, 46
	v_lshl_add_u64 v[98:99], v[102:103], 2, s[90:91]
	global_load_dwordx4 v[104:107], v[98:99], off
	v_readlane_b32 s86, v254, 47
	v_readlane_b32 s87, v254, 48
	v_readlane_b32 s88, v254, 49
	v_readlane_b32 s89, v254, 50
	s_waitcnt vmcnt(0)
	v_pk_add_f32 v[96:97], v[96:97], v[106:107]
	v_pk_add_f32 v[94:95], v[94:95], v[104:105]
	global_store_dwordx4 v[98:99], v[94:97], off
	s_cbranch_vccnz .LBB0_1730
	v_cvt_pk_bf16_f32 v104, v94, v95
	v_mul_f32_e32 v95, v95, v95
	v_cvt_pk_bf16_f32 v105, v96, v97
	v_lshl_add_u64 v[102:103], v[102:103], 1, s[4:5]
	v_fmac_f32_e32 v95, v94, v94
	v_mul_f32_e32 v94, v97, v97
	global_store_dwordx2 v[102:103], v[104:105], off
	v_fmac_f32_e32 v94, v96, v96
	v_add_f32_e32 v106, v95, v94
	global_load_dwordx4 v[94:97], v[98:99], off offset:64
	s_waitcnt vmcnt(0)
	v_pk_add_f32 v[96:97], v[92:93], v[96:97]
	v_pk_add_f32 v[94:95], v[90:91], v[94:95]
	global_store_dwordx4 v[98:99], v[94:97], off offset:64
	v_cvt_pk_bf16_f32 v104, v94, v95
	v_cvt_pk_bf16_f32 v105, v96, v97
	v_mul_f32_e32 v95, v95, v95
	v_fmac_f32_e32 v95, v94, v94
	v_mul_f32_e32 v94, v97, v97
	v_fmac_f32_e32 v94, v96, v96
	global_store_dwordx2 v[102:103], v[104:105], off offset:32
	v_add_f32_e32 v94, v95, v94
	v_add_f32_e32 v106, v106, v94
	global_load_dwordx4 v[94:97], v[98:99], off offset:512
	s_waitcnt vmcnt(0)
	v_pk_add_f32 v[96:97], v[88:89], v[96:97]
	v_pk_add_f32 v[94:95], v[86:87], v[94:95]
	global_store_dwordx4 v[98:99], v[94:97], off offset:512
	v_cvt_pk_bf16_f32 v104, v94, v95
	v_cvt_pk_bf16_f32 v105, v96, v97
	v_mul_f32_e32 v95, v95, v95
	v_fmac_f32_e32 v95, v94, v94
	v_mul_f32_e32 v94, v97, v97
	v_fmac_f32_e32 v94, v96, v96
	global_store_dwordx2 v[102:103], v[104:105], off offset:256
	v_add_f32_e32 v94, v95, v94
	v_add_f32_e32 v106, v106, v94
	global_load_dwordx4 v[94:97], v[98:99], off offset:576
	s_waitcnt vmcnt(0)
	v_pk_add_f32 v[96:97], v[84:85], v[96:97]
	v_pk_add_f32 v[94:95], v[82:83], v[94:95]
	global_store_dwordx4 v[98:99], v[94:97], off offset:576
	v_cvt_pk_bf16_f32 v104, v94, v95
	v_cvt_pk_bf16_f32 v105, v96, v97
	v_mul_f32_e32 v95, v95, v95
	v_fmac_f32_e32 v95, v94, v94
	v_mul_f32_e32 v94, v97, v97
	v_fmac_f32_e32 v94, v96, v96
	v_and_b32_e32 v96, 64, v197
	v_add_f32_e32 v94, v95, v94
	v_xor_b32_e32 v95, 16, v197
	v_add_u32_e32 v96, 64, v96
	v_cmp_lt_i32_e32 vcc, v95, v96
	v_add_f32_e32 v94, v106, v94
	global_store_dwordx2 v[102:103], v[104:105], off offset:288
	v_cndmask_b32_e32 v95, v197, v95, vcc
	v_lshlrev_b32_e32 v95, 2, v95
	ds_bpermute_b32 v95, v95, v94
	s_waitcnt lgkmcnt(0)
	v_add_f32_e32 v94, v94, v95
	v_xor_b32_e32 v95, 32, v197
	v_cmp_lt_i32_e32 vcc, v95, v96
	s_nop 1
	v_cndmask_b32_e32 v95, v197, v95, vcc
	v_lshlrev_b32_e32 v95, 2, v95
	ds_bpermute_b32 v95, v95, v94
	s_and_saveexec_b64 s[52:53], s[0:1]
	s_cbranch_execz .LBB0_1698
	v_lshlrev_b64 v[96:97], 6, v[100:101]
	v_readlane_b32 s26, v254, 43
	v_lshl_add_u64 v[96:97], s[30:31], 0, v[96:97]
	v_readlane_b32 s27, v254, 44
	v_lshl_add_u64 v[96:97], s[50:51], 2, v[96:97]
	s_mov_b32 s29, s27
	s_lshl_b32 s28, s65, 2
	v_writelane_b32 v254, s26, 43
	v_lshl_add_u64 v[96:97], v[96:97], 0, s[28:29]
	s_waitcnt lgkmcnt(0)
	v_add_f32_e32 v94, v94, v95
	v_writelane_b32 v254, s27, 44
	global_store_dword v[96:97], v94, off

.LBB0_1700:
	s_nop 1
	v_or_b32_e32 v84, 48, v138
	v_ashrrev_i32_e32 v85, 31, v84
	v_lshlrev_b64 v[82:83], 10, v[84:85]
	v_readlane_b32 s84, v254, 45
	v_lshl_add_u64 v[86:87], v[82:83], 0, v[136:137]
	v_readlane_b32 s90, v254, 51
	v_readlane_b32 s91, v254, 52
	s_and_b64 vcc, exec, s[38:39]
	v_readlane_b32 s85, v254, 46
	v_lshl_add_u64 v[82:83], v[86:87], 2, s[90:91]
	global_load_dwordx4 v[88:91], v[82:83], off
	v_readlane_b32 s86, v254, 47
	v_readlane_b32 s87, v254, 48
	v_readlane_b32 s88, v254, 49
	v_readlane_b32 s89, v254, 50
	s_waitcnt vmcnt(0)
	v_pk_add_f32 v[80:81], v[80:81], v[90:91]
	v_pk_add_f32 v[78:79], v[78:79], v[88:89]
	global_store_dwordx4 v[82:83], v[78:81], off
	s_cbranch_vccnz .LBB0_1731
	v_cvt_pk_bf16_f32 v88, v78, v79
	v_mul_f32_e32 v79, v79, v79
	v_cvt_pk_bf16_f32 v89, v80, v81
	v_lshl_add_u64 v[86:87], v[86:87], 1, s[4:5]
	v_fmac_f32_e32 v79, v78, v78
	v_mul_f32_e32 v78, v81, v81
	global_store_dwordx2 v[86:87], v[88:89], off
	v_fmac_f32_e32 v78, v80, v80
	v_add_f32_e32 v90, v79, v78
	global_load_dwordx4 v[78:81], v[82:83], off offset:64
	s_waitcnt vmcnt(0)
	v_pk_add_f32 v[80:81], v[76:77], v[80:81]
	v_pk_add_f32 v[78:79], v[74:75], v[78:79]
	global_store_dwordx4 v[82:83], v[78:81], off offset:64
	v_cvt_pk_bf16_f32 v88, v78, v79
	v_cvt_pk_bf16_f32 v89, v80, v81
	v_mul_f32_e32 v79, v79, v79
	v_fmac_f32_e32 v79, v78, v78
	v_mul_f32_e32 v78, v81, v81
	v_fmac_f32_e32 v78, v80, v80
	global_store_dwordx2 v[86:87], v[88:89], off offset:32
	v_add_f32_e32 v78, v79, v78
	v_add_f32_e32 v90, v90, v78
	global_load_dwordx4 v[78:81], v[82:83], off offset:512
	s_waitcnt vmcnt(0)
	v_pk_add_f32 v[80:81], v[72:73], v[80:81]
	v_pk_add_f32 v[78:79], v[70:71], v[78:79]
	global_store_dwordx4 v[82:83], v[78:81], off offset:512
	v_cvt_pk_bf16_f32 v88, v78, v79
	v_cvt_pk_bf16_f32 v89, v80, v81
	v_mul_f32_e32 v79, v79, v79
	v_fmac_f32_e32 v79, v78, v78
	v_mul_f32_e32 v78, v81, v81
	v_fmac_f32_e32 v78, v80, v80
	global_store_dwordx2 v[86:87], v[88:89], off offset:256
	v_add_f32_e32 v78, v79, v78
	v_add_f32_e32 v90, v90, v78
	global_load_dwordx4 v[78:81], v[82:83], off offset:576
	s_waitcnt vmcnt(0)
	v_pk_add_f32 v[80:81], v[68:69], v[80:81]
	v_pk_add_f32 v[78:79], v[66:67], v[78:79]
	global_store_dwordx4 v[82:83], v[78:81], off offset:576
	v_cvt_pk_bf16_f32 v88, v78, v79
	v_cvt_pk_bf16_f32 v89, v80, v81
	v_mul_f32_e32 v79, v79, v79
	v_fmac_f32_e32 v79, v78, v78
	v_mul_f32_e32 v78, v81, v81
	v_fmac_f32_e32 v78, v80, v80
	v_and_b32_e32 v80, 64, v197
	v_add_f32_e32 v78, v79, v78
	v_xor_b32_e32 v79, 16, v197
	v_add_u32_e32 v80, 64, v80
	v_cmp_lt_i32_e32 vcc, v79, v80
	v_add_f32_e32 v78, v90, v78
	global_store_dwordx2 v[86:87], v[88:89], off offset:288
	v_cndmask_b32_e32 v79, v197, v79, vcc
	v_lshlrev_b32_e32 v79, 2, v79
	ds_bpermute_b32 v79, v79, v78
	s_waitcnt lgkmcnt(0)
	v_add_f32_e32 v78, v78, v79
	v_xor_b32_e32 v79, 32, v197
	v_cmp_lt_i32_e32 vcc, v79, v80
	s_nop 1
	v_cndmask_b32_e32 v79, v197, v79, vcc
	v_lshlrev_b32_e32 v79, 2, v79
	ds_bpermute_b32 v79, v79, v78
	s_and_saveexec_b64 s[52:53], s[0:1]
	s_cbranch_execz .LBB0_1703
	v_lshlrev_b64 v[80:81], 6, v[84:85]
	v_readlane_b32 s26, v254, 43
	v_lshl_add_u64 v[80:81], s[30:31], 0, v[80:81]
	v_readlane_b32 s27, v254, 44
	v_lshl_add_u64 v[80:81], s[50:51], 2, v[80:81]
	s_mov_b32 s29, s27
	s_lshl_b32 s28, s65, 2
	v_writelane_b32 v254, s26, 43
	v_lshl_add_u64 v[80:81], v[80:81], 0, s[28:29]
	s_waitcnt lgkmcnt(0)
	v_add_f32_e32 v78, v78, v79
	v_writelane_b32 v254, s27, 44
	global_store_dword v[80:81], v78, off

.LBB0_1705:
	s_nop 1
	v_add_u32_e32 v68, 0x80, v138
	v_ashrrev_i32_e32 v69, 31, v68
	v_lshlrev_b64 v[66:67], 10, v[68:69]
	v_readlane_b32 s84, v254, 45
	v_lshl_add_u64 v[70:71], v[66:67], 0, v[136:137]
	v_readlane_b32 s90, v254, 51
	v_readlane_b32 s91, v254, 52
	s_and_b64 vcc, exec, s[38:39]
	v_readlane_b32 s85, v254, 46
	v_lshl_add_u64 v[66:67], v[70:71], 2, s[90:91]
	global_load_dwordx4 v[72:75], v[66:67], off
	v_readlane_b32 s86, v254, 47
	v_readlane_b32 s87, v254, 48
	v_readlane_b32 s88, v254, 49
	v_readlane_b32 s89, v254, 50
	s_waitcnt vmcnt(0)
	v_pk_add_f32 v[62:63], v[62:63], v[74:75]
	v_pk_add_f32 v[60:61], v[60:61], v[72:73]
	global_store_dwordx4 v[66:67], v[60:63], off
	s_cbranch_vccnz .LBB0_1732
	v_cvt_pk_bf16_f32 v72, v60, v61
	v_mul_f32_e32 v61, v61, v61
	v_cvt_pk_bf16_f32 v73, v62, v63
	v_lshl_add_u64 v[70:71], v[70:71], 1, s[4:5]
	v_fmac_f32_e32 v61, v60, v60
	v_mul_f32_e32 v60, v63, v63
	global_store_dwordx2 v[70:71], v[72:73], off
	v_fmac_f32_e32 v60, v62, v62
	v_add_f32_e32 v74, v61, v60
	global_load_dwordx4 v[60:63], v[66:67], off offset:64
	s_waitcnt vmcnt(0)
	v_pk_add_f32 v[62:63], v[58:59], v[62:63]
	v_pk_add_f32 v[60:61], v[56:57], v[60:61]
	global_store_dwordx4 v[66:67], v[60:63], off offset:64
	v_cvt_pk_bf16_f32 v72, v60, v61
	v_cvt_pk_bf16_f32 v73, v62, v63
	v_mul_f32_e32 v61, v61, v61
	v_fmac_f32_e32 v61, v60, v60
	v_mul_f32_e32 v60, v63, v63
	v_fmac_f32_e32 v60, v62, v62
	global_store_dwordx2 v[70:71], v[72:73], off offset:32
	v_add_f32_e32 v60, v61, v60
	v_add_f32_e32 v74, v74, v60
	global_load_dwordx4 v[60:63], v[66:67], off offset:512
	s_waitcnt vmcnt(0)
	v_pk_add_f32 v[62:63], v[54:55], v[62:63]
	v_pk_add_f32 v[60:61], v[52:53], v[60:61]
	global_store_dwordx4 v[66:67], v[60:63], off offset:512
	v_cvt_pk_bf16_f32 v72, v60, v61
	v_cvt_pk_bf16_f32 v73, v62, v63
	v_mul_f32_e32 v61, v61, v61
	v_fmac_f32_e32 v61, v60, v60
	v_mul_f32_e32 v60, v63, v63
	v_fmac_f32_e32 v60, v62, v62
	global_store_dwordx2 v[70:71], v[72:73], off offset:256
	v_add_f32_e32 v60, v61, v60
	v_add_f32_e32 v74, v74, v60
	global_load_dwordx4 v[60:63], v[66:67], off offset:576
	s_waitcnt vmcnt(0)
	v_pk_add_f32 v[62:63], v[50:51], v[62:63]
	v_pk_add_f32 v[60:61], v[48:49], v[60:61]
	global_store_dwordx4 v[66:67], v[60:63], off offset:576
	v_cvt_pk_bf16_f32 v72, v60, v61
	v_cvt_pk_bf16_f32 v73, v62, v63
	v_mul_f32_e32 v61, v61, v61
	v_fmac_f32_e32 v61, v60, v60
	v_mul_f32_e32 v60, v63, v63
	v_fmac_f32_e32 v60, v62, v62
	v_and_b32_e32 v62, 64, v197
	v_add_f32_e32 v60, v61, v60
	v_xor_b32_e32 v61, 16, v197
	v_add_u32_e32 v62, 64, v62
	v_cmp_lt_i32_e32 vcc, v61, v62
	v_add_f32_e32 v60, v74, v60
	global_store_dwordx2 v[70:71], v[72:73], off offset:288
	v_cndmask_b32_e32 v61, v197, v61, vcc
	v_lshlrev_b32_e32 v61, 2, v61
	ds_bpermute_b32 v61, v61, v60
	s_waitcnt lgkmcnt(0)
	v_add_f32_e32 v60, v60, v61
	v_xor_b32_e32 v61, 32, v197
	v_cmp_lt_i32_e32 vcc, v61, v62
	s_nop 1
	v_cndmask_b32_e32 v61, v197, v61, vcc
	v_lshlrev_b32_e32 v61, 2, v61
	ds_bpermute_b32 v61, v61, v60
	s_and_saveexec_b64 s[52:53], s[0:1]
	s_cbranch_execz .LBB0_1708
	v_lshlrev_b64 v[62:63], 6, v[68:69]
	v_readlane_b32 s26, v254, 43
	v_lshl_add_u64 v[62:63], s[30:31], 0, v[62:63]
	v_readlane_b32 s27, v254, 44
	v_lshl_add_u64 v[62:63], s[50:51], 2, v[62:63]
	s_mov_b32 s29, s27
	s_lshl_b32 s28, s65, 2
	v_writelane_b32 v254, s26, 43
	v_lshl_add_u64 v[62:63], v[62:63], 0, s[28:29]
	s_waitcnt lgkmcnt(0)
	v_add_f32_e32 v60, v60, v61
	v_writelane_b32 v254, s27, 44
	global_store_dword v[62:63], v60, off

.LBB0_1710:
	s_nop 1
	v_add_u32_e32 v50, 0x90, v138
	v_ashrrev_i32_e32 v51, 31, v50
	v_lshlrev_b64 v[48:49], 10, v[50:51]
	v_readlane_b32 s84, v254, 45
	v_lshl_add_u64 v[52:53], v[48:49], 0, v[136:137]
	v_readlane_b32 s90, v254, 51
	v_readlane_b32 s91, v254, 52
	s_and_b64 vcc, exec, s[38:39]
	v_readlane_b32 s85, v254, 46
	v_lshl_add_u64 v[48:49], v[52:53], 2, s[90:91]
	global_load_dwordx4 v[54:57], v[48:49], off
	v_readlane_b32 s86, v254, 47
	v_readlane_b32 s87, v254, 48
	v_readlane_b32 s88, v254, 49
	v_readlane_b32 s89, v254, 50
	s_waitcnt vmcnt(0)
	v_pk_add_f32 v[46:47], v[46:47], v[56:57]
	v_pk_add_f32 v[44:45], v[44:45], v[54:55]
	global_store_dwordx4 v[48:49], v[44:47], off
	s_cbranch_vccnz .LBB0_1733
	v_cvt_pk_bf16_f32 v54, v44, v45
	v_mul_f32_e32 v45, v45, v45
	v_cvt_pk_bf16_f32 v55, v46, v47
	v_lshl_add_u64 v[52:53], v[52:53], 1, s[4:5]
	v_fmac_f32_e32 v45, v44, v44
	v_mul_f32_e32 v44, v47, v47
	global_store_dwordx2 v[52:53], v[54:55], off
	v_fmac_f32_e32 v44, v46, v46
	v_add_f32_e32 v56, v45, v44
	global_load_dwordx4 v[44:47], v[48:49], off offset:64
	s_waitcnt vmcnt(0)
	v_pk_add_f32 v[46:47], v[42:43], v[46:47]
	v_pk_add_f32 v[44:45], v[40:41], v[44:45]
	global_store_dwordx4 v[48:49], v[44:47], off offset:64
	v_cvt_pk_bf16_f32 v54, v44, v45
	v_cvt_pk_bf16_f32 v55, v46, v47
	v_mul_f32_e32 v45, v45, v45
	v_fmac_f32_e32 v45, v44, v44
	v_mul_f32_e32 v44, v47, v47
	v_fmac_f32_e32 v44, v46, v46
	global_store_dwordx2 v[52:53], v[54:55], off offset:32
	v_add_f32_e32 v44, v45, v44
	v_add_f32_e32 v56, v56, v44
	global_load_dwordx4 v[44:47], v[48:49], off offset:512
	s_waitcnt vmcnt(0)
	v_pk_add_f32 v[46:47], v[38:39], v[46:47]
	v_pk_add_f32 v[44:45], v[36:37], v[44:45]
	global_store_dwordx4 v[48:49], v[44:47], off offset:512
	v_cvt_pk_bf16_f32 v54, v44, v45
	v_cvt_pk_bf16_f32 v55, v46, v47
	v_mul_f32_e32 v45, v45, v45
	v_fmac_f32_e32 v45, v44, v44
	v_mul_f32_e32 v44, v47, v47
	v_fmac_f32_e32 v44, v46, v46
	global_store_dwordx2 v[52:53], v[54:55], off offset:256
	v_add_f32_e32 v44, v45, v44
	v_add_f32_e32 v56, v56, v44
	global_load_dwordx4 v[44:47], v[48:49], off offset:576
	s_waitcnt vmcnt(0)
	v_pk_add_f32 v[46:47], v[34:35], v[46:47]
	v_pk_add_f32 v[44:45], v[32:33], v[44:45]
	global_store_dwordx4 v[48:49], v[44:47], off offset:576
	v_cvt_pk_bf16_f32 v54, v44, v45
	v_cvt_pk_bf16_f32 v55, v46, v47
	v_mul_f32_e32 v45, v45, v45
	v_fmac_f32_e32 v45, v44, v44
	v_mul_f32_e32 v44, v47, v47
	v_fmac_f32_e32 v44, v46, v46
	v_and_b32_e32 v46, 64, v197
	v_add_f32_e32 v44, v45, v44
	v_xor_b32_e32 v45, 16, v197
	v_add_u32_e32 v46, 64, v46
	v_cmp_lt_i32_e32 vcc, v45, v46
	v_add_f32_e32 v44, v56, v44
	global_store_dwordx2 v[52:53], v[54:55], off offset:288
	v_cndmask_b32_e32 v45, v197, v45, vcc
	v_lshlrev_b32_e32 v45, 2, v45
	ds_bpermute_b32 v45, v45, v44
	s_waitcnt lgkmcnt(0)
	v_add_f32_e32 v44, v44, v45
	v_xor_b32_e32 v45, 32, v197
	v_cmp_lt_i32_e32 vcc, v45, v46
	s_nop 1
	v_cndmask_b32_e32 v45, v197, v45, vcc
	v_lshlrev_b32_e32 v45, 2, v45
	ds_bpermute_b32 v45, v45, v44
	s_and_saveexec_b64 s[52:53], s[0:1]
	s_cbranch_execz .LBB0_1713
	v_lshlrev_b64 v[46:47], 6, v[50:51]
	v_readlane_b32 s26, v254, 43
	v_lshl_add_u64 v[46:47], s[30:31], 0, v[46:47]
	v_readlane_b32 s27, v254, 44
	v_lshl_add_u64 v[46:47], s[50:51], 2, v[46:47]
	s_mov_b32 s29, s27
	s_lshl_b32 s28, s65, 2
	v_writelane_b32 v254, s26, 43
	v_lshl_add_u64 v[46:47], v[46:47], 0, s[28:29]
	s_waitcnt lgkmcnt(0)
	v_add_f32_e32 v44, v44, v45
	v_writelane_b32 v254, s27, 44
	global_store_dword v[46:47], v44, off

.LBB0_1715:
	s_nop 1
	v_add_u32_e32 v34, 0xa0, v138
	v_ashrrev_i32_e32 v35, 31, v34
	v_lshlrev_b64 v[32:33], 10, v[34:35]
	v_readlane_b32 s84, v254, 45
	v_lshl_add_u64 v[36:37], v[32:33], 0, v[136:137]
	v_readlane_b32 s90, v254, 51
	v_readlane_b32 s91, v254, 52
	s_and_b64 vcc, exec, s[38:39]
	v_readlane_b32 s85, v254, 46
	v_lshl_add_u64 v[32:33], v[36:37], 2, s[90:91]
	global_load_dwordx4 v[38:41], v[32:33], off
	v_readlane_b32 s86, v254, 47
	v_readlane_b32 s87, v254, 48
	v_readlane_b32 s88, v254, 49
	v_readlane_b32 s89, v254, 50
	s_waitcnt vmcnt(0)
	v_pk_add_f32 v[30:31], v[30:31], v[40:41]
	v_pk_add_f32 v[28:29], v[28:29], v[38:39]
	global_store_dwordx4 v[32:33], v[28:31], off
	s_cbranch_vccnz .LBB0_1734
	v_cvt_pk_bf16_f32 v38, v28, v29
	v_mul_f32_e32 v29, v29, v29
	v_cvt_pk_bf16_f32 v39, v30, v31
	v_lshl_add_u64 v[36:37], v[36:37], 1, s[4:5]
	v_fmac_f32_e32 v29, v28, v28
	v_mul_f32_e32 v28, v31, v31
	global_store_dwordx2 v[36:37], v[38:39], off
	v_fmac_f32_e32 v28, v30, v30
	v_add_f32_e32 v40, v29, v28
	global_load_dwordx4 v[28:31], v[32:33], off offset:64
	s_waitcnt vmcnt(0)
	v_pk_add_f32 v[30:31], v[26:27], v[30:31]
	v_pk_add_f32 v[28:29], v[24:25], v[28:29]
	global_store_dwordx4 v[32:33], v[28:31], off offset:64
	v_cvt_pk_bf16_f32 v38, v28, v29
	v_cvt_pk_bf16_f32 v39, v30, v31
	v_mul_f32_e32 v29, v29, v29
	v_fmac_f32_e32 v29, v28, v28
	v_mul_f32_e32 v28, v31, v31
	v_fmac_f32_e32 v28, v30, v30
	global_store_dwordx2 v[36:37], v[38:39], off offset:32
	v_add_f32_e32 v28, v29, v28
	v_add_f32_e32 v40, v40, v28
	global_load_dwordx4 v[28:31], v[32:33], off offset:512
	s_waitcnt vmcnt(0)
	v_pk_add_f32 v[30:31], v[22:23], v[30:31]
	v_pk_add_f32 v[28:29], v[20:21], v[28:29]
	global_store_dwordx4 v[32:33], v[28:31], off offset:512
	v_cvt_pk_bf16_f32 v38, v28, v29
	v_cvt_pk_bf16_f32 v39, v30, v31
	v_mul_f32_e32 v29, v29, v29
	v_fmac_f32_e32 v29, v28, v28
	v_mul_f32_e32 v28, v31, v31
	v_fmac_f32_e32 v28, v30, v30
	global_store_dwordx2 v[36:37], v[38:39], off offset:256
	v_add_f32_e32 v28, v29, v28
	v_add_f32_e32 v40, v40, v28
	global_load_dwordx4 v[28:31], v[32:33], off offset:576
	s_waitcnt vmcnt(0)
	v_pk_add_f32 v[30:31], v[18:19], v[30:31]
	v_pk_add_f32 v[28:29], v[16:17], v[28:29]
	global_store_dwordx4 v[32:33], v[28:31], off offset:576
	v_cvt_pk_bf16_f32 v38, v28, v29
	v_cvt_pk_bf16_f32 v39, v30, v31
	v_mul_f32_e32 v29, v29, v29
	v_fmac_f32_e32 v29, v28, v28
	v_mul_f32_e32 v28, v31, v31
	v_fmac_f32_e32 v28, v30, v30
	v_and_b32_e32 v30, 64, v197
	v_add_f32_e32 v28, v29, v28
	v_xor_b32_e32 v29, 16, v197
	v_add_u32_e32 v30, 64, v30
	v_cmp_lt_i32_e32 vcc, v29, v30
	v_add_f32_e32 v28, v40, v28
	global_store_dwordx2 v[36:37], v[38:39], off offset:288
	v_cndmask_b32_e32 v29, v197, v29, vcc
	v_lshlrev_b32_e32 v29, 2, v29
	ds_bpermute_b32 v29, v29, v28
	s_waitcnt lgkmcnt(0)
	v_add_f32_e32 v28, v28, v29
	v_xor_b32_e32 v29, 32, v197
	v_cmp_lt_i32_e32 vcc, v29, v30
	s_nop 1
	v_cndmask_b32_e32 v29, v197, v29, vcc
	v_lshlrev_b32_e32 v29, 2, v29
	ds_bpermute_b32 v29, v29, v28
	s_and_saveexec_b64 s[52:53], s[0:1]
	s_cbranch_execz .LBB0_1718
	v_lshlrev_b64 v[30:31], 6, v[34:35]
	v_readlane_b32 s26, v254, 43
	v_lshl_add_u64 v[30:31], s[30:31], 0, v[30:31]
	v_readlane_b32 s27, v254, 44
	v_lshl_add_u64 v[30:31], s[50:51], 2, v[30:31]
	s_mov_b32 s29, s27
	s_lshl_b32 s28, s65, 2
	v_writelane_b32 v254, s26, 43
	v_lshl_add_u64 v[30:31], v[30:31], 0, s[28:29]
	s_waitcnt lgkmcnt(0)
	v_add_f32_e32 v28, v28, v29
	v_writelane_b32 v254, s27, 44
	global_store_dword v[30:31], v28, off

.LBB0_1720:
	s_nop 1
	v_add_u32_e32 v18, 0xb0, v138
	v_ashrrev_i32_e32 v19, 31, v18
	v_lshlrev_b64 v[16:17], 10, v[18:19]
	v_readlane_b32 s84, v254, 45
	v_lshl_add_u64 v[20:21], v[16:17], 0, v[136:137]
	v_readlane_b32 s90, v254, 51
	v_readlane_b32 s91, v254, 52
	s_and_b64 vcc, exec, s[38:39]
	v_readlane_b32 s85, v254, 46
	v_lshl_add_u64 v[16:17], v[20:21], 2, s[90:91]
	global_load_dwordx4 v[22:25], v[16:17], off
	v_readlane_b32 s86, v254, 47
	v_readlane_b32 s87, v254, 48
	v_readlane_b32 s88, v254, 49
	v_readlane_b32 s89, v254, 50
	s_waitcnt vmcnt(0)
	v_pk_add_f32 v[14:15], v[14:15], v[24:25]
	v_pk_add_f32 v[12:13], v[12:13], v[22:23]
	global_store_dwordx4 v[16:17], v[12:15], off
	s_cbranch_vccnz .LBB0_1735
	v_cvt_pk_bf16_f32 v22, v12, v13
	v_mul_f32_e32 v13, v13, v13
	v_cvt_pk_bf16_f32 v23, v14, v15
	v_lshl_add_u64 v[20:21], v[20:21], 1, s[4:5]
	v_fmac_f32_e32 v13, v12, v12
	v_mul_f32_e32 v12, v15, v15
	global_store_dwordx2 v[20:21], v[22:23], off
	v_fmac_f32_e32 v12, v14, v14
	v_add_f32_e32 v24, v13, v12
	global_load_dwordx4 v[12:15], v[16:17], off offset:64
	s_waitcnt vmcnt(0)
	v_pk_add_f32 v[14:15], v[10:11], v[14:15]
	v_pk_add_f32 v[12:13], v[8:9], v[12:13]
	global_store_dwordx4 v[16:17], v[12:15], off offset:64
	v_cvt_pk_bf16_f32 v22, v12, v13
	v_cvt_pk_bf16_f32 v23, v14, v15
	v_mul_f32_e32 v13, v13, v13
	v_fmac_f32_e32 v13, v12, v12
	v_mul_f32_e32 v12, v15, v15
	v_fmac_f32_e32 v12, v14, v14
	global_store_dwordx2 v[20:21], v[22:23], off offset:32
	v_add_f32_e32 v12, v13, v12
	v_add_f32_e32 v24, v24, v12
	global_load_dwordx4 v[12:15], v[16:17], off offset:512
	s_waitcnt vmcnt(0)
	v_pk_add_f32 v[14:15], v[6:7], v[14:15]
	v_pk_add_f32 v[12:13], v[4:5], v[12:13]
	global_store_dwordx4 v[16:17], v[12:15], off offset:512
	v_cvt_pk_bf16_f32 v22, v12, v13
	v_cvt_pk_bf16_f32 v23, v14, v15
	v_mul_f32_e32 v13, v13, v13
	v_fmac_f32_e32 v13, v12, v12
	v_mul_f32_e32 v12, v15, v15
	v_fmac_f32_e32 v12, v14, v14
	global_store_dwordx2 v[20:21], v[22:23], off offset:256
	v_add_f32_e32 v12, v13, v12
	v_add_f32_e32 v24, v24, v12
	global_load_dwordx4 v[12:15], v[16:17], off offset:576
	s_waitcnt vmcnt(0)
	v_pk_add_f32 v[14:15], v[2:3], v[14:15]
	v_pk_add_f32 v[12:13], v[0:1], v[12:13]
	global_store_dwordx4 v[16:17], v[12:15], off offset:576
	v_cvt_pk_bf16_f32 v22, v12, v13
	v_cvt_pk_bf16_f32 v23, v14, v15
	v_mul_f32_e32 v13, v13, v13
	v_fmac_f32_e32 v13, v12, v12
	v_mul_f32_e32 v12, v15, v15
	v_fmac_f32_e32 v12, v14, v14
	v_and_b32_e32 v14, 64, v197
	v_add_f32_e32 v12, v13, v12
	v_xor_b32_e32 v13, 16, v197
	v_add_u32_e32 v14, 64, v14
	v_cmp_lt_i32_e32 vcc, v13, v14
	v_add_f32_e32 v12, v24, v12
	global_store_dwordx2 v[20:21], v[22:23], off offset:288
	v_cndmask_b32_e32 v13, v197, v13, vcc
	v_lshlrev_b32_e32 v13, 2, v13
	ds_bpermute_b32 v13, v13, v12
	s_waitcnt lgkmcnt(0)
	v_add_f32_e32 v12, v12, v13
	v_xor_b32_e32 v13, 32, v197
	v_cmp_lt_i32_e32 vcc, v13, v14
	s_nop 1
	v_cndmask_b32_e32 v13, v197, v13, vcc
	v_lshlrev_b32_e32 v13, 2, v13
	ds_bpermute_b32 v13, v13, v12
	s_and_saveexec_b64 s[38:39], s[0:1]
	s_cbranch_execz .LBB0_1723
	v_lshlrev_b64 v[14:15], 6, v[18:19]
	v_readlane_b32 s26, v254, 43
	v_lshl_add_u64 v[14:15], s[30:31], 0, v[14:15]
	v_readlane_b32 s27, v254, 44
	v_lshl_add_u64 v[14:15], s[50:51], 2, v[14:15]
	s_mov_b32 s29, s27
	s_lshl_b32 s28, s65, 2
	v_writelane_b32 v254, s26, 43
	v_lshl_add_u64 v[14:15], v[14:15], 0, s[28:29]
	s_waitcnt lgkmcnt(0)
	v_add_f32_e32 v12, v12, v13
	v_writelane_b32 v254, s27, 44
	global_store_dword v[14:15], v12, off
